# GEMM K-loops: the mid-phase s_setprio 0 / s_setprio 1 toggle pair removed, priority stays raised across each phase's 32 MFMAs
# speedup vs baseline: 1.0028x; 1.0028x over previous
; #define PG8_STAGE(bufoff, gbase, voff) do { _Pragma("unroll") for (int _i = 0; _i < 2; ++_i) \
;         __builtin_amdgcn_global_load_lds((const unsigned*)((const char*)(gbase) + (voff)[_i]), (PG8_LAS unsigned*)(lds + (bufoff) + ldsw + _i * 8192), 16, 0, 0); } while (0)
; #define PG8_LDA(dst, b, h) do { _Pragma("unroll") for (int m = 0; m < 4; ++m) _Pragma("unroll") for (int k = 0; k < 2; ++k) dst[m][k] = *(const PG8_LAS bf16x8*)(lds + PG8_SA(b, h) + aoff + m * 2048 + k * 1024); } while (0)
; #define PG8_LDB(dst, b, h) do { _Pragma("unroll") for (int n = 0; n < 2; ++n) _Pragma("unroll") for (int k = 0; k < 2; ++k) dst[n][k] = *(const PG8_LAS bf16x8*)(lds + PG8_SB(b, h) + boff + n * 2048 + k * 1024); } while (0)
; #define PG8_MMA(ai, bj, At, Bt) do { __builtin_amdgcn_s_setprio(1); _Pragma("unroll") for (int m = 0; m < 4; ++m) _Pragma("unroll") for (int n = 0; n < 2; ++n) _Pragma("unroll") for (int k = 0; k < 2; ++k) \
;         acc[ai][bj][m][n] = __builtin_amdgcn_mfma_f32_16x16x32_bf16(Bt[n][k], At[m][k], acc[ai][bj][m][n], 0, 0, 0); __builtin_amdgcn_s_setprio(0); } while (0)
; #define PG8_WAIT_V(n) asm volatile("s_waitcnt vmcnt(" #n ")" ::: "memory")
; #define PG8_WAIT_L(n) asm volatile("s_waitcnt lgkmcnt(" #n ")" ::: "memory")
; #define PG8_BAR __builtin_amdgcn_s_barrier()
; #define PG8_SCHED __builtin_amdgcn_sched_barrier(0)
; template <class Epi, class Sched>
; __device__ __forceinline__ void gemm_phase(PG8_LAS unsigned char* lds, const Gemm g, const Sched& S, const Epi& E) {
;     ...
;             PG8_LDB(B0, 0, 0); PG8_LDB(B1, 0, 1); PG8_SCHED; PG8_LDA(At, 0, 0); PG8_STAGE(PG8_SA(1, 1), a1 + hstepA, voffA);
;             PG8_WAIT_V(8); PG8_WAIT_L(0); PG8_BAR; PG8_MMA(0, 0, At, B0); PG8_MMA(0, 1, At, B1); PG8_BAR; PG8_SCHED;
;             PG8_LDA(At, 0, 1); PG8_STAGE(PG8_SB(0, 0), b2, voffB); PG8_STAGE(PG8_SB(0, 1), b2 + hstepB, voffB); PG8_STAGE(PG8_SA(0, 0), a2, voffA);
;             PG8_WAIT_V(8); PG8_WAIT_L(0); PG8_BAR; PG8_MMA(1, 0, At, B0); PG8_MMA(1, 1, At, B1); PG8_BAR; PG8_SCHED;
.LBB0_1379:
	ds_read_b128 v[152:155], v149
	ds_read_b128 v[156:159], v149 offset:1024
	ds_read_b128 v[160:163], v149 offset:2048
	ds_read_b128 v[164:167], v149 offset:3072
	ds_read_b128 v[168:171], v150
	ds_read_b128 v[172:175], v150 offset:1024
	ds_read_b128 v[176:179], v150 offset:2048
	ds_read_b128 v[180:183], v150 offset:3072
	s_add_u32 s44, s42, 0xfffc0080
	s_addc_u32 s45, s43, -1
	s_cmp_eq_u32 s66, 12
	s_cselect_b32 s47, s15, s45
	s_cselect_b32 s46, s29, s44
	s_cselect_b32 s45, s62, s65
	s_cselect_b32 s44, s63, s64
	v_lshl_add_u64 v[144:145], s[42:43], 0, v[136:137]
	s_add_i32 m0, s41, 0xc000
	ds_read_b128 v[184:187], v151
	ds_read_b128 v[188:191], v151 offset:1024
	ds_read_b128 v[192:195], v151 offset:2048
	ds_read_b128 v[200:203], v151 offset:3072
	ds_read_b128 v[204:207], v151 offset:4096
	ds_read_b128 v[208:211], v151 offset:5120
	ds_read_b128 v[212:215], v151 offset:6144
	ds_read_b128 v[216:219], v151 offset:7168
	global_load_lds_dwordx4 v[144:145], off
	v_lshl_add_u64 v[144:145], s[42:43], 0, v[138:139]
	s_add_i32 m0, s41, 0xe000
	s_nop 0
	global_load_lds_dwordx4 v[144:145], off
	s_waitcnt vmcnt(8)
	s_waitcnt lgkmcnt(0)
	s_barrier
	s_setprio 1
	s_waitcnt lgkmcnt(0)
	v_mfma_f32_16x16x32_bf16 v[124:127], v[152:155], v[184:187], v[124:127]
	v_mfma_f32_16x16x32_bf16 v[120:123], v[160:163], v[184:187], v[120:123]
	v_mfma_f32_16x16x32_bf16 v[108:111], v[152:155], v[192:195], v[108:111]
	v_mfma_f32_16x16x32_bf16 v[104:107], v[160:163], v[192:195], v[104:107]
	v_mfma_f32_16x16x32_bf16 v[92:95], v[152:155], v[204:207], v[92:95]
	v_mfma_f32_16x16x32_bf16 v[88:91], v[160:163], v[204:207], v[88:91]
	v_mfma_f32_16x16x32_bf16 v[76:79], v[152:155], v[212:215], v[76:79]
	v_mfma_f32_16x16x32_bf16 v[72:75], v[160:163], v[212:215], v[72:75]
	v_mfma_f32_16x16x32_bf16 v[124:127], v[156:159], v[188:191], v[124:127]
	v_mfma_f32_16x16x32_bf16 v[120:123], v[164:167], v[188:191], v[120:123]
	v_mfma_f32_16x16x32_bf16 v[108:111], v[156:159], v[200:203], v[108:111]
	v_mfma_f32_16x16x32_bf16 v[104:107], v[164:167], v[200:203], v[104:107]
	v_mfma_f32_16x16x32_bf16 v[92:95], v[156:159], v[208:211], v[92:95]
	v_mfma_f32_16x16x32_bf16 v[88:91], v[164:167], v[208:211], v[88:91]
	v_mfma_f32_16x16x32_bf16 v[76:79], v[156:159], v[216:219], v[76:79]
	v_mfma_f32_16x16x32_bf16 v[72:75], v[164:167], v[216:219], v[72:75]
	v_mfma_f32_16x16x32_bf16 v[116:119], v[168:171], v[184:187], v[116:119]
	v_mfma_f32_16x16x32_bf16 v[112:115], v[176:179], v[184:187], v[112:115]
	v_mfma_f32_16x16x32_bf16 v[100:103], v[168:171], v[192:195], v[100:103]
	v_mfma_f32_16x16x32_bf16 v[96:99], v[176:179], v[192:195], v[96:99]
	v_mfma_f32_16x16x32_bf16 v[84:87], v[168:171], v[204:207], v[84:87]
	v_mfma_f32_16x16x32_bf16 v[80:83], v[176:179], v[204:207], v[80:83]
	v_mfma_f32_16x16x32_bf16 v[68:71], v[168:171], v[212:215], v[68:71]
	v_mfma_f32_16x16x32_bf16 v[64:67], v[176:179], v[212:215], v[64:67]
	v_mfma_f32_16x16x32_bf16 v[116:119], v[172:175], v[188:191], v[116:119]
	v_mfma_f32_16x16x32_bf16 v[112:115], v[180:183], v[188:191], v[112:115]
	v_mfma_f32_16x16x32_bf16 v[100:103], v[172:175], v[200:203], v[100:103]
	v_mfma_f32_16x16x32_bf16 v[96:99], v[180:183], v[200:203], v[96:99]
	v_mfma_f32_16x16x32_bf16 v[84:87], v[172:175], v[208:211], v[84:87]
	v_mfma_f32_16x16x32_bf16 v[80:83], v[180:183], v[208:211], v[80:83]
	v_mfma_f32_16x16x32_bf16 v[68:71], v[172:175], v[216:219], v[68:71]
	v_mfma_f32_16x16x32_bf16 v[64:67], v[180:183], v[216:219], v[64:67]
	s_setprio 0
	s_barrier
	s_add_i32 s67, s58, s33
	v_lshl_add_u64 v[144:145], s[44:45], 0, v[132:133]
	s_mov_b32 m0, s67
	ds_read_b128 v[184:187], v151 offset:16384
	ds_read_b128 v[188:191], v151 offset:17408
	ds_read_b128 v[192:195], v151 offset:18432
	ds_read_b128 v[200:203], v151 offset:19456
	ds_read_b128 v[204:207], v151 offset:20480
	ds_read_b128 v[208:211], v151 offset:21504
	ds_read_b128 v[212:215], v151 offset:22528
	ds_read_b128 v[216:219], v151 offset:23552
	global_load_lds_dwordx4 v[144:145], off
	s_add_i32 m0, s67, 0x2000
	s_add_u32 s68, s44, 0x40000
	v_lshl_add_u64 v[196:197], s[44:45], 0, v[128:129]
	s_addc_u32 s69, s45, 0
	s_add_i32 s67, s59, s33
	global_load_lds_dwordx4 v[196:197], off
	v_lshl_add_u64 v[220:221], s[68:69], 0, v[132:133]
	s_mov_b32 m0, s67
	v_lshl_add_u64 v[222:223], s[46:47], 0, v[130:131]
	global_load_lds_dwordx4 v[220:221], off
	v_lshl_add_u64 v[220:221], s[68:69], 0, v[128:129]
	s_add_i32 m0, s67, 0x2000
	s_nop 0
	global_load_lds_dwordx4 v[220:221], off
	v_lshl_add_u64 v[220:221], s[46:47], 0, v[134:135]
	s_mov_b32 m0, s41
	s_nop 0
	global_load_lds_dwordx4 v[220:221], off
	s_mov_b32 m0, s50
	s_nop 0
	global_load_lds_dwordx4 v[222:223], off
	s_waitcnt vmcnt(8)
	s_waitcnt lgkmcnt(0)
	s_barrier
; #define PG8_STAGE(bufoff, gbase, voff) do { _Pragma("unroll") for (int _i = 0; _i < 2; ++_i) \
;         __builtin_amdgcn_global_load_lds((const unsigned*)((const char*)(gbase) + (voff)[_i]), (PG8_LAS unsigned*)(lds + (bufoff) + ldsw + _i * 8192), 16, 0, 0); } while (0)
; #define PG8_LDA(dst, b, h) do { _Pragma("unroll") for (int m = 0; m < 4; ++m) _Pragma("unroll") for (int k = 0; k < 2; ++k) dst[m][k] = *(const PG8_LAS bf16x8*)(lds + PG8_SA(b, h) + aoff + m * 2048 + k * 1024); } while (0)
; #define PG8_LDB(dst, b, h) do { _Pragma("unroll") for (int n = 0; n < 2; ++n) _Pragma("unroll") for (int k = 0; k < 2; ++k) dst[n][k] = *(const PG8_LAS bf16x8*)(lds + PG8_SB(b, h) + boff + n * 2048 + k * 1024); } while (0)
; #define PG8_MMA(ai, bj, At, Bt) do { __builtin_amdgcn_s_setprio(1); _Pragma("unroll") for (int m = 0; m < 4; ++m) _Pragma("unroll") for (int n = 0; n < 2; ++n) _Pragma("unroll") for (int k = 0; k < 2; ++k) \
;         acc[ai][bj][m][n] = __builtin_amdgcn_mfma_f32_16x16x32_bf16(Bt[n][k], At[m][k], acc[ai][bj][m][n], 0, 0, 0); __builtin_amdgcn_s_setprio(0); } while (0)
; #define PG8_WAIT_V(n) asm volatile("s_waitcnt vmcnt(" #n ")" ::: "memory")
; #define PG8_WAIT_L(n) asm volatile("s_waitcnt lgkmcnt(" #n ")" ::: "memory")
; #define PG8_BAR __builtin_amdgcn_s_barrier()
; #define PG8_SCHED __builtin_amdgcn_sched_barrier(0)
; template <class Epi, class Sched>
; __device__ __forceinline__ void gemm_phase(PG8_LAS unsigned char* lds, const Gemm g, const Sched& S, const Epi& E) {
;     ...
;             PG8_WAIT_V(8); PG8_WAIT_L(0); PG8_BAR; PG8_MMA(1, 0, At, B0); PG8_MMA(1, 1, At, B1); PG8_BAR; PG8_SCHED;
;             PG8_LDB(B0, 1, 0); PG8_LDB(B1, 1, 1); PG8_SCHED; PG8_LDA(At, 1, 0); PG8_STAGE(PG8_SA(0, 1), a2 + hstepA, voffA);
;             PG8_WAIT_V(8); PG8_WAIT_L(0); PG8_BAR; PG8_MMA(0, 0, At, B0); PG8_MMA(0, 1, At, B1); PG8_BAR; PG8_SCHED;
	s_setprio 1
	s_waitcnt lgkmcnt(0)
	v_mfma_f32_16x16x32_bf16 v[60:63], v[152:155], v[184:187], v[60:63]
	v_mfma_f32_16x16x32_bf16 v[56:59], v[160:163], v[184:187], v[56:59]
	v_mfma_f32_16x16x32_bf16 v[44:47], v[152:155], v[192:195], v[44:47]
	v_mfma_f32_16x16x32_bf16 v[40:43], v[160:163], v[192:195], v[40:43]
	v_mfma_f32_16x16x32_bf16 v[28:31], v[152:155], v[204:207], v[28:31]
	v_mfma_f32_16x16x32_bf16 v[24:27], v[160:163], v[204:207], v[24:27]
	v_mfma_f32_16x16x32_bf16 v[12:15], v[152:155], v[212:215], v[12:15]
	v_mfma_f32_16x16x32_bf16 v[8:11], v[160:163], v[212:215], v[8:11]
	v_mfma_f32_16x16x32_bf16 v[60:63], v[156:159], v[188:191], v[60:63]
	v_mfma_f32_16x16x32_bf16 v[56:59], v[164:167], v[188:191], v[56:59]
	v_mfma_f32_16x16x32_bf16 v[44:47], v[156:159], v[200:203], v[44:47]
	v_mfma_f32_16x16x32_bf16 v[40:43], v[164:167], v[200:203], v[40:43]
	v_mfma_f32_16x16x32_bf16 v[28:31], v[156:159], v[208:211], v[28:31]
	v_mfma_f32_16x16x32_bf16 v[24:27], v[164:167], v[208:211], v[24:27]
	v_mfma_f32_16x16x32_bf16 v[12:15], v[156:159], v[216:219], v[12:15]
	v_mfma_f32_16x16x32_bf16 v[8:11], v[164:167], v[216:219], v[8:11]
	v_mfma_f32_16x16x32_bf16 v[52:55], v[168:171], v[184:187], v[52:55]
	v_mfma_f32_16x16x32_bf16 v[48:51], v[176:179], v[184:187], v[48:51]
	v_mfma_f32_16x16x32_bf16 v[36:39], v[168:171], v[192:195], v[36:39]
	v_mfma_f32_16x16x32_bf16 v[32:35], v[176:179], v[192:195], v[32:35]
	v_mfma_f32_16x16x32_bf16 v[20:23], v[168:171], v[204:207], v[20:23]
	v_mfma_f32_16x16x32_bf16 v[16:19], v[176:179], v[204:207], v[16:19]
	v_mfma_f32_16x16x32_bf16 v[4:7], v[168:171], v[212:215], v[4:7]
	v_mfma_f32_16x16x32_bf16 v[0:3], v[176:179], v[212:215], v[0:3]
	v_mfma_f32_16x16x32_bf16 v[52:55], v[172:175], v[188:191], v[52:55]
	v_mfma_f32_16x16x32_bf16 v[48:51], v[180:183], v[188:191], v[48:51]
	v_mfma_f32_16x16x32_bf16 v[36:39], v[172:175], v[200:203], v[36:39]
	v_mfma_f32_16x16x32_bf16 v[32:35], v[180:183], v[200:203], v[32:35]
	v_mfma_f32_16x16x32_bf16 v[20:23], v[172:175], v[208:211], v[20:23]
	v_mfma_f32_16x16x32_bf16 v[16:19], v[180:183], v[208:211], v[16:19]
	v_mfma_f32_16x16x32_bf16 v[4:7], v[172:175], v[216:219], v[4:7]
	v_mfma_f32_16x16x32_bf16 v[0:3], v[180:183], v[216:219], v[0:3]
	s_setprio 0
	s_barrier
	s_add_i32 s67, 0, 0x18000
	s_add_i32 s68, 0, 0x1c000
	v_add_u32_e32 v164, s67, v147
	v_add_u32_e32 v180, s68, v147
	ds_read_b128 v[152:155], v164
	ds_read_b128 v[156:159], v164 offset:1024
	ds_read_b128 v[160:163], v164 offset:2048
	ds_read_b128 v[164:167], v164 offset:3072
	ds_read_b128 v[168:171], v180
	ds_read_b128 v[172:175], v180 offset:1024
	ds_read_b128 v[176:179], v180 offset:2048
	ds_read_b128 v[180:183], v180 offset:3072
	s_add_u32 s46, s46, 0x40000
	s_addc_u32 s47, s47, 0
	s_mov_b32 m0, s51
	v_lshl_add_u64 v[224:225], s[46:47], 0, v[134:135]
	ds_read_b128 v[184:187], v151 offset:32768
	ds_read_b128 v[188:191], v151 offset:33792
	ds_read_b128 v[192:195], v151 offset:34816
	ds_read_b128 v[200:203], v151 offset:35840
	ds_read_b128 v[204:207], v151 offset:36864
	ds_read_b128 v[208:211], v151 offset:37888
	ds_read_b128 v[212:215], v151 offset:38912
	ds_read_b128 v[216:219], v151 offset:39936
	global_load_lds_dwordx4 v[224:225], off
	v_lshl_add_u64 v[224:225], s[46:47], 0, v[130:131]
	s_mov_b32 m0, s52
	s_nop 0
	global_load_lds_dwordx4 v[224:225], off
	s_waitcnt vmcnt(8)
	s_waitcnt lgkmcnt(0)
	s_barrier
	s_setprio 1
	s_waitcnt lgkmcnt(0)
	v_mfma_f32_16x16x32_bf16 v[124:127], v[152:155], v[184:187], v[124:127]
	v_mfma_f32_16x16x32_bf16 v[120:123], v[160:163], v[184:187], v[120:123]
	v_mfma_f32_16x16x32_bf16 v[108:111], v[152:155], v[192:195], v[108:111]
	v_mfma_f32_16x16x32_bf16 v[104:107], v[160:163], v[192:195], v[104:107]
	v_mfma_f32_16x16x32_bf16 v[92:95], v[152:155], v[204:207], v[92:95]
	v_mfma_f32_16x16x32_bf16 v[88:91], v[160:163], v[204:207], v[88:91]
	v_mfma_f32_16x16x32_bf16 v[76:79], v[152:155], v[212:215], v[76:79]
	v_mfma_f32_16x16x32_bf16 v[72:75], v[160:163], v[212:215], v[72:75]
	v_mfma_f32_16x16x32_bf16 v[124:127], v[156:159], v[188:191], v[124:127]
	v_mfma_f32_16x16x32_bf16 v[120:123], v[164:167], v[188:191], v[120:123]
	v_mfma_f32_16x16x32_bf16 v[108:111], v[156:159], v[200:203], v[108:111]
	v_mfma_f32_16x16x32_bf16 v[104:107], v[164:167], v[200:203], v[104:107]
	v_mfma_f32_16x16x32_bf16 v[92:95], v[156:159], v[208:211], v[92:95]
	v_mfma_f32_16x16x32_bf16 v[88:91], v[164:167], v[208:211], v[88:91]
	v_mfma_f32_16x16x32_bf16 v[76:79], v[156:159], v[216:219], v[76:79]
	v_mfma_f32_16x16x32_bf16 v[72:75], v[164:167], v[216:219], v[72:75]
	v_mfma_f32_16x16x32_bf16 v[116:119], v[168:171], v[184:187], v[116:119]
	v_mfma_f32_16x16x32_bf16 v[112:115], v[176:179], v[184:187], v[112:115]
	v_mfma_f32_16x16x32_bf16 v[100:103], v[168:171], v[192:195], v[100:103]
	v_mfma_f32_16x16x32_bf16 v[96:99], v[176:179], v[192:195], v[96:99]
	v_mfma_f32_16x16x32_bf16 v[84:87], v[168:171], v[204:207], v[84:87]
	v_mfma_f32_16x16x32_bf16 v[80:83], v[176:179], v[204:207], v[80:83]
	v_mfma_f32_16x16x32_bf16 v[68:71], v[168:171], v[212:215], v[68:71]
	v_mfma_f32_16x16x32_bf16 v[64:67], v[176:179], v[212:215], v[64:67]
	v_mfma_f32_16x16x32_bf16 v[116:119], v[172:175], v[188:191], v[116:119]
	v_mfma_f32_16x16x32_bf16 v[112:115], v[180:183], v[188:191], v[112:115]
	v_mfma_f32_16x16x32_bf16 v[100:103], v[172:175], v[200:203], v[100:103]
	v_mfma_f32_16x16x32_bf16 v[96:99], v[180:183], v[200:203], v[96:99]
	v_mfma_f32_16x16x32_bf16 v[84:87], v[172:175], v[208:211], v[84:87]
	v_mfma_f32_16x16x32_bf16 v[80:83], v[180:183], v[208:211], v[80:83]
	v_mfma_f32_16x16x32_bf16 v[68:71], v[172:175], v[216:219], v[68:71]
	v_mfma_f32_16x16x32_bf16 v[64:67], v[180:183], v[216:219], v[64:67]
	s_setprio 0
	s_barrier
; #define PG8_STAGE(bufoff, gbase, voff) do { _Pragma("unroll") for (int _i = 0; _i < 2; ++_i) \
;         __builtin_amdgcn_global_load_lds((const unsigned*)((const char*)(gbase) + (voff)[_i]), (PG8_LAS unsigned*)(lds + (bufoff) + ldsw + _i * 8192), 16, 0, 0); } while (0)
; #define PG8_LDA(dst, b, h) do { _Pragma("unroll") for (int m = 0; m < 4; ++m) _Pragma("unroll") for (int k = 0; k < 2; ++k) dst[m][k] = *(const PG8_LAS bf16x8*)(lds + PG8_SA(b, h) + aoff + m * 2048 + k * 1024); } while (0)
; #define PG8_MMA(ai, bj, At, Bt) do { __builtin_amdgcn_s_setprio(1); _Pragma("unroll") for (int m = 0; m < 4; ++m) _Pragma("unroll") for (int n = 0; n < 2; ++n) _Pragma("unroll") for (int k = 0; k < 2; ++k) \
;         acc[ai][bj][m][n] = __builtin_amdgcn_mfma_f32_16x16x32_bf16(Bt[n][k], At[m][k], acc[ai][bj][m][n], 0, 0, 0); __builtin_amdgcn_s_setprio(0); } while (0)
; #define PG8_WAIT_V(n) asm volatile("s_waitcnt vmcnt(" #n ")" ::: "memory")
; #define PG8_WAIT_L(n) asm volatile("s_waitcnt lgkmcnt(" #n ")" ::: "memory")
; #define PG8_BAR __builtin_amdgcn_s_barrier()
; #define PG8_SCHED __builtin_amdgcn_sched_barrier(0)
; template <class Epi, class Sched>
; __device__ __forceinline__ void gemm_phase(PG8_LAS unsigned char* lds, const Gemm g, const Sched& S, const Epi& E) {
;     ...
;             PG8_LDA(At, 1, 1); PG8_STAGE(PG8_SB(1, 0), b3, voffB); PG8_STAGE(PG8_SB(1, 1), b3 + hstepB, voffB); PG8_STAGE(PG8_SA(1, 0), a3, voffA);
;             PG8_WAIT_V(8); PG8_WAIT_L(0); PG8_BAR; PG8_MMA(1, 0, At, B0); PG8_MMA(1, 1, At, B1); PG8_BAR; PG8_SCHED;
;         }
;         if (wr == 0) PG8_BAR;
	s_add_i32 s46, s67, s33
	v_lshl_add_u64 v[144:145], v[144:145], 0, s[10:11]
	s_mov_b32 m0, s46
	ds_read_b128 v[184:187], v151 offset:49152
	ds_read_b128 v[188:191], v151 offset:50176
	ds_read_b128 v[192:195], v151 offset:51200
	ds_read_b128 v[200:203], v151 offset:52224
	ds_read_b128 v[204:207], v151 offset:53248
	ds_read_b128 v[208:211], v151 offset:54272
	ds_read_b128 v[212:215], v151 offset:55296
	ds_read_b128 v[216:219], v151 offset:56320
	global_load_lds_dwordx4 v[144:145], off
	s_add_i32 m0, s46, 0x2000
	s_add_u32 s44, s44, 0x40080
	v_lshl_add_u64 v[144:145], v[196:197], 0, s[10:11]
	s_addc_u32 s45, s45, 0
	s_add_i32 s46, s68, s33
	global_load_lds_dwordx4 v[144:145], off
	v_lshl_add_u64 v[144:145], s[44:45], 0, v[132:133]
	s_mov_b32 m0, s46
	s_nop 0
	global_load_lds_dwordx4 v[144:145], off
	v_lshl_add_u64 v[144:145], s[44:45], 0, v[128:129]
	s_add_i32 m0, s46, 0x2000
	s_nop 0
	global_load_lds_dwordx4 v[144:145], off
	v_lshl_add_u64 v[144:145], v[220:221], 0, s[10:11]
	s_mov_b32 m0, s54
	s_nop 0
	global_load_lds_dwordx4 v[144:145], off
	v_lshl_add_u64 v[144:145], v[222:223], 0, s[10:11]
	s_mov_b32 m0, s55
	s_nop 0
	global_load_lds_dwordx4 v[144:145], off
	s_waitcnt vmcnt(8)
	s_waitcnt lgkmcnt(0)
	s_barrier
	s_setprio 1
	s_waitcnt lgkmcnt(0)
	v_mfma_f32_16x16x32_bf16 v[60:63], v[152:155], v[184:187], v[60:63]
	v_mfma_f32_16x16x32_bf16 v[56:59], v[160:163], v[184:187], v[56:59]
	v_mfma_f32_16x16x32_bf16 v[44:47], v[152:155], v[192:195], v[44:47]
	v_mfma_f32_16x16x32_bf16 v[40:43], v[160:163], v[192:195], v[40:43]
	v_mfma_f32_16x16x32_bf16 v[28:31], v[152:155], v[204:207], v[28:31]
	v_mfma_f32_16x16x32_bf16 v[24:27], v[160:163], v[204:207], v[24:27]
	v_mfma_f32_16x16x32_bf16 v[12:15], v[152:155], v[212:215], v[12:15]
	v_mfma_f32_16x16x32_bf16 v[8:11], v[160:163], v[212:215], v[8:11]
	v_mfma_f32_16x16x32_bf16 v[60:63], v[156:159], v[188:191], v[60:63]
	v_mfma_f32_16x16x32_bf16 v[56:59], v[164:167], v[188:191], v[56:59]
	v_mfma_f32_16x16x32_bf16 v[44:47], v[156:159], v[200:203], v[44:47]
	v_mfma_f32_16x16x32_bf16 v[40:43], v[164:167], v[200:203], v[40:43]
	v_mfma_f32_16x16x32_bf16 v[28:31], v[156:159], v[208:211], v[28:31]
	v_mfma_f32_16x16x32_bf16 v[24:27], v[164:167], v[208:211], v[24:27]
	v_mfma_f32_16x16x32_bf16 v[12:15], v[156:159], v[216:219], v[12:15]
	v_mfma_f32_16x16x32_bf16 v[8:11], v[164:167], v[216:219], v[8:11]
	v_mfma_f32_16x16x32_bf16 v[52:55], v[168:171], v[184:187], v[52:55]
	v_mfma_f32_16x16x32_bf16 v[48:51], v[176:179], v[184:187], v[48:51]
	v_mfma_f32_16x16x32_bf16 v[36:39], v[168:171], v[192:195], v[36:39]
	v_mfma_f32_16x16x32_bf16 v[32:35], v[176:179], v[192:195], v[32:35]
	v_mfma_f32_16x16x32_bf16 v[20:23], v[168:171], v[204:207], v[20:23]
	v_mfma_f32_16x16x32_bf16 v[16:19], v[176:179], v[204:207], v[16:19]
	v_mfma_f32_16x16x32_bf16 v[4:7], v[168:171], v[212:215], v[4:7]
	v_mfma_f32_16x16x32_bf16 v[0:3], v[176:179], v[212:215], v[0:3]
	v_mfma_f32_16x16x32_bf16 v[52:55], v[172:175], v[188:191], v[52:55]
	v_mfma_f32_16x16x32_bf16 v[48:51], v[180:183], v[188:191], v[48:51]
	v_mfma_f32_16x16x32_bf16 v[36:39], v[172:175], v[200:203], v[36:39]
	v_mfma_f32_16x16x32_bf16 v[32:35], v[180:183], v[200:203], v[32:35]
	v_mfma_f32_16x16x32_bf16 v[20:23], v[172:175], v[208:211], v[20:23]
	v_mfma_f32_16x16x32_bf16 v[16:19], v[180:183], v[208:211], v[16:19]
	v_mfma_f32_16x16x32_bf16 v[4:7], v[172:175], v[216:219], v[4:7]
	v_mfma_f32_16x16x32_bf16 v[0:3], v[180:183], v[216:219], v[0:3]
	s_setprio 0
	s_barrier
	s_add_i32 s66, s66, 2
	s_add_u32 s42, s42, 0x100
	s_addc_u32 s43, s43, 0
	s_add_u32 s64, s64, 0x100
	s_addc_u32 s65, s65, 0
	s_cmp_gt_u32 s66, 13
	s_cbranch_scc0 .LBB0_1379
	s_and_b64 vcc, exec, s[12:13]
	s_cbranch_vccz .LBB0_1382
	s_barrier

; #define PG8_STAGE(bufoff, gbase, voff) do { _Pragma("unroll") for (int _i = 0; _i < 2; ++_i) \
;         __builtin_amdgcn_global_load_lds((const unsigned*)((const char*)(gbase) + (voff)[_i]), (PG8_LAS unsigned*)(lds + (bufoff) + ldsw + _i * 8192), 16, 0, 0); } while (0)
; #define PG8_LDA(dst, b, h) do { _Pragma("unroll") for (int m = 0; m < 4; ++m) _Pragma("unroll") for (int k = 0; k < 2; ++k) dst[m][k] = *(const PG8_LAS bf16x8*)(lds + PG8_SA(b, h) + aoff + m * 2048 + k * 1024); } while (0)
; #define PG8_LDB(dst, b, h) do { _Pragma("unroll") for (int n = 0; n < 2; ++n) _Pragma("unroll") for (int k = 0; k < 2; ++k) dst[n][k] = *(const PG8_LAS bf16x8*)(lds + PG8_SB(b, h) + boff + n * 2048 + k * 1024); } while (0)
; #define PG8_MMA(ai, bj, At, Bt) do { __builtin_amdgcn_s_setprio(1); _Pragma("unroll") for (int m = 0; m < 4; ++m) _Pragma("unroll") for (int n = 0; n < 2; ++n) _Pragma("unroll") for (int k = 0; k < 2; ++k) \
;         acc[ai][bj][m][n] = __builtin_amdgcn_mfma_f32_16x16x32_bf16(Bt[n][k], At[m][k], acc[ai][bj][m][n], 0, 0, 0); __builtin_amdgcn_s_setprio(0); } while (0)
; #define PG8_WAIT_V(n) asm volatile("s_waitcnt vmcnt(" #n ")" ::: "memory")
; #define PG8_WAIT_L(n) asm volatile("s_waitcnt lgkmcnt(" #n ")" ::: "memory")
; #define PG8_BAR __builtin_amdgcn_s_barrier()
; #define PG8_SCHED __builtin_amdgcn_sched_barrier(0)
; template <class Epi, class Sched>
; __device__ __forceinline__ void gemm_phase(PG8_LAS unsigned char* lds, const Gemm g, const Sched& S, const Epi& E) {
;     ...
;             PG8_LDB(B0, 0, 0); PG8_LDB(B1, 0, 1); PG8_SCHED; PG8_LDA(At, 0, 0); PG8_STAGE(PG8_SA(1, 1), a1 + hstepA, voffA);
;             PG8_WAIT_V(8); PG8_WAIT_L(0); PG8_BAR; PG8_MMA(0, 0, At, B0); PG8_MMA(0, 1, At, B1); PG8_BAR; PG8_SCHED;
;             PG8_LDA(At, 0, 1); PG8_STAGE(PG8_SB(0, 0), b2, voffB); PG8_STAGE(PG8_SB(0, 1), b2 + hstepB, voffB); PG8_STAGE(PG8_SA(0, 0), a2, voffA);
.LBB0_1458:
	s_waitcnt lgkmcnt(0)
	ds_read_b128 v[0:3], v201
	ds_read_b128 v[4:7], v201 offset:1024
	ds_read_b128 v[8:11], v201 offset:2048
	ds_read_b128 v[12:15], v201 offset:3072
	ds_read_b128 v[16:19], v202
	ds_read_b128 v[20:23], v202 offset:1024
	ds_read_b128 v[104:107], v202 offset:2048
	ds_read_b128 v[116:119], v202 offset:3072
	s_add_u32 s14, s12, 0x100
	s_addc_u32 s15, s13, 0
	s_cmp_eq_u32 s74, 40
	s_cselect_b32 s51, s6, s15
	s_cselect_b32 s50, s69, s14
	s_cselect_b32 s49, s70, s73
	s_cselect_b32 s48, s71, s72
	v_lshl_add_u64 v[218:219], s[12:13], 0, v[176:177]
	s_add_i32 m0, s52, 0xc000
	ds_read_b128 v[124:127], v203
	ds_read_b128 v[132:135], v203 offset:1024
	ds_read_b128 v[184:187], v203 offset:2048
	ds_read_b128 v[188:191], v203 offset:3072
	ds_read_b128 v[192:195], v203 offset:4096
	ds_read_b128 v[206:209], v203 offset:5120
	ds_read_b128 v[210:213], v203 offset:6144
	ds_read_b128 v[214:217], v203 offset:7168
	global_load_lds_dwordx4 v[218:219], off
	v_lshl_add_u64 v[218:219], s[12:13], 0, v[178:179]
	s_add_i32 m0, s52, 0xe000
	s_nop 0
	global_load_lds_dwordx4 v[218:219], off
	s_waitcnt vmcnt(8)
	s_waitcnt lgkmcnt(0)
	s_barrier
	s_setprio 1
	s_waitcnt lgkmcnt(0)
	v_mfma_f32_16x16x32_bf16 v[28:31], v[0:3], v[124:127], v[28:31]
	v_mfma_f32_16x16x32_bf16 v[24:27], v[8:11], v[124:127], v[24:27]
	v_mfma_f32_16x16x32_bf16 v[44:47], v[0:3], v[184:187], v[44:47]
	v_mfma_f32_16x16x32_bf16 v[40:43], v[8:11], v[184:187], v[40:43]
	v_mfma_f32_16x16x32_bf16 v[156:159], v[0:3], v[192:195], v[156:159]
	v_mfma_f32_16x16x32_bf16 v[152:155], v[8:11], v[192:195], v[152:155]
	v_mfma_f32_16x16x32_bf16 v[140:143], v[0:3], v[210:213], v[140:143]
	v_mfma_f32_16x16x32_bf16 v[136:139], v[8:11], v[210:213], v[136:139]
	v_mfma_f32_16x16x32_bf16 v[28:31], v[4:7], v[132:135], v[28:31]
	v_mfma_f32_16x16x32_bf16 v[24:27], v[12:15], v[132:135], v[24:27]
	v_mfma_f32_16x16x32_bf16 v[44:47], v[4:7], v[188:191], v[44:47]
	v_mfma_f32_16x16x32_bf16 v[40:43], v[12:15], v[188:191], v[40:43]
	v_mfma_f32_16x16x32_bf16 v[156:159], v[4:7], v[206:209], v[156:159]
	v_mfma_f32_16x16x32_bf16 v[152:155], v[12:15], v[206:209], v[152:155]
	v_mfma_f32_16x16x32_bf16 v[140:143], v[4:7], v[214:217], v[140:143]
	v_mfma_f32_16x16x32_bf16 v[136:139], v[12:15], v[214:217], v[136:139]
	v_mfma_f32_16x16x32_bf16 v[36:39], v[16:19], v[124:127], v[36:39]
	v_mfma_f32_16x16x32_bf16 v[32:35], v[104:107], v[124:127], v[32:35]
	v_mfma_f32_16x16x32_bf16 v[148:151], v[16:19], v[192:195], v[148:151]
	v_mfma_f32_16x16x32_bf16 v[144:147], v[104:107], v[192:195], v[144:147]
	v_mfma_f32_16x16x32_bf16 v[128:131], v[16:19], v[210:213], v[128:131]
	v_mfma_f32_16x16x32_bf16 v[120:123], v[104:107], v[210:213], v[120:123]
	v_mfma_f32_16x16x32_bf16 v[36:39], v[20:23], v[132:135], v[36:39]
	v_mfma_f32_16x16x32_bf16 v[32:35], v[116:119], v[132:135], v[32:35]
	v_mfma_f32_16x16x32_bf16 v[124:127], v[16:19], v[184:187], v[164:167]
	v_mfma_f32_16x16x32_bf16 v[132:135], v[104:107], v[184:187], v[160:163]
	v_mfma_f32_16x16x32_bf16 v[148:151], v[20:23], v[206:209], v[148:151]
	v_mfma_f32_16x16x32_bf16 v[144:147], v[116:119], v[206:209], v[144:147]
	v_mfma_f32_16x16x32_bf16 v[128:131], v[20:23], v[214:217], v[128:131]
	v_mfma_f32_16x16x32_bf16 v[120:123], v[116:119], v[214:217], v[120:123]
	v_mfma_f32_16x16x32_bf16 v[124:127], v[20:23], v[188:191], v[124:127]
	v_mfma_f32_16x16x32_bf16 v[132:135], v[116:119], v[188:191], v[132:135]
	s_setprio 0
	s_barrier
	s_add_i32 s12, s62, s33
	v_lshl_add_u64 v[226:227], s[48:49], 0, v[170:171]
	s_mov_b32 m0, s12
	ds_read_b128 v[160:163], v203 offset:16384
	ds_read_b128 v[164:167], v203 offset:17408
	ds_read_b128 v[184:187], v203 offset:18432
	ds_read_b128 v[188:191], v203 offset:19456
	ds_read_b128 v[192:195], v203 offset:20480
	ds_read_b128 v[206:209], v203 offset:21504
	ds_read_b128 v[210:213], v203 offset:22528
	ds_read_b128 v[214:217], v203 offset:23552
	global_load_lds_dwordx4 v[226:227], off
	s_add_i32 m0, s12, 0x2000
	s_add_u32 s12, s48, 0xb0000
	v_lshl_add_u64 v[228:229], s[48:49], 0, v[174:175]
	s_addc_u32 s13, s49, 0
	s_add_i32 s75, s63, s33
	global_load_lds_dwordx4 v[228:229], off
	v_lshl_add_u64 v[218:219], s[12:13], 0, v[170:171]
	s_mov_b32 m0, s75
	v_lshl_add_u64 v[230:231], s[50:51], 0, v[168:169]
	global_load_lds_dwordx4 v[218:219], off
	v_lshl_add_u64 v[218:219], s[12:13], 0, v[174:175]
	s_add_i32 m0, s75, 0x2000
	v_lshl_add_u64 v[232:233], s[50:51], 0, v[172:173]
	global_load_lds_dwordx4 v[218:219], off
	s_mov_b32 m0, s52
	s_nop 0
	global_load_lds_dwordx4 v[230:231], off
	s_mov_b32 m0, s53
	s_nop 0
	global_load_lds_dwordx4 v[232:233], off
	s_waitcnt vmcnt(8)
	s_waitcnt lgkmcnt(0)
	s_barrier
; #define PG8_STAGE(bufoff, gbase, voff) do { _Pragma("unroll") for (int _i = 0; _i < 2; ++_i) \
;         __builtin_amdgcn_global_load_lds((const unsigned*)((const char*)(gbase) + (voff)[_i]), (PG8_LAS unsigned*)(lds + (bufoff) + ldsw + _i * 8192), 16, 0, 0); } while (0)
; #define PG8_LDA(dst, b, h) do { _Pragma("unroll") for (int m = 0; m < 4; ++m) _Pragma("unroll") for (int k = 0; k < 2; ++k) dst[m][k] = *(const PG8_LAS bf16x8*)(lds + PG8_SA(b, h) + aoff + m * 2048 + k * 1024); } while (0)
; #define PG8_LDB(dst, b, h) do { _Pragma("unroll") for (int n = 0; n < 2; ++n) _Pragma("unroll") for (int k = 0; k < 2; ++k) dst[n][k] = *(const PG8_LAS bf16x8*)(lds + PG8_SB(b, h) + boff + n * 2048 + k * 1024); } while (0)
; #define PG8_MMA(ai, bj, At, Bt) do { __builtin_amdgcn_s_setprio(1); _Pragma("unroll") for (int m = 0; m < 4; ++m) _Pragma("unroll") for (int n = 0; n < 2; ++n) _Pragma("unroll") for (int k = 0; k < 2; ++k) \
;         acc[ai][bj][m][n] = __builtin_amdgcn_mfma_f32_16x16x32_bf16(Bt[n][k], At[m][k], acc[ai][bj][m][n], 0, 0, 0); __builtin_amdgcn_s_setprio(0); } while (0)
; #define PG8_WAIT_V(n) asm volatile("s_waitcnt vmcnt(" #n ")" ::: "memory")
; #define PG8_WAIT_L(n) asm volatile("s_waitcnt lgkmcnt(" #n ")" ::: "memory")
; #define PG8_BAR __builtin_amdgcn_s_barrier()
; #define PG8_SCHED __builtin_amdgcn_sched_barrier(0)
; template <class Epi, class Sched>
; __device__ __forceinline__ void gemm_phase(PG8_LAS unsigned char* lds, const Gemm g, const Sched& S, const Epi& E) {
;     ...
;             PG8_WAIT_V(8); PG8_WAIT_L(0); PG8_BAR; PG8_MMA(1, 0, At, B0); PG8_MMA(1, 1, At, B1); PG8_BAR; PG8_SCHED;
;             PG8_LDB(B0, 1, 0); PG8_LDB(B1, 1, 1); PG8_SCHED; PG8_LDA(At, 1, 0); PG8_STAGE(PG8_SA(0, 1), a2 + hstepA, voffA);
;             PG8_WAIT_V(8); PG8_WAIT_L(0); PG8_BAR; PG8_MMA(0, 0, At, B0); PG8_MMA(0, 1, At, B1); PG8_BAR; PG8_SCHED;
	s_setprio 1
	s_waitcnt lgkmcnt(0)
	v_mfma_f32_16x16x32_bf16 v[112:115], v[0:3], v[160:163], v[112:115]
	v_mfma_f32_16x16x32_bf16 v[108:111], v[8:11], v[160:163], v[108:111]
	v_mfma_f32_16x16x32_bf16 v[92:95], v[0:3], v[184:187], v[92:95]
	v_mfma_f32_16x16x32_bf16 v[88:91], v[8:11], v[184:187], v[88:91]
	v_mfma_f32_16x16x32_bf16 v[76:79], v[0:3], v[192:195], v[76:79]
	v_mfma_f32_16x16x32_bf16 v[72:75], v[8:11], v[192:195], v[72:75]
	v_mfma_f32_16x16x32_bf16 v[0:3], v[0:3], v[210:213], v[60:63]
	v_mfma_f32_16x16x32_bf16 v[112:115], v[4:7], v[164:167], v[112:115]
	v_mfma_f32_16x16x32_bf16 v[108:111], v[12:15], v[164:167], v[108:111]
	v_mfma_f32_16x16x32_bf16 v[92:95], v[4:7], v[188:191], v[92:95]
	v_mfma_f32_16x16x32_bf16 v[88:91], v[12:15], v[188:191], v[88:91]
	v_mfma_f32_16x16x32_bf16 v[76:79], v[4:7], v[206:209], v[76:79]
	v_mfma_f32_16x16x32_bf16 v[72:75], v[12:15], v[206:209], v[72:75]
	v_mfma_f32_16x16x32_bf16 v[0:3], v[4:7], v[214:217], v[0:3]
	v_mfma_f32_16x16x32_bf16 v[4:7], v[8:11], v[210:213], v[56:59]
	v_mfma_f32_16x16x32_bf16 v[4:7], v[12:15], v[214:217], v[4:7]
	v_mfma_f32_16x16x32_bf16 v[56:59], v[16:19], v[184:187], v[84:87]
	v_mfma_f32_16x16x32_bf16 v[84:87], v[20:23], v[188:191], v[56:59]
	v_mfma_f32_16x16x32_bf16 v[56:59], v[104:107], v[184:187], v[80:83]
	v_mfma_f32_16x16x32_bf16 v[80:83], v[116:119], v[188:191], v[56:59]
	v_mfma_f32_16x16x32_bf16 v[56:59], v[16:19], v[192:195], v[68:71]
	v_mfma_f32_16x16x32_bf16 v[8:11], v[16:19], v[160:163], v[100:103]
	v_mfma_f32_16x16x32_bf16 v[68:71], v[20:23], v[206:209], v[56:59]
	v_mfma_f32_16x16x32_bf16 v[56:59], v[104:107], v[192:195], v[64:67]
	v_mfma_f32_16x16x32_bf16 v[16:19], v[16:19], v[210:213], v[52:55]
	v_mfma_f32_16x16x32_bf16 v[8:11], v[20:23], v[164:167], v[8:11]
	v_mfma_f32_16x16x32_bf16 v[12:15], v[104:107], v[160:163], v[96:99]
	v_mfma_f32_16x16x32_bf16 v[64:67], v[116:119], v[206:209], v[56:59]
	v_mfma_f32_16x16x32_bf16 v[16:19], v[20:23], v[214:217], v[16:19]
	v_mfma_f32_16x16x32_bf16 v[20:23], v[104:107], v[210:213], v[48:51]
	v_mfma_f32_16x16x32_bf16 v[12:15], v[116:119], v[164:167], v[12:15]
	v_mfma_f32_16x16x32_bf16 v[20:23], v[116:119], v[214:217], v[20:23]
	s_setprio 0
	s_barrier
	s_add_i32 s75, 0, 0x18000
	v_add_u32_e32 v60, s75, v197
	s_add_i32 s76, 0, 0x1c000
	ds_read_b128 v[48:51], v60
	ds_read_b128 v[52:55], v60 offset:1024
	ds_read_b128 v[56:59], v60 offset:2048
	ds_read_b128 v[96:99], v60 offset:3072
	v_add_u32_e32 v60, s76, v197
	ds_read_b128 v[104:107], v60
	ds_read_b128 v[116:119], v60 offset:1024
	ds_read_b128 v[184:187], v60 offset:2048
	ds_read_b128 v[188:191], v60 offset:3072
	s_add_u32 s12, s50, 0xb0000
	s_addc_u32 s13, s51, 0
	s_mov_b32 m0, s54
	v_lshl_add_u64 v[164:165], s[12:13], 0, v[168:169]
	ds_read_b128 v[60:63], v203 offset:32768
	ds_read_b128 v[100:103], v203 offset:33792
	ds_read_b128 v[160:163], v203 offset:34816
	ds_read_b128 v[192:195], v203 offset:35840
	ds_read_b128 v[206:209], v203 offset:36864
	ds_read_b128 v[210:213], v203 offset:37888
	ds_read_b128 v[214:217], v203 offset:38912
	ds_read_b128 v[218:221], v203 offset:39936
	global_load_lds_dwordx4 v[164:165], off
	v_lshl_add_u64 v[164:165], s[12:13], 0, v[172:173]
	s_mov_b32 m0, s55
	s_nop 0
	global_load_lds_dwordx4 v[164:165], off
	s_waitcnt vmcnt(8)
	s_waitcnt lgkmcnt(0)
	s_barrier
	s_setprio 1
	s_waitcnt lgkmcnt(0)
	v_mfma_f32_16x16x32_bf16 v[28:31], v[48:51], v[60:63], v[28:31]
	v_mfma_f32_16x16x32_bf16 v[24:27], v[56:59], v[60:63], v[24:27]
	v_mfma_f32_16x16x32_bf16 v[44:47], v[48:51], v[160:163], v[44:47]
	v_mfma_f32_16x16x32_bf16 v[40:43], v[56:59], v[160:163], v[40:43]
	v_mfma_f32_16x16x32_bf16 v[156:159], v[48:51], v[206:209], v[156:159]
	v_mfma_f32_16x16x32_bf16 v[152:155], v[56:59], v[206:209], v[152:155]
	v_mfma_f32_16x16x32_bf16 v[140:143], v[48:51], v[214:217], v[140:143]
	v_mfma_f32_16x16x32_bf16 v[136:139], v[56:59], v[214:217], v[136:139]
	v_mfma_f32_16x16x32_bf16 v[28:31], v[52:55], v[100:103], v[28:31]
	v_mfma_f32_16x16x32_bf16 v[24:27], v[96:99], v[100:103], v[24:27]
	v_mfma_f32_16x16x32_bf16 v[44:47], v[52:55], v[192:195], v[44:47]
	v_mfma_f32_16x16x32_bf16 v[40:43], v[96:99], v[192:195], v[40:43]
	v_mfma_f32_16x16x32_bf16 v[156:159], v[52:55], v[210:213], v[156:159]
	v_mfma_f32_16x16x32_bf16 v[152:155], v[96:99], v[210:213], v[152:155]
	v_mfma_f32_16x16x32_bf16 v[140:143], v[52:55], v[218:221], v[140:143]
	v_mfma_f32_16x16x32_bf16 v[136:139], v[96:99], v[218:221], v[136:139]
	v_mfma_f32_16x16x32_bf16 v[36:39], v[104:107], v[60:63], v[36:39]
	v_mfma_f32_16x16x32_bf16 v[32:35], v[184:187], v[60:63], v[32:35]
	v_mfma_f32_16x16x32_bf16 v[60:63], v[104:107], v[160:163], v[124:127]
	v_mfma_f32_16x16x32_bf16 v[164:167], v[116:119], v[192:195], v[60:63]
	v_mfma_f32_16x16x32_bf16 v[60:63], v[184:187], v[160:163], v[132:135]
	v_mfma_f32_16x16x32_bf16 v[160:163], v[188:191], v[192:195], v[60:63]
	v_mfma_f32_16x16x32_bf16 v[60:63], v[104:107], v[206:209], v[148:151]
	v_mfma_f32_16x16x32_bf16 v[148:151], v[116:119], v[210:213], v[60:63]
	v_mfma_f32_16x16x32_bf16 v[60:63], v[184:187], v[206:209], v[144:147]
	v_mfma_f32_16x16x32_bf16 v[144:147], v[188:191], v[210:213], v[60:63]
	v_mfma_f32_16x16x32_bf16 v[60:63], v[104:107], v[214:217], v[128:131]
	v_mfma_f32_16x16x32_bf16 v[128:131], v[116:119], v[218:221], v[60:63]
	v_mfma_f32_16x16x32_bf16 v[60:63], v[184:187], v[214:217], v[120:123]
	v_mfma_f32_16x16x32_bf16 v[36:39], v[116:119], v[100:103], v[36:39]
	v_mfma_f32_16x16x32_bf16 v[32:35], v[188:191], v[100:103], v[32:35]
	v_mfma_f32_16x16x32_bf16 v[120:123], v[188:191], v[218:221], v[60:63]
	s_setprio 0
	s_barrier
; #define PG8_STAGE(bufoff, gbase, voff) do { _Pragma("unroll") for (int _i = 0; _i < 2; ++_i) \
;         __builtin_amdgcn_global_load_lds((const unsigned*)((const char*)(gbase) + (voff)[_i]), (PG8_LAS unsigned*)(lds + (bufoff) + ldsw + _i * 8192), 16, 0, 0); } while (0)
; #define PG8_LDA(dst, b, h) do { _Pragma("unroll") for (int m = 0; m < 4; ++m) _Pragma("unroll") for (int k = 0; k < 2; ++k) dst[m][k] = *(const PG8_LAS bf16x8*)(lds + PG8_SA(b, h) + aoff + m * 2048 + k * 1024); } while (0)
; #define PG8_MMA(ai, bj, At, Bt) do { __builtin_amdgcn_s_setprio(1); _Pragma("unroll") for (int m = 0; m < 4; ++m) _Pragma("unroll") for (int n = 0; n < 2; ++n) _Pragma("unroll") for (int k = 0; k < 2; ++k) \
;         acc[ai][bj][m][n] = __builtin_amdgcn_mfma_f32_16x16x32_bf16(Bt[n][k], At[m][k], acc[ai][bj][m][n], 0, 0, 0); __builtin_amdgcn_s_setprio(0); } while (0)
; #define PG8_WAIT_V(n) asm volatile("s_waitcnt vmcnt(" #n ")" ::: "memory")
; #define PG8_WAIT_L(n) asm volatile("s_waitcnt lgkmcnt(" #n ")" ::: "memory")
; #define PG8_BAR __builtin_amdgcn_s_barrier()
; #define PG8_SCHED __builtin_amdgcn_sched_barrier(0)
; template <class Epi, class Sched>
; __device__ __forceinline__ void gemm_phase(PG8_LAS unsigned char* lds, const Gemm g, const Sched& S, const Epi& E) {
;     ...
;             PG8_LDA(At, 1, 1); PG8_STAGE(PG8_SB(1, 0), b3, voffB); PG8_STAGE(PG8_SB(1, 1), b3 + hstepB, voffB); PG8_STAGE(PG8_SA(1, 0), a3, voffA);
;             PG8_WAIT_V(8); PG8_WAIT_L(0); PG8_BAR; PG8_MMA(1, 0, At, B0); PG8_MMA(1, 1, At, B1); PG8_BAR; PG8_SCHED;
;         }
;         if (wr == 0) PG8_BAR;
	s_add_i32 s12, s75, s33
	s_nop 1
	v_lshl_add_u64 v[60:61], v[226:227], 0, s[30:31]
	s_mov_b32 m0, s12
	ds_read_b128 v[124:127], v203 offset:49152
	ds_read_b128 v[132:135], v203 offset:50176
	ds_read_b128 v[192:195], v203 offset:51200
	ds_read_b128 v[206:209], v203 offset:52224
	ds_read_b128 v[210:213], v203 offset:53248
	ds_read_b128 v[214:217], v203 offset:54272
	ds_read_b128 v[218:221], v203 offset:55296
	ds_read_b128 v[222:225], v203 offset:56320
	global_load_lds_dwordx4 v[60:61], off
	s_add_i32 m0, s12, 0x2000
	s_add_u32 s12, s48, 0xb0080
	v_lshl_add_u64 v[60:61], v[228:229], 0, s[30:31]
	s_addc_u32 s13, s49, 0
	s_add_i32 s48, s76, s33
	global_load_lds_dwordx4 v[60:61], off
	v_lshl_add_u64 v[60:61], s[12:13], 0, v[170:171]
	s_mov_b32 m0, s48
	s_nop 0
	global_load_lds_dwordx4 v[60:61], off
	v_lshl_add_u64 v[60:61], s[12:13], 0, v[174:175]
	s_add_i32 m0, s48, 0x2000
	s_nop 0
	global_load_lds_dwordx4 v[60:61], off
	v_lshl_add_u64 v[60:61], v[230:231], 0, s[30:31]
	s_mov_b32 m0, s57
	s_nop 0
	global_load_lds_dwordx4 v[60:61], off
	v_lshl_add_u64 v[60:61], v[232:233], 0, s[30:31]
	s_mov_b32 m0, s58
	s_nop 0
	global_load_lds_dwordx4 v[60:61], off
	s_waitcnt vmcnt(8)
	s_waitcnt lgkmcnt(0)
	s_barrier
	s_setprio 1
	s_waitcnt lgkmcnt(0)
	v_mfma_f32_16x16x32_bf16 v[60:63], v[48:51], v[124:127], v[112:115]
	v_mfma_f32_16x16x32_bf16 v[112:115], v[52:55], v[132:135], v[60:63]
	v_mfma_f32_16x16x32_bf16 v[60:63], v[56:59], v[124:127], v[108:111]
	v_mfma_f32_16x16x32_bf16 v[108:111], v[96:99], v[132:135], v[60:63]
	v_mfma_f32_16x16x32_bf16 v[60:63], v[48:51], v[192:195], v[92:95]
	v_mfma_f32_16x16x32_bf16 v[92:95], v[52:55], v[206:209], v[60:63]
	v_mfma_f32_16x16x32_bf16 v[60:63], v[56:59], v[192:195], v[88:91]
	v_mfma_f32_16x16x32_bf16 v[88:91], v[96:99], v[206:209], v[60:63]
	v_mfma_f32_16x16x32_bf16 v[60:63], v[48:51], v[210:213], v[76:79]
	v_mfma_f32_16x16x32_bf16 v[76:79], v[52:55], v[214:217], v[60:63]
	v_mfma_f32_16x16x32_bf16 v[60:63], v[56:59], v[210:213], v[72:75]
	v_mfma_f32_16x16x32_bf16 v[0:3], v[48:51], v[218:221], v[0:3]
	v_mfma_f32_16x16x32_bf16 v[72:75], v[96:99], v[214:217], v[60:63]
	v_mfma_f32_16x16x32_bf16 v[60:63], v[52:55], v[222:225], v[0:3]
	v_mfma_f32_16x16x32_bf16 v[0:3], v[56:59], v[218:221], v[4:7]
	v_mfma_f32_16x16x32_bf16 v[56:59], v[96:99], v[222:225], v[0:3]
	v_mfma_f32_16x16x32_bf16 v[0:3], v[104:107], v[124:127], v[8:11]
	v_mfma_f32_16x16x32_bf16 v[100:103], v[116:119], v[132:135], v[0:3]
	v_mfma_f32_16x16x32_bf16 v[0:3], v[184:187], v[124:127], v[12:15]
	v_mfma_f32_16x16x32_bf16 v[96:99], v[188:191], v[132:135], v[0:3]
	v_mfma_f32_16x16x32_bf16 v[0:3], v[104:107], v[192:195], v[84:87]
	v_mfma_f32_16x16x32_bf16 v[84:87], v[116:119], v[206:209], v[0:3]
	v_mfma_f32_16x16x32_bf16 v[0:3], v[184:187], v[192:195], v[80:83]
	v_mfma_f32_16x16x32_bf16 v[80:83], v[188:191], v[206:209], v[0:3]
	v_mfma_f32_16x16x32_bf16 v[0:3], v[104:107], v[210:213], v[68:71]
	v_mfma_f32_16x16x32_bf16 v[68:71], v[116:119], v[214:217], v[0:3]
	v_mfma_f32_16x16x32_bf16 v[0:3], v[184:187], v[210:213], v[64:67]
	v_mfma_f32_16x16x32_bf16 v[64:67], v[188:191], v[214:217], v[0:3]
	v_mfma_f32_16x16x32_bf16 v[0:3], v[104:107], v[218:221], v[16:19]
	v_mfma_f32_16x16x32_bf16 v[52:55], v[116:119], v[222:225], v[0:3]
	v_mfma_f32_16x16x32_bf16 v[0:3], v[184:187], v[218:221], v[20:23]
	v_mfma_f32_16x16x32_bf16 v[48:51], v[188:191], v[222:225], v[0:3]
	s_setprio 0
	s_barrier
	s_add_i32 s74, s74, 2
	s_add_u32 s72, s72, 0x100
	s_addc_u32 s73, s73, 0
	s_cmp_gt_u32 s74, 41
	s_mov_b64 s[12:13], s[14:15]
	s_cbranch_scc0 .LBB0_1458
	s_and_b64 vcc, exec, s[34:35]
	s_cbranch_vccz .LBB0_1461
	s_barrier

; #define PG8_STAGE(bufoff, gbase, voff) do { _Pragma("unroll") for (int _i = 0; _i < 2; ++_i) \
;         __builtin_amdgcn_global_load_lds((const unsigned*)((const char*)(gbase) + (voff)[_i]), (PG8_LAS unsigned*)(lds + (bufoff) + ldsw + _i * 8192), 16, 0, 0); } while (0)
; #define PG8_LDA(dst, b, h) do { _Pragma("unroll") for (int m = 0; m < 4; ++m) _Pragma("unroll") for (int k = 0; k < 2; ++k) dst[m][k] = *(const PG8_LAS bf16x8*)(lds + PG8_SA(b, h) + aoff + m * 2048 + k * 1024); } while (0)
; #define PG8_LDB(dst, b, h) do { _Pragma("unroll") for (int n = 0; n < 2; ++n) _Pragma("unroll") for (int k = 0; k < 2; ++k) dst[n][k] = *(const PG8_LAS bf16x8*)(lds + PG8_SB(b, h) + boff + n * 2048 + k * 1024); } while (0)
; #define PG8_MMA(ai, bj, At, Bt) do { __builtin_amdgcn_s_setprio(1); _Pragma("unroll") for (int m = 0; m < 4; ++m) _Pragma("unroll") for (int n = 0; n < 2; ++n) _Pragma("unroll") for (int k = 0; k < 2; ++k) \
;         acc[ai][bj][m][n] = __builtin_amdgcn_mfma_f32_16x16x32_bf16(Bt[n][k], At[m][k], acc[ai][bj][m][n], 0, 0, 0); __builtin_amdgcn_s_setprio(0); } while (0)
; #define PG8_WAIT_V(n) asm volatile("s_waitcnt vmcnt(" #n ")" ::: "memory")
; #define PG8_WAIT_L(n) asm volatile("s_waitcnt lgkmcnt(" #n ")" ::: "memory")
; #define PG8_BAR __builtin_amdgcn_s_barrier()
; #define PG8_SCHED __builtin_amdgcn_sched_barrier(0)
; template <class Epi, class Sched>
; __device__ __forceinline__ void gemm_phase(PG8_LAS unsigned char* lds, const Gemm g, const Sched& S, const Epi& E) {
;     ...
;             PG8_LDB(B0, 0, 0); PG8_LDB(B1, 0, 1); PG8_SCHED; PG8_LDA(At, 0, 0); PG8_STAGE(PG8_SA(1, 1), a1 + hstepA, voffA);
;             PG8_WAIT_V(8); PG8_WAIT_L(0); PG8_BAR; PG8_MMA(0, 0, At, B0); PG8_MMA(0, 1, At, B1); PG8_BAR; PG8_SCHED;
;             PG8_LDA(At, 0, 1); PG8_STAGE(PG8_SB(0, 0), b2, voffB); PG8_STAGE(PG8_SB(0, 1), b2 + hstepB, voffB); PG8_STAGE(PG8_SA(0, 0), a2, voffA);
.LBB0_1654:
	ds_read_b128 v[128:131], v203
	ds_read_b128 v[132:135], v203 offset:1024
	ds_read_b128 v[136:139], v203 offset:2048
	ds_read_b128 v[140:143], v203 offset:3072
	ds_read_b128 v[144:147], v204
	ds_read_b128 v[148:151], v204 offset:1024
	ds_read_b128 v[152:155], v204 offset:2048
	ds_read_b128 v[156:159], v204 offset:3072
	s_add_u32 s40, s38, 0xfffc0080
	s_addc_u32 s41, s39, -1
	s_cmp_eq_u32 s61, 12
	s_cselect_b32 s43, s13, s41
	s_cselect_b32 s42, s15, s40
	s_cselect_b32 s41, s57, s60
	s_cselect_b32 s40, s58, s59
	v_lshl_add_u64 v[196:197], s[38:39], 0, v[176:177]
	s_add_i32 m0, s37, 0xc000
	ds_read_b128 v[160:163], v205
	ds_read_b128 v[164:167], v205 offset:1024
	ds_read_b128 v[184:187], v205 offset:2048
	ds_read_b128 v[188:191], v205 offset:3072
	ds_read_b128 v[192:195], v205 offset:4096
	ds_read_b128 v[208:211], v205 offset:5120
	ds_read_b128 v[212:215], v205 offset:6144
	ds_read_b128 v[216:219], v205 offset:7168
	global_load_lds_dwordx4 v[196:197], off
	v_lshl_add_u64 v[196:197], s[38:39], 0, v[178:179]
	s_add_i32 m0, s37, 0xe000
	s_nop 0
	global_load_lds_dwordx4 v[196:197], off
	s_waitcnt vmcnt(8)
	s_waitcnt lgkmcnt(0)
	s_barrier
	s_setprio 1
	s_waitcnt lgkmcnt(0)
	v_mfma_f32_16x16x32_bf16 v[124:127], v[128:131], v[160:163], v[124:127]
	v_mfma_f32_16x16x32_bf16 v[120:123], v[136:139], v[160:163], v[120:123]
	v_mfma_f32_16x16x32_bf16 v[108:111], v[128:131], v[184:187], v[108:111]
	v_mfma_f32_16x16x32_bf16 v[104:107], v[136:139], v[184:187], v[104:107]
	v_mfma_f32_16x16x32_bf16 v[92:95], v[128:131], v[192:195], v[92:95]
	v_mfma_f32_16x16x32_bf16 v[88:91], v[136:139], v[192:195], v[88:91]
	v_mfma_f32_16x16x32_bf16 v[76:79], v[128:131], v[212:215], v[76:79]
	v_mfma_f32_16x16x32_bf16 v[72:75], v[136:139], v[212:215], v[72:75]
	v_mfma_f32_16x16x32_bf16 v[124:127], v[132:135], v[164:167], v[124:127]
	v_mfma_f32_16x16x32_bf16 v[120:123], v[140:143], v[164:167], v[120:123]
	v_mfma_f32_16x16x32_bf16 v[108:111], v[132:135], v[188:191], v[108:111]
	v_mfma_f32_16x16x32_bf16 v[104:107], v[140:143], v[188:191], v[104:107]
	v_mfma_f32_16x16x32_bf16 v[92:95], v[132:135], v[208:211], v[92:95]
	v_mfma_f32_16x16x32_bf16 v[88:91], v[140:143], v[208:211], v[88:91]
	v_mfma_f32_16x16x32_bf16 v[76:79], v[132:135], v[216:219], v[76:79]
	v_mfma_f32_16x16x32_bf16 v[72:75], v[140:143], v[216:219], v[72:75]
	v_mfma_f32_16x16x32_bf16 v[116:119], v[144:147], v[160:163], v[116:119]
	v_mfma_f32_16x16x32_bf16 v[112:115], v[152:155], v[160:163], v[112:115]
	v_mfma_f32_16x16x32_bf16 v[100:103], v[144:147], v[184:187], v[100:103]
	v_mfma_f32_16x16x32_bf16 v[96:99], v[152:155], v[184:187], v[96:99]
	v_mfma_f32_16x16x32_bf16 v[84:87], v[144:147], v[192:195], v[84:87]
	v_mfma_f32_16x16x32_bf16 v[80:83], v[152:155], v[192:195], v[80:83]
	v_mfma_f32_16x16x32_bf16 v[68:71], v[144:147], v[212:215], v[68:71]
	v_mfma_f32_16x16x32_bf16 v[64:67], v[152:155], v[212:215], v[64:67]
	v_mfma_f32_16x16x32_bf16 v[116:119], v[148:151], v[164:167], v[116:119]
	v_mfma_f32_16x16x32_bf16 v[112:115], v[156:159], v[164:167], v[112:115]
	v_mfma_f32_16x16x32_bf16 v[100:103], v[148:151], v[188:191], v[100:103]
	v_mfma_f32_16x16x32_bf16 v[96:99], v[156:159], v[188:191], v[96:99]
	v_mfma_f32_16x16x32_bf16 v[84:87], v[148:151], v[208:211], v[84:87]
	v_mfma_f32_16x16x32_bf16 v[80:83], v[156:159], v[208:211], v[80:83]
	v_mfma_f32_16x16x32_bf16 v[68:71], v[148:151], v[216:219], v[68:71]
	v_mfma_f32_16x16x32_bf16 v[64:67], v[156:159], v[216:219], v[64:67]
	s_setprio 0
	s_barrier
	s_add_i32 s62, s54, s33
	v_lshl_add_u64 v[196:197], s[40:41], 0, v[172:173]
	s_mov_b32 m0, s62
	ds_read_b128 v[160:163], v205 offset:16384
	ds_read_b128 v[164:167], v205 offset:17408
	ds_read_b128 v[184:187], v205 offset:18432
	ds_read_b128 v[188:191], v205 offset:19456
	ds_read_b128 v[192:195], v205 offset:20480
	ds_read_b128 v[208:211], v205 offset:21504
	ds_read_b128 v[212:215], v205 offset:22528
	ds_read_b128 v[216:219], v205 offset:23552
	global_load_lds_dwordx4 v[196:197], off
	s_add_i32 m0, s62, 0x2000
	s_add_u32 s62, s40, 0x40000
	v_lshl_add_u64 v[220:221], s[40:41], 0, v[168:169]
	s_addc_u32 s63, s41, 0
	s_add_i32 s64, s55, s33
	global_load_lds_dwordx4 v[220:221], off
	v_lshl_add_u64 v[222:223], s[62:63], 0, v[172:173]
	s_mov_b32 m0, s64
	v_lshl_add_u64 v[224:225], s[42:43], 0, v[170:171]
	global_load_lds_dwordx4 v[222:223], off
	v_lshl_add_u64 v[222:223], s[62:63], 0, v[168:169]
	s_add_i32 m0, s64, 0x2000
	s_nop 0
	global_load_lds_dwordx4 v[222:223], off
	v_lshl_add_u64 v[222:223], s[42:43], 0, v[174:175]
	s_mov_b32 m0, s37
	s_nop 0
	global_load_lds_dwordx4 v[222:223], off
	s_mov_b32 m0, s46
	s_nop 0
	global_load_lds_dwordx4 v[224:225], off
	s_waitcnt vmcnt(8)
	s_waitcnt lgkmcnt(0)
	s_barrier
; #define PG8_STAGE(bufoff, gbase, voff) do { _Pragma("unroll") for (int _i = 0; _i < 2; ++_i) \
;         __builtin_amdgcn_global_load_lds((const unsigned*)((const char*)(gbase) + (voff)[_i]), (PG8_LAS unsigned*)(lds + (bufoff) + ldsw + _i * 8192), 16, 0, 0); } while (0)
; #define PG8_LDA(dst, b, h) do { _Pragma("unroll") for (int m = 0; m < 4; ++m) _Pragma("unroll") for (int k = 0; k < 2; ++k) dst[m][k] = *(const PG8_LAS bf16x8*)(lds + PG8_SA(b, h) + aoff + m * 2048 + k * 1024); } while (0)
; #define PG8_LDB(dst, b, h) do { _Pragma("unroll") for (int n = 0; n < 2; ++n) _Pragma("unroll") for (int k = 0; k < 2; ++k) dst[n][k] = *(const PG8_LAS bf16x8*)(lds + PG8_SB(b, h) + boff + n * 2048 + k * 1024); } while (0)
; #define PG8_MMA(ai, bj, At, Bt) do { __builtin_amdgcn_s_setprio(1); _Pragma("unroll") for (int m = 0; m < 4; ++m) _Pragma("unroll") for (int n = 0; n < 2; ++n) _Pragma("unroll") for (int k = 0; k < 2; ++k) \
;         acc[ai][bj][m][n] = __builtin_amdgcn_mfma_f32_16x16x32_bf16(Bt[n][k], At[m][k], acc[ai][bj][m][n], 0, 0, 0); __builtin_amdgcn_s_setprio(0); } while (0)
; #define PG8_WAIT_V(n) asm volatile("s_waitcnt vmcnt(" #n ")" ::: "memory")
; #define PG8_WAIT_L(n) asm volatile("s_waitcnt lgkmcnt(" #n ")" ::: "memory")
; #define PG8_BAR __builtin_amdgcn_s_barrier()
; #define PG8_SCHED __builtin_amdgcn_sched_barrier(0)
; template <class Epi, class Sched>
; __device__ __forceinline__ void gemm_phase(PG8_LAS unsigned char* lds, const Gemm g, const Sched& S, const Epi& E) {
;     ...
;             PG8_WAIT_V(8); PG8_WAIT_L(0); PG8_BAR; PG8_MMA(1, 0, At, B0); PG8_MMA(1, 1, At, B1); PG8_BAR; PG8_SCHED;
;             PG8_LDB(B0, 1, 0); PG8_LDB(B1, 1, 1); PG8_SCHED; PG8_LDA(At, 1, 0); PG8_STAGE(PG8_SA(0, 1), a2 + hstepA, voffA);
;             PG8_WAIT_V(8); PG8_WAIT_L(0); PG8_BAR; PG8_MMA(0, 0, At, B0); PG8_MMA(0, 1, At, B1); PG8_BAR; PG8_SCHED;
	s_setprio 1
	s_waitcnt lgkmcnt(0)
	v_mfma_f32_16x16x32_bf16 v[60:63], v[128:131], v[160:163], v[60:63]
	v_mfma_f32_16x16x32_bf16 v[56:59], v[136:139], v[160:163], v[56:59]
	v_mfma_f32_16x16x32_bf16 v[44:47], v[128:131], v[184:187], v[44:47]
	v_mfma_f32_16x16x32_bf16 v[40:43], v[136:139], v[184:187], v[40:43]
	v_mfma_f32_16x16x32_bf16 v[28:31], v[128:131], v[192:195], v[28:31]
	v_mfma_f32_16x16x32_bf16 v[24:27], v[136:139], v[192:195], v[24:27]
	v_mfma_f32_16x16x32_bf16 v[12:15], v[128:131], v[212:215], v[12:15]
	v_mfma_f32_16x16x32_bf16 v[8:11], v[136:139], v[212:215], v[8:11]
	v_mfma_f32_16x16x32_bf16 v[60:63], v[132:135], v[164:167], v[60:63]
	v_mfma_f32_16x16x32_bf16 v[56:59], v[140:143], v[164:167], v[56:59]
	v_mfma_f32_16x16x32_bf16 v[44:47], v[132:135], v[188:191], v[44:47]
	v_mfma_f32_16x16x32_bf16 v[40:43], v[140:143], v[188:191], v[40:43]
	v_mfma_f32_16x16x32_bf16 v[28:31], v[132:135], v[208:211], v[28:31]
	v_mfma_f32_16x16x32_bf16 v[24:27], v[140:143], v[208:211], v[24:27]
	v_mfma_f32_16x16x32_bf16 v[12:15], v[132:135], v[216:219], v[12:15]
	v_mfma_f32_16x16x32_bf16 v[8:11], v[140:143], v[216:219], v[8:11]
	v_mfma_f32_16x16x32_bf16 v[52:55], v[144:147], v[160:163], v[52:55]
	v_mfma_f32_16x16x32_bf16 v[48:51], v[152:155], v[160:163], v[48:51]
	v_mfma_f32_16x16x32_bf16 v[36:39], v[144:147], v[184:187], v[36:39]
	v_mfma_f32_16x16x32_bf16 v[32:35], v[152:155], v[184:187], v[32:35]
	v_mfma_f32_16x16x32_bf16 v[20:23], v[144:147], v[192:195], v[20:23]
	v_mfma_f32_16x16x32_bf16 v[16:19], v[152:155], v[192:195], v[16:19]
	v_mfma_f32_16x16x32_bf16 v[4:7], v[144:147], v[212:215], v[4:7]
	v_mfma_f32_16x16x32_bf16 v[0:3], v[152:155], v[212:215], v[0:3]
	v_mfma_f32_16x16x32_bf16 v[52:55], v[148:151], v[164:167], v[52:55]
	v_mfma_f32_16x16x32_bf16 v[48:51], v[156:159], v[164:167], v[48:51]
	v_mfma_f32_16x16x32_bf16 v[36:39], v[148:151], v[188:191], v[36:39]
	v_mfma_f32_16x16x32_bf16 v[32:35], v[156:159], v[188:191], v[32:35]
	v_mfma_f32_16x16x32_bf16 v[20:23], v[148:151], v[208:211], v[20:23]
	v_mfma_f32_16x16x32_bf16 v[16:19], v[156:159], v[208:211], v[16:19]
	v_mfma_f32_16x16x32_bf16 v[4:7], v[148:151], v[216:219], v[4:7]
	v_mfma_f32_16x16x32_bf16 v[0:3], v[156:159], v[216:219], v[0:3]
	s_setprio 0
	s_barrier
	s_add_i32 s62, 0, 0x18000
	s_add_i32 s63, 0, 0x1c000
	v_add_u32_e32 v140, s62, v201
	v_add_u32_e32 v156, s63, v201
	ds_read_b128 v[128:131], v140
	ds_read_b128 v[132:135], v140 offset:1024
	ds_read_b128 v[136:139], v140 offset:2048
	ds_read_b128 v[140:143], v140 offset:3072
	ds_read_b128 v[144:147], v156
	ds_read_b128 v[148:151], v156 offset:1024
	ds_read_b128 v[152:155], v156 offset:2048
	ds_read_b128 v[156:159], v156 offset:3072
	s_add_u32 s42, s42, 0x40000
	s_addc_u32 s43, s43, 0
	s_mov_b32 m0, s47
	v_lshl_add_u64 v[226:227], s[42:43], 0, v[174:175]
	ds_read_b128 v[160:163], v205 offset:32768
	ds_read_b128 v[164:167], v205 offset:33792
	ds_read_b128 v[184:187], v205 offset:34816
	ds_read_b128 v[188:191], v205 offset:35840
	ds_read_b128 v[192:195], v205 offset:36864
	ds_read_b128 v[208:211], v205 offset:37888
	ds_read_b128 v[212:215], v205 offset:38912
	ds_read_b128 v[216:219], v205 offset:39936
	global_load_lds_dwordx4 v[226:227], off
	v_lshl_add_u64 v[226:227], s[42:43], 0, v[170:171]
	s_mov_b32 m0, s48
	s_nop 0
	global_load_lds_dwordx4 v[226:227], off
	s_waitcnt vmcnt(8)
	s_waitcnt lgkmcnt(0)
	s_barrier
	s_setprio 1
	s_waitcnt lgkmcnt(0)
	v_mfma_f32_16x16x32_bf16 v[124:127], v[128:131], v[160:163], v[124:127]
	v_mfma_f32_16x16x32_bf16 v[120:123], v[136:139], v[160:163], v[120:123]
	v_mfma_f32_16x16x32_bf16 v[108:111], v[128:131], v[184:187], v[108:111]
	v_mfma_f32_16x16x32_bf16 v[104:107], v[136:139], v[184:187], v[104:107]
	v_mfma_f32_16x16x32_bf16 v[92:95], v[128:131], v[192:195], v[92:95]
	v_mfma_f32_16x16x32_bf16 v[88:91], v[136:139], v[192:195], v[88:91]
	v_mfma_f32_16x16x32_bf16 v[76:79], v[128:131], v[212:215], v[76:79]
	v_mfma_f32_16x16x32_bf16 v[72:75], v[136:139], v[212:215], v[72:75]
	v_mfma_f32_16x16x32_bf16 v[124:127], v[132:135], v[164:167], v[124:127]
	v_mfma_f32_16x16x32_bf16 v[120:123], v[140:143], v[164:167], v[120:123]
	v_mfma_f32_16x16x32_bf16 v[108:111], v[132:135], v[188:191], v[108:111]
	v_mfma_f32_16x16x32_bf16 v[104:107], v[140:143], v[188:191], v[104:107]
	v_mfma_f32_16x16x32_bf16 v[92:95], v[132:135], v[208:211], v[92:95]
	v_mfma_f32_16x16x32_bf16 v[88:91], v[140:143], v[208:211], v[88:91]
	v_mfma_f32_16x16x32_bf16 v[76:79], v[132:135], v[216:219], v[76:79]
	v_mfma_f32_16x16x32_bf16 v[72:75], v[140:143], v[216:219], v[72:75]
	v_mfma_f32_16x16x32_bf16 v[116:119], v[144:147], v[160:163], v[116:119]
	v_mfma_f32_16x16x32_bf16 v[112:115], v[152:155], v[160:163], v[112:115]
	v_mfma_f32_16x16x32_bf16 v[100:103], v[144:147], v[184:187], v[100:103]
	v_mfma_f32_16x16x32_bf16 v[96:99], v[152:155], v[184:187], v[96:99]
	v_mfma_f32_16x16x32_bf16 v[84:87], v[144:147], v[192:195], v[84:87]
	v_mfma_f32_16x16x32_bf16 v[80:83], v[152:155], v[192:195], v[80:83]
	v_mfma_f32_16x16x32_bf16 v[68:71], v[144:147], v[212:215], v[68:71]
	v_mfma_f32_16x16x32_bf16 v[64:67], v[152:155], v[212:215], v[64:67]
	v_mfma_f32_16x16x32_bf16 v[116:119], v[148:151], v[164:167], v[116:119]
	v_mfma_f32_16x16x32_bf16 v[112:115], v[156:159], v[164:167], v[112:115]
	v_mfma_f32_16x16x32_bf16 v[100:103], v[148:151], v[188:191], v[100:103]
	v_mfma_f32_16x16x32_bf16 v[96:99], v[156:159], v[188:191], v[96:99]
	v_mfma_f32_16x16x32_bf16 v[84:87], v[148:151], v[208:211], v[84:87]
	v_mfma_f32_16x16x32_bf16 v[80:83], v[156:159], v[208:211], v[80:83]
	v_mfma_f32_16x16x32_bf16 v[68:71], v[148:151], v[216:219], v[68:71]
	v_mfma_f32_16x16x32_bf16 v[64:67], v[156:159], v[216:219], v[64:67]
	s_setprio 0
	s_barrier
; #define PG8_STAGE(bufoff, gbase, voff) do { _Pragma("unroll") for (int _i = 0; _i < 2; ++_i) \
;         __builtin_amdgcn_global_load_lds((const unsigned*)((const char*)(gbase) + (voff)[_i]), (PG8_LAS unsigned*)(lds + (bufoff) + ldsw + _i * 8192), 16, 0, 0); } while (0)
; #define PG8_LDA(dst, b, h) do { _Pragma("unroll") for (int m = 0; m < 4; ++m) _Pragma("unroll") for (int k = 0; k < 2; ++k) dst[m][k] = *(const PG8_LAS bf16x8*)(lds + PG8_SA(b, h) + aoff + m * 2048 + k * 1024); } while (0)
; #define PG8_MMA(ai, bj, At, Bt) do { __builtin_amdgcn_s_setprio(1); _Pragma("unroll") for (int m = 0; m < 4; ++m) _Pragma("unroll") for (int n = 0; n < 2; ++n) _Pragma("unroll") for (int k = 0; k < 2; ++k) \
;         acc[ai][bj][m][n] = __builtin_amdgcn_mfma_f32_16x16x32_bf16(Bt[n][k], At[m][k], acc[ai][bj][m][n], 0, 0, 0); __builtin_amdgcn_s_setprio(0); } while (0)
; #define PG8_WAIT_V(n) asm volatile("s_waitcnt vmcnt(" #n ")" ::: "memory")
; #define PG8_WAIT_L(n) asm volatile("s_waitcnt lgkmcnt(" #n ")" ::: "memory")
; #define PG8_BAR __builtin_amdgcn_s_barrier()
; #define PG8_SCHED __builtin_amdgcn_sched_barrier(0)
; template <class Epi, class Sched>
; __device__ __forceinline__ void gemm_phase(PG8_LAS unsigned char* lds, const Gemm g, const Sched& S, const Epi& E) {
;     ...
;             PG8_LDA(At, 1, 1); PG8_STAGE(PG8_SB(1, 0), b3, voffB); PG8_STAGE(PG8_SB(1, 1), b3 + hstepB, voffB); PG8_STAGE(PG8_SA(1, 0), a3, voffA);
;             PG8_WAIT_V(8); PG8_WAIT_L(0); PG8_BAR; PG8_MMA(1, 0, At, B0); PG8_MMA(1, 1, At, B1); PG8_BAR; PG8_SCHED;
;         }
;         if (wr == 0) PG8_BAR;
	s_add_i32 s42, s62, s33
	v_lshl_add_u64 v[196:197], v[196:197], 0, s[6:7]
	s_mov_b32 m0, s42
	ds_read_b128 v[160:163], v205 offset:49152
	ds_read_b128 v[164:167], v205 offset:50176
	ds_read_b128 v[184:187], v205 offset:51200
	ds_read_b128 v[188:191], v205 offset:52224
	ds_read_b128 v[192:195], v205 offset:53248
	ds_read_b128 v[208:211], v205 offset:54272
	ds_read_b128 v[212:215], v205 offset:55296
	ds_read_b128 v[216:219], v205 offset:56320
	global_load_lds_dwordx4 v[196:197], off
	s_add_i32 m0, s42, 0x2000
	s_add_u32 s40, s40, 0x40080
	v_lshl_add_u64 v[196:197], v[220:221], 0, s[6:7]
	s_addc_u32 s41, s41, 0
	s_add_i32 s42, s63, s33
	global_load_lds_dwordx4 v[196:197], off
	v_lshl_add_u64 v[196:197], s[40:41], 0, v[172:173]
	s_mov_b32 m0, s42
	s_nop 0
	global_load_lds_dwordx4 v[196:197], off
	v_lshl_add_u64 v[196:197], s[40:41], 0, v[168:169]
	s_add_i32 m0, s42, 0x2000
	s_nop 0
	global_load_lds_dwordx4 v[196:197], off
	v_lshl_add_u64 v[196:197], v[222:223], 0, s[6:7]
	s_mov_b32 m0, s50
	s_nop 0
	global_load_lds_dwordx4 v[196:197], off
	v_lshl_add_u64 v[196:197], v[224:225], 0, s[6:7]
	s_mov_b32 m0, s51
	s_nop 0
	global_load_lds_dwordx4 v[196:197], off
	s_waitcnt vmcnt(8)
	s_waitcnt lgkmcnt(0)
	s_barrier
	s_setprio 1
	s_waitcnt lgkmcnt(0)
	v_mfma_f32_16x16x32_bf16 v[60:63], v[128:131], v[160:163], v[60:63]
	v_mfma_f32_16x16x32_bf16 v[56:59], v[136:139], v[160:163], v[56:59]
	v_mfma_f32_16x16x32_bf16 v[44:47], v[128:131], v[184:187], v[44:47]
	v_mfma_f32_16x16x32_bf16 v[40:43], v[136:139], v[184:187], v[40:43]
	v_mfma_f32_16x16x32_bf16 v[28:31], v[128:131], v[192:195], v[28:31]
	v_mfma_f32_16x16x32_bf16 v[24:27], v[136:139], v[192:195], v[24:27]
	v_mfma_f32_16x16x32_bf16 v[12:15], v[128:131], v[212:215], v[12:15]
	v_mfma_f32_16x16x32_bf16 v[8:11], v[136:139], v[212:215], v[8:11]
	v_mfma_f32_16x16x32_bf16 v[60:63], v[132:135], v[164:167], v[60:63]
	v_mfma_f32_16x16x32_bf16 v[56:59], v[140:143], v[164:167], v[56:59]
	v_mfma_f32_16x16x32_bf16 v[44:47], v[132:135], v[188:191], v[44:47]
	v_mfma_f32_16x16x32_bf16 v[40:43], v[140:143], v[188:191], v[40:43]
	v_mfma_f32_16x16x32_bf16 v[28:31], v[132:135], v[208:211], v[28:31]
	v_mfma_f32_16x16x32_bf16 v[24:27], v[140:143], v[208:211], v[24:27]
	v_mfma_f32_16x16x32_bf16 v[12:15], v[132:135], v[216:219], v[12:15]
	v_mfma_f32_16x16x32_bf16 v[8:11], v[140:143], v[216:219], v[8:11]
	v_mfma_f32_16x16x32_bf16 v[52:55], v[144:147], v[160:163], v[52:55]
	v_mfma_f32_16x16x32_bf16 v[48:51], v[152:155], v[160:163], v[48:51]
	v_mfma_f32_16x16x32_bf16 v[36:39], v[144:147], v[184:187], v[36:39]
	v_mfma_f32_16x16x32_bf16 v[32:35], v[152:155], v[184:187], v[32:35]
	v_mfma_f32_16x16x32_bf16 v[20:23], v[144:147], v[192:195], v[20:23]
	v_mfma_f32_16x16x32_bf16 v[16:19], v[152:155], v[192:195], v[16:19]
	v_mfma_f32_16x16x32_bf16 v[4:7], v[144:147], v[212:215], v[4:7]
	v_mfma_f32_16x16x32_bf16 v[0:3], v[152:155], v[212:215], v[0:3]
	v_mfma_f32_16x16x32_bf16 v[52:55], v[148:151], v[164:167], v[52:55]
	v_mfma_f32_16x16x32_bf16 v[48:51], v[156:159], v[164:167], v[48:51]
	v_mfma_f32_16x16x32_bf16 v[36:39], v[148:151], v[188:191], v[36:39]
	v_mfma_f32_16x16x32_bf16 v[32:35], v[156:159], v[188:191], v[32:35]
	v_mfma_f32_16x16x32_bf16 v[20:23], v[148:151], v[208:211], v[20:23]
	v_mfma_f32_16x16x32_bf16 v[16:19], v[156:159], v[208:211], v[16:19]
	v_mfma_f32_16x16x32_bf16 v[4:7], v[148:151], v[216:219], v[4:7]
	v_mfma_f32_16x16x32_bf16 v[0:3], v[156:159], v[216:219], v[0:3]
	s_setprio 0
	s_barrier
	s_add_i32 s61, s61, 2
	s_add_u32 s38, s38, 0x100
	s_addc_u32 s39, s39, 0
	s_add_u32 s59, s59, 0x100
	s_addc_u32 s60, s60, 0
	s_cmp_gt_u32 s61, 13
	s_cbranch_scc0 .LBB0_1654
	s_and_b64 vcc, exec, s[10:11]
	s_cbranch_vccz .LBB0_1657
	s_barrier

; #define PG8_STAGE(bufoff, gbase, voff) do { _Pragma("unroll") for (int _i = 0; _i < 2; ++_i) \
;         __builtin_amdgcn_global_load_lds((const unsigned*)((const char*)(gbase) + (voff)[_i]), (PG8_LAS unsigned*)(lds + (bufoff) + ldsw + _i * 8192), 16, 0, 0); } while (0)
; #define PG8_LDA(dst, b, h) do { _Pragma("unroll") for (int m = 0; m < 4; ++m) _Pragma("unroll") for (int k = 0; k < 2; ++k) dst[m][k] = *(const PG8_LAS bf16x8*)(lds + PG8_SA(b, h) + aoff + m * 2048 + k * 1024); } while (0)
; #define PG8_LDB(dst, b, h) do { _Pragma("unroll") for (int n = 0; n < 2; ++n) _Pragma("unroll") for (int k = 0; k < 2; ++k) dst[n][k] = *(const PG8_LAS bf16x8*)(lds + PG8_SB(b, h) + boff + n * 2048 + k * 1024); } while (0)
; #define PG8_MMA(ai, bj, At, Bt) do { __builtin_amdgcn_s_setprio(1); _Pragma("unroll") for (int m = 0; m < 4; ++m) _Pragma("unroll") for (int n = 0; n < 2; ++n) _Pragma("unroll") for (int k = 0; k < 2; ++k) \
;         acc[ai][bj][m][n] = __builtin_amdgcn_mfma_f32_16x16x32_bf16(Bt[n][k], At[m][k], acc[ai][bj][m][n], 0, 0, 0); __builtin_amdgcn_s_setprio(0); } while (0)
; #define PG8_WAIT_V(n) asm volatile("s_waitcnt vmcnt(" #n ")" ::: "memory")
; #define PG8_WAIT_L(n) asm volatile("s_waitcnt lgkmcnt(" #n ")" ::: "memory")
; #define PG8_BAR __builtin_amdgcn_s_barrier()
; #define PG8_SCHED __builtin_amdgcn_sched_barrier(0)
; template <class Epi, class Sched>
; __device__ __forceinline__ void gemm_phase(PG8_LAS unsigned char* lds, const Gemm g, const Sched& S, const Epi& E) {
;     ...
;             PG8_LDB(B0, 0, 0); PG8_LDB(B1, 0, 1); PG8_SCHED; PG8_LDA(At, 0, 0); PG8_STAGE(PG8_SA(1, 1), a1 + hstepA, voffA);
;             PG8_WAIT_V(8); PG8_WAIT_L(0); PG8_BAR; PG8_MMA(0, 0, At, B0); PG8_MMA(0, 1, At, B1); PG8_BAR; PG8_SCHED;
;             PG8_LDA(At, 0, 1); PG8_STAGE(PG8_SB(0, 0), b2, voffB); PG8_STAGE(PG8_SB(0, 1), b2 + hstepB, voffB); PG8_STAGE(PG8_SA(0, 0), a2, voffA);
.LBB0_1722:
	ds_read_b128 v[150:153], v147
	ds_read_b128 v[154:157], v147 offset:1024
	ds_read_b128 v[158:161], v147 offset:2048
	ds_read_b128 v[162:165], v147 offset:3072
	ds_read_b128 v[166:169], v148
	ds_read_b128 v[170:173], v148 offset:1024
	ds_read_b128 v[174:177], v148 offset:2048
	ds_read_b128 v[178:181], v148 offset:3072
	s_add_u32 s36, s8, 0x2400
	s_addc_u32 s37, s9, 0
	s_cmp_eq_u32 s61, 28
	s_cselect_b32 s42, s56, s36
	s_cselect_b32 s43, s55, s37
	s_cselect_b32 s40, s58, s59
	s_cselect_b32 s41, s57, s60
	s_add_u32 s38, s42, 0x1200
	s_addc_u32 s39, s43, 0
	v_lshl_add_u64 v[142:143], s[8:9], 0, v[138:139]
	s_add_i32 m0, s44, 0xc000
	ds_read_b128 v[182:185], v149
	ds_read_b128 v[186:189], v149 offset:1024
	ds_read_b128 v[190:193], v149 offset:2048
	ds_read_b128 v[194:197], v149 offset:3072
	ds_read_b128 v[200:203], v149 offset:4096
	ds_read_b128 v[204:207], v149 offset:5120
	ds_read_b128 v[208:211], v149 offset:6144
	ds_read_b128 v[212:215], v149 offset:7168
	global_load_lds_dwordx4 v[142:143], off
	v_lshl_add_u64 v[142:143], s[8:9], 0, v[140:141]
	s_add_i32 m0, s44, 0xe000
	s_nop 0
	global_load_lds_dwordx4 v[142:143], off
	s_waitcnt vmcnt(8)
	s_waitcnt lgkmcnt(0)
	s_barrier
	s_setprio 1
	s_waitcnt lgkmcnt(0)
	v_mfma_f32_16x16x32_bf16 v[124:127], v[150:153], v[182:185], v[124:127]
	v_mfma_f32_16x16x32_bf16 v[120:123], v[158:161], v[182:185], v[120:123]
	v_mfma_f32_16x16x32_bf16 v[108:111], v[150:153], v[190:193], v[108:111]
	v_mfma_f32_16x16x32_bf16 v[104:107], v[158:161], v[190:193], v[104:107]
	v_mfma_f32_16x16x32_bf16 v[92:95], v[150:153], v[200:203], v[92:95]
	v_mfma_f32_16x16x32_bf16 v[88:91], v[158:161], v[200:203], v[88:91]
	v_mfma_f32_16x16x32_bf16 v[76:79], v[150:153], v[208:211], v[76:79]
	v_mfma_f32_16x16x32_bf16 v[72:75], v[158:161], v[208:211], v[72:75]
	v_mfma_f32_16x16x32_bf16 v[124:127], v[154:157], v[186:189], v[124:127]
	v_mfma_f32_16x16x32_bf16 v[120:123], v[162:165], v[186:189], v[120:123]
	v_mfma_f32_16x16x32_bf16 v[108:111], v[154:157], v[194:197], v[108:111]
	v_mfma_f32_16x16x32_bf16 v[104:107], v[162:165], v[194:197], v[104:107]
	v_mfma_f32_16x16x32_bf16 v[92:95], v[154:157], v[204:207], v[92:95]
	v_mfma_f32_16x16x32_bf16 v[88:91], v[162:165], v[204:207], v[88:91]
	v_mfma_f32_16x16x32_bf16 v[76:79], v[154:157], v[212:215], v[76:79]
	v_mfma_f32_16x16x32_bf16 v[72:75], v[162:165], v[212:215], v[72:75]
	v_mfma_f32_16x16x32_bf16 v[116:119], v[166:169], v[182:185], v[116:119]
	v_mfma_f32_16x16x32_bf16 v[112:115], v[174:177], v[182:185], v[112:115]
	v_mfma_f32_16x16x32_bf16 v[100:103], v[166:169], v[190:193], v[100:103]
	v_mfma_f32_16x16x32_bf16 v[96:99], v[174:177], v[190:193], v[96:99]
	v_mfma_f32_16x16x32_bf16 v[84:87], v[166:169], v[200:203], v[84:87]
	v_mfma_f32_16x16x32_bf16 v[80:83], v[174:177], v[200:203], v[80:83]
	v_mfma_f32_16x16x32_bf16 v[68:71], v[166:169], v[208:211], v[68:71]
	v_mfma_f32_16x16x32_bf16 v[64:67], v[174:177], v[208:211], v[64:67]
	v_mfma_f32_16x16x32_bf16 v[116:119], v[170:173], v[186:189], v[116:119]
	v_mfma_f32_16x16x32_bf16 v[112:115], v[178:181], v[186:189], v[112:115]
	v_mfma_f32_16x16x32_bf16 v[100:103], v[170:173], v[194:197], v[100:103]
	v_mfma_f32_16x16x32_bf16 v[96:99], v[178:181], v[194:197], v[96:99]
	v_mfma_f32_16x16x32_bf16 v[84:87], v[170:173], v[204:207], v[84:87]
	v_mfma_f32_16x16x32_bf16 v[80:83], v[178:181], v[204:207], v[80:83]
	v_mfma_f32_16x16x32_bf16 v[68:71], v[170:173], v[212:215], v[68:71]
	v_mfma_f32_16x16x32_bf16 v[64:67], v[178:181], v[212:215], v[64:67]
	s_setprio 0
	s_barrier
	s_add_i32 s8, s51, s33
	v_lshl_add_u64 v[142:143], s[40:41], 0, v[132:133]
	s_mov_b32 m0, s8
	ds_read_b128 v[182:185], v149 offset:16384
	ds_read_b128 v[186:189], v149 offset:17408
	ds_read_b128 v[190:193], v149 offset:18432
	ds_read_b128 v[194:197], v149 offset:19456
	ds_read_b128 v[200:203], v149 offset:20480
	ds_read_b128 v[204:207], v149 offset:21504
	ds_read_b128 v[208:211], v149 offset:22528
	ds_read_b128 v[212:215], v149 offset:23552
	global_load_lds_dwordx4 v[142:143], off
	s_add_i32 m0, s8, 0x2000
	s_add_u32 s8, s40, 0x80000
	v_lshl_add_u64 v[216:217], s[40:41], 0, v[128:129]
	s_addc_u32 s9, s41, 0
	s_add_i32 s62, s52, s33
	global_load_lds_dwordx4 v[216:217], off
	v_lshl_add_u64 v[218:219], s[8:9], 0, v[132:133]
	s_mov_b32 m0, s62
	s_nop 0
	global_load_lds_dwordx4 v[218:219], off
	v_lshl_add_u64 v[218:219], s[8:9], 0, v[128:129]
	s_add_i32 m0, s62, 0x2000
	s_nop 0
	global_load_lds_dwordx4 v[218:219], off
	v_lshl_add_u64 v[218:219], s[42:43], 0, v[134:135]
	s_mov_b32 m0, s44
	s_nop 0
	global_load_lds_dwordx4 v[218:219], off
	v_lshl_add_u64 v[218:219], s[42:43], 0, v[130:131]
	s_mov_b32 m0, s45
	s_nop 0
	global_load_lds_dwordx4 v[218:219], off
	s_waitcnt vmcnt(8)
	s_waitcnt lgkmcnt(0)
	s_barrier
; #define PG8_STAGE(bufoff, gbase, voff) do { _Pragma("unroll") for (int _i = 0; _i < 2; ++_i) \
;         __builtin_amdgcn_global_load_lds((const unsigned*)((const char*)(gbase) + (voff)[_i]), (PG8_LAS unsigned*)(lds + (bufoff) + ldsw + _i * 8192), 16, 0, 0); } while (0)
; #define PG8_LDA(dst, b, h) do { _Pragma("unroll") for (int m = 0; m < 4; ++m) _Pragma("unroll") for (int k = 0; k < 2; ++k) dst[m][k] = *(const PG8_LAS bf16x8*)(lds + PG8_SA(b, h) + aoff + m * 2048 + k * 1024); } while (0)
; #define PG8_LDB(dst, b, h) do { _Pragma("unroll") for (int n = 0; n < 2; ++n) _Pragma("unroll") for (int k = 0; k < 2; ++k) dst[n][k] = *(const PG8_LAS bf16x8*)(lds + PG8_SB(b, h) + boff + n * 2048 + k * 1024); } while (0)
; #define PG8_MMA(ai, bj, At, Bt) do { __builtin_amdgcn_s_setprio(1); _Pragma("unroll") for (int m = 0; m < 4; ++m) _Pragma("unroll") for (int n = 0; n < 2; ++n) _Pragma("unroll") for (int k = 0; k < 2; ++k) \
;         acc[ai][bj][m][n] = __builtin_amdgcn_mfma_f32_16x16x32_bf16(Bt[n][k], At[m][k], acc[ai][bj][m][n], 0, 0, 0); __builtin_amdgcn_s_setprio(0); } while (0)
; #define PG8_WAIT_V(n) asm volatile("s_waitcnt vmcnt(" #n ")" ::: "memory")
; #define PG8_WAIT_L(n) asm volatile("s_waitcnt lgkmcnt(" #n ")" ::: "memory")
; #define PG8_BAR __builtin_amdgcn_s_barrier()
; #define PG8_SCHED __builtin_amdgcn_sched_barrier(0)
; template <class Epi, class Sched>
; __device__ __forceinline__ void gemm_phase(PG8_LAS unsigned char* lds, const Gemm g, const Sched& S, const Epi& E) {
;     ...
;             PG8_WAIT_V(8); PG8_WAIT_L(0); PG8_BAR; PG8_MMA(1, 0, At, B0); PG8_MMA(1, 1, At, B1); PG8_BAR; PG8_SCHED;
;             PG8_LDB(B0, 1, 0); PG8_LDB(B1, 1, 1); PG8_SCHED; PG8_LDA(At, 1, 0); PG8_STAGE(PG8_SA(0, 1), a2 + hstepA, voffA);
;             PG8_WAIT_V(8); PG8_WAIT_L(0); PG8_BAR; PG8_MMA(0, 0, At, B0); PG8_MMA(0, 1, At, B1); PG8_BAR; PG8_SCHED;
	s_setprio 1
	s_waitcnt lgkmcnt(0)
	v_mfma_f32_16x16x32_bf16 v[60:63], v[150:153], v[182:185], v[60:63]
	v_mfma_f32_16x16x32_bf16 v[56:59], v[158:161], v[182:185], v[56:59]
	v_mfma_f32_16x16x32_bf16 v[44:47], v[150:153], v[190:193], v[44:47]
	v_mfma_f32_16x16x32_bf16 v[40:43], v[158:161], v[190:193], v[40:43]
	v_mfma_f32_16x16x32_bf16 v[28:31], v[150:153], v[200:203], v[28:31]
	v_mfma_f32_16x16x32_bf16 v[24:27], v[158:161], v[200:203], v[24:27]
	v_mfma_f32_16x16x32_bf16 v[12:15], v[150:153], v[208:211], v[12:15]
	v_mfma_f32_16x16x32_bf16 v[8:11], v[158:161], v[208:211], v[8:11]
	v_mfma_f32_16x16x32_bf16 v[60:63], v[154:157], v[186:189], v[60:63]
	v_mfma_f32_16x16x32_bf16 v[56:59], v[162:165], v[186:189], v[56:59]
	v_mfma_f32_16x16x32_bf16 v[44:47], v[154:157], v[194:197], v[44:47]
	v_mfma_f32_16x16x32_bf16 v[40:43], v[162:165], v[194:197], v[40:43]
	v_mfma_f32_16x16x32_bf16 v[28:31], v[154:157], v[204:207], v[28:31]
	v_mfma_f32_16x16x32_bf16 v[24:27], v[162:165], v[204:207], v[24:27]
	v_mfma_f32_16x16x32_bf16 v[12:15], v[154:157], v[212:215], v[12:15]
	v_mfma_f32_16x16x32_bf16 v[8:11], v[162:165], v[212:215], v[8:11]
	v_mfma_f32_16x16x32_bf16 v[52:55], v[166:169], v[182:185], v[52:55]
	v_mfma_f32_16x16x32_bf16 v[48:51], v[174:177], v[182:185], v[48:51]
	v_mfma_f32_16x16x32_bf16 v[36:39], v[166:169], v[190:193], v[36:39]
	v_mfma_f32_16x16x32_bf16 v[32:35], v[174:177], v[190:193], v[32:35]
	v_mfma_f32_16x16x32_bf16 v[20:23], v[166:169], v[200:203], v[20:23]
	v_mfma_f32_16x16x32_bf16 v[16:19], v[174:177], v[200:203], v[16:19]
	v_mfma_f32_16x16x32_bf16 v[4:7], v[166:169], v[208:211], v[4:7]
	v_mfma_f32_16x16x32_bf16 v[0:3], v[174:177], v[208:211], v[0:3]
	v_mfma_f32_16x16x32_bf16 v[52:55], v[170:173], v[186:189], v[52:55]
	v_mfma_f32_16x16x32_bf16 v[48:51], v[178:181], v[186:189], v[48:51]
	v_mfma_f32_16x16x32_bf16 v[36:39], v[170:173], v[194:197], v[36:39]
	v_mfma_f32_16x16x32_bf16 v[32:35], v[178:181], v[194:197], v[32:35]
	v_mfma_f32_16x16x32_bf16 v[20:23], v[170:173], v[204:207], v[20:23]
	v_mfma_f32_16x16x32_bf16 v[16:19], v[178:181], v[204:207], v[16:19]
	v_mfma_f32_16x16x32_bf16 v[4:7], v[170:173], v[212:215], v[4:7]
	v_mfma_f32_16x16x32_bf16 v[0:3], v[178:181], v[212:215], v[0:3]
	s_setprio 0
	s_barrier
	s_add_i32 s62, 0, 0x18000
	s_add_i32 s63, 0, 0x1c000
	v_add_u32_e32 v162, s62, v145
	v_add_u32_e32 v178, s63, v145
	ds_read_b128 v[150:153], v162
	ds_read_b128 v[154:157], v162 offset:1024
	ds_read_b128 v[158:161], v162 offset:2048
	ds_read_b128 v[162:165], v162 offset:3072
	ds_read_b128 v[166:169], v178
	ds_read_b128 v[170:173], v178 offset:1024
	ds_read_b128 v[174:177], v178 offset:2048
	ds_read_b128 v[178:181], v178 offset:3072
	s_add_u32 s8, s42, 0x900000
	s_addc_u32 s9, s43, 0
	s_mov_b32 m0, s46
	v_lshl_add_u64 v[218:219], s[8:9], 0, v[134:135]
	ds_read_b128 v[182:185], v149 offset:32768
	ds_read_b128 v[186:189], v149 offset:33792
	ds_read_b128 v[190:193], v149 offset:34816
	ds_read_b128 v[194:197], v149 offset:35840
	ds_read_b128 v[200:203], v149 offset:36864
	ds_read_b128 v[204:207], v149 offset:37888
	ds_read_b128 v[208:211], v149 offset:38912
	ds_read_b128 v[212:215], v149 offset:39936
	global_load_lds_dwordx4 v[218:219], off
	v_lshl_add_u64 v[218:219], s[8:9], 0, v[130:131]
	s_mov_b32 m0, s47
	s_nop 0
	global_load_lds_dwordx4 v[218:219], off
	s_waitcnt vmcnt(8)
	s_waitcnt lgkmcnt(0)
	s_barrier
	s_setprio 1
	s_waitcnt lgkmcnt(0)
	v_mfma_f32_16x16x32_bf16 v[124:127], v[150:153], v[182:185], v[124:127]
	v_mfma_f32_16x16x32_bf16 v[120:123], v[158:161], v[182:185], v[120:123]
	v_mfma_f32_16x16x32_bf16 v[108:111], v[150:153], v[190:193], v[108:111]
	v_mfma_f32_16x16x32_bf16 v[104:107], v[158:161], v[190:193], v[104:107]
	v_mfma_f32_16x16x32_bf16 v[92:95], v[150:153], v[200:203], v[92:95]
	v_mfma_f32_16x16x32_bf16 v[88:91], v[158:161], v[200:203], v[88:91]
	v_mfma_f32_16x16x32_bf16 v[76:79], v[150:153], v[208:211], v[76:79]
	v_mfma_f32_16x16x32_bf16 v[72:75], v[158:161], v[208:211], v[72:75]
	v_mfma_f32_16x16x32_bf16 v[124:127], v[154:157], v[186:189], v[124:127]
	v_mfma_f32_16x16x32_bf16 v[120:123], v[162:165], v[186:189], v[120:123]
	v_mfma_f32_16x16x32_bf16 v[108:111], v[154:157], v[194:197], v[108:111]
	v_mfma_f32_16x16x32_bf16 v[104:107], v[162:165], v[194:197], v[104:107]
	v_mfma_f32_16x16x32_bf16 v[92:95], v[154:157], v[204:207], v[92:95]
	v_mfma_f32_16x16x32_bf16 v[88:91], v[162:165], v[204:207], v[88:91]
	v_mfma_f32_16x16x32_bf16 v[76:79], v[154:157], v[212:215], v[76:79]
	v_mfma_f32_16x16x32_bf16 v[72:75], v[162:165], v[212:215], v[72:75]
	v_mfma_f32_16x16x32_bf16 v[116:119], v[166:169], v[182:185], v[116:119]
	v_mfma_f32_16x16x32_bf16 v[112:115], v[174:177], v[182:185], v[112:115]
	v_mfma_f32_16x16x32_bf16 v[100:103], v[166:169], v[190:193], v[100:103]
	v_mfma_f32_16x16x32_bf16 v[96:99], v[174:177], v[190:193], v[96:99]
	v_mfma_f32_16x16x32_bf16 v[84:87], v[166:169], v[200:203], v[84:87]
	v_mfma_f32_16x16x32_bf16 v[80:83], v[174:177], v[200:203], v[80:83]
	v_mfma_f32_16x16x32_bf16 v[68:71], v[166:169], v[208:211], v[68:71]
	v_mfma_f32_16x16x32_bf16 v[64:67], v[174:177], v[208:211], v[64:67]
	v_mfma_f32_16x16x32_bf16 v[116:119], v[170:173], v[186:189], v[116:119]
	v_mfma_f32_16x16x32_bf16 v[112:115], v[178:181], v[186:189], v[112:115]
	v_mfma_f32_16x16x32_bf16 v[100:103], v[170:173], v[194:197], v[100:103]
	v_mfma_f32_16x16x32_bf16 v[96:99], v[178:181], v[194:197], v[96:99]
	v_mfma_f32_16x16x32_bf16 v[84:87], v[170:173], v[204:207], v[84:87]
	v_mfma_f32_16x16x32_bf16 v[80:83], v[178:181], v[204:207], v[80:83]
	v_mfma_f32_16x16x32_bf16 v[68:71], v[170:173], v[212:215], v[68:71]
	v_mfma_f32_16x16x32_bf16 v[64:67], v[178:181], v[212:215], v[64:67]
	s_setprio 0
	s_barrier
; #define PG8_STAGE(bufoff, gbase, voff) do { _Pragma("unroll") for (int _i = 0; _i < 2; ++_i) \
;         __builtin_amdgcn_global_load_lds((const unsigned*)((const char*)(gbase) + (voff)[_i]), (PG8_LAS unsigned*)(lds + (bufoff) + ldsw + _i * 8192), 16, 0, 0); } while (0)
; #define PG8_LDA(dst, b, h) do { _Pragma("unroll") for (int m = 0; m < 4; ++m) _Pragma("unroll") for (int k = 0; k < 2; ++k) dst[m][k] = *(const PG8_LAS bf16x8*)(lds + PG8_SA(b, h) + aoff + m * 2048 + k * 1024); } while (0)
; #define PG8_MMA(ai, bj, At, Bt) do { __builtin_amdgcn_s_setprio(1); _Pragma("unroll") for (int m = 0; m < 4; ++m) _Pragma("unroll") for (int n = 0; n < 2; ++n) _Pragma("unroll") for (int k = 0; k < 2; ++k) \
;         acc[ai][bj][m][n] = __builtin_amdgcn_mfma_f32_16x16x32_bf16(Bt[n][k], At[m][k], acc[ai][bj][m][n], 0, 0, 0); __builtin_amdgcn_s_setprio(0); } while (0)
; #define PG8_WAIT_V(n) asm volatile("s_waitcnt vmcnt(" #n ")" ::: "memory")
; #define PG8_WAIT_L(n) asm volatile("s_waitcnt lgkmcnt(" #n ")" ::: "memory")
; #define PG8_BAR __builtin_amdgcn_s_barrier()
; #define PG8_SCHED __builtin_amdgcn_sched_barrier(0)
; template <class Epi, class Sched>
; __device__ __forceinline__ void gemm_phase(PG8_LAS unsigned char* lds, const Gemm g, const Sched& S, const Epi& E) {
;     ...
;             PG8_LDA(At, 1, 1); PG8_STAGE(PG8_SB(1, 0), b3, voffB); PG8_STAGE(PG8_SB(1, 1), b3 + hstepB, voffB); PG8_STAGE(PG8_SA(1, 0), a3, voffA);
;             PG8_WAIT_V(8); PG8_WAIT_L(0); PG8_BAR; PG8_MMA(1, 0, At, B0); PG8_MMA(1, 1, At, B1); PG8_BAR; PG8_SCHED;
;         }
;         if (wr == 0) PG8_BAR;
	s_add_i32 s8, s62, s33
	v_lshl_add_u64 v[142:143], v[142:143], 0, s[10:11]
	s_mov_b32 m0, s8
	ds_read_b128 v[182:185], v149 offset:49152
	ds_read_b128 v[186:189], v149 offset:50176
	ds_read_b128 v[190:193], v149 offset:51200
	ds_read_b128 v[194:197], v149 offset:52224
	ds_read_b128 v[200:203], v149 offset:53248
	ds_read_b128 v[204:207], v149 offset:54272
	ds_read_b128 v[208:211], v149 offset:55296
	ds_read_b128 v[212:215], v149 offset:56320
	global_load_lds_dwordx4 v[142:143], off
	s_add_i32 m0, s8, 0x2000
	s_add_u32 s8, s40, 0x80080
	v_lshl_add_u64 v[142:143], v[216:217], 0, s[10:11]
	s_addc_u32 s9, s41, 0
	s_add_i32 s40, s63, s33
	global_load_lds_dwordx4 v[142:143], off
	v_lshl_add_u64 v[142:143], s[8:9], 0, v[132:133]
	s_mov_b32 m0, s40
	s_nop 0
	global_load_lds_dwordx4 v[142:143], off
	v_lshl_add_u64 v[142:143], s[8:9], 0, v[128:129]
	s_add_i32 m0, s40, 0x2000
	s_nop 0
	global_load_lds_dwordx4 v[142:143], off
	v_lshl_add_u64 v[142:143], s[38:39], 0, v[134:135]
	s_mov_b32 m0, s49
	s_nop 0
	global_load_lds_dwordx4 v[142:143], off
	v_lshl_add_u64 v[142:143], s[38:39], 0, v[130:131]
	s_mov_b32 m0, s50
	s_nop 0
	global_load_lds_dwordx4 v[142:143], off
	s_waitcnt vmcnt(8)
	s_waitcnt lgkmcnt(0)
	s_barrier
	s_setprio 1
	s_waitcnt lgkmcnt(0)
	v_mfma_f32_16x16x32_bf16 v[60:63], v[150:153], v[182:185], v[60:63]
	v_mfma_f32_16x16x32_bf16 v[56:59], v[158:161], v[182:185], v[56:59]
	v_mfma_f32_16x16x32_bf16 v[44:47], v[150:153], v[190:193], v[44:47]
	v_mfma_f32_16x16x32_bf16 v[40:43], v[158:161], v[190:193], v[40:43]
	v_mfma_f32_16x16x32_bf16 v[28:31], v[150:153], v[200:203], v[28:31]
	v_mfma_f32_16x16x32_bf16 v[24:27], v[158:161], v[200:203], v[24:27]
	v_mfma_f32_16x16x32_bf16 v[12:15], v[150:153], v[208:211], v[12:15]
	v_mfma_f32_16x16x32_bf16 v[8:11], v[158:161], v[208:211], v[8:11]
	v_mfma_f32_16x16x32_bf16 v[60:63], v[154:157], v[186:189], v[60:63]
	v_mfma_f32_16x16x32_bf16 v[56:59], v[162:165], v[186:189], v[56:59]
	v_mfma_f32_16x16x32_bf16 v[44:47], v[154:157], v[194:197], v[44:47]
	v_mfma_f32_16x16x32_bf16 v[40:43], v[162:165], v[194:197], v[40:43]
	v_mfma_f32_16x16x32_bf16 v[28:31], v[154:157], v[204:207], v[28:31]
	v_mfma_f32_16x16x32_bf16 v[24:27], v[162:165], v[204:207], v[24:27]
	v_mfma_f32_16x16x32_bf16 v[12:15], v[154:157], v[212:215], v[12:15]
	v_mfma_f32_16x16x32_bf16 v[8:11], v[162:165], v[212:215], v[8:11]
	v_mfma_f32_16x16x32_bf16 v[52:55], v[166:169], v[182:185], v[52:55]
	v_mfma_f32_16x16x32_bf16 v[48:51], v[174:177], v[182:185], v[48:51]
	v_mfma_f32_16x16x32_bf16 v[36:39], v[166:169], v[190:193], v[36:39]
	v_mfma_f32_16x16x32_bf16 v[32:35], v[174:177], v[190:193], v[32:35]
	v_mfma_f32_16x16x32_bf16 v[20:23], v[166:169], v[200:203], v[20:23]
	v_mfma_f32_16x16x32_bf16 v[16:19], v[174:177], v[200:203], v[16:19]
	v_mfma_f32_16x16x32_bf16 v[4:7], v[166:169], v[208:211], v[4:7]
	v_mfma_f32_16x16x32_bf16 v[0:3], v[174:177], v[208:211], v[0:3]
	v_mfma_f32_16x16x32_bf16 v[52:55], v[170:173], v[186:189], v[52:55]
	v_mfma_f32_16x16x32_bf16 v[48:51], v[178:181], v[186:189], v[48:51]
	v_mfma_f32_16x16x32_bf16 v[36:39], v[170:173], v[194:197], v[36:39]
	v_mfma_f32_16x16x32_bf16 v[32:35], v[178:181], v[194:197], v[32:35]
	v_mfma_f32_16x16x32_bf16 v[20:23], v[170:173], v[204:207], v[20:23]
	v_mfma_f32_16x16x32_bf16 v[16:19], v[178:181], v[204:207], v[16:19]
	v_mfma_f32_16x16x32_bf16 v[4:7], v[170:173], v[212:215], v[4:7]
	v_mfma_f32_16x16x32_bf16 v[0:3], v[178:181], v[212:215], v[0:3]
	s_setprio 0
	s_barrier
	s_add_i32 s61, s61, 2
	s_add_u32 s59, s59, 0x100
	s_addc_u32 s60, s60, 0
	s_cmp_gt_u32 s61, 29
	s_mov_b64 s[8:9], s[36:37]
	s_cbranch_scc0 .LBB0_1722
	s_and_b64 vcc, exec, s[12:13]
	s_cbranch_vccz .LBB0_1725
	s_barrier

; #define PG8_STAGE(bufoff, gbase, voff) do { _Pragma("unroll") for (int _i = 0; _i < 2; ++_i) \
;         __builtin_amdgcn_global_load_lds((const unsigned*)((const char*)(gbase) + (voff)[_i]), (PG8_LAS unsigned*)(lds + (bufoff) + ldsw + _i * 8192), 16, 0, 0); } while (0)
; #define PG8_LDA(dst, b, h) do { _Pragma("unroll") for (int m = 0; m < 4; ++m) _Pragma("unroll") for (int k = 0; k < 2; ++k) dst[m][k] = *(const PG8_LAS bf16x8*)(lds + PG8_SA(b, h) + aoff + m * 2048 + k * 1024); } while (0)
; #define PG8_LDB(dst, b, h) do { _Pragma("unroll") for (int n = 0; n < 2; ++n) _Pragma("unroll") for (int k = 0; k < 2; ++k) dst[n][k] = *(const PG8_LAS bf16x8*)(lds + PG8_SB(b, h) + boff + n * 2048 + k * 1024); } while (0)
; #define PG8_MMA(ai, bj, At, Bt) do { __builtin_amdgcn_s_setprio(1); _Pragma("unroll") for (int m = 0; m < 4; ++m) _Pragma("unroll") for (int n = 0; n < 2; ++n) _Pragma("unroll") for (int k = 0; k < 2; ++k) \
;         acc[ai][bj][m][n] = __builtin_amdgcn_mfma_f32_16x16x32_bf16(Bt[n][k], At[m][k], acc[ai][bj][m][n], 0, 0, 0); __builtin_amdgcn_s_setprio(0); } while (0)
; #define PG8_WAIT_V(n) asm volatile("s_waitcnt vmcnt(" #n ")" ::: "memory")
; #define PG8_WAIT_L(n) asm volatile("s_waitcnt lgkmcnt(" #n ")" ::: "memory")
; template <class Epi, class Sched>
; __device__ __forceinline__ void gemm_phase(PG8_LAS unsigned char* lds, const Gemm g, const Sched& S, const Epi& E) {
;     ...
;         for (int t = 0; t < nt; t += 2) {
;             const bool last = (t == nt - 2);
;             const char* a1 = cA + (size_t)(t + 1) * kstepA;
;             const char* a2 = last ? nA : cA + (size_t)(t + 2) * kstepA; const char* b2 = last ? nB : cB + (size_t)(t + 2) * kstep;
;             const char* a3 = a2 + kstepA; const char* b3 = b2 + kstep;
;             if constexpr (epi_has_hook<Epi>::value) { if (t == nt / 2) E.hook(acc, cur, wr, wc, fr, fq); }
;             PG8_LDB(B0, 0, 0); PG8_LDB(B1, 0, 1); PG8_SCHED; PG8_LDA(At, 0, 0); PG8_STAGE(PG8_SA(1, 1), a1 + hstepA, voffA);
;             PG8_WAIT_V(8); PG8_WAIT_L(0); PG8_BAR; PG8_MMA(0, 0, At, B0); PG8_MMA(0, 1, At, B1); PG8_BAR; PG8_SCHED;
;             PG8_LDA(At, 0, 1); PG8_STAGE(PG8_SB(0, 0), b2, voffB); PG8_STAGE(PG8_SB(0, 1), b2 + hstepB, voffB); PG8_STAGE(PG8_SA(0, 0), a2, voffA);
;             PG8_WAIT_V(8); PG8_WAIT_L(0); PG8_BAR; PG8_MMA(1, 0, At, B0); PG8_MMA(1, 1, At, B1); PG8_BAR; PG8_SCHED;
.LBB0_1989:
	ds_read_b128 v[148:151], v142
	ds_read_b128 v[152:155], v142 offset:1024
	ds_read_b128 v[156:159], v142 offset:2048
	ds_read_b128 v[160:163], v142 offset:3072
	ds_read_b128 v[164:167], v143
	ds_read_b128 v[168:171], v143 offset:1024
	ds_read_b128 v[172:175], v143 offset:2048
	ds_read_b128 v[176:179], v143 offset:3072
	s_add_u32 s20, s14, s18
	s_addc_u32 s21, s15, s19
	s_add_u32 s20, s20, 0x3e100100
	s_addc_u32 s21, s21, 0
	s_add_u32 s47, s34, s18
	s_addc_u32 s48, s35, s19
	s_cmpk_eq_i32 s18, 0x700
	s_cselect_b32 s23, s11, s21
	s_cselect_b32 s22, s10, s20
	s_cselect_b32 s21, s9, s48
	s_cselect_b32 s20, s8, s47
	s_mov_b32 m0, s37
	v_lshl_add_u64 v[196:197], v[136:137], 0, s[18:19]
	ds_read_b128 v[180:183], v144
	ds_read_b128 v[184:187], v144 offset:1024
	ds_read_b128 v[188:191], v144 offset:2048
	ds_read_b128 v[192:195], v144 offset:3072
	ds_read_b128 v[200:203], v144 offset:4096
	ds_read_b128 v[204:207], v144 offset:5120
	ds_read_b128 v[208:211], v144 offset:6144
	ds_read_b128 v[212:215], v144 offset:7168
	global_load_lds_dwordx4 v[196:197], off
	v_lshl_add_u64 v[196:197], v[138:139], 0, s[18:19]
	s_mov_b32 m0, s38
	s_nop 0
	global_load_lds_dwordx4 v[196:197], off
	s_waitcnt vmcnt(8)
	s_waitcnt lgkmcnt(0)
	s_barrier
	s_setprio 1
	s_waitcnt lgkmcnt(0)
	v_mfma_f32_16x16x32_bf16 v[124:127], v[148:151], v[180:183], v[124:127]
	v_mfma_f32_16x16x32_bf16 v[120:123], v[156:159], v[180:183], v[120:123]
	v_mfma_f32_16x16x32_bf16 v[116:119], v[148:151], v[188:191], v[116:119]
	v_mfma_f32_16x16x32_bf16 v[108:111], v[156:159], v[188:191], v[108:111]
	v_mfma_f32_16x16x32_bf16 v[100:103], v[148:151], v[200:203], v[100:103]
	v_mfma_f32_16x16x32_bf16 v[92:95], v[156:159], v[200:203], v[92:95]
	v_mfma_f32_16x16x32_bf16 v[84:87], v[148:151], v[208:211], v[84:87]
	v_mfma_f32_16x16x32_bf16 v[76:79], v[156:159], v[208:211], v[76:79]
	v_mfma_f32_16x16x32_bf16 v[124:127], v[152:155], v[184:187], v[124:127]
	v_mfma_f32_16x16x32_bf16 v[120:123], v[160:163], v[184:187], v[120:123]
	v_mfma_f32_16x16x32_bf16 v[116:119], v[152:155], v[192:195], v[116:119]
	v_mfma_f32_16x16x32_bf16 v[108:111], v[160:163], v[192:195], v[108:111]
	v_mfma_f32_16x16x32_bf16 v[100:103], v[152:155], v[204:207], v[100:103]
	v_mfma_f32_16x16x32_bf16 v[92:95], v[160:163], v[204:207], v[92:95]
	v_mfma_f32_16x16x32_bf16 v[84:87], v[152:155], v[212:215], v[84:87]
	v_mfma_f32_16x16x32_bf16 v[76:79], v[160:163], v[212:215], v[76:79]
	v_mfma_f32_16x16x32_bf16 v[112:115], v[164:167], v[180:183], v[112:115]
	v_mfma_f32_16x16x32_bf16 v[104:107], v[172:175], v[180:183], v[104:107]
	v_mfma_f32_16x16x32_bf16 v[96:99], v[164:167], v[188:191], v[96:99]
	v_mfma_f32_16x16x32_bf16 v[88:91], v[172:175], v[188:191], v[88:91]
	v_mfma_f32_16x16x32_bf16 v[80:83], v[164:167], v[200:203], v[80:83]
	v_mfma_f32_16x16x32_bf16 v[72:75], v[172:175], v[200:203], v[72:75]
	v_mfma_f32_16x16x32_bf16 v[68:71], v[164:167], v[208:211], v[68:71]
	v_mfma_f32_16x16x32_bf16 v[64:67], v[172:175], v[208:211], v[64:67]
	v_mfma_f32_16x16x32_bf16 v[112:115], v[168:171], v[184:187], v[112:115]
	v_mfma_f32_16x16x32_bf16 v[104:107], v[176:179], v[184:187], v[104:107]
	v_mfma_f32_16x16x32_bf16 v[96:99], v[168:171], v[192:195], v[96:99]
	v_mfma_f32_16x16x32_bf16 v[88:91], v[176:179], v[192:195], v[88:91]
	v_mfma_f32_16x16x32_bf16 v[80:83], v[168:171], v[204:207], v[80:83]
	v_mfma_f32_16x16x32_bf16 v[72:75], v[176:179], v[204:207], v[72:75]
	v_mfma_f32_16x16x32_bf16 v[68:71], v[168:171], v[212:215], v[68:71]
	v_mfma_f32_16x16x32_bf16 v[64:67], v[176:179], v[212:215], v[64:67]
	s_setprio 0
	s_barrier
	s_mov_b32 m0, s39
	v_lshl_add_u64 v[196:197], s[20:21], 0, v[132:133]
	s_add_u32 s48, s20, 0x40000
	ds_read_b128 v[180:183], v144 offset:16384
	ds_read_b128 v[184:187], v144 offset:17408
	ds_read_b128 v[188:191], v144 offset:18432
	ds_read_b128 v[192:195], v144 offset:19456
	ds_read_b128 v[200:203], v144 offset:20480
	ds_read_b128 v[204:207], v144 offset:21504
	ds_read_b128 v[208:211], v144 offset:22528
	ds_read_b128 v[212:215], v144 offset:23552
	global_load_lds_dwordx4 v[196:197], off
	v_lshl_add_u64 v[216:217], s[20:21], 0, v[128:129]
	s_mov_b32 m0, s40
	s_addc_u32 s49, s21, 0
	global_load_lds_dwordx4 v[216:217], off
	v_lshl_add_u64 v[218:219], s[48:49], 0, v[132:133]
	s_mov_b32 m0, s41
	v_lshl_add_u64 v[220:221], s[22:23], 0, v[130:131]
	global_load_lds_dwordx4 v[218:219], off
	v_lshl_add_u64 v[218:219], s[48:49], 0, v[128:129]
	s_mov_b32 m0, s42
	s_nop 0
	global_load_lds_dwordx4 v[218:219], off
	v_lshl_add_u64 v[218:219], s[22:23], 0, v[134:135]
	s_mov_b32 m0, s7
	s_nop 0
	global_load_lds_dwordx4 v[218:219], off
	s_mov_b32 m0, s24
	s_nop 0
	global_load_lds_dwordx4 v[220:221], off
	s_waitcnt vmcnt(8)
	s_waitcnt lgkmcnt(0)
	s_barrier
; #define PG8_STAGE(bufoff, gbase, voff) do { _Pragma("unroll") for (int _i = 0; _i < 2; ++_i) \
;         __builtin_amdgcn_global_load_lds((const unsigned*)((const char*)(gbase) + (voff)[_i]), (PG8_LAS unsigned*)(lds + (bufoff) + ldsw + _i * 8192), 16, 0, 0); } while (0)
; #define PG8_LDA(dst, b, h) do { _Pragma("unroll") for (int m = 0; m < 4; ++m) _Pragma("unroll") for (int k = 0; k < 2; ++k) dst[m][k] = *(const PG8_LAS bf16x8*)(lds + PG8_SA(b, h) + aoff + m * 2048 + k * 1024); } while (0)
; #define PG8_LDB(dst, b, h) do { _Pragma("unroll") for (int n = 0; n < 2; ++n) _Pragma("unroll") for (int k = 0; k < 2; ++k) dst[n][k] = *(const PG8_LAS bf16x8*)(lds + PG8_SB(b, h) + boff + n * 2048 + k * 1024); } while (0)
; #define PG8_MMA(ai, bj, At, Bt) do { __builtin_amdgcn_s_setprio(1); _Pragma("unroll") for (int m = 0; m < 4; ++m) _Pragma("unroll") for (int n = 0; n < 2; ++n) _Pragma("unroll") for (int k = 0; k < 2; ++k) \
;         acc[ai][bj][m][n] = __builtin_amdgcn_mfma_f32_16x16x32_bf16(Bt[n][k], At[m][k], acc[ai][bj][m][n], 0, 0, 0); __builtin_amdgcn_s_setprio(0); } while (0)
; #define PG8_WAIT_V(n) asm volatile("s_waitcnt vmcnt(" #n ")" ::: "memory")
; #define PG8_WAIT_L(n) asm volatile("s_waitcnt lgkmcnt(" #n ")" ::: "memory")
; #define PG8_BAR __builtin_amdgcn_s_barrier()
; #define PG8_SCHED __builtin_amdgcn_sched_barrier(0)
; template <class Epi, class Sched>
; __device__ __forceinline__ void gemm_phase(PG8_LAS unsigned char* lds, const Gemm g, const Sched& S, const Epi& E) {
;     ...
;             PG8_WAIT_V(8); PG8_WAIT_L(0); PG8_BAR; PG8_MMA(1, 0, At, B0); PG8_MMA(1, 1, At, B1); PG8_BAR; PG8_SCHED;
;             PG8_LDB(B0, 1, 0); PG8_LDB(B1, 1, 1); PG8_SCHED; PG8_LDA(At, 1, 0); PG8_STAGE(PG8_SA(0, 1), a2 + hstepA, voffA);
;             PG8_WAIT_V(8); PG8_WAIT_L(0); PG8_BAR; PG8_MMA(0, 0, At, B0); PG8_MMA(0, 1, At, B1); PG8_BAR; PG8_SCHED;
	s_setprio 1
	s_waitcnt lgkmcnt(0)
	v_mfma_f32_16x16x32_bf16 v[60:63], v[148:151], v[180:183], v[60:63]
	v_mfma_f32_16x16x32_bf16 v[56:59], v[156:159], v[180:183], v[56:59]
	v_mfma_f32_16x16x32_bf16 v[52:55], v[148:151], v[188:191], v[52:55]
	v_mfma_f32_16x16x32_bf16 v[44:47], v[156:159], v[188:191], v[44:47]
	v_mfma_f32_16x16x32_bf16 v[36:39], v[148:151], v[200:203], v[36:39]
	v_mfma_f32_16x16x32_bf16 v[28:31], v[156:159], v[200:203], v[28:31]
	v_mfma_f32_16x16x32_bf16 v[20:23], v[148:151], v[208:211], v[20:23]
	v_mfma_f32_16x16x32_bf16 v[12:15], v[156:159], v[208:211], v[12:15]
	v_mfma_f32_16x16x32_bf16 v[60:63], v[152:155], v[184:187], v[60:63]
	v_mfma_f32_16x16x32_bf16 v[56:59], v[160:163], v[184:187], v[56:59]
	v_mfma_f32_16x16x32_bf16 v[52:55], v[152:155], v[192:195], v[52:55]
	v_mfma_f32_16x16x32_bf16 v[44:47], v[160:163], v[192:195], v[44:47]
	v_mfma_f32_16x16x32_bf16 v[36:39], v[152:155], v[204:207], v[36:39]
	v_mfma_f32_16x16x32_bf16 v[28:31], v[160:163], v[204:207], v[28:31]
	v_mfma_f32_16x16x32_bf16 v[20:23], v[152:155], v[212:215], v[20:23]
	v_mfma_f32_16x16x32_bf16 v[12:15], v[160:163], v[212:215], v[12:15]
	v_mfma_f32_16x16x32_bf16 v[48:51], v[164:167], v[180:183], v[48:51]
	v_mfma_f32_16x16x32_bf16 v[40:43], v[172:175], v[180:183], v[40:43]
	v_mfma_f32_16x16x32_bf16 v[32:35], v[164:167], v[188:191], v[32:35]
	v_mfma_f32_16x16x32_bf16 v[24:27], v[172:175], v[188:191], v[24:27]
	v_mfma_f32_16x16x32_bf16 v[16:19], v[164:167], v[200:203], v[16:19]
	v_mfma_f32_16x16x32_bf16 v[8:11], v[172:175], v[200:203], v[8:11]
	v_mfma_f32_16x16x32_bf16 v[4:7], v[164:167], v[208:211], v[4:7]
	v_mfma_f32_16x16x32_bf16 v[0:3], v[172:175], v[208:211], v[0:3]
	v_mfma_f32_16x16x32_bf16 v[48:51], v[168:171], v[184:187], v[48:51]
	v_mfma_f32_16x16x32_bf16 v[40:43], v[176:179], v[184:187], v[40:43]
	v_mfma_f32_16x16x32_bf16 v[32:35], v[168:171], v[192:195], v[32:35]
	v_mfma_f32_16x16x32_bf16 v[24:27], v[176:179], v[192:195], v[24:27]
	v_mfma_f32_16x16x32_bf16 v[16:19], v[168:171], v[204:207], v[16:19]
	v_mfma_f32_16x16x32_bf16 v[8:11], v[176:179], v[204:207], v[8:11]
	v_mfma_f32_16x16x32_bf16 v[4:7], v[168:171], v[212:215], v[4:7]
	v_mfma_f32_16x16x32_bf16 v[0:3], v[176:179], v[212:215], v[0:3]
	s_setprio 0
	s_barrier
	ds_read_b128 v[148:151], v145
	ds_read_b128 v[152:155], v145 offset:1024
	ds_read_b128 v[156:159], v145 offset:2048
	ds_read_b128 v[160:163], v145 offset:3072
	ds_read_b128 v[164:167], v146
	ds_read_b128 v[168:171], v146 offset:1024
	ds_read_b128 v[172:175], v146 offset:2048
	ds_read_b128 v[176:179], v146 offset:3072
	s_add_u32 s22, s22, 0x40000
	s_addc_u32 s23, s23, 0
	s_mov_b32 m0, s25
	v_lshl_add_u64 v[222:223], s[22:23], 0, v[134:135]
	ds_read_b128 v[180:183], v144 offset:32768
	ds_read_b128 v[184:187], v144 offset:33792
	ds_read_b128 v[188:191], v144 offset:34816
	ds_read_b128 v[192:195], v144 offset:35840
	ds_read_b128 v[200:203], v144 offset:36864
	ds_read_b128 v[204:207], v144 offset:37888
	ds_read_b128 v[208:211], v144 offset:38912
	ds_read_b128 v[212:215], v144 offset:39936
	global_load_lds_dwordx4 v[222:223], off
	v_lshl_add_u64 v[222:223], s[22:23], 0, v[130:131]
	s_mov_b32 m0, s29
	s_nop 0
	global_load_lds_dwordx4 v[222:223], off
	s_waitcnt vmcnt(8)
	s_waitcnt lgkmcnt(0)
	s_barrier
	s_setprio 1
	s_waitcnt lgkmcnt(0)
	v_mfma_f32_16x16x32_bf16 v[124:127], v[148:151], v[180:183], v[124:127]
	v_mfma_f32_16x16x32_bf16 v[120:123], v[156:159], v[180:183], v[120:123]
	v_mfma_f32_16x16x32_bf16 v[116:119], v[148:151], v[188:191], v[116:119]
	v_mfma_f32_16x16x32_bf16 v[108:111], v[156:159], v[188:191], v[108:111]
	v_mfma_f32_16x16x32_bf16 v[100:103], v[148:151], v[200:203], v[100:103]
	v_mfma_f32_16x16x32_bf16 v[92:95], v[156:159], v[200:203], v[92:95]
	v_mfma_f32_16x16x32_bf16 v[84:87], v[148:151], v[208:211], v[84:87]
	v_mfma_f32_16x16x32_bf16 v[76:79], v[156:159], v[208:211], v[76:79]
	v_mfma_f32_16x16x32_bf16 v[124:127], v[152:155], v[184:187], v[124:127]
	v_mfma_f32_16x16x32_bf16 v[120:123], v[160:163], v[184:187], v[120:123]
	v_mfma_f32_16x16x32_bf16 v[116:119], v[152:155], v[192:195], v[116:119]
	v_mfma_f32_16x16x32_bf16 v[108:111], v[160:163], v[192:195], v[108:111]
	v_mfma_f32_16x16x32_bf16 v[100:103], v[152:155], v[204:207], v[100:103]
	v_mfma_f32_16x16x32_bf16 v[92:95], v[160:163], v[204:207], v[92:95]
	v_mfma_f32_16x16x32_bf16 v[84:87], v[152:155], v[212:215], v[84:87]
	v_mfma_f32_16x16x32_bf16 v[76:79], v[160:163], v[212:215], v[76:79]
	v_mfma_f32_16x16x32_bf16 v[112:115], v[164:167], v[180:183], v[112:115]
	v_mfma_f32_16x16x32_bf16 v[104:107], v[172:175], v[180:183], v[104:107]
	v_mfma_f32_16x16x32_bf16 v[96:99], v[164:167], v[188:191], v[96:99]
	v_mfma_f32_16x16x32_bf16 v[88:91], v[172:175], v[188:191], v[88:91]
	v_mfma_f32_16x16x32_bf16 v[80:83], v[164:167], v[200:203], v[80:83]
	v_mfma_f32_16x16x32_bf16 v[72:75], v[172:175], v[200:203], v[72:75]
	v_mfma_f32_16x16x32_bf16 v[68:71], v[164:167], v[208:211], v[68:71]
	v_mfma_f32_16x16x32_bf16 v[64:67], v[172:175], v[208:211], v[64:67]
	v_mfma_f32_16x16x32_bf16 v[112:115], v[168:171], v[184:187], v[112:115]
	v_mfma_f32_16x16x32_bf16 v[104:107], v[176:179], v[184:187], v[104:107]
	v_mfma_f32_16x16x32_bf16 v[96:99], v[168:171], v[192:195], v[96:99]
	v_mfma_f32_16x16x32_bf16 v[88:91], v[176:179], v[192:195], v[88:91]
	v_mfma_f32_16x16x32_bf16 v[80:83], v[168:171], v[204:207], v[80:83]
	v_mfma_f32_16x16x32_bf16 v[72:75], v[176:179], v[204:207], v[72:75]
	v_mfma_f32_16x16x32_bf16 v[68:71], v[168:171], v[212:215], v[68:71]
	v_mfma_f32_16x16x32_bf16 v[64:67], v[176:179], v[212:215], v[64:67]
	s_setprio 0
	s_barrier
; #define PG8_STAGE(bufoff, gbase, voff) do { _Pragma("unroll") for (int _i = 0; _i < 2; ++_i) \
;         __builtin_amdgcn_global_load_lds((const unsigned*)((const char*)(gbase) + (voff)[_i]), (PG8_LAS unsigned*)(lds + (bufoff) + ldsw + _i * 8192), 16, 0, 0); } while (0)
; #define PG8_LDA(dst, b, h) do { _Pragma("unroll") for (int m = 0; m < 4; ++m) _Pragma("unroll") for (int k = 0; k < 2; ++k) dst[m][k] = *(const PG8_LAS bf16x8*)(lds + PG8_SA(b, h) + aoff + m * 2048 + k * 1024); } while (0)
; #define PG8_MMA(ai, bj, At, Bt) do { __builtin_amdgcn_s_setprio(1); _Pragma("unroll") for (int m = 0; m < 4; ++m) _Pragma("unroll") for (int n = 0; n < 2; ++n) _Pragma("unroll") for (int k = 0; k < 2; ++k) \
;         acc[ai][bj][m][n] = __builtin_amdgcn_mfma_f32_16x16x32_bf16(Bt[n][k], At[m][k], acc[ai][bj][m][n], 0, 0, 0); __builtin_amdgcn_s_setprio(0); } while (0)
; #define PG8_WAIT_V(n) asm volatile("s_waitcnt vmcnt(" #n ")" ::: "memory")
; #define PG8_WAIT_L(n) asm volatile("s_waitcnt lgkmcnt(" #n ")" ::: "memory")
; #define PG8_BAR __builtin_amdgcn_s_barrier()
; #define PG8_SCHED __builtin_amdgcn_sched_barrier(0)
; template <class Epi, class Sched>
; __device__ __forceinline__ void gemm_phase(PG8_LAS unsigned char* lds, const Gemm g, const Sched& S, const Epi& E) {
;     ...
;             PG8_LDA(At, 1, 1); PG8_STAGE(PG8_SB(1, 0), b3, voffB); PG8_STAGE(PG8_SB(1, 1), b3 + hstepB, voffB); PG8_STAGE(PG8_SA(1, 0), a3, voffA);
;             PG8_WAIT_V(8); PG8_WAIT_L(0); PG8_BAR; PG8_MMA(1, 0, At, B0); PG8_MMA(1, 1, At, B1); PG8_BAR; PG8_SCHED;
;         }
;         if (wr == 0) PG8_BAR;
	s_mov_b32 m0, s43
	v_lshl_add_u64 v[196:197], v[196:197], 0, s[12:13]
	s_add_u32 s20, s20, 0x40080
	ds_read_b128 v[180:183], v144 offset:49152
	ds_read_b128 v[184:187], v144 offset:50176
	ds_read_b128 v[188:191], v144 offset:51200
	ds_read_b128 v[192:195], v144 offset:52224
	ds_read_b128 v[200:203], v144 offset:53248
	ds_read_b128 v[204:207], v144 offset:54272
	ds_read_b128 v[208:211], v144 offset:55296
	ds_read_b128 v[212:215], v144 offset:56320
	global_load_lds_dwordx4 v[196:197], off
	v_lshl_add_u64 v[196:197], v[216:217], 0, s[12:13]
	s_mov_b32 m0, s44
	s_addc_u32 s21, s21, 0
	global_load_lds_dwordx4 v[196:197], off
	v_lshl_add_u64 v[196:197], s[20:21], 0, v[132:133]
	s_mov_b32 m0, s45
	s_nop 0
	global_load_lds_dwordx4 v[196:197], off
	v_lshl_add_u64 v[196:197], s[20:21], 0, v[128:129]
	s_mov_b32 m0, s46
	s_nop 0
	global_load_lds_dwordx4 v[196:197], off
	v_lshl_add_u64 v[196:197], v[218:219], 0, s[12:13]
	s_mov_b32 m0, s31
	s_nop 0
	global_load_lds_dwordx4 v[196:197], off
	v_lshl_add_u64 v[196:197], v[220:221], 0, s[12:13]
	s_mov_b32 m0, s33
	s_nop 0
	global_load_lds_dwordx4 v[196:197], off
	s_waitcnt vmcnt(8)
	s_waitcnt lgkmcnt(0)
	s_barrier
	s_setprio 1
	s_waitcnt lgkmcnt(0)
	v_mfma_f32_16x16x32_bf16 v[60:63], v[148:151], v[180:183], v[60:63]
	v_mfma_f32_16x16x32_bf16 v[56:59], v[156:159], v[180:183], v[56:59]
	v_mfma_f32_16x16x32_bf16 v[52:55], v[148:151], v[188:191], v[52:55]
	v_mfma_f32_16x16x32_bf16 v[44:47], v[156:159], v[188:191], v[44:47]
	v_mfma_f32_16x16x32_bf16 v[36:39], v[148:151], v[200:203], v[36:39]
	v_mfma_f32_16x16x32_bf16 v[28:31], v[156:159], v[200:203], v[28:31]
	v_mfma_f32_16x16x32_bf16 v[20:23], v[148:151], v[208:211], v[20:23]
	v_mfma_f32_16x16x32_bf16 v[12:15], v[156:159], v[208:211], v[12:15]
	v_mfma_f32_16x16x32_bf16 v[60:63], v[152:155], v[184:187], v[60:63]
	v_mfma_f32_16x16x32_bf16 v[56:59], v[160:163], v[184:187], v[56:59]
	v_mfma_f32_16x16x32_bf16 v[52:55], v[152:155], v[192:195], v[52:55]
	v_mfma_f32_16x16x32_bf16 v[44:47], v[160:163], v[192:195], v[44:47]
	v_mfma_f32_16x16x32_bf16 v[36:39], v[152:155], v[204:207], v[36:39]
	v_mfma_f32_16x16x32_bf16 v[28:31], v[160:163], v[204:207], v[28:31]
	v_mfma_f32_16x16x32_bf16 v[20:23], v[152:155], v[212:215], v[20:23]
	v_mfma_f32_16x16x32_bf16 v[12:15], v[160:163], v[212:215], v[12:15]
	v_mfma_f32_16x16x32_bf16 v[48:51], v[164:167], v[180:183], v[48:51]
	v_mfma_f32_16x16x32_bf16 v[40:43], v[172:175], v[180:183], v[40:43]
	v_mfma_f32_16x16x32_bf16 v[32:35], v[164:167], v[188:191], v[32:35]
	v_mfma_f32_16x16x32_bf16 v[24:27], v[172:175], v[188:191], v[24:27]
	v_mfma_f32_16x16x32_bf16 v[16:19], v[164:167], v[200:203], v[16:19]
	v_mfma_f32_16x16x32_bf16 v[8:11], v[172:175], v[200:203], v[8:11]
	v_mfma_f32_16x16x32_bf16 v[4:7], v[164:167], v[208:211], v[4:7]
	v_mfma_f32_16x16x32_bf16 v[0:3], v[172:175], v[208:211], v[0:3]
	v_mfma_f32_16x16x32_bf16 v[48:51], v[168:171], v[184:187], v[48:51]
	v_mfma_f32_16x16x32_bf16 v[40:43], v[176:179], v[184:187], v[40:43]
	v_mfma_f32_16x16x32_bf16 v[32:35], v[168:171], v[192:195], v[32:35]
	v_mfma_f32_16x16x32_bf16 v[24:27], v[176:179], v[192:195], v[24:27]
	v_mfma_f32_16x16x32_bf16 v[16:19], v[168:171], v[204:207], v[16:19]
	v_mfma_f32_16x16x32_bf16 v[8:11], v[176:179], v[204:207], v[8:11]
	v_mfma_f32_16x16x32_bf16 v[4:7], v[168:171], v[212:215], v[4:7]
	v_mfma_f32_16x16x32_bf16 v[0:3], v[176:179], v[212:215], v[0:3]
	s_setprio 0
	s_barrier
	s_add_i32 s36, s36, 2
	s_add_u32 s18, s18, 0x100
	s_addc_u32 s19, s19, 0
	s_cmp_gt_u32 s36, 13
	s_cbranch_scc0 .LBB0_1989
	s_cmpk_lt_u32 s28, 0x100
	s_cbranch_scc0 .LBB0_1992
	s_barrier

; #define PG8_STAGE(bufoff, gbase, voff) do { _Pragma("unroll") for (int _i = 0; _i < 2; ++_i) \
;         __builtin_amdgcn_global_load_lds((const unsigned*)((const char*)(gbase) + (voff)[_i]), (PG8_LAS unsigned*)(lds + (bufoff) + ldsw + _i * 8192), 16, 0, 0); } while (0)
; #define PG8_LDA(dst, b, h) do { _Pragma("unroll") for (int m = 0; m < 4; ++m) _Pragma("unroll") for (int k = 0; k < 2; ++k) dst[m][k] = *(const PG8_LAS bf16x8*)(lds + PG8_SA(b, h) + aoff + m * 2048 + k * 1024); } while (0)
; #define PG8_LDB(dst, b, h) do { _Pragma("unroll") for (int n = 0; n < 2; ++n) _Pragma("unroll") for (int k = 0; k < 2; ++k) dst[n][k] = *(const PG8_LAS bf16x8*)(lds + PG8_SB(b, h) + boff + n * 2048 + k * 1024); } while (0)
; #define PG8_MMA(ai, bj, At, Bt) do { __builtin_amdgcn_s_setprio(1); _Pragma("unroll") for (int m = 0; m < 4; ++m) _Pragma("unroll") for (int n = 0; n < 2; ++n) _Pragma("unroll") for (int k = 0; k < 2; ++k) \
;         acc[ai][bj][m][n] = __builtin_amdgcn_mfma_f32_16x16x32_bf16(Bt[n][k], At[m][k], acc[ai][bj][m][n], 0, 0, 0); __builtin_amdgcn_s_setprio(0); } while (0)
; #define PG8_WAIT_V(n) asm volatile("s_waitcnt vmcnt(" #n ")" ::: "memory")
; #define PG8_WAIT_L(n) asm volatile("s_waitcnt lgkmcnt(" #n ")" ::: "memory")
; template <class Epi, class Sched>
; __device__ __forceinline__ void gemm_phase(PG8_LAS unsigned char* lds, const Gemm g, const Sched& S, const Epi& E) {
;     ...
;         for (int t = 0; t < nt; t += 2) {
;             const bool last = (t == nt - 2);
;             const char* a1 = cA + (size_t)(t + 1) * kstepA;
;             const char* a2 = last ? nA : cA + (size_t)(t + 2) * kstepA; const char* b2 = last ? nB : cB + (size_t)(t + 2) * kstep;
;             const char* a3 = a2 + kstepA; const char* b3 = b2 + kstep;
;             if constexpr (epi_has_hook<Epi>::value) { if (t == nt / 2) E.hook(acc, cur, wr, wc, fr, fq); }
;             PG8_LDB(B0, 0, 0); PG8_LDB(B1, 0, 1); PG8_SCHED; PG8_LDA(At, 0, 0); PG8_STAGE(PG8_SA(1, 1), a1 + hstepA, voffA);
;             PG8_WAIT_V(8); PG8_WAIT_L(0); PG8_BAR; PG8_MMA(0, 0, At, B0); PG8_MMA(0, 1, At, B1); PG8_BAR; PG8_SCHED;
;             PG8_LDA(At, 0, 1); PG8_STAGE(PG8_SB(0, 0), b2, voffB); PG8_STAGE(PG8_SB(0, 1), b2 + hstepB, voffB); PG8_STAGE(PG8_SA(0, 0), a2, voffA);
;             PG8_WAIT_V(8); PG8_WAIT_L(0); PG8_BAR; PG8_MMA(1, 0, At, B0); PG8_MMA(1, 1, At, B1); PG8_BAR; PG8_SCHED;
.LBB0_2006:
	ds_read_b128 v[148:151], v142
	ds_read_b128 v[152:155], v142 offset:1024
	ds_read_b128 v[156:159], v142 offset:2048
	ds_read_b128 v[160:163], v142 offset:3072
	ds_read_b128 v[164:167], v143
	ds_read_b128 v[168:171], v143 offset:1024
	ds_read_b128 v[172:175], v143 offset:2048
	ds_read_b128 v[176:179], v143 offset:3072
	s_add_u32 s18, s12, s14
	s_addc_u32 s19, s13, s15
	s_add_u32 s18, s18, 0x3700100
	s_addc_u32 s19, s19, 0
	s_add_u32 s43, s29, s14
	s_addc_u32 s44, s30, s15
	s_cmpk_eq_i32 s14, 0x700
	s_cselect_b32 s21, s9, s19
	s_cselect_b32 s20, s8, s18
	s_cselect_b32 s19, s3, s44
	s_cselect_b32 s18, s2, s43
	s_mov_b32 m0, s33
	v_lshl_add_u64 v[196:197], v[136:137], 0, s[14:15]
	ds_read_b128 v[180:183], v144
	ds_read_b128 v[184:187], v144 offset:1024
	ds_read_b128 v[188:191], v144 offset:2048
	ds_read_b128 v[192:195], v144 offset:3072
	ds_read_b128 v[200:203], v144 offset:4096
	ds_read_b128 v[204:207], v144 offset:5120
	ds_read_b128 v[208:211], v144 offset:6144
	ds_read_b128 v[212:215], v144 offset:7168
	global_load_lds_dwordx4 v[196:197], off
	v_lshl_add_u64 v[196:197], v[138:139], 0, s[14:15]
	s_mov_b32 m0, s34
	s_nop 0
	global_load_lds_dwordx4 v[196:197], off
	s_waitcnt vmcnt(8)
	s_waitcnt lgkmcnt(0)
	s_barrier
	s_setprio 1
	s_waitcnt lgkmcnt(0)
	v_mfma_f32_16x16x32_bf16 v[124:127], v[148:151], v[180:183], v[124:127]
	v_mfma_f32_16x16x32_bf16 v[120:123], v[156:159], v[180:183], v[120:123]
	v_mfma_f32_16x16x32_bf16 v[116:119], v[148:151], v[188:191], v[116:119]
	v_mfma_f32_16x16x32_bf16 v[108:111], v[156:159], v[188:191], v[108:111]
	v_mfma_f32_16x16x32_bf16 v[100:103], v[148:151], v[200:203], v[100:103]
	v_mfma_f32_16x16x32_bf16 v[92:95], v[156:159], v[200:203], v[92:95]
	v_mfma_f32_16x16x32_bf16 v[84:87], v[148:151], v[208:211], v[84:87]
	v_mfma_f32_16x16x32_bf16 v[76:79], v[156:159], v[208:211], v[76:79]
	v_mfma_f32_16x16x32_bf16 v[124:127], v[152:155], v[184:187], v[124:127]
	v_mfma_f32_16x16x32_bf16 v[120:123], v[160:163], v[184:187], v[120:123]
	v_mfma_f32_16x16x32_bf16 v[116:119], v[152:155], v[192:195], v[116:119]
	v_mfma_f32_16x16x32_bf16 v[108:111], v[160:163], v[192:195], v[108:111]
	v_mfma_f32_16x16x32_bf16 v[100:103], v[152:155], v[204:207], v[100:103]
	v_mfma_f32_16x16x32_bf16 v[92:95], v[160:163], v[204:207], v[92:95]
	v_mfma_f32_16x16x32_bf16 v[84:87], v[152:155], v[212:215], v[84:87]
	v_mfma_f32_16x16x32_bf16 v[76:79], v[160:163], v[212:215], v[76:79]
	v_mfma_f32_16x16x32_bf16 v[112:115], v[164:167], v[180:183], v[112:115]
	v_mfma_f32_16x16x32_bf16 v[104:107], v[172:175], v[180:183], v[104:107]
	v_mfma_f32_16x16x32_bf16 v[96:99], v[164:167], v[188:191], v[96:99]
	v_mfma_f32_16x16x32_bf16 v[88:91], v[172:175], v[188:191], v[88:91]
	v_mfma_f32_16x16x32_bf16 v[80:83], v[164:167], v[200:203], v[80:83]
	v_mfma_f32_16x16x32_bf16 v[72:75], v[172:175], v[200:203], v[72:75]
	v_mfma_f32_16x16x32_bf16 v[68:71], v[164:167], v[208:211], v[68:71]
	v_mfma_f32_16x16x32_bf16 v[64:67], v[172:175], v[208:211], v[64:67]
	v_mfma_f32_16x16x32_bf16 v[112:115], v[168:171], v[184:187], v[112:115]
	v_mfma_f32_16x16x32_bf16 v[104:107], v[176:179], v[184:187], v[104:107]
	v_mfma_f32_16x16x32_bf16 v[96:99], v[168:171], v[192:195], v[96:99]
	v_mfma_f32_16x16x32_bf16 v[88:91], v[176:179], v[192:195], v[88:91]
	v_mfma_f32_16x16x32_bf16 v[80:83], v[168:171], v[204:207], v[80:83]
	v_mfma_f32_16x16x32_bf16 v[72:75], v[176:179], v[204:207], v[72:75]
	v_mfma_f32_16x16x32_bf16 v[68:71], v[168:171], v[212:215], v[68:71]
	v_mfma_f32_16x16x32_bf16 v[64:67], v[176:179], v[212:215], v[64:67]
	s_setprio 0
	s_barrier
	s_mov_b32 m0, s35
	v_lshl_add_u64 v[196:197], s[18:19], 0, v[132:133]
	s_add_u32 s44, s18, 0x40000
	ds_read_b128 v[180:183], v144 offset:16384
	ds_read_b128 v[184:187], v144 offset:17408
	ds_read_b128 v[188:191], v144 offset:18432
	ds_read_b128 v[192:195], v144 offset:19456
	ds_read_b128 v[200:203], v144 offset:20480
	ds_read_b128 v[204:207], v144 offset:21504
	ds_read_b128 v[208:211], v144 offset:22528
	ds_read_b128 v[212:215], v144 offset:23552
	global_load_lds_dwordx4 v[196:197], off
	v_lshl_add_u64 v[216:217], s[18:19], 0, v[128:129]
	s_mov_b32 m0, s36
	s_addc_u32 s45, s19, 0
	global_load_lds_dwordx4 v[216:217], off
	v_lshl_add_u64 v[218:219], s[44:45], 0, v[132:133]
	s_mov_b32 m0, s37
	v_lshl_add_u64 v[220:221], s[20:21], 0, v[130:131]
	global_load_lds_dwordx4 v[218:219], off
	v_lshl_add_u64 v[218:219], s[44:45], 0, v[128:129]
	s_mov_b32 m0, s38
	s_nop 0
	global_load_lds_dwordx4 v[218:219], off
	v_lshl_add_u64 v[218:219], s[20:21], 0, v[134:135]
	s_mov_b32 m0, s7
	s_nop 0
	global_load_lds_dwordx4 v[218:219], off
	s_mov_b32 m0, s23
	s_nop 0
	global_load_lds_dwordx4 v[220:221], off
	s_waitcnt vmcnt(8)
	s_waitcnt lgkmcnt(0)
	s_barrier
; #define PG8_STAGE(bufoff, gbase, voff) do { _Pragma("unroll") for (int _i = 0; _i < 2; ++_i) \
;         __builtin_amdgcn_global_load_lds((const unsigned*)((const char*)(gbase) + (voff)[_i]), (PG8_LAS unsigned*)(lds + (bufoff) + ldsw + _i * 8192), 16, 0, 0); } while (0)
; #define PG8_LDA(dst, b, h) do { _Pragma("unroll") for (int m = 0; m < 4; ++m) _Pragma("unroll") for (int k = 0; k < 2; ++k) dst[m][k] = *(const PG8_LAS bf16x8*)(lds + PG8_SA(b, h) + aoff + m * 2048 + k * 1024); } while (0)
; #define PG8_LDB(dst, b, h) do { _Pragma("unroll") for (int n = 0; n < 2; ++n) _Pragma("unroll") for (int k = 0; k < 2; ++k) dst[n][k] = *(const PG8_LAS bf16x8*)(lds + PG8_SB(b, h) + boff + n * 2048 + k * 1024); } while (0)
; #define PG8_MMA(ai, bj, At, Bt) do { __builtin_amdgcn_s_setprio(1); _Pragma("unroll") for (int m = 0; m < 4; ++m) _Pragma("unroll") for (int n = 0; n < 2; ++n) _Pragma("unroll") for (int k = 0; k < 2; ++k) \
;         acc[ai][bj][m][n] = __builtin_amdgcn_mfma_f32_16x16x32_bf16(Bt[n][k], At[m][k], acc[ai][bj][m][n], 0, 0, 0); __builtin_amdgcn_s_setprio(0); } while (0)
; #define PG8_WAIT_V(n) asm volatile("s_waitcnt vmcnt(" #n ")" ::: "memory")
; #define PG8_WAIT_L(n) asm volatile("s_waitcnt lgkmcnt(" #n ")" ::: "memory")
; #define PG8_BAR __builtin_amdgcn_s_barrier()
; #define PG8_SCHED __builtin_amdgcn_sched_barrier(0)
; template <class Epi, class Sched>
; __device__ __forceinline__ void gemm_phase(PG8_LAS unsigned char* lds, const Gemm g, const Sched& S, const Epi& E) {
;     ...
;             PG8_WAIT_V(8); PG8_WAIT_L(0); PG8_BAR; PG8_MMA(1, 0, At, B0); PG8_MMA(1, 1, At, B1); PG8_BAR; PG8_SCHED;
;             PG8_LDB(B0, 1, 0); PG8_LDB(B1, 1, 1); PG8_SCHED; PG8_LDA(At, 1, 0); PG8_STAGE(PG8_SA(0, 1), a2 + hstepA, voffA);
;             PG8_WAIT_V(8); PG8_WAIT_L(0); PG8_BAR; PG8_MMA(0, 0, At, B0); PG8_MMA(0, 1, At, B1); PG8_BAR; PG8_SCHED;
	s_setprio 1
	s_waitcnt lgkmcnt(0)
	v_mfma_f32_16x16x32_bf16 v[60:63], v[148:151], v[180:183], v[60:63]
	v_mfma_f32_16x16x32_bf16 v[56:59], v[156:159], v[180:183], v[56:59]
	v_mfma_f32_16x16x32_bf16 v[52:55], v[148:151], v[188:191], v[52:55]
	v_mfma_f32_16x16x32_bf16 v[44:47], v[156:159], v[188:191], v[44:47]
	v_mfma_f32_16x16x32_bf16 v[36:39], v[148:151], v[200:203], v[36:39]
	v_mfma_f32_16x16x32_bf16 v[28:31], v[156:159], v[200:203], v[28:31]
	v_mfma_f32_16x16x32_bf16 v[20:23], v[148:151], v[208:211], v[20:23]
	v_mfma_f32_16x16x32_bf16 v[12:15], v[156:159], v[208:211], v[12:15]
	v_mfma_f32_16x16x32_bf16 v[60:63], v[152:155], v[184:187], v[60:63]
	v_mfma_f32_16x16x32_bf16 v[56:59], v[160:163], v[184:187], v[56:59]
	v_mfma_f32_16x16x32_bf16 v[52:55], v[152:155], v[192:195], v[52:55]
	v_mfma_f32_16x16x32_bf16 v[44:47], v[160:163], v[192:195], v[44:47]
	v_mfma_f32_16x16x32_bf16 v[36:39], v[152:155], v[204:207], v[36:39]
	v_mfma_f32_16x16x32_bf16 v[28:31], v[160:163], v[204:207], v[28:31]
	v_mfma_f32_16x16x32_bf16 v[20:23], v[152:155], v[212:215], v[20:23]
	v_mfma_f32_16x16x32_bf16 v[12:15], v[160:163], v[212:215], v[12:15]
	v_mfma_f32_16x16x32_bf16 v[48:51], v[164:167], v[180:183], v[48:51]
	v_mfma_f32_16x16x32_bf16 v[40:43], v[172:175], v[180:183], v[40:43]
	v_mfma_f32_16x16x32_bf16 v[32:35], v[164:167], v[188:191], v[32:35]
	v_mfma_f32_16x16x32_bf16 v[24:27], v[172:175], v[188:191], v[24:27]
	v_mfma_f32_16x16x32_bf16 v[16:19], v[164:167], v[200:203], v[16:19]
	v_mfma_f32_16x16x32_bf16 v[8:11], v[172:175], v[200:203], v[8:11]
	v_mfma_f32_16x16x32_bf16 v[4:7], v[164:167], v[208:211], v[4:7]
	v_mfma_f32_16x16x32_bf16 v[0:3], v[172:175], v[208:211], v[0:3]
	v_mfma_f32_16x16x32_bf16 v[48:51], v[168:171], v[184:187], v[48:51]
	v_mfma_f32_16x16x32_bf16 v[40:43], v[176:179], v[184:187], v[40:43]
	v_mfma_f32_16x16x32_bf16 v[32:35], v[168:171], v[192:195], v[32:35]
	v_mfma_f32_16x16x32_bf16 v[24:27], v[176:179], v[192:195], v[24:27]
	v_mfma_f32_16x16x32_bf16 v[16:19], v[168:171], v[204:207], v[16:19]
	v_mfma_f32_16x16x32_bf16 v[8:11], v[176:179], v[204:207], v[8:11]
	v_mfma_f32_16x16x32_bf16 v[4:7], v[168:171], v[212:215], v[4:7]
	v_mfma_f32_16x16x32_bf16 v[0:3], v[176:179], v[212:215], v[0:3]
	s_setprio 0
	s_barrier
	ds_read_b128 v[148:151], v145
	ds_read_b128 v[152:155], v145 offset:1024
	ds_read_b128 v[156:159], v145 offset:2048
	ds_read_b128 v[160:163], v145 offset:3072
	ds_read_b128 v[164:167], v146
	ds_read_b128 v[168:171], v146 offset:1024
	ds_read_b128 v[172:175], v146 offset:2048
	ds_read_b128 v[176:179], v146 offset:3072
	s_add_u32 s20, s20, 0x40000
	s_addc_u32 s21, s21, 0
	s_mov_b32 m0, s24
	v_lshl_add_u64 v[222:223], s[20:21], 0, v[134:135]
	ds_read_b128 v[180:183], v144 offset:32768
	ds_read_b128 v[184:187], v144 offset:33792
	ds_read_b128 v[188:191], v144 offset:34816
	ds_read_b128 v[192:195], v144 offset:35840
	ds_read_b128 v[200:203], v144 offset:36864
	ds_read_b128 v[204:207], v144 offset:37888
	ds_read_b128 v[208:211], v144 offset:38912
	ds_read_b128 v[212:215], v144 offset:39936
	global_load_lds_dwordx4 v[222:223], off
	v_lshl_add_u64 v[222:223], s[20:21], 0, v[130:131]
	s_mov_b32 m0, s25
	s_nop 0
	global_load_lds_dwordx4 v[222:223], off
	s_waitcnt vmcnt(8)
	s_waitcnt lgkmcnt(0)
	s_barrier
	s_setprio 1
	s_waitcnt lgkmcnt(0)
	v_mfma_f32_16x16x32_bf16 v[124:127], v[148:151], v[180:183], v[124:127]
	v_mfma_f32_16x16x32_bf16 v[120:123], v[156:159], v[180:183], v[120:123]
	v_mfma_f32_16x16x32_bf16 v[116:119], v[148:151], v[188:191], v[116:119]
	v_mfma_f32_16x16x32_bf16 v[108:111], v[156:159], v[188:191], v[108:111]
	v_mfma_f32_16x16x32_bf16 v[100:103], v[148:151], v[200:203], v[100:103]
	v_mfma_f32_16x16x32_bf16 v[92:95], v[156:159], v[200:203], v[92:95]
	v_mfma_f32_16x16x32_bf16 v[84:87], v[148:151], v[208:211], v[84:87]
	v_mfma_f32_16x16x32_bf16 v[76:79], v[156:159], v[208:211], v[76:79]
	v_mfma_f32_16x16x32_bf16 v[124:127], v[152:155], v[184:187], v[124:127]
	v_mfma_f32_16x16x32_bf16 v[120:123], v[160:163], v[184:187], v[120:123]
	v_mfma_f32_16x16x32_bf16 v[116:119], v[152:155], v[192:195], v[116:119]
	v_mfma_f32_16x16x32_bf16 v[108:111], v[160:163], v[192:195], v[108:111]
	v_mfma_f32_16x16x32_bf16 v[100:103], v[152:155], v[204:207], v[100:103]
	v_mfma_f32_16x16x32_bf16 v[92:95], v[160:163], v[204:207], v[92:95]
	v_mfma_f32_16x16x32_bf16 v[84:87], v[152:155], v[212:215], v[84:87]
	v_mfma_f32_16x16x32_bf16 v[76:79], v[160:163], v[212:215], v[76:79]
	v_mfma_f32_16x16x32_bf16 v[112:115], v[164:167], v[180:183], v[112:115]
	v_mfma_f32_16x16x32_bf16 v[104:107], v[172:175], v[180:183], v[104:107]
	v_mfma_f32_16x16x32_bf16 v[96:99], v[164:167], v[188:191], v[96:99]
	v_mfma_f32_16x16x32_bf16 v[88:91], v[172:175], v[188:191], v[88:91]
	v_mfma_f32_16x16x32_bf16 v[80:83], v[164:167], v[200:203], v[80:83]
	v_mfma_f32_16x16x32_bf16 v[72:75], v[172:175], v[200:203], v[72:75]
	v_mfma_f32_16x16x32_bf16 v[68:71], v[164:167], v[208:211], v[68:71]
	v_mfma_f32_16x16x32_bf16 v[64:67], v[172:175], v[208:211], v[64:67]
	v_mfma_f32_16x16x32_bf16 v[112:115], v[168:171], v[184:187], v[112:115]
	v_mfma_f32_16x16x32_bf16 v[104:107], v[176:179], v[184:187], v[104:107]
	v_mfma_f32_16x16x32_bf16 v[96:99], v[168:171], v[192:195], v[96:99]
	v_mfma_f32_16x16x32_bf16 v[88:91], v[176:179], v[192:195], v[88:91]
	v_mfma_f32_16x16x32_bf16 v[80:83], v[168:171], v[204:207], v[80:83]
	v_mfma_f32_16x16x32_bf16 v[72:75], v[176:179], v[204:207], v[72:75]
	v_mfma_f32_16x16x32_bf16 v[68:71], v[168:171], v[212:215], v[68:71]
	v_mfma_f32_16x16x32_bf16 v[64:67], v[176:179], v[212:215], v[64:67]
	s_setprio 0
	s_barrier
; #define PG8_STAGE(bufoff, gbase, voff) do { _Pragma("unroll") for (int _i = 0; _i < 2; ++_i) \
;         __builtin_amdgcn_global_load_lds((const unsigned*)((const char*)(gbase) + (voff)[_i]), (PG8_LAS unsigned*)(lds + (bufoff) + ldsw + _i * 8192), 16, 0, 0); } while (0)
; #define PG8_LDA(dst, b, h) do { _Pragma("unroll") for (int m = 0; m < 4; ++m) _Pragma("unroll") for (int k = 0; k < 2; ++k) dst[m][k] = *(const PG8_LAS bf16x8*)(lds + PG8_SA(b, h) + aoff + m * 2048 + k * 1024); } while (0)
; #define PG8_MMA(ai, bj, At, Bt) do { __builtin_amdgcn_s_setprio(1); _Pragma("unroll") for (int m = 0; m < 4; ++m) _Pragma("unroll") for (int n = 0; n < 2; ++n) _Pragma("unroll") for (int k = 0; k < 2; ++k) \
;         acc[ai][bj][m][n] = __builtin_amdgcn_mfma_f32_16x16x32_bf16(Bt[n][k], At[m][k], acc[ai][bj][m][n], 0, 0, 0); __builtin_amdgcn_s_setprio(0); } while (0)
; #define PG8_WAIT_V(n) asm volatile("s_waitcnt vmcnt(" #n ")" ::: "memory")
; #define PG8_WAIT_L(n) asm volatile("s_waitcnt lgkmcnt(" #n ")" ::: "memory")
; #define PG8_BAR __builtin_amdgcn_s_barrier()
; #define PG8_SCHED __builtin_amdgcn_sched_barrier(0)
; template <class Epi, class Sched>
; __device__ __forceinline__ void gemm_phase(PG8_LAS unsigned char* lds, const Gemm g, const Sched& S, const Epi& E) {
;     ...
;             PG8_LDA(At, 1, 1); PG8_STAGE(PG8_SB(1, 0), b3, voffB); PG8_STAGE(PG8_SB(1, 1), b3 + hstepB, voffB); PG8_STAGE(PG8_SA(1, 0), a3, voffA);
;             PG8_WAIT_V(8); PG8_WAIT_L(0); PG8_BAR; PG8_MMA(1, 0, At, B0); PG8_MMA(1, 1, At, B1); PG8_BAR; PG8_SCHED;
;         }
;         if (wr == 0) PG8_BAR;
	s_mov_b32 m0, s39
	v_lshl_add_u64 v[196:197], v[196:197], 0, s[10:11]
	s_add_u32 s18, s18, 0x40080
	ds_read_b128 v[180:183], v144 offset:49152
	ds_read_b128 v[184:187], v144 offset:50176
	ds_read_b128 v[188:191], v144 offset:51200
	ds_read_b128 v[192:195], v144 offset:52224
	ds_read_b128 v[200:203], v144 offset:53248
	ds_read_b128 v[204:207], v144 offset:54272
	ds_read_b128 v[208:211], v144 offset:55296
	ds_read_b128 v[212:215], v144 offset:56320
	global_load_lds_dwordx4 v[196:197], off
	v_lshl_add_u64 v[196:197], v[216:217], 0, s[10:11]
	s_mov_b32 m0, s40
	s_addc_u32 s19, s19, 0
	global_load_lds_dwordx4 v[196:197], off
	v_lshl_add_u64 v[196:197], s[18:19], 0, v[132:133]
	s_mov_b32 m0, s41
	s_nop 0
	global_load_lds_dwordx4 v[196:197], off
	v_lshl_add_u64 v[196:197], s[18:19], 0, v[128:129]
	s_mov_b32 m0, s42
	s_nop 0
	global_load_lds_dwordx4 v[196:197], off
	v_lshl_add_u64 v[196:197], v[218:219], 0, s[10:11]
	s_mov_b32 m0, s27
	s_nop 0
	global_load_lds_dwordx4 v[196:197], off
	v_lshl_add_u64 v[196:197], v[220:221], 0, s[10:11]
	s_mov_b32 m0, s28
	s_nop 0
	global_load_lds_dwordx4 v[196:197], off
	s_waitcnt vmcnt(8)
	s_waitcnt lgkmcnt(0)
	s_barrier
	s_setprio 1
	s_waitcnt lgkmcnt(0)
	v_mfma_f32_16x16x32_bf16 v[60:63], v[148:151], v[180:183], v[60:63]
	v_mfma_f32_16x16x32_bf16 v[56:59], v[156:159], v[180:183], v[56:59]
	v_mfma_f32_16x16x32_bf16 v[52:55], v[148:151], v[188:191], v[52:55]
	v_mfma_f32_16x16x32_bf16 v[44:47], v[156:159], v[188:191], v[44:47]
	v_mfma_f32_16x16x32_bf16 v[36:39], v[148:151], v[200:203], v[36:39]
	v_mfma_f32_16x16x32_bf16 v[28:31], v[156:159], v[200:203], v[28:31]
	v_mfma_f32_16x16x32_bf16 v[20:23], v[148:151], v[208:211], v[20:23]
	v_mfma_f32_16x16x32_bf16 v[12:15], v[156:159], v[208:211], v[12:15]
	v_mfma_f32_16x16x32_bf16 v[60:63], v[152:155], v[184:187], v[60:63]
	v_mfma_f32_16x16x32_bf16 v[56:59], v[160:163], v[184:187], v[56:59]
	v_mfma_f32_16x16x32_bf16 v[52:55], v[152:155], v[192:195], v[52:55]
	v_mfma_f32_16x16x32_bf16 v[44:47], v[160:163], v[192:195], v[44:47]
	v_mfma_f32_16x16x32_bf16 v[36:39], v[152:155], v[204:207], v[36:39]
	v_mfma_f32_16x16x32_bf16 v[28:31], v[160:163], v[204:207], v[28:31]
	v_mfma_f32_16x16x32_bf16 v[20:23], v[152:155], v[212:215], v[20:23]
	v_mfma_f32_16x16x32_bf16 v[12:15], v[160:163], v[212:215], v[12:15]
	v_mfma_f32_16x16x32_bf16 v[48:51], v[164:167], v[180:183], v[48:51]
	v_mfma_f32_16x16x32_bf16 v[40:43], v[172:175], v[180:183], v[40:43]
	v_mfma_f32_16x16x32_bf16 v[32:35], v[164:167], v[188:191], v[32:35]
	v_mfma_f32_16x16x32_bf16 v[24:27], v[172:175], v[188:191], v[24:27]
	v_mfma_f32_16x16x32_bf16 v[16:19], v[164:167], v[200:203], v[16:19]
	v_mfma_f32_16x16x32_bf16 v[8:11], v[172:175], v[200:203], v[8:11]
	v_mfma_f32_16x16x32_bf16 v[4:7], v[164:167], v[208:211], v[4:7]
	v_mfma_f32_16x16x32_bf16 v[0:3], v[172:175], v[208:211], v[0:3]
	v_mfma_f32_16x16x32_bf16 v[48:51], v[168:171], v[184:187], v[48:51]
	v_mfma_f32_16x16x32_bf16 v[40:43], v[176:179], v[184:187], v[40:43]
	v_mfma_f32_16x16x32_bf16 v[32:35], v[168:171], v[192:195], v[32:35]
	v_mfma_f32_16x16x32_bf16 v[24:27], v[176:179], v[192:195], v[24:27]
	v_mfma_f32_16x16x32_bf16 v[16:19], v[168:171], v[204:207], v[16:19]
	v_mfma_f32_16x16x32_bf16 v[8:11], v[176:179], v[204:207], v[8:11]
	v_mfma_f32_16x16x32_bf16 v[4:7], v[168:171], v[212:215], v[4:7]
	v_mfma_f32_16x16x32_bf16 v[0:3], v[176:179], v[212:215], v[0:3]
	s_setprio 0
	s_barrier
	s_add_i32 s31, s31, 2
	s_add_u32 s14, s14, 0x100
	s_addc_u32 s15, s15, 0
	s_cmp_gt_u32 s31, 13
	s_cbranch_scc0 .LBB0_2006
	s_cmpk_lt_u32 s22, 0x100
	s_cbranch_scc0 .LBB0_2009
	s_barrier

; #define PG8_STAGE(bufoff, gbase, voff) do { _Pragma("unroll") for (int _i = 0; _i < 2; ++_i) \
;         __builtin_amdgcn_global_load_lds((const unsigned*)((const char*)(gbase) + (voff)[_i]), (PG8_LAS unsigned*)(lds + (bufoff) + ldsw + _i * 8192), 16, 0, 0); } while (0)
; #define PG8_LDA(dst, b, h) do { _Pragma("unroll") for (int m = 0; m < 4; ++m) _Pragma("unroll") for (int k = 0; k < 2; ++k) dst[m][k] = *(const PG8_LAS bf16x8*)(lds + PG8_SA(b, h) + aoff + m * 2048 + k * 1024); } while (0)
; #define PG8_LDB(dst, b, h) do { _Pragma("unroll") for (int n = 0; n < 2; ++n) _Pragma("unroll") for (int k = 0; k < 2; ++k) dst[n][k] = *(const PG8_LAS bf16x8*)(lds + PG8_SB(b, h) + boff + n * 2048 + k * 1024); } while (0)
; #define PG8_MMA(ai, bj, At, Bt) do { __builtin_amdgcn_s_setprio(1); _Pragma("unroll") for (int m = 0; m < 4; ++m) _Pragma("unroll") for (int n = 0; n < 2; ++n) _Pragma("unroll") for (int k = 0; k < 2; ++k) \
;         acc[ai][bj][m][n] = __builtin_amdgcn_mfma_f32_16x16x32_bf16(Bt[n][k], At[m][k], acc[ai][bj][m][n], 0, 0, 0); __builtin_amdgcn_s_setprio(0); } while (0)
; #define PG8_WAIT_V(n) asm volatile("s_waitcnt vmcnt(" #n ")" ::: "memory")
; #define PG8_WAIT_L(n) asm volatile("s_waitcnt lgkmcnt(" #n ")" ::: "memory")
; template <class Epi, class Sched>
; __device__ __forceinline__ void gemm_phase(PG8_LAS unsigned char* lds, const Gemm g, const Sched& S, const Epi& E) {
;     ...
;         for (int t = 0; t < nt; t += 2) {
;             const bool last = (t == nt - 2);
;             const char* a1 = cA + (size_t)(t + 1) * kstepA;
;             const char* a2 = last ? nA : cA + (size_t)(t + 2) * kstepA; const char* b2 = last ? nB : cB + (size_t)(t + 2) * kstep;
;             const char* a3 = a2 + kstepA; const char* b3 = b2 + kstep;
;             if constexpr (epi_has_hook<Epi>::value) { if (t == nt / 2) E.hook(acc, cur, wr, wc, fr, fq); }
;             PG8_LDB(B0, 0, 0); PG8_LDB(B1, 0, 1); PG8_SCHED; PG8_LDA(At, 0, 0); PG8_STAGE(PG8_SA(1, 1), a1 + hstepA, voffA);
;             PG8_WAIT_V(8); PG8_WAIT_L(0); PG8_BAR; PG8_MMA(0, 0, At, B0); PG8_MMA(0, 1, At, B1); PG8_BAR; PG8_SCHED;
;             PG8_LDA(At, 0, 1); PG8_STAGE(PG8_SB(0, 0), b2, voffB); PG8_STAGE(PG8_SB(0, 1), b2 + hstepB, voffB); PG8_STAGE(PG8_SA(0, 0), a2, voffA);
;             PG8_WAIT_V(8); PG8_WAIT_L(0); PG8_BAR; PG8_MMA(1, 0, At, B0); PG8_MMA(1, 1, At, B1); PG8_BAR; PG8_SCHED;
.LBB0_2019:
	s_add_u32 s6, s26, s34
	s_addc_u32 s7, s27, s35
	s_add_u32 s38, s6, 0x100
	s_addc_u32 s39, s7, 0
	s_and_b64 s[36:37], s[30:31], exec
	s_cselect_b32 s37, s59, s39
	s_cselect_b32 s36, s60, s38
	s_add_u32 s34, s8, s34
	s_addc_u32 s35, s9, s35
	s_add_u32 s34, s34, 0x100
	s_addc_u32 s35, s35, 0
	s_and_b64 s[30:31], s[30:31], exec
	s_cselect_b32 s39, s61, s35
	s_cselect_b32 s38, s62, s34
	s_add_u32 s42, s6, 0x10080
	s_addc_u32 s43, s7, 0
	s_add_i32 s7, s56, s33
	s_add_i32 m0, s44, 0xc000
	s_add_i32 s6, s44, 0xe000
	s_add_i32 s65, s7, 0x2000
	s_add_u32 s40, s38, 0x10000
	ds_read_b128 v[76:79], v84
	ds_read_b128 v[86:89], v84 offset:1024
	ds_read_b128 v[90:93], v84 offset:2048
	ds_read_b128 v[94:97], v84 offset:3072
	s_addc_u32 s41, s39, 0
	s_add_i32 s66, 0, 0x18000
	s_add_u32 s34, s36, 0x10000
	s_addc_u32 s35, s37, 0
	s_add_i32 s64, s66, s33
	s_add_i32 s63, s64, 0x2000
	s_add_u32 s30, s38, 0x10080
	s_addc_u32 s31, s39, 0
	v_lshl_add_u64 v[130:131], s[42:43], 0, v[70:71]
	ds_read_b128 v[98:101], v85
	ds_read_b128 v[102:105], v85 offset:1024
	ds_read_b128 v[106:109], v85 offset:2048
	ds_read_b128 v[110:113], v85 offset:3072
	ds_read_b128 v[114:117], v85 offset:4096
	ds_read_b128 v[118:121], v85 offset:5120
	ds_read_b128 v[122:125], v85 offset:6144
	ds_read_b128 v[126:129], v85 offset:7168
	global_load_lds_dwordx4 v[130:131], off
	v_lshl_add_u64 v[130:131], s[42:43], 0, v[66:67]
	s_mov_b32 m0, s6
	s_nop 0
	global_load_lds_dwordx4 v[130:131], off
	s_waitcnt vmcnt(8)
	s_waitcnt lgkmcnt(0)
	s_barrier
	s_setprio 1
	s_waitcnt lgkmcnt(0)
	v_mfma_f32_16x16x32_bf16 v[60:63], v[76:79], v[98:101], v[60:63]
	v_mfma_f32_16x16x32_bf16 v[56:59], v[90:93], v[98:101], v[56:59]
	v_mfma_f32_16x16x32_bf16 v[52:55], v[76:79], v[106:109], v[52:55]
	v_mfma_f32_16x16x32_bf16 v[48:51], v[90:93], v[106:109], v[48:51]
	v_mfma_f32_16x16x32_bf16 v[44:47], v[76:79], v[114:117], v[44:47]
	v_mfma_f32_16x16x32_bf16 v[40:43], v[90:93], v[114:117], v[40:43]
	v_mfma_f32_16x16x32_bf16 v[36:39], v[76:79], v[122:125], v[36:39]
	v_mfma_f32_16x16x32_bf16 v[32:35], v[90:93], v[122:125], v[32:35]
	v_mfma_f32_16x16x32_bf16 v[60:63], v[86:89], v[102:105], v[60:63]
	v_mfma_f32_16x16x32_bf16 v[56:59], v[94:97], v[102:105], v[56:59]
	v_mfma_f32_16x16x32_bf16 v[52:55], v[86:89], v[110:113], v[52:55]
	v_mfma_f32_16x16x32_bf16 v[48:51], v[94:97], v[110:113], v[48:51]
	v_mfma_f32_16x16x32_bf16 v[44:47], v[86:89], v[118:121], v[44:47]
	v_mfma_f32_16x16x32_bf16 v[40:43], v[94:97], v[118:121], v[40:43]
	v_mfma_f32_16x16x32_bf16 v[36:39], v[86:89], v[126:129], v[36:39]
	v_mfma_f32_16x16x32_bf16 v[32:35], v[94:97], v[126:129], v[32:35]
	s_setprio 0
	s_barrier
	s_mov_b32 m0, s7
	v_lshl_add_u64 v[130:131], s[38:39], 0, v[68:69]
	ds_read_b128 v[98:101], v85 offset:16384
	ds_read_b128 v[102:105], v85 offset:17408
	ds_read_b128 v[106:109], v85 offset:18432
	ds_read_b128 v[110:113], v85 offset:19456
	ds_read_b128 v[114:117], v85 offset:20480
	ds_read_b128 v[118:121], v85 offset:21504
	ds_read_b128 v[122:125], v85 offset:22528
	ds_read_b128 v[126:129], v85 offset:23552
	global_load_lds_dwordx4 v[130:131], off
	v_lshl_add_u64 v[132:133], s[38:39], 0, v[64:65]
	s_mov_b32 m0, s65
	v_lshl_add_u64 v[134:135], s[40:41], 0, v[68:69]
	global_load_lds_dwordx4 v[132:133], off
	s_mov_b32 m0, s45
	v_lshl_add_u64 v[136:137], s[36:37], 0, v[66:67]
	global_load_lds_dwordx4 v[134:135], off
	v_lshl_add_u64 v[134:135], s[40:41], 0, v[64:65]
	s_mov_b32 m0, s46
	s_nop 0
	global_load_lds_dwordx4 v[134:135], off
	v_lshl_add_u64 v[134:135], s[36:37], 0, v[70:71]
	s_mov_b32 m0, s44
	s_nop 0
	global_load_lds_dwordx4 v[134:135], off
	s_mov_b32 m0, s47
	s_nop 0
	global_load_lds_dwordx4 v[136:137], off
	s_waitcnt vmcnt(8)
	s_waitcnt lgkmcnt(0)
	s_barrier
	s_setprio 1
	s_waitcnt lgkmcnt(0)
	v_mfma_f32_16x16x32_bf16 v[28:31], v[76:79], v[98:101], v[28:31]
	v_mfma_f32_16x16x32_bf16 v[24:27], v[90:93], v[98:101], v[24:27]
	v_mfma_f32_16x16x32_bf16 v[20:23], v[76:79], v[106:109], v[20:23]
	v_mfma_f32_16x16x32_bf16 v[16:19], v[90:93], v[106:109], v[16:19]
	v_mfma_f32_16x16x32_bf16 v[12:15], v[76:79], v[114:117], v[12:15]
	v_mfma_f32_16x16x32_bf16 v[8:11], v[90:93], v[114:117], v[8:11]
	v_mfma_f32_16x16x32_bf16 v[4:7], v[76:79], v[122:125], v[4:7]
	v_mfma_f32_16x16x32_bf16 v[0:3], v[90:93], v[122:125], v[0:3]
	v_mfma_f32_16x16x32_bf16 v[28:31], v[86:89], v[102:105], v[28:31]
	v_mfma_f32_16x16x32_bf16 v[24:27], v[94:97], v[102:105], v[24:27]
	v_mfma_f32_16x16x32_bf16 v[20:23], v[86:89], v[110:113], v[20:23]
	v_mfma_f32_16x16x32_bf16 v[16:19], v[94:97], v[110:113], v[16:19]
	v_mfma_f32_16x16x32_bf16 v[12:15], v[86:89], v[118:121], v[12:15]
	v_mfma_f32_16x16x32_bf16 v[8:11], v[94:97], v[118:121], v[8:11]
	v_mfma_f32_16x16x32_bf16 v[4:7], v[86:89], v[126:129], v[4:7]
	v_mfma_f32_16x16x32_bf16 v[0:3], v[94:97], v[126:129], v[0:3]
	s_setprio 0
	s_barrier
; #define PG8_STAGE(bufoff, gbase, voff) do { _Pragma("unroll") for (int _i = 0; _i < 2; ++_i) \
;         __builtin_amdgcn_global_load_lds((const unsigned*)((const char*)(gbase) + (voff)[_i]), (PG8_LAS unsigned*)(lds + (bufoff) + ldsw + _i * 8192), 16, 0, 0); } while (0)
; #define PG8_LDA(dst, b, h) do { _Pragma("unroll") for (int m = 0; m < 4; ++m) _Pragma("unroll") for (int k = 0; k < 2; ++k) dst[m][k] = *(const PG8_LAS bf16x8*)(lds + PG8_SA(b, h) + aoff + m * 2048 + k * 1024); } while (0)
; #define PG8_LDB(dst, b, h) do { _Pragma("unroll") for (int n = 0; n < 2; ++n) _Pragma("unroll") for (int k = 0; k < 2; ++k) dst[n][k] = *(const PG8_LAS bf16x8*)(lds + PG8_SB(b, h) + boff + n * 2048 + k * 1024); } while (0)
; #define PG8_MMA(ai, bj, At, Bt) do { __builtin_amdgcn_s_setprio(1); _Pragma("unroll") for (int m = 0; m < 4; ++m) _Pragma("unroll") for (int n = 0; n < 2; ++n) _Pragma("unroll") for (int k = 0; k < 2; ++k) \
;         acc[ai][bj][m][n] = __builtin_amdgcn_mfma_f32_16x16x32_bf16(Bt[n][k], At[m][k], acc[ai][bj][m][n], 0, 0, 0); __builtin_amdgcn_s_setprio(0); } while (0)
; #define PG8_WAIT_V(n) asm volatile("s_waitcnt vmcnt(" #n ")" ::: "memory")
; #define PG8_WAIT_L(n) asm volatile("s_waitcnt lgkmcnt(" #n ")" ::: "memory")
; #define PG8_BAR __builtin_amdgcn_s_barrier()
; #define PG8_SCHED __builtin_amdgcn_sched_barrier(0)
; template <class Epi, class Sched>
; __device__ __forceinline__ void gemm_phase(PG8_LAS unsigned char* lds, const Gemm g, const Sched& S, const Epi& E) {
;     ...
;             PG8_LDB(B0, 1, 0); PG8_LDB(B1, 1, 1); PG8_SCHED; PG8_LDA(At, 1, 0); PG8_STAGE(PG8_SA(0, 1), a2 + hstepA, voffA);
;             PG8_WAIT_V(8); PG8_WAIT_L(0); PG8_BAR; PG8_MMA(0, 0, At, B0); PG8_MMA(0, 1, At, B1); PG8_BAR; PG8_SCHED;
;             PG8_LDA(At, 1, 1); PG8_STAGE(PG8_SB(1, 0), b3, voffB); PG8_STAGE(PG8_SB(1, 1), b3 + hstepB, voffB); PG8_STAGE(PG8_SA(1, 0), a3, voffA);
;             PG8_WAIT_V(8); PG8_WAIT_L(0); PG8_BAR; PG8_MMA(1, 0, At, B0); PG8_MMA(1, 1, At, B1); PG8_BAR; PG8_SCHED;
;         }
;         if (wr == 0) PG8_BAR;
	v_add_u32_e32 v72, s66, v81
	ds_read_b128 v[76:79], v72
	ds_read_b128 v[86:89], v72 offset:1024
	ds_read_b128 v[90:93], v72 offset:2048
	ds_read_b128 v[94:97], v72 offset:3072
	s_mov_b32 m0, s48
	v_lshl_add_u64 v[138:139], s[34:35], 0, v[70:71]
	ds_read_b128 v[98:101], v85 offset:32768
	ds_read_b128 v[102:105], v85 offset:33792
	ds_read_b128 v[106:109], v85 offset:34816
	ds_read_b128 v[110:113], v85 offset:35840
	ds_read_b128 v[114:117], v85 offset:36864
	ds_read_b128 v[118:121], v85 offset:37888
	ds_read_b128 v[122:125], v85 offset:38912
	ds_read_b128 v[126:129], v85 offset:39936
	global_load_lds_dwordx4 v[138:139], off
	v_lshl_add_u64 v[138:139], s[34:35], 0, v[66:67]
	s_mov_b32 m0, s49
	s_nop 0
	global_load_lds_dwordx4 v[138:139], off
	s_waitcnt vmcnt(8)
	s_waitcnt lgkmcnt(0)
	s_barrier
	s_setprio 1
	s_waitcnt lgkmcnt(0)
	v_mfma_f32_16x16x32_bf16 v[60:63], v[76:79], v[98:101], v[60:63]
	v_mfma_f32_16x16x32_bf16 v[56:59], v[90:93], v[98:101], v[56:59]
	v_mfma_f32_16x16x32_bf16 v[52:55], v[76:79], v[106:109], v[52:55]
	v_mfma_f32_16x16x32_bf16 v[48:51], v[90:93], v[106:109], v[48:51]
	v_mfma_f32_16x16x32_bf16 v[44:47], v[76:79], v[114:117], v[44:47]
	v_mfma_f32_16x16x32_bf16 v[40:43], v[90:93], v[114:117], v[40:43]
	v_mfma_f32_16x16x32_bf16 v[36:39], v[76:79], v[122:125], v[36:39]
	v_mfma_f32_16x16x32_bf16 v[32:35], v[90:93], v[122:125], v[32:35]
	v_mfma_f32_16x16x32_bf16 v[60:63], v[86:89], v[102:105], v[60:63]
	v_mfma_f32_16x16x32_bf16 v[56:59], v[94:97], v[102:105], v[56:59]
	v_mfma_f32_16x16x32_bf16 v[52:55], v[86:89], v[110:113], v[52:55]
	v_mfma_f32_16x16x32_bf16 v[48:51], v[94:97], v[110:113], v[48:51]
	v_mfma_f32_16x16x32_bf16 v[44:47], v[86:89], v[118:121], v[44:47]
	v_mfma_f32_16x16x32_bf16 v[40:43], v[94:97], v[118:121], v[40:43]
	v_mfma_f32_16x16x32_bf16 v[36:39], v[86:89], v[126:129], v[36:39]
	v_mfma_f32_16x16x32_bf16 v[32:35], v[94:97], v[126:129], v[32:35]
	s_setprio 0
	s_barrier
	s_mov_b32 m0, s64
	v_lshl_add_u64 v[130:131], v[130:131], 0, s[4:5]
	ds_read_b128 v[98:101], v85 offset:49152
	ds_read_b128 v[102:105], v85 offset:50176
	ds_read_b128 v[106:109], v85 offset:51200
	ds_read_b128 v[110:113], v85 offset:52224
	ds_read_b128 v[114:117], v85 offset:53248
	ds_read_b128 v[118:121], v85 offset:54272
	ds_read_b128 v[122:125], v85 offset:55296
	ds_read_b128 v[126:129], v85 offset:56320
	global_load_lds_dwordx4 v[130:131], off
	v_lshl_add_u64 v[130:131], v[132:133], 0, s[4:5]
	s_mov_b32 m0, s63
	s_nop 0
	global_load_lds_dwordx4 v[130:131], off
	v_lshl_add_u64 v[130:131], s[30:31], 0, v[68:69]
	s_mov_b32 m0, s54
	s_nop 0
	global_load_lds_dwordx4 v[130:131], off
	v_lshl_add_u64 v[130:131], s[30:31], 0, v[64:65]
	s_mov_b32 m0, s55
	s_nop 0
	global_load_lds_dwordx4 v[130:131], off
	v_lshl_add_u64 v[130:131], v[134:135], 0, s[4:5]
	s_mov_b32 m0, s52
	s_nop 0
	global_load_lds_dwordx4 v[130:131], off
	v_lshl_add_u64 v[130:131], v[136:137], 0, s[4:5]
	s_mov_b32 m0, s53
	s_nop 0
	global_load_lds_dwordx4 v[130:131], off
	s_waitcnt vmcnt(8)
	s_waitcnt lgkmcnt(0)
	s_barrier
	s_setprio 1
	s_waitcnt lgkmcnt(0)
	v_mfma_f32_16x16x32_bf16 v[28:31], v[76:79], v[98:101], v[28:31]
	v_mfma_f32_16x16x32_bf16 v[24:27], v[90:93], v[98:101], v[24:27]
	v_mfma_f32_16x16x32_bf16 v[20:23], v[76:79], v[106:109], v[20:23]
	v_mfma_f32_16x16x32_bf16 v[16:19], v[90:93], v[106:109], v[16:19]
	v_mfma_f32_16x16x32_bf16 v[12:15], v[76:79], v[114:117], v[12:15]
	v_mfma_f32_16x16x32_bf16 v[8:11], v[90:93], v[114:117], v[8:11]
	v_mfma_f32_16x16x32_bf16 v[4:7], v[76:79], v[122:125], v[4:7]
	v_mfma_f32_16x16x32_bf16 v[0:3], v[90:93], v[122:125], v[0:3]
	v_mfma_f32_16x16x32_bf16 v[28:31], v[86:89], v[102:105], v[28:31]
	v_mfma_f32_16x16x32_bf16 v[24:27], v[94:97], v[102:105], v[24:27]
	v_mfma_f32_16x16x32_bf16 v[20:23], v[86:89], v[110:113], v[20:23]
	v_mfma_f32_16x16x32_bf16 v[16:19], v[94:97], v[110:113], v[16:19]
	v_mfma_f32_16x16x32_bf16 v[12:15], v[86:89], v[118:121], v[12:15]
	v_mfma_f32_16x16x32_bf16 v[8:11], v[94:97], v[118:121], v[8:11]
	v_mfma_f32_16x16x32_bf16 v[4:7], v[86:89], v[126:129], v[4:7]
	v_mfma_f32_16x16x32_bf16 v[0:3], v[94:97], v[126:129], v[0:3]
	s_setprio 0
	s_barrier
	s_andn2_b64 vcc, exec, s[28:29]
	s_mov_b64 s[30:31], -1
	s_mov_b64 s[28:29], 0
	s_mov_b64 s[34:35], 0x100
	s_cbranch_vccz .LBB0_2019
	s_and_b64 vcc, exec, s[10:11]
	s_cbranch_vccz .LBB0_2022
	s_barrier

; #define PG8_STAGE(bufoff, gbase, voff) do { _Pragma("unroll") for (int _i = 0; _i < 2; ++_i) \
;         __builtin_amdgcn_global_load_lds((const unsigned*)((const char*)(gbase) + (voff)[_i]), (PG8_LAS unsigned*)(lds + (bufoff) + ldsw + _i * 8192), 16, 0, 0); } while (0)
; #define PG8_LDA(dst, b, h) do { _Pragma("unroll") for (int m = 0; m < 4; ++m) _Pragma("unroll") for (int k = 0; k < 2; ++k) dst[m][k] = *(const PG8_LAS bf16x8*)(lds + PG8_SA(b, h) + aoff + m * 2048 + k * 1024); } while (0)
; #define PG8_LDB(dst, b, h) do { _Pragma("unroll") for (int n = 0; n < 2; ++n) _Pragma("unroll") for (int k = 0; k < 2; ++k) dst[n][k] = *(const PG8_LAS bf16x8*)(lds + PG8_SB(b, h) + boff + n * 2048 + k * 1024); } while (0)
; #define PG8_MMA(ai, bj, At, Bt) do { __builtin_amdgcn_s_setprio(1); _Pragma("unroll") for (int m = 0; m < 4; ++m) _Pragma("unroll") for (int n = 0; n < 2; ++n) _Pragma("unroll") for (int k = 0; k < 2; ++k) \
;         acc[ai][bj][m][n] = __builtin_amdgcn_mfma_f32_16x16x32_bf16(Bt[n][k], At[m][k], acc[ai][bj][m][n], 0, 0, 0); __builtin_amdgcn_s_setprio(0); } while (0)
; #define PG8_WAIT_V(n) asm volatile("s_waitcnt vmcnt(" #n ")" ::: "memory")
; #define PG8_WAIT_L(n) asm volatile("s_waitcnt lgkmcnt(" #n ")" ::: "memory")
; template <class Epi, class Sched>
; __device__ __forceinline__ void gemm_phase(PG8_LAS unsigned char* lds, const Gemm g, const Sched& S, const Epi& E) {
;     ...
;         for (int t = 0; t < nt; t += 2) {
;             const bool last = (t == nt - 2);
;             const char* a1 = cA + (size_t)(t + 1) * kstepA;
;             const char* a2 = last ? nA : cA + (size_t)(t + 2) * kstepA; const char* b2 = last ? nB : cB + (size_t)(t + 2) * kstep;
;             const char* a3 = a2 + kstepA; const char* b3 = b2 + kstep;
;             if constexpr (epi_has_hook<Epi>::value) { if (t == nt / 2) E.hook(acc, cur, wr, wc, fr, fq); }
;             PG8_LDB(B0, 0, 0); PG8_LDB(B1, 0, 1); PG8_SCHED; PG8_LDA(At, 0, 0); PG8_STAGE(PG8_SA(1, 1), a1 + hstepA, voffA);
;             PG8_WAIT_V(8); PG8_WAIT_L(0); PG8_BAR; PG8_MMA(0, 0, At, B0); PG8_MMA(0, 1, At, B1); PG8_BAR; PG8_SCHED;
;             PG8_LDA(At, 0, 1); PG8_STAGE(PG8_SB(0, 0), b2, voffB); PG8_STAGE(PG8_SB(0, 1), b2 + hstepB, voffB); PG8_STAGE(PG8_SA(0, 0), a2, voffA);
;             PG8_WAIT_V(8); PG8_WAIT_L(0); PG8_BAR; PG8_MMA(1, 0, At, B0); PG8_MMA(1, 1, At, B1); PG8_BAR; PG8_SCHED;
.LBB0_2809:
	s_add_u32 s26, s22, s24
	s_addc_u32 s27, s23, s25
	s_add_u32 s26, s26, 0x100
	s_addc_u32 s27, s27, 0
	s_add_u32 s48, s45, s24
	s_addc_u32 s49, s46, s25
	s_cmpk_eq_i32 s24, 0x700
	s_cselect_b32 s29, s11, s27
	s_cselect_b32 s28, s13, s26
	s_cselect_b32 s27, s43, s49
	s_cselect_b32 s26, s44, s48
	s_add_i32 s48, 0, 0x10000
	v_add_u32_e32 v140, s48, v169
	v_add_u32_e32 v161, s42, v169
	ds_read_b128 v[128:131], v140
	ds_read_b128 v[132:135], v140 offset:1024
	ds_read_b128 v[136:139], v140 offset:2048
	ds_read_b128 v[140:143], v140 offset:3072
	ds_read_b128 v[172:175], v161
	ds_read_b128 v[176:179], v161 offset:1024
	ds_read_b128 v[180:183], v161 offset:2048
	ds_read_b128 v[184:187], v161 offset:3072
	v_lshl_add_u64 v[196:197], v[164:165], 0, s[24:25]
	s_add_i32 m0, s33, 0xc000
	ds_read_b128 v[188:191], v171
	ds_read_b128 v[192:195], v171 offset:1024
	ds_read_b128 v[200:203], v171 offset:2048
	ds_read_b128 v[204:207], v171 offset:3072
	ds_read_b128 v[208:211], v171 offset:4096
	ds_read_b128 v[212:215], v171 offset:5120
	ds_read_b128 v[216:219], v171 offset:6144
	ds_read_b128 v[220:223], v171 offset:7168
	global_load_lds_dwordx4 v[196:197], off
	v_lshl_add_u64 v[196:197], v[166:167], 0, s[24:25]
	s_add_i32 m0, s33, 0xe000
	s_nop 0
	global_load_lds_dwordx4 v[196:197], off
	s_waitcnt vmcnt(8)
	s_waitcnt lgkmcnt(0)
	s_barrier
	s_setprio 1
	s_waitcnt lgkmcnt(0)
	v_mfma_f32_16x16x32_bf16 v[124:127], v[128:131], v[188:191], v[124:127]
	v_mfma_f32_16x16x32_bf16 v[120:123], v[136:139], v[188:191], v[120:123]
	v_mfma_f32_16x16x32_bf16 v[116:119], v[128:131], v[200:203], v[116:119]
	v_mfma_f32_16x16x32_bf16 v[112:115], v[136:139], v[200:203], v[112:115]
	v_mfma_f32_16x16x32_bf16 v[96:99], v[128:131], v[208:211], v[96:99]
	v_mfma_f32_16x16x32_bf16 v[88:91], v[136:139], v[208:211], v[88:91]
	v_mfma_f32_16x16x32_bf16 v[80:83], v[128:131], v[216:219], v[80:83]
	v_mfma_f32_16x16x32_bf16 v[72:75], v[136:139], v[216:219], v[72:75]
	v_mfma_f32_16x16x32_bf16 v[124:127], v[132:135], v[192:195], v[124:127]
	v_mfma_f32_16x16x32_bf16 v[120:123], v[140:143], v[192:195], v[120:123]
	v_mfma_f32_16x16x32_bf16 v[116:119], v[132:135], v[204:207], v[116:119]
	v_mfma_f32_16x16x32_bf16 v[112:115], v[140:143], v[204:207], v[112:115]
	v_mfma_f32_16x16x32_bf16 v[96:99], v[132:135], v[212:215], v[96:99]
	v_mfma_f32_16x16x32_bf16 v[88:91], v[140:143], v[212:215], v[88:91]
	v_mfma_f32_16x16x32_bf16 v[80:83], v[132:135], v[220:223], v[80:83]
	v_mfma_f32_16x16x32_bf16 v[72:75], v[140:143], v[220:223], v[72:75]
	v_mfma_f32_16x16x32_bf16 v[108:111], v[172:175], v[188:191], v[108:111]
	v_mfma_f32_16x16x32_bf16 v[104:107], v[180:183], v[188:191], v[104:107]
	v_mfma_f32_16x16x32_bf16 v[100:103], v[172:175], v[200:203], v[100:103]
	v_mfma_f32_16x16x32_bf16 v[92:95], v[180:183], v[200:203], v[92:95]
	v_mfma_f32_16x16x32_bf16 v[84:87], v[172:175], v[208:211], v[84:87]
	v_mfma_f32_16x16x32_bf16 v[76:79], v[180:183], v[208:211], v[76:79]
	v_mfma_f32_16x16x32_bf16 v[68:71], v[172:175], v[216:219], v[68:71]
	v_mfma_f32_16x16x32_bf16 v[64:67], v[180:183], v[216:219], v[64:67]
	v_mfma_f32_16x16x32_bf16 v[108:111], v[176:179], v[192:195], v[108:111]
	v_mfma_f32_16x16x32_bf16 v[104:107], v[184:187], v[192:195], v[104:107]
	v_mfma_f32_16x16x32_bf16 v[100:103], v[176:179], v[204:207], v[100:103]
	v_mfma_f32_16x16x32_bf16 v[92:95], v[184:187], v[204:207], v[92:95]
	v_mfma_f32_16x16x32_bf16 v[84:87], v[176:179], v[212:215], v[84:87]
	v_mfma_f32_16x16x32_bf16 v[76:79], v[184:187], v[212:215], v[76:79]
	v_mfma_f32_16x16x32_bf16 v[68:71], v[176:179], v[220:223], v[68:71]
	v_mfma_f32_16x16x32_bf16 v[64:67], v[184:187], v[220:223], v[64:67]
	s_setprio 0
	s_barrier
	s_add_i32 s48, s48, s31
	v_lshl_add_u64 v[196:197], s[26:27], 0, v[146:147]
	s_mov_b32 m0, s48
	ds_read_b128 v[188:191], v171 offset:16384
	ds_read_b128 v[192:195], v171 offset:17408
	ds_read_b128 v[200:203], v171 offset:18432
	ds_read_b128 v[204:207], v171 offset:19456
	ds_read_b128 v[208:211], v171 offset:20480
	ds_read_b128 v[212:215], v171 offset:21504
	ds_read_b128 v[216:219], v171 offset:22528
	ds_read_b128 v[220:223], v171 offset:23552
	global_load_lds_dwordx4 v[196:197], off
	s_add_i32 m0, s48, 0x2000
	s_add_u32 s48, s26, 0x40000
	v_lshl_add_u64 v[224:225], s[26:27], 0, v[150:151]
	s_addc_u32 s49, s27, 0
	s_add_i32 s50, s42, s31
	global_load_lds_dwordx4 v[224:225], off
	v_lshl_add_u64 v[226:227], s[48:49], 0, v[146:147]
	s_mov_b32 m0, s50
	v_lshl_add_u64 v[228:229], s[28:29], 0, v[148:149]
	global_load_lds_dwordx4 v[226:227], off
	v_lshl_add_u64 v[226:227], s[48:49], 0, v[150:151]
	s_add_i32 m0, s50, 0x2000
	s_nop 0
	global_load_lds_dwordx4 v[226:227], off
	v_lshl_add_u64 v[226:227], s[28:29], 0, v[144:145]
	s_mov_b32 m0, s33
	s_nop 0
	global_load_lds_dwordx4 v[226:227], off
	s_mov_b32 m0, s34
	s_nop 0
	global_load_lds_dwordx4 v[228:229], off
	s_waitcnt vmcnt(8)
	s_waitcnt lgkmcnt(0)
	s_barrier
; #define PG8_STAGE(bufoff, gbase, voff) do { _Pragma("unroll") for (int _i = 0; _i < 2; ++_i) \
;         __builtin_amdgcn_global_load_lds((const unsigned*)((const char*)(gbase) + (voff)[_i]), (PG8_LAS unsigned*)(lds + (bufoff) + ldsw + _i * 8192), 16, 0, 0); } while (0)
; #define PG8_LDA(dst, b, h) do { _Pragma("unroll") for (int m = 0; m < 4; ++m) _Pragma("unroll") for (int k = 0; k < 2; ++k) dst[m][k] = *(const PG8_LAS bf16x8*)(lds + PG8_SA(b, h) + aoff + m * 2048 + k * 1024); } while (0)
; #define PG8_LDB(dst, b, h) do { _Pragma("unroll") for (int n = 0; n < 2; ++n) _Pragma("unroll") for (int k = 0; k < 2; ++k) dst[n][k] = *(const PG8_LAS bf16x8*)(lds + PG8_SB(b, h) + boff + n * 2048 + k * 1024); } while (0)
; #define PG8_MMA(ai, bj, At, Bt) do { __builtin_amdgcn_s_setprio(1); _Pragma("unroll") for (int m = 0; m < 4; ++m) _Pragma("unroll") for (int n = 0; n < 2; ++n) _Pragma("unroll") for (int k = 0; k < 2; ++k) \
;         acc[ai][bj][m][n] = __builtin_amdgcn_mfma_f32_16x16x32_bf16(Bt[n][k], At[m][k], acc[ai][bj][m][n], 0, 0, 0); __builtin_amdgcn_s_setprio(0); } while (0)
; #define PG8_WAIT_V(n) asm volatile("s_waitcnt vmcnt(" #n ")" ::: "memory")
; #define PG8_WAIT_L(n) asm volatile("s_waitcnt lgkmcnt(" #n ")" ::: "memory")
; #define PG8_BAR __builtin_amdgcn_s_barrier()
; #define PG8_SCHED __builtin_amdgcn_sched_barrier(0)
; template <class Epi, class Sched>
; __device__ __forceinline__ void gemm_phase(PG8_LAS unsigned char* lds, const Gemm g, const Sched& S, const Epi& E) {
;     ...
;             PG8_WAIT_V(8); PG8_WAIT_L(0); PG8_BAR; PG8_MMA(1, 0, At, B0); PG8_MMA(1, 1, At, B1); PG8_BAR; PG8_SCHED;
;             PG8_LDB(B0, 1, 0); PG8_LDB(B1, 1, 1); PG8_SCHED; PG8_LDA(At, 1, 0); PG8_STAGE(PG8_SA(0, 1), a2 + hstepA, voffA);
;             PG8_WAIT_V(8); PG8_WAIT_L(0); PG8_BAR; PG8_MMA(0, 0, At, B0); PG8_MMA(0, 1, At, B1); PG8_BAR; PG8_SCHED;
	s_setprio 1
	s_waitcnt lgkmcnt(0)
	v_mfma_f32_16x16x32_bf16 v[60:63], v[128:131], v[188:191], v[60:63]
	v_mfma_f32_16x16x32_bf16 v[56:59], v[136:139], v[188:191], v[56:59]
	v_mfma_f32_16x16x32_bf16 v[48:51], v[128:131], v[200:203], v[48:51]
	v_mfma_f32_16x16x32_bf16 v[40:43], v[136:139], v[200:203], v[40:43]
	v_mfma_f32_16x16x32_bf16 v[32:35], v[128:131], v[208:211], v[32:35]
	v_mfma_f32_16x16x32_bf16 v[24:27], v[136:139], v[208:211], v[24:27]
	v_mfma_f32_16x16x32_bf16 v[16:19], v[128:131], v[216:219], v[16:19]
	v_mfma_f32_16x16x32_bf16 v[8:11], v[136:139], v[216:219], v[8:11]
	v_mfma_f32_16x16x32_bf16 v[60:63], v[132:135], v[192:195], v[60:63]
	v_mfma_f32_16x16x32_bf16 v[56:59], v[140:143], v[192:195], v[56:59]
	v_mfma_f32_16x16x32_bf16 v[48:51], v[132:135], v[204:207], v[48:51]
	v_mfma_f32_16x16x32_bf16 v[40:43], v[140:143], v[204:207], v[40:43]
	v_mfma_f32_16x16x32_bf16 v[32:35], v[132:135], v[212:215], v[32:35]
	v_mfma_f32_16x16x32_bf16 v[24:27], v[140:143], v[212:215], v[24:27]
	v_mfma_f32_16x16x32_bf16 v[16:19], v[132:135], v[220:223], v[16:19]
	v_mfma_f32_16x16x32_bf16 v[8:11], v[140:143], v[220:223], v[8:11]
	v_mfma_f32_16x16x32_bf16 v[52:55], v[172:175], v[188:191], v[52:55]
	v_mfma_f32_16x16x32_bf16 v[44:47], v[180:183], v[188:191], v[44:47]
	v_mfma_f32_16x16x32_bf16 v[36:39], v[172:175], v[200:203], v[36:39]
	v_mfma_f32_16x16x32_bf16 v[28:31], v[180:183], v[200:203], v[28:31]
	v_mfma_f32_16x16x32_bf16 v[20:23], v[172:175], v[208:211], v[20:23]
	v_mfma_f32_16x16x32_bf16 v[12:15], v[180:183], v[208:211], v[12:15]
	v_mfma_f32_16x16x32_bf16 v[4:7], v[172:175], v[216:219], v[4:7]
	v_mfma_f32_16x16x32_bf16 v[0:3], v[180:183], v[216:219], v[0:3]
	v_mfma_f32_16x16x32_bf16 v[52:55], v[176:179], v[192:195], v[52:55]
	v_mfma_f32_16x16x32_bf16 v[44:47], v[184:187], v[192:195], v[44:47]
	v_mfma_f32_16x16x32_bf16 v[36:39], v[176:179], v[204:207], v[36:39]
	v_mfma_f32_16x16x32_bf16 v[28:31], v[184:187], v[204:207], v[28:31]
	v_mfma_f32_16x16x32_bf16 v[20:23], v[176:179], v[212:215], v[20:23]
	v_mfma_f32_16x16x32_bf16 v[12:15], v[184:187], v[212:215], v[12:15]
	v_mfma_f32_16x16x32_bf16 v[4:7], v[176:179], v[220:223], v[4:7]
	v_mfma_f32_16x16x32_bf16 v[0:3], v[184:187], v[220:223], v[0:3]
	s_setprio 0
	s_barrier
	s_add_i32 s48, 0, 0x18000
	s_add_i32 s49, 0, 0x1c000
	v_add_u32_e32 v140, s48, v169
	v_add_u32_e32 v161, s49, v169
	ds_read_b128 v[128:131], v140
	ds_read_b128 v[132:135], v140 offset:1024
	ds_read_b128 v[136:139], v140 offset:2048
	ds_read_b128 v[140:143], v140 offset:3072
	ds_read_b128 v[172:175], v161
	ds_read_b128 v[176:179], v161 offset:1024
	ds_read_b128 v[180:183], v161 offset:2048
	ds_read_b128 v[184:187], v161 offset:3072
	s_add_u32 s28, s28, 0x40000
	s_addc_u32 s29, s29, 0
	s_mov_b32 m0, s35
	v_lshl_add_u64 v[230:231], s[28:29], 0, v[144:145]
	ds_read_b128 v[188:191], v171 offset:32768
	ds_read_b128 v[192:195], v171 offset:33792
	ds_read_b128 v[200:203], v171 offset:34816
	ds_read_b128 v[204:207], v171 offset:35840
	ds_read_b128 v[208:211], v171 offset:36864
	ds_read_b128 v[212:215], v171 offset:37888
	ds_read_b128 v[216:219], v171 offset:38912
	ds_read_b128 v[220:223], v171 offset:39936
	global_load_lds_dwordx4 v[230:231], off
	v_lshl_add_u64 v[230:231], s[28:29], 0, v[148:149]
	s_mov_b32 m0, s36
	s_nop 0
	global_load_lds_dwordx4 v[230:231], off
	s_waitcnt vmcnt(8)
	s_waitcnt lgkmcnt(0)
	s_barrier
	s_setprio 1
	s_waitcnt lgkmcnt(0)
	v_mfma_f32_16x16x32_bf16 v[124:127], v[128:131], v[188:191], v[124:127]
	v_mfma_f32_16x16x32_bf16 v[120:123], v[136:139], v[188:191], v[120:123]
	v_mfma_f32_16x16x32_bf16 v[116:119], v[128:131], v[200:203], v[116:119]
	v_mfma_f32_16x16x32_bf16 v[112:115], v[136:139], v[200:203], v[112:115]
	v_mfma_f32_16x16x32_bf16 v[96:99], v[128:131], v[208:211], v[96:99]
	v_mfma_f32_16x16x32_bf16 v[88:91], v[136:139], v[208:211], v[88:91]
	v_mfma_f32_16x16x32_bf16 v[80:83], v[128:131], v[216:219], v[80:83]
	v_mfma_f32_16x16x32_bf16 v[72:75], v[136:139], v[216:219], v[72:75]
	v_mfma_f32_16x16x32_bf16 v[124:127], v[132:135], v[192:195], v[124:127]
	v_mfma_f32_16x16x32_bf16 v[120:123], v[140:143], v[192:195], v[120:123]
	v_mfma_f32_16x16x32_bf16 v[116:119], v[132:135], v[204:207], v[116:119]
	v_mfma_f32_16x16x32_bf16 v[112:115], v[140:143], v[204:207], v[112:115]
	v_mfma_f32_16x16x32_bf16 v[96:99], v[132:135], v[212:215], v[96:99]
	v_mfma_f32_16x16x32_bf16 v[88:91], v[140:143], v[212:215], v[88:91]
	v_mfma_f32_16x16x32_bf16 v[80:83], v[132:135], v[220:223], v[80:83]
	v_mfma_f32_16x16x32_bf16 v[72:75], v[140:143], v[220:223], v[72:75]
	v_mfma_f32_16x16x32_bf16 v[108:111], v[172:175], v[188:191], v[108:111]
	v_mfma_f32_16x16x32_bf16 v[104:107], v[180:183], v[188:191], v[104:107]
	v_mfma_f32_16x16x32_bf16 v[100:103], v[172:175], v[200:203], v[100:103]
	v_mfma_f32_16x16x32_bf16 v[92:95], v[180:183], v[200:203], v[92:95]
	v_mfma_f32_16x16x32_bf16 v[84:87], v[172:175], v[208:211], v[84:87]
	v_mfma_f32_16x16x32_bf16 v[76:79], v[180:183], v[208:211], v[76:79]
	v_mfma_f32_16x16x32_bf16 v[68:71], v[172:175], v[216:219], v[68:71]
	v_mfma_f32_16x16x32_bf16 v[64:67], v[180:183], v[216:219], v[64:67]
	v_mfma_f32_16x16x32_bf16 v[108:111], v[176:179], v[192:195], v[108:111]
	v_mfma_f32_16x16x32_bf16 v[104:107], v[184:187], v[192:195], v[104:107]
	v_mfma_f32_16x16x32_bf16 v[100:103], v[176:179], v[204:207], v[100:103]
	v_mfma_f32_16x16x32_bf16 v[92:95], v[184:187], v[204:207], v[92:95]
	v_mfma_f32_16x16x32_bf16 v[84:87], v[176:179], v[212:215], v[84:87]
	v_mfma_f32_16x16x32_bf16 v[76:79], v[184:187], v[212:215], v[76:79]
	v_mfma_f32_16x16x32_bf16 v[68:71], v[176:179], v[220:223], v[68:71]
	v_mfma_f32_16x16x32_bf16 v[64:67], v[184:187], v[220:223], v[64:67]
	s_setprio 0
	s_barrier
; #define PG8_STAGE(bufoff, gbase, voff) do { _Pragma("unroll") for (int _i = 0; _i < 2; ++_i) \
;         __builtin_amdgcn_global_load_lds((const unsigned*)((const char*)(gbase) + (voff)[_i]), (PG8_LAS unsigned*)(lds + (bufoff) + ldsw + _i * 8192), 16, 0, 0); } while (0)
; #define PG8_LDA(dst, b, h) do { _Pragma("unroll") for (int m = 0; m < 4; ++m) _Pragma("unroll") for (int k = 0; k < 2; ++k) dst[m][k] = *(const PG8_LAS bf16x8*)(lds + PG8_SA(b, h) + aoff + m * 2048 + k * 1024); } while (0)
; #define PG8_MMA(ai, bj, At, Bt) do { __builtin_amdgcn_s_setprio(1); _Pragma("unroll") for (int m = 0; m < 4; ++m) _Pragma("unroll") for (int n = 0; n < 2; ++n) _Pragma("unroll") for (int k = 0; k < 2; ++k) \
;         acc[ai][bj][m][n] = __builtin_amdgcn_mfma_f32_16x16x32_bf16(Bt[n][k], At[m][k], acc[ai][bj][m][n], 0, 0, 0); __builtin_amdgcn_s_setprio(0); } while (0)
; #define PG8_WAIT_V(n) asm volatile("s_waitcnt vmcnt(" #n ")" ::: "memory")
; #define PG8_WAIT_L(n) asm volatile("s_waitcnt lgkmcnt(" #n ")" ::: "memory")
; #define PG8_BAR __builtin_amdgcn_s_barrier()
; #define PG8_SCHED __builtin_amdgcn_sched_barrier(0)
; template <class Epi, class Sched>
; __device__ __forceinline__ void gemm_phase(PG8_LAS unsigned char* lds, const Gemm g, const Sched& S, const Epi& E) {
;     ...
;             PG8_LDA(At, 1, 1); PG8_STAGE(PG8_SB(1, 0), b3, voffB); PG8_STAGE(PG8_SB(1, 1), b3 + hstepB, voffB); PG8_STAGE(PG8_SA(1, 0), a3, voffA);
;             PG8_WAIT_V(8); PG8_WAIT_L(0); PG8_BAR; PG8_MMA(1, 0, At, B0); PG8_MMA(1, 1, At, B1); PG8_BAR; PG8_SCHED;
;         }
	s_add_i32 s28, s48, s31
	v_lshl_add_u64 v[196:197], v[196:197], 0, s[2:3]
	s_mov_b32 m0, s28
	ds_read_b128 v[188:191], v171 offset:49152
	ds_read_b128 v[192:195], v171 offset:50176
	ds_read_b128 v[200:203], v171 offset:51200
	ds_read_b128 v[204:207], v171 offset:52224
	ds_read_b128 v[208:211], v171 offset:53248
	ds_read_b128 v[212:215], v171 offset:54272
	ds_read_b128 v[216:219], v171 offset:55296
	ds_read_b128 v[220:223], v171 offset:56320
	global_load_lds_dwordx4 v[196:197], off
	s_add_i32 m0, s28, 0x2000
	s_add_u32 s26, s26, 0x40080
	v_lshl_add_u64 v[196:197], v[224:225], 0, s[2:3]
	s_addc_u32 s27, s27, 0
	s_add_i32 s28, s49, s31
	global_load_lds_dwordx4 v[196:197], off
	v_lshl_add_u64 v[196:197], s[26:27], 0, v[146:147]
	s_mov_b32 m0, s28
	s_nop 0
	global_load_lds_dwordx4 v[196:197], off
	v_lshl_add_u64 v[196:197], s[26:27], 0, v[150:151]
	s_add_i32 m0, s28, 0x2000
	s_nop 0
	global_load_lds_dwordx4 v[196:197], off
	v_lshl_add_u64 v[196:197], v[226:227], 0, s[2:3]
	s_mov_b32 m0, s38
	s_nop 0
	global_load_lds_dwordx4 v[196:197], off
	v_lshl_add_u64 v[196:197], v[228:229], 0, s[2:3]
	s_mov_b32 m0, s39
	s_nop 0
	global_load_lds_dwordx4 v[196:197], off
	s_waitcnt vmcnt(8)
	s_waitcnt lgkmcnt(0)
	s_barrier
	s_setprio 1
	s_waitcnt lgkmcnt(0)
	v_mfma_f32_16x16x32_bf16 v[60:63], v[128:131], v[188:191], v[60:63]
	v_mfma_f32_16x16x32_bf16 v[56:59], v[136:139], v[188:191], v[56:59]
	v_mfma_f32_16x16x32_bf16 v[48:51], v[128:131], v[200:203], v[48:51]
	v_mfma_f32_16x16x32_bf16 v[40:43], v[136:139], v[200:203], v[40:43]
	v_mfma_f32_16x16x32_bf16 v[32:35], v[128:131], v[208:211], v[32:35]
	v_mfma_f32_16x16x32_bf16 v[24:27], v[136:139], v[208:211], v[24:27]
	v_mfma_f32_16x16x32_bf16 v[16:19], v[128:131], v[216:219], v[16:19]
	v_mfma_f32_16x16x32_bf16 v[8:11], v[136:139], v[216:219], v[8:11]
	v_mfma_f32_16x16x32_bf16 v[60:63], v[132:135], v[192:195], v[60:63]
	v_mfma_f32_16x16x32_bf16 v[56:59], v[140:143], v[192:195], v[56:59]
	v_mfma_f32_16x16x32_bf16 v[48:51], v[132:135], v[204:207], v[48:51]
	v_mfma_f32_16x16x32_bf16 v[40:43], v[140:143], v[204:207], v[40:43]
	v_mfma_f32_16x16x32_bf16 v[32:35], v[132:135], v[212:215], v[32:35]
	v_mfma_f32_16x16x32_bf16 v[24:27], v[140:143], v[212:215], v[24:27]
	v_mfma_f32_16x16x32_bf16 v[16:19], v[132:135], v[220:223], v[16:19]
	v_mfma_f32_16x16x32_bf16 v[8:11], v[140:143], v[220:223], v[8:11]
	v_mfma_f32_16x16x32_bf16 v[52:55], v[172:175], v[188:191], v[52:55]
	v_mfma_f32_16x16x32_bf16 v[44:47], v[180:183], v[188:191], v[44:47]
	v_mfma_f32_16x16x32_bf16 v[36:39], v[172:175], v[200:203], v[36:39]
	v_mfma_f32_16x16x32_bf16 v[28:31], v[180:183], v[200:203], v[28:31]
	v_mfma_f32_16x16x32_bf16 v[20:23], v[172:175], v[208:211], v[20:23]
	v_mfma_f32_16x16x32_bf16 v[12:15], v[180:183], v[208:211], v[12:15]
	v_mfma_f32_16x16x32_bf16 v[4:7], v[172:175], v[216:219], v[4:7]
	v_mfma_f32_16x16x32_bf16 v[0:3], v[180:183], v[216:219], v[0:3]
	v_mfma_f32_16x16x32_bf16 v[52:55], v[176:179], v[192:195], v[52:55]
	v_mfma_f32_16x16x32_bf16 v[44:47], v[184:187], v[192:195], v[44:47]
	v_mfma_f32_16x16x32_bf16 v[36:39], v[176:179], v[204:207], v[36:39]
	v_mfma_f32_16x16x32_bf16 v[28:31], v[184:187], v[204:207], v[28:31]
	v_mfma_f32_16x16x32_bf16 v[20:23], v[176:179], v[212:215], v[20:23]
	v_mfma_f32_16x16x32_bf16 v[12:15], v[184:187], v[212:215], v[12:15]
	v_mfma_f32_16x16x32_bf16 v[4:7], v[176:179], v[220:223], v[4:7]
	v_mfma_f32_16x16x32_bf16 v[0:3], v[184:187], v[220:223], v[0:3]
	s_setprio 0
	s_barrier
	s_add_i32 s47, s47, 2
	s_add_u32 s24, s24, 0x100
	s_addc_u32 s25, s25, 0
	s_cmp_gt_u32 s47, 13
	s_cbranch_scc1 .LBB0_2812

; #define PG8_STAGE(bufoff, gbase, voff) do { _Pragma("unroll") for (int _i = 0; _i < 2; ++_i) \
;         __builtin_amdgcn_global_load_lds((const unsigned*)((const char*)(gbase) + (voff)[_i]), (PG8_LAS unsigned*)(lds + (bufoff) + ldsw + _i * 8192), 16, 0, 0); } while (0)
; #define PG8_LDA(dst, b, h) do { _Pragma("unroll") for (int m = 0; m < 4; ++m) _Pragma("unroll") for (int k = 0; k < 2; ++k) dst[m][k] = *(const PG8_LAS bf16x8*)(lds + PG8_SA(b, h) + aoff + m * 2048 + k * 1024); } while (0)
; #define PG8_LDB(dst, b, h) do { _Pragma("unroll") for (int n = 0; n < 2; ++n) _Pragma("unroll") for (int k = 0; k < 2; ++k) dst[n][k] = *(const PG8_LAS bf16x8*)(lds + PG8_SB(b, h) + boff + n * 2048 + k * 1024); } while (0)
; #define PG8_MMA(ai, bj, At, Bt) do { __builtin_amdgcn_s_setprio(1); _Pragma("unroll") for (int m = 0; m < 4; ++m) _Pragma("unroll") for (int n = 0; n < 2; ++n) _Pragma("unroll") for (int k = 0; k < 2; ++k) \
;         acc[ai][bj][m][n] = __builtin_amdgcn_mfma_f32_16x16x32_bf16(Bt[n][k], At[m][k], acc[ai][bj][m][n], 0, 0, 0); __builtin_amdgcn_s_setprio(0); } while (0)
; #define PG8_WAIT_V(n) asm volatile("s_waitcnt vmcnt(" #n ")" ::: "memory")
; #define PG8_WAIT_L(n) asm volatile("s_waitcnt lgkmcnt(" #n ")" ::: "memory")
; template <class Epi, class Sched>
; __device__ __forceinline__ void gemm_phase(PG8_LAS unsigned char* lds, const Gemm g, const Sched& S, const Epi& E) {
;     ...
;         for (int t = 0; t < nt; t += 2) {
;             const bool last = (t == nt - 2);
;             const char* a1 = cA + (size_t)(t + 1) * kstepA;
;             const char* a2 = last ? nA : cA + (size_t)(t + 2) * kstepA; const char* b2 = last ? nB : cB + (size_t)(t + 2) * kstep;
;             const char* a3 = a2 + kstepA; const char* b3 = b2 + kstep;
;             if constexpr (epi_has_hook<Epi>::value) { if (t == nt / 2) E.hook(acc, cur, wr, wc, fr, fq); }
;             PG8_LDB(B0, 0, 0); PG8_LDB(B1, 0, 1); PG8_SCHED; PG8_LDA(At, 0, 0); PG8_STAGE(PG8_SA(1, 1), a1 + hstepA, voffA);
;             PG8_WAIT_V(8); PG8_WAIT_L(0); PG8_BAR; PG8_MMA(0, 0, At, B0); PG8_MMA(0, 1, At, B1); PG8_BAR; PG8_SCHED;
;             PG8_LDA(At, 0, 1); PG8_STAGE(PG8_SB(0, 0), b2, voffB); PG8_STAGE(PG8_SB(0, 1), b2 + hstepB, voffB); PG8_STAGE(PG8_SA(0, 0), a2, voffA);
;             PG8_WAIT_V(8); PG8_WAIT_L(0); PG8_BAR; PG8_MMA(1, 0, At, B0); PG8_MMA(1, 1, At, B1); PG8_BAR; PG8_SCHED;
.LBB0_2890:
	ds_read_b128 v[128:131], v165
	ds_read_b128 v[132:135], v165 offset:1024
	ds_read_b128 v[152:155], v165 offset:2048
	ds_read_b128 v[156:159], v165 offset:3072
	ds_read_b128 v[170:173], v166
	ds_read_b128 v[174:177], v166 offset:1024
	ds_read_b128 v[178:181], v166 offset:2048
	ds_read_b128 v[182:185], v166 offset:3072
	s_add_u32 s28, s26, 0xfffc0080
	s_addc_u32 s29, s27, -1
	s_cmp_eq_u32 s52, 12
	s_cselect_b32 s31, s15, s29
	s_cselect_b32 s30, s17, s28
	s_cselect_b32 s29, s48, s51
	s_cselect_b32 s28, s49, s50
	v_lshl_add_u64 v[160:161], s[26:27], 0, v[144:145]
	s_add_i32 m0, s34, 0xc000
	ds_read_b128 v[186:189], v167
	ds_read_b128 v[190:193], v167 offset:1024
	ds_read_b128 v[194:197], v167 offset:2048
	ds_read_b128 v[200:203], v167 offset:3072
	ds_read_b128 v[204:207], v167 offset:4096
	ds_read_b128 v[208:211], v167 offset:5120
	ds_read_b128 v[212:215], v167 offset:6144
	ds_read_b128 v[216:219], v167 offset:7168
	global_load_lds_dwordx4 v[160:161], off
	v_lshl_add_u64 v[160:161], s[26:27], 0, v[146:147]
	s_add_i32 m0, s34, 0xe000
	s_nop 0
	global_load_lds_dwordx4 v[160:161], off
	s_waitcnt vmcnt(8)
	s_waitcnt lgkmcnt(0)
	s_barrier
	s_setprio 1
	s_waitcnt lgkmcnt(0)
	v_mfma_f32_16x16x32_bf16 v[124:127], v[128:131], v[186:189], v[124:127]
	v_mfma_f32_16x16x32_bf16 v[120:123], v[152:155], v[186:189], v[120:123]
	v_mfma_f32_16x16x32_bf16 v[108:111], v[128:131], v[194:197], v[108:111]
	v_mfma_f32_16x16x32_bf16 v[104:107], v[152:155], v[194:197], v[104:107]
	v_mfma_f32_16x16x32_bf16 v[92:95], v[128:131], v[204:207], v[92:95]
	v_mfma_f32_16x16x32_bf16 v[88:91], v[152:155], v[204:207], v[88:91]
	v_mfma_f32_16x16x32_bf16 v[76:79], v[128:131], v[212:215], v[76:79]
	v_mfma_f32_16x16x32_bf16 v[72:75], v[152:155], v[212:215], v[72:75]
	v_mfma_f32_16x16x32_bf16 v[124:127], v[132:135], v[190:193], v[124:127]
	v_mfma_f32_16x16x32_bf16 v[120:123], v[156:159], v[190:193], v[120:123]
	v_mfma_f32_16x16x32_bf16 v[108:111], v[132:135], v[200:203], v[108:111]
	v_mfma_f32_16x16x32_bf16 v[104:107], v[156:159], v[200:203], v[104:107]
	v_mfma_f32_16x16x32_bf16 v[92:95], v[132:135], v[208:211], v[92:95]
	v_mfma_f32_16x16x32_bf16 v[88:91], v[156:159], v[208:211], v[88:91]
	v_mfma_f32_16x16x32_bf16 v[76:79], v[132:135], v[216:219], v[76:79]
	v_mfma_f32_16x16x32_bf16 v[72:75], v[156:159], v[216:219], v[72:75]
	v_mfma_f32_16x16x32_bf16 v[116:119], v[170:173], v[186:189], v[116:119]
	v_mfma_f32_16x16x32_bf16 v[112:115], v[178:181], v[186:189], v[112:115]
	v_mfma_f32_16x16x32_bf16 v[100:103], v[170:173], v[194:197], v[100:103]
	v_mfma_f32_16x16x32_bf16 v[96:99], v[178:181], v[194:197], v[96:99]
	v_mfma_f32_16x16x32_bf16 v[84:87], v[170:173], v[204:207], v[84:87]
	v_mfma_f32_16x16x32_bf16 v[80:83], v[178:181], v[204:207], v[80:83]
	v_mfma_f32_16x16x32_bf16 v[68:71], v[170:173], v[212:215], v[68:71]
	v_mfma_f32_16x16x32_bf16 v[64:67], v[178:181], v[212:215], v[64:67]
	v_mfma_f32_16x16x32_bf16 v[116:119], v[174:177], v[190:193], v[116:119]
	v_mfma_f32_16x16x32_bf16 v[112:115], v[182:185], v[190:193], v[112:115]
	v_mfma_f32_16x16x32_bf16 v[100:103], v[174:177], v[200:203], v[100:103]
	v_mfma_f32_16x16x32_bf16 v[96:99], v[182:185], v[200:203], v[96:99]
	v_mfma_f32_16x16x32_bf16 v[84:87], v[174:177], v[208:211], v[84:87]
	v_mfma_f32_16x16x32_bf16 v[80:83], v[182:185], v[208:211], v[80:83]
	v_mfma_f32_16x16x32_bf16 v[68:71], v[174:177], v[216:219], v[68:71]
	v_mfma_f32_16x16x32_bf16 v[64:67], v[182:185], v[216:219], v[64:67]
	s_setprio 0
	s_barrier
	s_add_i32 s53, s44, s33
	v_lshl_add_u64 v[160:161], s[28:29], 0, v[138:139]
	s_mov_b32 m0, s53
	ds_read_b128 v[186:189], v167 offset:16384
	ds_read_b128 v[190:193], v167 offset:17408
	ds_read_b128 v[194:197], v167 offset:18432
	ds_read_b128 v[200:203], v167 offset:19456
	ds_read_b128 v[204:207], v167 offset:20480
	ds_read_b128 v[208:211], v167 offset:21504
	ds_read_b128 v[212:215], v167 offset:22528
	ds_read_b128 v[216:219], v167 offset:23552
	global_load_lds_dwordx4 v[160:161], off
	s_add_i32 m0, s53, 0x2000
	s_add_u32 s54, s28, 0x40000
	v_lshl_add_u64 v[220:221], s[28:29], 0, v[142:143]
	s_addc_u32 s55, s29, 0
	s_add_i32 s53, s45, s33
	global_load_lds_dwordx4 v[220:221], off
	v_lshl_add_u64 v[222:223], s[54:55], 0, v[138:139]
	s_mov_b32 m0, s53
	v_lshl_add_u64 v[224:225], s[30:31], 0, v[140:141]
	global_load_lds_dwordx4 v[222:223], off
	v_lshl_add_u64 v[222:223], s[54:55], 0, v[142:143]
	s_add_i32 m0, s53, 0x2000
	s_nop 0
	global_load_lds_dwordx4 v[222:223], off
	v_lshl_add_u64 v[222:223], s[30:31], 0, v[136:137]
	s_mov_b32 m0, s34
	s_nop 0
	global_load_lds_dwordx4 v[222:223], off
	s_mov_b32 m0, s35
	s_nop 0
	global_load_lds_dwordx4 v[224:225], off
	s_waitcnt vmcnt(8)
	s_waitcnt lgkmcnt(0)
	s_barrier
; #define PG8_STAGE(bufoff, gbase, voff) do { _Pragma("unroll") for (int _i = 0; _i < 2; ++_i) \
;         __builtin_amdgcn_global_load_lds((const unsigned*)((const char*)(gbase) + (voff)[_i]), (PG8_LAS unsigned*)(lds + (bufoff) + ldsw + _i * 8192), 16, 0, 0); } while (0)
; #define PG8_LDA(dst, b, h) do { _Pragma("unroll") for (int m = 0; m < 4; ++m) _Pragma("unroll") for (int k = 0; k < 2; ++k) dst[m][k] = *(const PG8_LAS bf16x8*)(lds + PG8_SA(b, h) + aoff + m * 2048 + k * 1024); } while (0)
; #define PG8_LDB(dst, b, h) do { _Pragma("unroll") for (int n = 0; n < 2; ++n) _Pragma("unroll") for (int k = 0; k < 2; ++k) dst[n][k] = *(const PG8_LAS bf16x8*)(lds + PG8_SB(b, h) + boff + n * 2048 + k * 1024); } while (0)
; #define PG8_MMA(ai, bj, At, Bt) do { __builtin_amdgcn_s_setprio(1); _Pragma("unroll") for (int m = 0; m < 4; ++m) _Pragma("unroll") for (int n = 0; n < 2; ++n) _Pragma("unroll") for (int k = 0; k < 2; ++k) \
;         acc[ai][bj][m][n] = __builtin_amdgcn_mfma_f32_16x16x32_bf16(Bt[n][k], At[m][k], acc[ai][bj][m][n], 0, 0, 0); __builtin_amdgcn_s_setprio(0); } while (0)
; #define PG8_WAIT_V(n) asm volatile("s_waitcnt vmcnt(" #n ")" ::: "memory")
; #define PG8_WAIT_L(n) asm volatile("s_waitcnt lgkmcnt(" #n ")" ::: "memory")
; #define PG8_BAR __builtin_amdgcn_s_barrier()
; #define PG8_SCHED __builtin_amdgcn_sched_barrier(0)
; template <class Epi, class Sched>
; __device__ __forceinline__ void gemm_phase(PG8_LAS unsigned char* lds, const Gemm g, const Sched& S, const Epi& E) {
;     ...
;             PG8_WAIT_V(8); PG8_WAIT_L(0); PG8_BAR; PG8_MMA(1, 0, At, B0); PG8_MMA(1, 1, At, B1); PG8_BAR; PG8_SCHED;
;             PG8_LDB(B0, 1, 0); PG8_LDB(B1, 1, 1); PG8_SCHED; PG8_LDA(At, 1, 0); PG8_STAGE(PG8_SA(0, 1), a2 + hstepA, voffA);
;             PG8_WAIT_V(8); PG8_WAIT_L(0); PG8_BAR; PG8_MMA(0, 0, At, B0); PG8_MMA(0, 1, At, B1); PG8_BAR; PG8_SCHED;
	s_setprio 1
	s_waitcnt lgkmcnt(0)
	v_mfma_f32_16x16x32_bf16 v[60:63], v[128:131], v[186:189], v[60:63]
	v_mfma_f32_16x16x32_bf16 v[56:59], v[152:155], v[186:189], v[56:59]
	v_mfma_f32_16x16x32_bf16 v[44:47], v[128:131], v[194:197], v[44:47]
	v_mfma_f32_16x16x32_bf16 v[40:43], v[152:155], v[194:197], v[40:43]
	v_mfma_f32_16x16x32_bf16 v[28:31], v[128:131], v[204:207], v[28:31]
	v_mfma_f32_16x16x32_bf16 v[24:27], v[152:155], v[204:207], v[24:27]
	v_mfma_f32_16x16x32_bf16 v[12:15], v[128:131], v[212:215], v[12:15]
	v_mfma_f32_16x16x32_bf16 v[8:11], v[152:155], v[212:215], v[8:11]
	v_mfma_f32_16x16x32_bf16 v[60:63], v[132:135], v[190:193], v[60:63]
	v_mfma_f32_16x16x32_bf16 v[56:59], v[156:159], v[190:193], v[56:59]
	v_mfma_f32_16x16x32_bf16 v[44:47], v[132:135], v[200:203], v[44:47]
	v_mfma_f32_16x16x32_bf16 v[40:43], v[156:159], v[200:203], v[40:43]
	v_mfma_f32_16x16x32_bf16 v[28:31], v[132:135], v[208:211], v[28:31]
	v_mfma_f32_16x16x32_bf16 v[24:27], v[156:159], v[208:211], v[24:27]
	v_mfma_f32_16x16x32_bf16 v[12:15], v[132:135], v[216:219], v[12:15]
	v_mfma_f32_16x16x32_bf16 v[8:11], v[156:159], v[216:219], v[8:11]
	v_mfma_f32_16x16x32_bf16 v[52:55], v[170:173], v[186:189], v[52:55]
	v_mfma_f32_16x16x32_bf16 v[48:51], v[178:181], v[186:189], v[48:51]
	v_mfma_f32_16x16x32_bf16 v[36:39], v[170:173], v[194:197], v[36:39]
	v_mfma_f32_16x16x32_bf16 v[32:35], v[178:181], v[194:197], v[32:35]
	v_mfma_f32_16x16x32_bf16 v[20:23], v[170:173], v[204:207], v[20:23]
	v_mfma_f32_16x16x32_bf16 v[16:19], v[178:181], v[204:207], v[16:19]
	v_mfma_f32_16x16x32_bf16 v[4:7], v[170:173], v[212:215], v[4:7]
	v_mfma_f32_16x16x32_bf16 v[0:3], v[178:181], v[212:215], v[0:3]
	v_mfma_f32_16x16x32_bf16 v[52:55], v[174:177], v[190:193], v[52:55]
	v_mfma_f32_16x16x32_bf16 v[48:51], v[182:185], v[190:193], v[48:51]
	v_mfma_f32_16x16x32_bf16 v[36:39], v[174:177], v[200:203], v[36:39]
	v_mfma_f32_16x16x32_bf16 v[32:35], v[182:185], v[200:203], v[32:35]
	v_mfma_f32_16x16x32_bf16 v[20:23], v[174:177], v[208:211], v[20:23]
	v_mfma_f32_16x16x32_bf16 v[16:19], v[182:185], v[208:211], v[16:19]
	v_mfma_f32_16x16x32_bf16 v[4:7], v[174:177], v[216:219], v[4:7]
	v_mfma_f32_16x16x32_bf16 v[0:3], v[182:185], v[216:219], v[0:3]
	s_setprio 0
	s_barrier
	s_add_i32 s53, 0, 0x18000
	s_add_i32 s54, 0, 0x1c000
	v_add_u32_e32 v156, s53, v163
	v_add_u32_e32 v169, s54, v163
	ds_read_b128 v[128:131], v156
	ds_read_b128 v[132:135], v156 offset:1024
	ds_read_b128 v[152:155], v156 offset:2048
	ds_read_b128 v[156:159], v156 offset:3072
	ds_read_b128 v[170:173], v169
	ds_read_b128 v[174:177], v169 offset:1024
	ds_read_b128 v[178:181], v169 offset:2048
	ds_read_b128 v[182:185], v169 offset:3072
	s_add_u32 s30, s30, 0x40000
	s_addc_u32 s31, s31, 0
	s_mov_b32 m0, s36
	v_lshl_add_u64 v[226:227], s[30:31], 0, v[136:137]
	ds_read_b128 v[186:189], v167 offset:32768
	ds_read_b128 v[190:193], v167 offset:33792
	ds_read_b128 v[194:197], v167 offset:34816
	ds_read_b128 v[200:203], v167 offset:35840
	ds_read_b128 v[204:207], v167 offset:36864
	ds_read_b128 v[208:211], v167 offset:37888
	ds_read_b128 v[212:215], v167 offset:38912
	ds_read_b128 v[216:219], v167 offset:39936
	global_load_lds_dwordx4 v[226:227], off
	v_lshl_add_u64 v[226:227], s[30:31], 0, v[140:141]
	s_mov_b32 m0, s37
	s_nop 0
	global_load_lds_dwordx4 v[226:227], off
	s_waitcnt vmcnt(8)
	s_waitcnt lgkmcnt(0)
	s_barrier
	s_setprio 1
	s_waitcnt lgkmcnt(0)
	v_mfma_f32_16x16x32_bf16 v[124:127], v[128:131], v[186:189], v[124:127]
	v_mfma_f32_16x16x32_bf16 v[120:123], v[152:155], v[186:189], v[120:123]
	v_mfma_f32_16x16x32_bf16 v[108:111], v[128:131], v[194:197], v[108:111]
	v_mfma_f32_16x16x32_bf16 v[104:107], v[152:155], v[194:197], v[104:107]
	v_mfma_f32_16x16x32_bf16 v[92:95], v[128:131], v[204:207], v[92:95]
	v_mfma_f32_16x16x32_bf16 v[88:91], v[152:155], v[204:207], v[88:91]
	v_mfma_f32_16x16x32_bf16 v[76:79], v[128:131], v[212:215], v[76:79]
	v_mfma_f32_16x16x32_bf16 v[72:75], v[152:155], v[212:215], v[72:75]
	v_mfma_f32_16x16x32_bf16 v[124:127], v[132:135], v[190:193], v[124:127]
	v_mfma_f32_16x16x32_bf16 v[120:123], v[156:159], v[190:193], v[120:123]
	v_mfma_f32_16x16x32_bf16 v[108:111], v[132:135], v[200:203], v[108:111]
	v_mfma_f32_16x16x32_bf16 v[104:107], v[156:159], v[200:203], v[104:107]
	v_mfma_f32_16x16x32_bf16 v[92:95], v[132:135], v[208:211], v[92:95]
	v_mfma_f32_16x16x32_bf16 v[88:91], v[156:159], v[208:211], v[88:91]
	v_mfma_f32_16x16x32_bf16 v[76:79], v[132:135], v[216:219], v[76:79]
	v_mfma_f32_16x16x32_bf16 v[72:75], v[156:159], v[216:219], v[72:75]
	v_mfma_f32_16x16x32_bf16 v[116:119], v[170:173], v[186:189], v[116:119]
	v_mfma_f32_16x16x32_bf16 v[112:115], v[178:181], v[186:189], v[112:115]
	v_mfma_f32_16x16x32_bf16 v[100:103], v[170:173], v[194:197], v[100:103]
	v_mfma_f32_16x16x32_bf16 v[96:99], v[178:181], v[194:197], v[96:99]
	v_mfma_f32_16x16x32_bf16 v[84:87], v[170:173], v[204:207], v[84:87]
	v_mfma_f32_16x16x32_bf16 v[80:83], v[178:181], v[204:207], v[80:83]
	v_mfma_f32_16x16x32_bf16 v[68:71], v[170:173], v[212:215], v[68:71]
	v_mfma_f32_16x16x32_bf16 v[64:67], v[178:181], v[212:215], v[64:67]
	v_mfma_f32_16x16x32_bf16 v[116:119], v[174:177], v[190:193], v[116:119]
	v_mfma_f32_16x16x32_bf16 v[112:115], v[182:185], v[190:193], v[112:115]
	v_mfma_f32_16x16x32_bf16 v[100:103], v[174:177], v[200:203], v[100:103]
	v_mfma_f32_16x16x32_bf16 v[96:99], v[182:185], v[200:203], v[96:99]
	v_mfma_f32_16x16x32_bf16 v[84:87], v[174:177], v[208:211], v[84:87]
	v_mfma_f32_16x16x32_bf16 v[80:83], v[182:185], v[208:211], v[80:83]
	v_mfma_f32_16x16x32_bf16 v[68:71], v[174:177], v[216:219], v[68:71]
	v_mfma_f32_16x16x32_bf16 v[64:67], v[182:185], v[216:219], v[64:67]
	s_setprio 0
	s_barrier
; #define PG8_STAGE(bufoff, gbase, voff) do { _Pragma("unroll") for (int _i = 0; _i < 2; ++_i) \
;         __builtin_amdgcn_global_load_lds((const unsigned*)((const char*)(gbase) + (voff)[_i]), (PG8_LAS unsigned*)(lds + (bufoff) + ldsw + _i * 8192), 16, 0, 0); } while (0)
; #define PG8_LDA(dst, b, h) do { _Pragma("unroll") for (int m = 0; m < 4; ++m) _Pragma("unroll") for (int k = 0; k < 2; ++k) dst[m][k] = *(const PG8_LAS bf16x8*)(lds + PG8_SA(b, h) + aoff + m * 2048 + k * 1024); } while (0)
; #define PG8_MMA(ai, bj, At, Bt) do { __builtin_amdgcn_s_setprio(1); _Pragma("unroll") for (int m = 0; m < 4; ++m) _Pragma("unroll") for (int n = 0; n < 2; ++n) _Pragma("unroll") for (int k = 0; k < 2; ++k) \
;         acc[ai][bj][m][n] = __builtin_amdgcn_mfma_f32_16x16x32_bf16(Bt[n][k], At[m][k], acc[ai][bj][m][n], 0, 0, 0); __builtin_amdgcn_s_setprio(0); } while (0)
; #define PG8_WAIT_V(n) asm volatile("s_waitcnt vmcnt(" #n ")" ::: "memory")
; #define PG8_WAIT_L(n) asm volatile("s_waitcnt lgkmcnt(" #n ")" ::: "memory")
; #define PG8_BAR __builtin_amdgcn_s_barrier()
; #define PG8_SCHED __builtin_amdgcn_sched_barrier(0)
; template <class Epi, class Sched>
; __device__ __forceinline__ void gemm_phase(PG8_LAS unsigned char* lds, const Gemm g, const Sched& S, const Epi& E) {
;     ...
;             PG8_LDA(At, 1, 1); PG8_STAGE(PG8_SB(1, 0), b3, voffB); PG8_STAGE(PG8_SB(1, 1), b3 + hstepB, voffB); PG8_STAGE(PG8_SA(1, 0), a3, voffA);
;             PG8_WAIT_V(8); PG8_WAIT_L(0); PG8_BAR; PG8_MMA(1, 0, At, B0); PG8_MMA(1, 1, At, B1); PG8_BAR; PG8_SCHED;
;         }
;         if (wr == 0) PG8_BAR;
	s_add_i32 s30, s53, s33
	v_lshl_add_u64 v[160:161], v[160:161], 0, s[6:7]
	s_mov_b32 m0, s30
	ds_read_b128 v[186:189], v167 offset:49152
	ds_read_b128 v[190:193], v167 offset:50176
	ds_read_b128 v[194:197], v167 offset:51200
	ds_read_b128 v[200:203], v167 offset:52224
	ds_read_b128 v[204:207], v167 offset:53248
	ds_read_b128 v[208:211], v167 offset:54272
	ds_read_b128 v[212:215], v167 offset:55296
	ds_read_b128 v[216:219], v167 offset:56320
	global_load_lds_dwordx4 v[160:161], off
	s_add_i32 m0, s30, 0x2000
	s_add_u32 s28, s28, 0x40080
	v_lshl_add_u64 v[160:161], v[220:221], 0, s[6:7]
	s_addc_u32 s29, s29, 0
	s_add_i32 s30, s54, s33
	global_load_lds_dwordx4 v[160:161], off
	v_lshl_add_u64 v[160:161], s[28:29], 0, v[138:139]
	s_mov_b32 m0, s30
	s_nop 0
	global_load_lds_dwordx4 v[160:161], off
	v_lshl_add_u64 v[160:161], s[28:29], 0, v[142:143]
	s_add_i32 m0, s30, 0x2000
	s_nop 0
	global_load_lds_dwordx4 v[160:161], off
	v_lshl_add_u64 v[160:161], v[222:223], 0, s[6:7]
	s_mov_b32 m0, s39
	s_nop 0
	global_load_lds_dwordx4 v[160:161], off
	v_lshl_add_u64 v[160:161], v[224:225], 0, s[6:7]
	s_mov_b32 m0, s40
	s_nop 0
	global_load_lds_dwordx4 v[160:161], off
	s_waitcnt vmcnt(8)
	s_waitcnt lgkmcnt(0)
	s_barrier
	s_setprio 1
	s_waitcnt lgkmcnt(0)
	v_mfma_f32_16x16x32_bf16 v[60:63], v[128:131], v[186:189], v[60:63]
	v_mfma_f32_16x16x32_bf16 v[56:59], v[152:155], v[186:189], v[56:59]
	v_mfma_f32_16x16x32_bf16 v[44:47], v[128:131], v[194:197], v[44:47]
	v_mfma_f32_16x16x32_bf16 v[40:43], v[152:155], v[194:197], v[40:43]
	v_mfma_f32_16x16x32_bf16 v[28:31], v[128:131], v[204:207], v[28:31]
	v_mfma_f32_16x16x32_bf16 v[24:27], v[152:155], v[204:207], v[24:27]
	v_mfma_f32_16x16x32_bf16 v[12:15], v[128:131], v[212:215], v[12:15]
	v_mfma_f32_16x16x32_bf16 v[8:11], v[152:155], v[212:215], v[8:11]
	v_mfma_f32_16x16x32_bf16 v[60:63], v[132:135], v[190:193], v[60:63]
	v_mfma_f32_16x16x32_bf16 v[56:59], v[156:159], v[190:193], v[56:59]
	v_mfma_f32_16x16x32_bf16 v[44:47], v[132:135], v[200:203], v[44:47]
	v_mfma_f32_16x16x32_bf16 v[40:43], v[156:159], v[200:203], v[40:43]
	v_mfma_f32_16x16x32_bf16 v[28:31], v[132:135], v[208:211], v[28:31]
	v_mfma_f32_16x16x32_bf16 v[24:27], v[156:159], v[208:211], v[24:27]
	v_mfma_f32_16x16x32_bf16 v[12:15], v[132:135], v[216:219], v[12:15]
	v_mfma_f32_16x16x32_bf16 v[8:11], v[156:159], v[216:219], v[8:11]
	v_mfma_f32_16x16x32_bf16 v[52:55], v[170:173], v[186:189], v[52:55]
	v_mfma_f32_16x16x32_bf16 v[48:51], v[178:181], v[186:189], v[48:51]
	v_mfma_f32_16x16x32_bf16 v[36:39], v[170:173], v[194:197], v[36:39]
	v_mfma_f32_16x16x32_bf16 v[32:35], v[178:181], v[194:197], v[32:35]
	v_mfma_f32_16x16x32_bf16 v[20:23], v[170:173], v[204:207], v[20:23]
	v_mfma_f32_16x16x32_bf16 v[16:19], v[178:181], v[204:207], v[16:19]
	v_mfma_f32_16x16x32_bf16 v[4:7], v[170:173], v[212:215], v[4:7]
	v_mfma_f32_16x16x32_bf16 v[0:3], v[178:181], v[212:215], v[0:3]
	v_mfma_f32_16x16x32_bf16 v[52:55], v[174:177], v[190:193], v[52:55]
	v_mfma_f32_16x16x32_bf16 v[48:51], v[182:185], v[190:193], v[48:51]
	v_mfma_f32_16x16x32_bf16 v[36:39], v[174:177], v[200:203], v[36:39]
	v_mfma_f32_16x16x32_bf16 v[32:35], v[182:185], v[200:203], v[32:35]
	v_mfma_f32_16x16x32_bf16 v[20:23], v[174:177], v[208:211], v[20:23]
	v_mfma_f32_16x16x32_bf16 v[16:19], v[182:185], v[208:211], v[16:19]
	v_mfma_f32_16x16x32_bf16 v[4:7], v[174:177], v[216:219], v[4:7]
	v_mfma_f32_16x16x32_bf16 v[0:3], v[182:185], v[216:219], v[0:3]
	s_setprio 0
	s_barrier
	s_add_i32 s52, s52, 2
	s_add_u32 s26, s26, 0x100
	s_addc_u32 s27, s27, 0
	s_add_u32 s50, s50, 0x100
	s_addc_u32 s51, s51, 0
	s_cmp_gt_u32 s52, 13
	s_cbranch_scc0 .LBB0_2890
	s_and_b64 vcc, exec, s[12:13]
	s_cbranch_vccz .LBB0_2893
	s_barrier

; #define PG8_STAGE(bufoff, gbase, voff) do { _Pragma("unroll") for (int _i = 0; _i < 2; ++_i) \
;         __builtin_amdgcn_global_load_lds((const unsigned*)((const char*)(gbase) + (voff)[_i]), (PG8_LAS unsigned*)(lds + (bufoff) + ldsw + _i * 8192), 16, 0, 0); } while (0)
; #define PG8_LDA(dst, b, h) do { _Pragma("unroll") for (int m = 0; m < 4; ++m) _Pragma("unroll") for (int k = 0; k < 2; ++k) dst[m][k] = *(const PG8_LAS bf16x8*)(lds + PG8_SA(b, h) + aoff + m * 2048 + k * 1024); } while (0)
; #define PG8_LDB(dst, b, h) do { _Pragma("unroll") for (int n = 0; n < 2; ++n) _Pragma("unroll") for (int k = 0; k < 2; ++k) dst[n][k] = *(const PG8_LAS bf16x8*)(lds + PG8_SB(b, h) + boff + n * 2048 + k * 1024); } while (0)
; #define PG8_MMA(ai, bj, At, Bt) do { __builtin_amdgcn_s_setprio(1); _Pragma("unroll") for (int m = 0; m < 4; ++m) _Pragma("unroll") for (int n = 0; n < 2; ++n) _Pragma("unroll") for (int k = 0; k < 2; ++k) \
;         acc[ai][bj][m][n] = __builtin_amdgcn_mfma_f32_16x16x32_bf16(Bt[n][k], At[m][k], acc[ai][bj][m][n], 0, 0, 0); __builtin_amdgcn_s_setprio(0); } while (0)
; #define PG8_WAIT_V(n) asm volatile("s_waitcnt vmcnt(" #n ")" ::: "memory")
; #define PG8_WAIT_L(n) asm volatile("s_waitcnt lgkmcnt(" #n ")" ::: "memory")
; template <class Epi, class Sched>
; __device__ __forceinline__ void gemm_phase(PG8_LAS unsigned char* lds, const Gemm g, const Sched& S, const Epi& E) {
;     ...
;         for (int t = 0; t < nt; t += 2) {
;             const bool last = (t == nt - 2);
;             const char* a1 = cA + (size_t)(t + 1) * kstepA;
;             const char* a2 = last ? nA : cA + (size_t)(t + 2) * kstepA; const char* b2 = last ? nB : cB + (size_t)(t + 2) * kstep;
;             const char* a3 = a2 + kstepA; const char* b3 = b2 + kstep;
;             if constexpr (epi_has_hook<Epi>::value) { if (t == nt / 2) E.hook(acc, cur, wr, wc, fr, fq); }
;             PG8_LDB(B0, 0, 0); PG8_LDB(B1, 0, 1); PG8_SCHED; PG8_LDA(At, 0, 0); PG8_STAGE(PG8_SA(1, 1), a1 + hstepA, voffA);
;             PG8_WAIT_V(8); PG8_WAIT_L(0); PG8_BAR; PG8_MMA(0, 0, At, B0); PG8_MMA(0, 1, At, B1); PG8_BAR; PG8_SCHED;
;             PG8_LDA(At, 0, 1); PG8_STAGE(PG8_SB(0, 0), b2, voffB); PG8_STAGE(PG8_SB(0, 1), b2 + hstepB, voffB); PG8_STAGE(PG8_SA(0, 0), a2, voffA);
;             PG8_WAIT_V(8); PG8_WAIT_L(0); PG8_BAR; PG8_MMA(1, 0, At, B0); PG8_MMA(1, 1, At, B1); PG8_BAR; PG8_SCHED;
.LBB0_2974:
	ds_read_b128 v[140:143], v159
	ds_read_b128 v[144:147], v159 offset:1024
	ds_read_b128 v[148:151], v159 offset:2048
	ds_read_b128 v[152:155], v159 offset:3072
	ds_read_b128 v[164:167], v160
	ds_read_b128 v[168:171], v160 offset:1024
	ds_read_b128 v[172:175], v160 offset:2048
	ds_read_b128 v[176:179], v160 offset:3072
	s_add_u32 s24, s22, 0xfffc0080
	s_addc_u32 s25, s23, -1
	s_cmp_eq_u32 s45, 12
	s_cselect_b32 s27, s11, s25
	s_cselect_b32 s26, s40, s24
	s_cselect_b32 s25, s41, s44
	s_cselect_b32 s24, s42, s43
	v_lshl_add_u64 v[196:197], s[22:23], 0, v[136:137]
	s_add_i32 m0, s21, 0xc000
	ds_read_b128 v[180:183], v161
	ds_read_b128 v[184:187], v161 offset:1024
	ds_read_b128 v[188:191], v161 offset:2048
	ds_read_b128 v[192:195], v161 offset:3072
	ds_read_b128 v[200:203], v161 offset:4096
	ds_read_b128 v[204:207], v161 offset:5120
	ds_read_b128 v[208:211], v161 offset:6144
	ds_read_b128 v[212:215], v161 offset:7168
	global_load_lds_dwordx4 v[196:197], off
	v_lshl_add_u64 v[196:197], s[22:23], 0, v[138:139]
	s_add_i32 m0, s21, 0xe000
	s_nop 0
	global_load_lds_dwordx4 v[196:197], off
	s_waitcnt vmcnt(8)
	s_waitcnt lgkmcnt(0)
	s_barrier
	s_setprio 1
	s_waitcnt lgkmcnt(0)
	v_mfma_f32_16x16x32_bf16 v[124:127], v[140:143], v[180:183], v[124:127]
	v_mfma_f32_16x16x32_bf16 v[120:123], v[148:151], v[180:183], v[120:123]
	v_mfma_f32_16x16x32_bf16 v[116:119], v[140:143], v[188:191], v[116:119]
	v_mfma_f32_16x16x32_bf16 v[108:111], v[148:151], v[188:191], v[108:111]
	v_mfma_f32_16x16x32_bf16 v[100:103], v[140:143], v[200:203], v[100:103]
	v_mfma_f32_16x16x32_bf16 v[92:95], v[148:151], v[200:203], v[92:95]
	v_mfma_f32_16x16x32_bf16 v[84:87], v[140:143], v[208:211], v[84:87]
	v_mfma_f32_16x16x32_bf16 v[76:79], v[148:151], v[208:211], v[76:79]
	v_mfma_f32_16x16x32_bf16 v[124:127], v[144:147], v[184:187], v[124:127]
	v_mfma_f32_16x16x32_bf16 v[120:123], v[152:155], v[184:187], v[120:123]
	v_mfma_f32_16x16x32_bf16 v[116:119], v[144:147], v[192:195], v[116:119]
	v_mfma_f32_16x16x32_bf16 v[108:111], v[152:155], v[192:195], v[108:111]
	v_mfma_f32_16x16x32_bf16 v[100:103], v[144:147], v[204:207], v[100:103]
	v_mfma_f32_16x16x32_bf16 v[92:95], v[152:155], v[204:207], v[92:95]
	v_mfma_f32_16x16x32_bf16 v[84:87], v[144:147], v[212:215], v[84:87]
	v_mfma_f32_16x16x32_bf16 v[76:79], v[152:155], v[212:215], v[76:79]
	v_mfma_f32_16x16x32_bf16 v[112:115], v[164:167], v[180:183], v[112:115]
	v_mfma_f32_16x16x32_bf16 v[104:107], v[172:175], v[180:183], v[104:107]
	v_mfma_f32_16x16x32_bf16 v[96:99], v[164:167], v[188:191], v[96:99]
	v_mfma_f32_16x16x32_bf16 v[88:91], v[172:175], v[188:191], v[88:91]
	v_mfma_f32_16x16x32_bf16 v[80:83], v[164:167], v[200:203], v[80:83]
	v_mfma_f32_16x16x32_bf16 v[72:75], v[172:175], v[200:203], v[72:75]
	v_mfma_f32_16x16x32_bf16 v[68:71], v[164:167], v[208:211], v[68:71]
	v_mfma_f32_16x16x32_bf16 v[64:67], v[172:175], v[208:211], v[64:67]
	v_mfma_f32_16x16x32_bf16 v[112:115], v[168:171], v[184:187], v[112:115]
	v_mfma_f32_16x16x32_bf16 v[104:107], v[176:179], v[184:187], v[104:107]
	v_mfma_f32_16x16x32_bf16 v[96:99], v[168:171], v[192:195], v[96:99]
	v_mfma_f32_16x16x32_bf16 v[88:91], v[176:179], v[192:195], v[88:91]
	v_mfma_f32_16x16x32_bf16 v[80:83], v[168:171], v[204:207], v[80:83]
	v_mfma_f32_16x16x32_bf16 v[72:75], v[176:179], v[204:207], v[72:75]
	v_mfma_f32_16x16x32_bf16 v[68:71], v[168:171], v[212:215], v[68:71]
	v_mfma_f32_16x16x32_bf16 v[64:67], v[176:179], v[212:215], v[64:67]
	s_setprio 0
	s_barrier
	s_add_i32 s46, s35, s28
	v_lshl_add_u64 v[196:197], s[24:25], 0, v[132:133]
	s_mov_b32 m0, s46
	ds_read_b128 v[180:183], v161 offset:16384
	ds_read_b128 v[184:187], v161 offset:17408
	ds_read_b128 v[188:191], v161 offset:18432
	ds_read_b128 v[192:195], v161 offset:19456
	ds_read_b128 v[200:203], v161 offset:20480
	ds_read_b128 v[204:207], v161 offset:21504
	ds_read_b128 v[208:211], v161 offset:22528
	ds_read_b128 v[212:215], v161 offset:23552
	global_load_lds_dwordx4 v[196:197], off
	s_add_i32 m0, s46, 0x2000
	s_add_u32 s46, s24, 0x40000
	v_lshl_add_u64 v[216:217], s[24:25], 0, v[128:129]
	s_addc_u32 s47, s25, 0
	s_add_i32 s48, s36, s28
	global_load_lds_dwordx4 v[216:217], off
	v_lshl_add_u64 v[218:219], s[46:47], 0, v[132:133]
	s_mov_b32 m0, s48
	v_lshl_add_u64 v[220:221], s[26:27], 0, v[130:131]
	global_load_lds_dwordx4 v[218:219], off
	v_lshl_add_u64 v[218:219], s[46:47], 0, v[128:129]
	s_add_i32 m0, s48, 0x2000
	s_nop 0
	global_load_lds_dwordx4 v[218:219], off
	v_lshl_add_u64 v[218:219], s[26:27], 0, v[134:135]
	s_mov_b32 m0, s21
	s_nop 0
	global_load_lds_dwordx4 v[218:219], off
	s_mov_b32 m0, s29
	s_nop 0
	global_load_lds_dwordx4 v[220:221], off
	s_waitcnt vmcnt(8)
	s_waitcnt lgkmcnt(0)
	s_barrier
; #define PG8_STAGE(bufoff, gbase, voff) do { _Pragma("unroll") for (int _i = 0; _i < 2; ++_i) \
;         __builtin_amdgcn_global_load_lds((const unsigned*)((const char*)(gbase) + (voff)[_i]), (PG8_LAS unsigned*)(lds + (bufoff) + ldsw + _i * 8192), 16, 0, 0); } while (0)
; #define PG8_LDA(dst, b, h) do { _Pragma("unroll") for (int m = 0; m < 4; ++m) _Pragma("unroll") for (int k = 0; k < 2; ++k) dst[m][k] = *(const PG8_LAS bf16x8*)(lds + PG8_SA(b, h) + aoff + m * 2048 + k * 1024); } while (0)
; #define PG8_LDB(dst, b, h) do { _Pragma("unroll") for (int n = 0; n < 2; ++n) _Pragma("unroll") for (int k = 0; k < 2; ++k) dst[n][k] = *(const PG8_LAS bf16x8*)(lds + PG8_SB(b, h) + boff + n * 2048 + k * 1024); } while (0)
; #define PG8_MMA(ai, bj, At, Bt) do { __builtin_amdgcn_s_setprio(1); _Pragma("unroll") for (int m = 0; m < 4; ++m) _Pragma("unroll") for (int n = 0; n < 2; ++n) _Pragma("unroll") for (int k = 0; k < 2; ++k) \
;         acc[ai][bj][m][n] = __builtin_amdgcn_mfma_f32_16x16x32_bf16(Bt[n][k], At[m][k], acc[ai][bj][m][n], 0, 0, 0); __builtin_amdgcn_s_setprio(0); } while (0)
; #define PG8_WAIT_V(n) asm volatile("s_waitcnt vmcnt(" #n ")" ::: "memory")
; #define PG8_WAIT_L(n) asm volatile("s_waitcnt lgkmcnt(" #n ")" ::: "memory")
; #define PG8_BAR __builtin_amdgcn_s_barrier()
; #define PG8_SCHED __builtin_amdgcn_sched_barrier(0)
; template <class Epi, class Sched>
; __device__ __forceinline__ void gemm_phase(PG8_LAS unsigned char* lds, const Gemm g, const Sched& S, const Epi& E) {
;     ...
;             PG8_WAIT_V(8); PG8_WAIT_L(0); PG8_BAR; PG8_MMA(1, 0, At, B0); PG8_MMA(1, 1, At, B1); PG8_BAR; PG8_SCHED;
;             PG8_LDB(B0, 1, 0); PG8_LDB(B1, 1, 1); PG8_SCHED; PG8_LDA(At, 1, 0); PG8_STAGE(PG8_SA(0, 1), a2 + hstepA, voffA);
;             PG8_WAIT_V(8); PG8_WAIT_L(0); PG8_BAR; PG8_MMA(0, 0, At, B0); PG8_MMA(0, 1, At, B1); PG8_BAR; PG8_SCHED;
	s_setprio 1
	s_waitcnt lgkmcnt(0)
	v_mfma_f32_16x16x32_bf16 v[60:63], v[140:143], v[180:183], v[60:63]
	v_mfma_f32_16x16x32_bf16 v[56:59], v[148:151], v[180:183], v[56:59]
	v_mfma_f32_16x16x32_bf16 v[52:55], v[140:143], v[188:191], v[52:55]
	v_mfma_f32_16x16x32_bf16 v[44:47], v[148:151], v[188:191], v[44:47]
	v_mfma_f32_16x16x32_bf16 v[36:39], v[140:143], v[200:203], v[36:39]
	v_mfma_f32_16x16x32_bf16 v[28:31], v[148:151], v[200:203], v[28:31]
	v_mfma_f32_16x16x32_bf16 v[20:23], v[140:143], v[208:211], v[20:23]
	v_mfma_f32_16x16x32_bf16 v[12:15], v[148:151], v[208:211], v[12:15]
	v_mfma_f32_16x16x32_bf16 v[60:63], v[144:147], v[184:187], v[60:63]
	v_mfma_f32_16x16x32_bf16 v[56:59], v[152:155], v[184:187], v[56:59]
	v_mfma_f32_16x16x32_bf16 v[52:55], v[144:147], v[192:195], v[52:55]
	v_mfma_f32_16x16x32_bf16 v[44:47], v[152:155], v[192:195], v[44:47]
	v_mfma_f32_16x16x32_bf16 v[36:39], v[144:147], v[204:207], v[36:39]
	v_mfma_f32_16x16x32_bf16 v[28:31], v[152:155], v[204:207], v[28:31]
	v_mfma_f32_16x16x32_bf16 v[20:23], v[144:147], v[212:215], v[20:23]
	v_mfma_f32_16x16x32_bf16 v[12:15], v[152:155], v[212:215], v[12:15]
	v_mfma_f32_16x16x32_bf16 v[48:51], v[164:167], v[180:183], v[48:51]
	v_mfma_f32_16x16x32_bf16 v[40:43], v[172:175], v[180:183], v[40:43]
	v_mfma_f32_16x16x32_bf16 v[32:35], v[164:167], v[188:191], v[32:35]
	v_mfma_f32_16x16x32_bf16 v[24:27], v[172:175], v[188:191], v[24:27]
	v_mfma_f32_16x16x32_bf16 v[16:19], v[164:167], v[200:203], v[16:19]
	v_mfma_f32_16x16x32_bf16 v[8:11], v[172:175], v[200:203], v[8:11]
	v_mfma_f32_16x16x32_bf16 v[4:7], v[164:167], v[208:211], v[4:7]
	v_mfma_f32_16x16x32_bf16 v[0:3], v[172:175], v[208:211], v[0:3]
	v_mfma_f32_16x16x32_bf16 v[48:51], v[168:171], v[184:187], v[48:51]
	v_mfma_f32_16x16x32_bf16 v[40:43], v[176:179], v[184:187], v[40:43]
	v_mfma_f32_16x16x32_bf16 v[32:35], v[168:171], v[192:195], v[32:35]
	v_mfma_f32_16x16x32_bf16 v[24:27], v[176:179], v[192:195], v[24:27]
	v_mfma_f32_16x16x32_bf16 v[16:19], v[168:171], v[204:207], v[16:19]
	v_mfma_f32_16x16x32_bf16 v[8:11], v[176:179], v[204:207], v[8:11]
	v_mfma_f32_16x16x32_bf16 v[4:7], v[168:171], v[212:215], v[4:7]
	v_mfma_f32_16x16x32_bf16 v[0:3], v[176:179], v[212:215], v[0:3]
	s_setprio 0
	s_barrier
	s_add_i32 s46, 0, 0x18000
	s_add_i32 s47, 0, 0x1c000
	v_add_u32_e32 v152, s46, v157
	v_add_u32_e32 v163, s47, v157
	ds_read_b128 v[140:143], v152
	ds_read_b128 v[144:147], v152 offset:1024
	ds_read_b128 v[148:151], v152 offset:2048
	ds_read_b128 v[152:155], v152 offset:3072
	ds_read_b128 v[164:167], v163
	ds_read_b128 v[168:171], v163 offset:1024
	ds_read_b128 v[172:175], v163 offset:2048
	ds_read_b128 v[176:179], v163 offset:3072
	s_add_u32 s26, s26, 0x40000
	s_addc_u32 s27, s27, 0
	s_mov_b32 m0, s30
	v_lshl_add_u64 v[222:223], s[26:27], 0, v[134:135]
	ds_read_b128 v[180:183], v161 offset:32768
	ds_read_b128 v[184:187], v161 offset:33792
	ds_read_b128 v[188:191], v161 offset:34816
	ds_read_b128 v[192:195], v161 offset:35840
	ds_read_b128 v[200:203], v161 offset:36864
	ds_read_b128 v[204:207], v161 offset:37888
	ds_read_b128 v[208:211], v161 offset:38912
	ds_read_b128 v[212:215], v161 offset:39936
	global_load_lds_dwordx4 v[222:223], off
	v_lshl_add_u64 v[222:223], s[26:27], 0, v[130:131]
	s_mov_b32 m0, s31
	s_nop 0
	global_load_lds_dwordx4 v[222:223], off
	s_waitcnt vmcnt(8)
	s_waitcnt lgkmcnt(0)
	s_barrier
	s_setprio 1
	s_waitcnt lgkmcnt(0)
	v_mfma_f32_16x16x32_bf16 v[124:127], v[140:143], v[180:183], v[124:127]
	v_mfma_f32_16x16x32_bf16 v[120:123], v[148:151], v[180:183], v[120:123]
	v_mfma_f32_16x16x32_bf16 v[116:119], v[140:143], v[188:191], v[116:119]
	v_mfma_f32_16x16x32_bf16 v[108:111], v[148:151], v[188:191], v[108:111]
	v_mfma_f32_16x16x32_bf16 v[100:103], v[140:143], v[200:203], v[100:103]
	v_mfma_f32_16x16x32_bf16 v[92:95], v[148:151], v[200:203], v[92:95]
	v_mfma_f32_16x16x32_bf16 v[84:87], v[140:143], v[208:211], v[84:87]
	v_mfma_f32_16x16x32_bf16 v[76:79], v[148:151], v[208:211], v[76:79]
	v_mfma_f32_16x16x32_bf16 v[124:127], v[144:147], v[184:187], v[124:127]
	v_mfma_f32_16x16x32_bf16 v[120:123], v[152:155], v[184:187], v[120:123]
	v_mfma_f32_16x16x32_bf16 v[116:119], v[144:147], v[192:195], v[116:119]
	v_mfma_f32_16x16x32_bf16 v[108:111], v[152:155], v[192:195], v[108:111]
	v_mfma_f32_16x16x32_bf16 v[100:103], v[144:147], v[204:207], v[100:103]
	v_mfma_f32_16x16x32_bf16 v[92:95], v[152:155], v[204:207], v[92:95]
	v_mfma_f32_16x16x32_bf16 v[84:87], v[144:147], v[212:215], v[84:87]
	v_mfma_f32_16x16x32_bf16 v[76:79], v[152:155], v[212:215], v[76:79]
	v_mfma_f32_16x16x32_bf16 v[112:115], v[164:167], v[180:183], v[112:115]
	v_mfma_f32_16x16x32_bf16 v[104:107], v[172:175], v[180:183], v[104:107]
	v_mfma_f32_16x16x32_bf16 v[96:99], v[164:167], v[188:191], v[96:99]
	v_mfma_f32_16x16x32_bf16 v[88:91], v[172:175], v[188:191], v[88:91]
	v_mfma_f32_16x16x32_bf16 v[80:83], v[164:167], v[200:203], v[80:83]
	v_mfma_f32_16x16x32_bf16 v[72:75], v[172:175], v[200:203], v[72:75]
	v_mfma_f32_16x16x32_bf16 v[68:71], v[164:167], v[208:211], v[68:71]
	v_mfma_f32_16x16x32_bf16 v[64:67], v[172:175], v[208:211], v[64:67]
	v_mfma_f32_16x16x32_bf16 v[112:115], v[168:171], v[184:187], v[112:115]
	v_mfma_f32_16x16x32_bf16 v[104:107], v[176:179], v[184:187], v[104:107]
	v_mfma_f32_16x16x32_bf16 v[96:99], v[168:171], v[192:195], v[96:99]
	v_mfma_f32_16x16x32_bf16 v[88:91], v[176:179], v[192:195], v[88:91]
	v_mfma_f32_16x16x32_bf16 v[80:83], v[168:171], v[204:207], v[80:83]
	v_mfma_f32_16x16x32_bf16 v[72:75], v[176:179], v[204:207], v[72:75]
	v_mfma_f32_16x16x32_bf16 v[68:71], v[168:171], v[212:215], v[68:71]
	v_mfma_f32_16x16x32_bf16 v[64:67], v[176:179], v[212:215], v[64:67]
	s_setprio 0
	s_barrier
; #define PG8_STAGE(bufoff, gbase, voff) do { _Pragma("unroll") for (int _i = 0; _i < 2; ++_i) \
;         __builtin_amdgcn_global_load_lds((const unsigned*)((const char*)(gbase) + (voff)[_i]), (PG8_LAS unsigned*)(lds + (bufoff) + ldsw + _i * 8192), 16, 0, 0); } while (0)
; #define PG8_LDA(dst, b, h) do { _Pragma("unroll") for (int m = 0; m < 4; ++m) _Pragma("unroll") for (int k = 0; k < 2; ++k) dst[m][k] = *(const PG8_LAS bf16x8*)(lds + PG8_SA(b, h) + aoff + m * 2048 + k * 1024); } while (0)
; #define PG8_MMA(ai, bj, At, Bt) do { __builtin_amdgcn_s_setprio(1); _Pragma("unroll") for (int m = 0; m < 4; ++m) _Pragma("unroll") for (int n = 0; n < 2; ++n) _Pragma("unroll") for (int k = 0; k < 2; ++k) \
;         acc[ai][bj][m][n] = __builtin_amdgcn_mfma_f32_16x16x32_bf16(Bt[n][k], At[m][k], acc[ai][bj][m][n], 0, 0, 0); __builtin_amdgcn_s_setprio(0); } while (0)
; #define PG8_WAIT_V(n) asm volatile("s_waitcnt vmcnt(" #n ")" ::: "memory")
; #define PG8_WAIT_L(n) asm volatile("s_waitcnt lgkmcnt(" #n ")" ::: "memory")
; #define PG8_BAR __builtin_amdgcn_s_barrier()
; #define PG8_SCHED __builtin_amdgcn_sched_barrier(0)
; template <class Epi, class Sched>
; __device__ __forceinline__ void gemm_phase(PG8_LAS unsigned char* lds, const Gemm g, const Sched& S, const Epi& E) {
;     ...
;             PG8_LDA(At, 1, 1); PG8_STAGE(PG8_SB(1, 0), b3, voffB); PG8_STAGE(PG8_SB(1, 1), b3 + hstepB, voffB); PG8_STAGE(PG8_SA(1, 0), a3, voffA);
;             PG8_WAIT_V(8); PG8_WAIT_L(0); PG8_BAR; PG8_MMA(1, 0, At, B0); PG8_MMA(1, 1, At, B1); PG8_BAR; PG8_SCHED;
;         }
;         if (wr == 0) PG8_BAR;
	s_add_i32 s26, s46, s28
	v_lshl_add_u64 v[196:197], v[196:197], 0, s[6:7]
	s_mov_b32 m0, s26
	ds_read_b128 v[180:183], v161 offset:49152
	ds_read_b128 v[184:187], v161 offset:50176
	ds_read_b128 v[188:191], v161 offset:51200
	ds_read_b128 v[192:195], v161 offset:52224
	ds_read_b128 v[200:203], v161 offset:53248
	ds_read_b128 v[204:207], v161 offset:54272
	ds_read_b128 v[208:211], v161 offset:55296
	ds_read_b128 v[212:215], v161 offset:56320
	global_load_lds_dwordx4 v[196:197], off
	s_add_i32 m0, s26, 0x2000
	s_add_u32 s24, s24, 0x40080
	v_lshl_add_u64 v[196:197], v[216:217], 0, s[6:7]
	s_addc_u32 s25, s25, 0
	s_add_i32 s26, s47, s28
	global_load_lds_dwordx4 v[196:197], off
	v_lshl_add_u64 v[196:197], s[24:25], 0, v[132:133]
	s_mov_b32 m0, s26
	s_nop 0
	global_load_lds_dwordx4 v[196:197], off
	v_lshl_add_u64 v[196:197], s[24:25], 0, v[128:129]
	s_add_i32 m0, s26, 0x2000
	s_nop 0
	global_load_lds_dwordx4 v[196:197], off
	v_lshl_add_u64 v[196:197], v[218:219], 0, s[6:7]
	s_mov_b32 m0, s33
	s_nop 0
	global_load_lds_dwordx4 v[196:197], off
	v_lshl_add_u64 v[196:197], v[220:221], 0, s[6:7]
	s_mov_b32 m0, s34
	s_nop 0
	global_load_lds_dwordx4 v[196:197], off
	s_waitcnt vmcnt(8)
	s_waitcnt lgkmcnt(0)
	s_barrier
	s_setprio 1
	s_waitcnt lgkmcnt(0)
	v_mfma_f32_16x16x32_bf16 v[60:63], v[140:143], v[180:183], v[60:63]
	v_mfma_f32_16x16x32_bf16 v[56:59], v[148:151], v[180:183], v[56:59]
	v_mfma_f32_16x16x32_bf16 v[52:55], v[140:143], v[188:191], v[52:55]
	v_mfma_f32_16x16x32_bf16 v[44:47], v[148:151], v[188:191], v[44:47]
	v_mfma_f32_16x16x32_bf16 v[36:39], v[140:143], v[200:203], v[36:39]
	v_mfma_f32_16x16x32_bf16 v[28:31], v[148:151], v[200:203], v[28:31]
	v_mfma_f32_16x16x32_bf16 v[20:23], v[140:143], v[208:211], v[20:23]
	v_mfma_f32_16x16x32_bf16 v[12:15], v[148:151], v[208:211], v[12:15]
	v_mfma_f32_16x16x32_bf16 v[60:63], v[144:147], v[184:187], v[60:63]
	v_mfma_f32_16x16x32_bf16 v[56:59], v[152:155], v[184:187], v[56:59]
	v_mfma_f32_16x16x32_bf16 v[52:55], v[144:147], v[192:195], v[52:55]
	v_mfma_f32_16x16x32_bf16 v[44:47], v[152:155], v[192:195], v[44:47]
	v_mfma_f32_16x16x32_bf16 v[36:39], v[144:147], v[204:207], v[36:39]
	v_mfma_f32_16x16x32_bf16 v[28:31], v[152:155], v[204:207], v[28:31]
	v_mfma_f32_16x16x32_bf16 v[20:23], v[144:147], v[212:215], v[20:23]
	v_mfma_f32_16x16x32_bf16 v[12:15], v[152:155], v[212:215], v[12:15]
	v_mfma_f32_16x16x32_bf16 v[48:51], v[164:167], v[180:183], v[48:51]
	v_mfma_f32_16x16x32_bf16 v[40:43], v[172:175], v[180:183], v[40:43]
	v_mfma_f32_16x16x32_bf16 v[32:35], v[164:167], v[188:191], v[32:35]
	v_mfma_f32_16x16x32_bf16 v[24:27], v[172:175], v[188:191], v[24:27]
	v_mfma_f32_16x16x32_bf16 v[16:19], v[164:167], v[200:203], v[16:19]
	v_mfma_f32_16x16x32_bf16 v[8:11], v[172:175], v[200:203], v[8:11]
	v_mfma_f32_16x16x32_bf16 v[4:7], v[164:167], v[208:211], v[4:7]
	v_mfma_f32_16x16x32_bf16 v[0:3], v[172:175], v[208:211], v[0:3]
	v_mfma_f32_16x16x32_bf16 v[48:51], v[168:171], v[184:187], v[48:51]
	v_mfma_f32_16x16x32_bf16 v[40:43], v[176:179], v[184:187], v[40:43]
	v_mfma_f32_16x16x32_bf16 v[32:35], v[168:171], v[192:195], v[32:35]
	v_mfma_f32_16x16x32_bf16 v[24:27], v[176:179], v[192:195], v[24:27]
	v_mfma_f32_16x16x32_bf16 v[16:19], v[168:171], v[204:207], v[16:19]
	v_mfma_f32_16x16x32_bf16 v[8:11], v[176:179], v[204:207], v[8:11]
	v_mfma_f32_16x16x32_bf16 v[4:7], v[168:171], v[212:215], v[4:7]
	v_mfma_f32_16x16x32_bf16 v[0:3], v[176:179], v[212:215], v[0:3]
	s_setprio 0
	s_barrier
	s_add_i32 s45, s45, 2
	s_add_u32 s22, s22, 0x100
	s_addc_u32 s23, s23, 0
	s_add_u32 s43, s43, 0x100
	s_addc_u32 s44, s44, 0
	s_cmp_gt_u32 s45, 13
	s_cbranch_scc0 .LBB0_2974
	s_and_b64 vcc, exec, s[8:9]
	s_cbranch_vccz .LBB0_2977
	s_barrier

; #define PG8_STAGE(bufoff, gbase, voff) do { _Pragma("unroll") for (int _i = 0; _i < 2; ++_i) \
;         __builtin_amdgcn_global_load_lds((const unsigned*)((const char*)(gbase) + (voff)[_i]), (PG8_LAS unsigned*)(lds + (bufoff) + ldsw + _i * 8192), 16, 0, 0); } while (0)
; #define PG8_LDA(dst, b, h) do { _Pragma("unroll") for (int m = 0; m < 4; ++m) _Pragma("unroll") for (int k = 0; k < 2; ++k) dst[m][k] = *(const PG8_LAS bf16x8*)(lds + PG8_SA(b, h) + aoff + m * 2048 + k * 1024); } while (0)
; #define PG8_LDB(dst, b, h) do { _Pragma("unroll") for (int n = 0; n < 2; ++n) _Pragma("unroll") for (int k = 0; k < 2; ++k) dst[n][k] = *(const PG8_LAS bf16x8*)(lds + PG8_SB(b, h) + boff + n * 2048 + k * 1024); } while (0)
; #define PG8_MMA(ai, bj, At, Bt) do { __builtin_amdgcn_s_setprio(1); _Pragma("unroll") for (int m = 0; m < 4; ++m) _Pragma("unroll") for (int n = 0; n < 2; ++n) _Pragma("unroll") for (int k = 0; k < 2; ++k) \
;         acc[ai][bj][m][n] = __builtin_amdgcn_mfma_f32_16x16x32_bf16(Bt[n][k], At[m][k], acc[ai][bj][m][n], 0, 0, 0); __builtin_amdgcn_s_setprio(0); } while (0)
; #define PG8_WAIT_V(n) asm volatile("s_waitcnt vmcnt(" #n ")" ::: "memory")
; #define PG8_WAIT_L(n) asm volatile("s_waitcnt lgkmcnt(" #n ")" ::: "memory")
; template <class Epi, class Sched>
; __device__ __forceinline__ void gemm_phase(PG8_LAS unsigned char* lds, const Gemm g, const Sched& S, const Epi& E) {
;     ...
;         for (int t = 0; t < nt; t += 2) {
;             const bool last = (t == nt - 2);
;             const char* a1 = cA + (size_t)(t + 1) * kstepA;
;             const char* a2 = last ? nA : cA + (size_t)(t + 2) * kstepA; const char* b2 = last ? nB : cB + (size_t)(t + 2) * kstep;
;             const char* a3 = a2 + kstepA; const char* b3 = b2 + kstep;
;             if constexpr (epi_has_hook<Epi>::value) { if (t == nt / 2) E.hook(acc, cur, wr, wc, fr, fq); }
;             PG8_LDB(B0, 0, 0); PG8_LDB(B1, 0, 1); PG8_SCHED; PG8_LDA(At, 0, 0); PG8_STAGE(PG8_SA(1, 1), a1 + hstepA, voffA);
;             PG8_WAIT_V(8); PG8_WAIT_L(0); PG8_BAR; PG8_MMA(0, 0, At, B0); PG8_MMA(0, 1, At, B1); PG8_BAR; PG8_SCHED;
;             PG8_LDA(At, 0, 1); PG8_STAGE(PG8_SB(0, 0), b2, voffB); PG8_STAGE(PG8_SB(0, 1), b2 + hstepB, voffB); PG8_STAGE(PG8_SA(0, 0), a2, voffA);
;             PG8_WAIT_V(8); PG8_WAIT_L(0); PG8_BAR; PG8_MMA(1, 0, At, B0); PG8_MMA(1, 1, At, B1); PG8_BAR; PG8_SCHED;
.LBB0_2993:
	s_add_u32 s44, s28, s38
	s_addc_u32 s45, s29, s39
	s_add_u32 s42, s44, 0x100
	s_addc_u32 s43, s45, 0
	s_and_b64 s[40:41], s[36:37], exec
	s_cselect_b32 s41, s15, s43
	s_cselect_b32 s40, s31, s42
	s_add_u32 s38, s26, s38
	s_addc_u32 s39, s27, s39
	s_add_u32 s38, s38, 0x100
	s_addc_u32 s39, s39, 0
	s_and_b64 s[36:37], s[36:37], exec
	s_cselect_b32 s43, s59, s39
	s_cselect_b32 s42, s60, s38
	s_add_u32 s46, s44, 0x40080
	ds_read_b128 v[136:139], v143
	ds_read_b128 v[148:151], v143 offset:1024
	ds_read_b128 v[152:155], v143 offset:2048
	ds_read_b128 v[156:159], v143 offset:3072
	ds_read_b128 v[160:163], v144
	ds_read_b128 v[164:167], v144 offset:1024
	ds_read_b128 v[168:171], v144 offset:2048
	ds_read_b128 v[172:175], v144 offset:3072
	s_addc_u32 s47, s45, 0
	s_add_i32 s70, s55, s33
	s_add_i32 m0, s48, 0xc000
	s_add_i32 s71, s48, 0xe000
	s_add_i32 s67, s70, 0x2000
	s_add_u32 s44, s42, 0x40000
	s_addc_u32 s45, s43, 0
	s_add_i32 s69, s56, s33
	s_add_i32 s68, s69, 0x2000
	s_add_i32 s66, 0, 0x18000
	s_add_i32 s65, 0, 0x1c000
	s_add_u32 s38, s40, 0x40000
	s_addc_u32 s39, s41, 0
	s_add_i32 s64, s66, s33
	s_add_i32 s62, s64, 0x2000
	s_add_u32 s36, s42, 0x40080
	s_addc_u32 s37, s43, 0
	s_add_i32 s63, s65, s33
	s_add_i32 s61, s63, 0x2000
	v_lshl_add_u64 v[196:197], s[46:47], 0, v[128:129]
	ds_read_b128 v[176:179], v145
	ds_read_b128 v[180:183], v145 offset:1024
	ds_read_b128 v[184:187], v145 offset:2048
	ds_read_b128 v[188:191], v145 offset:3072
	ds_read_b128 v[192:195], v145 offset:4096
	ds_read_b128 v[200:203], v145 offset:5120
	ds_read_b128 v[204:207], v145 offset:6144
	ds_read_b128 v[208:211], v145 offset:7168
	global_load_lds_dwordx4 v[196:197], off
	v_lshl_add_u64 v[196:197], s[46:47], 0, v[132:133]
	s_mov_b32 m0, s71
	s_nop 0
	global_load_lds_dwordx4 v[196:197], off
	s_waitcnt vmcnt(8)
	s_waitcnt lgkmcnt(0)
	s_barrier
	s_setprio 1
	s_waitcnt lgkmcnt(0)
	v_mfma_f32_16x16x32_bf16 v[124:127], v[136:139], v[176:179], v[124:127]
	v_mfma_f32_16x16x32_bf16 v[120:123], v[152:155], v[176:179], v[120:123]
	v_mfma_f32_16x16x32_bf16 v[108:111], v[136:139], v[184:187], v[108:111]
	v_mfma_f32_16x16x32_bf16 v[104:107], v[152:155], v[184:187], v[104:107]
	v_mfma_f32_16x16x32_bf16 v[92:95], v[136:139], v[192:195], v[92:95]
	v_mfma_f32_16x16x32_bf16 v[88:91], v[152:155], v[192:195], v[88:91]
	v_mfma_f32_16x16x32_bf16 v[76:79], v[136:139], v[204:207], v[76:79]
	v_mfma_f32_16x16x32_bf16 v[72:75], v[152:155], v[204:207], v[72:75]
	v_mfma_f32_16x16x32_bf16 v[124:127], v[148:151], v[180:183], v[124:127]
	v_mfma_f32_16x16x32_bf16 v[120:123], v[156:159], v[180:183], v[120:123]
	v_mfma_f32_16x16x32_bf16 v[108:111], v[148:151], v[188:191], v[108:111]
	v_mfma_f32_16x16x32_bf16 v[104:107], v[156:159], v[188:191], v[104:107]
	v_mfma_f32_16x16x32_bf16 v[92:95], v[148:151], v[200:203], v[92:95]
	v_mfma_f32_16x16x32_bf16 v[88:91], v[156:159], v[200:203], v[88:91]
	v_mfma_f32_16x16x32_bf16 v[76:79], v[148:151], v[208:211], v[76:79]
	v_mfma_f32_16x16x32_bf16 v[72:75], v[156:159], v[208:211], v[72:75]
	v_mfma_f32_16x16x32_bf16 v[116:119], v[160:163], v[176:179], v[116:119]
	v_mfma_f32_16x16x32_bf16 v[112:115], v[168:171], v[176:179], v[112:115]
	v_mfma_f32_16x16x32_bf16 v[100:103], v[160:163], v[184:187], v[100:103]
	v_mfma_f32_16x16x32_bf16 v[96:99], v[168:171], v[184:187], v[96:99]
	v_mfma_f32_16x16x32_bf16 v[84:87], v[160:163], v[192:195], v[84:87]
	v_mfma_f32_16x16x32_bf16 v[80:83], v[168:171], v[192:195], v[80:83]
	v_mfma_f32_16x16x32_bf16 v[68:71], v[160:163], v[204:207], v[68:71]
	v_mfma_f32_16x16x32_bf16 v[64:67], v[168:171], v[204:207], v[64:67]
	v_mfma_f32_16x16x32_bf16 v[116:119], v[164:167], v[180:183], v[116:119]
	v_mfma_f32_16x16x32_bf16 v[112:115], v[172:175], v[180:183], v[112:115]
	v_mfma_f32_16x16x32_bf16 v[100:103], v[164:167], v[188:191], v[100:103]
	v_mfma_f32_16x16x32_bf16 v[96:99], v[172:175], v[188:191], v[96:99]
	v_mfma_f32_16x16x32_bf16 v[84:87], v[164:167], v[200:203], v[84:87]
	v_mfma_f32_16x16x32_bf16 v[80:83], v[172:175], v[200:203], v[80:83]
	v_mfma_f32_16x16x32_bf16 v[68:71], v[164:167], v[208:211], v[68:71]
	v_mfma_f32_16x16x32_bf16 v[64:67], v[172:175], v[208:211], v[64:67]
	s_setprio 0
	s_barrier
	s_mov_b32 m0, s70
	v_lshl_add_u64 v[196:197], s[42:43], 0, v[130:131]
	ds_read_b128 v[176:179], v145 offset:16384
	ds_read_b128 v[180:183], v145 offset:17408
	ds_read_b128 v[184:187], v145 offset:18432
	ds_read_b128 v[188:191], v145 offset:19456
	ds_read_b128 v[192:195], v145 offset:20480
	ds_read_b128 v[200:203], v145 offset:21504
	ds_read_b128 v[204:207], v145 offset:22528
	ds_read_b128 v[208:211], v145 offset:23552
	global_load_lds_dwordx4 v[196:197], off
	v_lshl_add_u64 v[212:213], s[42:43], 0, v[134:135]
	s_mov_b32 m0, s67
	v_lshl_add_u64 v[214:215], s[44:45], 0, v[130:131]
	global_load_lds_dwordx4 v[212:213], off
	s_mov_b32 m0, s69
	v_lshl_add_u64 v[216:217], s[40:41], 0, v[132:133]
	global_load_lds_dwordx4 v[214:215], off
	v_lshl_add_u64 v[214:215], s[44:45], 0, v[134:135]
	s_mov_b32 m0, s68
	s_nop 0
	global_load_lds_dwordx4 v[214:215], off
	v_lshl_add_u64 v[214:215], s[40:41], 0, v[128:129]
	s_mov_b32 m0, s48
	s_nop 0
	global_load_lds_dwordx4 v[214:215], off
	s_mov_b32 m0, s49
	s_nop 0
	global_load_lds_dwordx4 v[216:217], off
	s_waitcnt vmcnt(8)
	s_waitcnt lgkmcnt(0)
	s_barrier
; #define PG8_STAGE(bufoff, gbase, voff) do { _Pragma("unroll") for (int _i = 0; _i < 2; ++_i) \
;         __builtin_amdgcn_global_load_lds((const unsigned*)((const char*)(gbase) + (voff)[_i]), (PG8_LAS unsigned*)(lds + (bufoff) + ldsw + _i * 8192), 16, 0, 0); } while (0)
; #define PG8_LDA(dst, b, h) do { _Pragma("unroll") for (int m = 0; m < 4; ++m) _Pragma("unroll") for (int k = 0; k < 2; ++k) dst[m][k] = *(const PG8_LAS bf16x8*)(lds + PG8_SA(b, h) + aoff + m * 2048 + k * 1024); } while (0)
; #define PG8_LDB(dst, b, h) do { _Pragma("unroll") for (int n = 0; n < 2; ++n) _Pragma("unroll") for (int k = 0; k < 2; ++k) dst[n][k] = *(const PG8_LAS bf16x8*)(lds + PG8_SB(b, h) + boff + n * 2048 + k * 1024); } while (0)
; #define PG8_MMA(ai, bj, At, Bt) do { __builtin_amdgcn_s_setprio(1); _Pragma("unroll") for (int m = 0; m < 4; ++m) _Pragma("unroll") for (int n = 0; n < 2; ++n) _Pragma("unroll") for (int k = 0; k < 2; ++k) \
;         acc[ai][bj][m][n] = __builtin_amdgcn_mfma_f32_16x16x32_bf16(Bt[n][k], At[m][k], acc[ai][bj][m][n], 0, 0, 0); __builtin_amdgcn_s_setprio(0); } while (0)
; #define PG8_WAIT_V(n) asm volatile("s_waitcnt vmcnt(" #n ")" ::: "memory")
; #define PG8_WAIT_L(n) asm volatile("s_waitcnt lgkmcnt(" #n ")" ::: "memory")
; #define PG8_BAR __builtin_amdgcn_s_barrier()
; #define PG8_SCHED __builtin_amdgcn_sched_barrier(0)
; template <class Epi, class Sched>
; __device__ __forceinline__ void gemm_phase(PG8_LAS unsigned char* lds, const Gemm g, const Sched& S, const Epi& E) {
;     ...
;             PG8_WAIT_V(8); PG8_WAIT_L(0); PG8_BAR; PG8_MMA(1, 0, At, B0); PG8_MMA(1, 1, At, B1); PG8_BAR; PG8_SCHED;
;             PG8_LDB(B0, 1, 0); PG8_LDB(B1, 1, 1); PG8_SCHED; PG8_LDA(At, 1, 0); PG8_STAGE(PG8_SA(0, 1), a2 + hstepA, voffA);
;             PG8_WAIT_V(8); PG8_WAIT_L(0); PG8_BAR; PG8_MMA(0, 0, At, B0); PG8_MMA(0, 1, At, B1); PG8_BAR; PG8_SCHED;
	s_setprio 1
	s_waitcnt lgkmcnt(0)
	v_mfma_f32_16x16x32_bf16 v[60:63], v[136:139], v[176:179], v[60:63]
	v_mfma_f32_16x16x32_bf16 v[56:59], v[152:155], v[176:179], v[56:59]
	v_mfma_f32_16x16x32_bf16 v[44:47], v[136:139], v[184:187], v[44:47]
	v_mfma_f32_16x16x32_bf16 v[40:43], v[152:155], v[184:187], v[40:43]
	v_mfma_f32_16x16x32_bf16 v[28:31], v[136:139], v[192:195], v[28:31]
	v_mfma_f32_16x16x32_bf16 v[24:27], v[152:155], v[192:195], v[24:27]
	v_mfma_f32_16x16x32_bf16 v[12:15], v[136:139], v[204:207], v[12:15]
	v_mfma_f32_16x16x32_bf16 v[8:11], v[152:155], v[204:207], v[8:11]
	v_mfma_f32_16x16x32_bf16 v[60:63], v[148:151], v[180:183], v[60:63]
	v_mfma_f32_16x16x32_bf16 v[56:59], v[156:159], v[180:183], v[56:59]
	v_mfma_f32_16x16x32_bf16 v[44:47], v[148:151], v[188:191], v[44:47]
	v_mfma_f32_16x16x32_bf16 v[40:43], v[156:159], v[188:191], v[40:43]
	v_mfma_f32_16x16x32_bf16 v[28:31], v[148:151], v[200:203], v[28:31]
	v_mfma_f32_16x16x32_bf16 v[24:27], v[156:159], v[200:203], v[24:27]
	v_mfma_f32_16x16x32_bf16 v[12:15], v[148:151], v[208:211], v[12:15]
	v_mfma_f32_16x16x32_bf16 v[8:11], v[156:159], v[208:211], v[8:11]
	v_mfma_f32_16x16x32_bf16 v[52:55], v[160:163], v[176:179], v[52:55]
	v_mfma_f32_16x16x32_bf16 v[48:51], v[168:171], v[176:179], v[48:51]
	v_mfma_f32_16x16x32_bf16 v[36:39], v[160:163], v[184:187], v[36:39]
	v_mfma_f32_16x16x32_bf16 v[32:35], v[168:171], v[184:187], v[32:35]
	v_mfma_f32_16x16x32_bf16 v[20:23], v[160:163], v[192:195], v[20:23]
	v_mfma_f32_16x16x32_bf16 v[16:19], v[168:171], v[192:195], v[16:19]
	v_mfma_f32_16x16x32_bf16 v[4:7], v[160:163], v[204:207], v[4:7]
	v_mfma_f32_16x16x32_bf16 v[0:3], v[168:171], v[204:207], v[0:3]
	v_mfma_f32_16x16x32_bf16 v[52:55], v[164:167], v[180:183], v[52:55]
	v_mfma_f32_16x16x32_bf16 v[48:51], v[172:175], v[180:183], v[48:51]
	v_mfma_f32_16x16x32_bf16 v[36:39], v[164:167], v[188:191], v[36:39]
	v_mfma_f32_16x16x32_bf16 v[32:35], v[172:175], v[188:191], v[32:35]
	v_mfma_f32_16x16x32_bf16 v[20:23], v[164:167], v[200:203], v[20:23]
	v_mfma_f32_16x16x32_bf16 v[16:19], v[172:175], v[200:203], v[16:19]
	v_mfma_f32_16x16x32_bf16 v[4:7], v[164:167], v[208:211], v[4:7]
	v_mfma_f32_16x16x32_bf16 v[0:3], v[172:175], v[208:211], v[0:3]
	s_setprio 0
	s_barrier
	v_add_u32_e32 v147, s66, v141
	ds_read_b128 v[136:139], v147
	ds_read_b128 v[148:151], v147 offset:1024
	ds_read_b128 v[152:155], v147 offset:2048
	ds_read_b128 v[156:159], v147 offset:3072
	v_add_u32_e32 v147, s65, v141
	ds_read_b128 v[160:163], v147
	ds_read_b128 v[164:167], v147 offset:1024
	ds_read_b128 v[168:171], v147 offset:2048
	ds_read_b128 v[172:175], v147 offset:3072
	s_mov_b32 m0, s50
	v_lshl_add_u64 v[218:219], s[38:39], 0, v[128:129]
	ds_read_b128 v[176:179], v145 offset:32768
	ds_read_b128 v[180:183], v145 offset:33792
	ds_read_b128 v[184:187], v145 offset:34816
	ds_read_b128 v[188:191], v145 offset:35840
	ds_read_b128 v[192:195], v145 offset:36864
	ds_read_b128 v[200:203], v145 offset:37888
	ds_read_b128 v[204:207], v145 offset:38912
	ds_read_b128 v[208:211], v145 offset:39936
	global_load_lds_dwordx4 v[218:219], off
	v_lshl_add_u64 v[218:219], s[38:39], 0, v[132:133]
	s_mov_b32 m0, s51
	s_nop 0
	global_load_lds_dwordx4 v[218:219], off
	s_waitcnt vmcnt(8)
	s_waitcnt lgkmcnt(0)
	s_barrier
	s_setprio 1
	s_waitcnt lgkmcnt(0)
	v_mfma_f32_16x16x32_bf16 v[124:127], v[136:139], v[176:179], v[124:127]
	v_mfma_f32_16x16x32_bf16 v[120:123], v[152:155], v[176:179], v[120:123]
	v_mfma_f32_16x16x32_bf16 v[108:111], v[136:139], v[184:187], v[108:111]
	v_mfma_f32_16x16x32_bf16 v[104:107], v[152:155], v[184:187], v[104:107]
	v_mfma_f32_16x16x32_bf16 v[92:95], v[136:139], v[192:195], v[92:95]
	v_mfma_f32_16x16x32_bf16 v[88:91], v[152:155], v[192:195], v[88:91]
	v_mfma_f32_16x16x32_bf16 v[76:79], v[136:139], v[204:207], v[76:79]
	v_mfma_f32_16x16x32_bf16 v[72:75], v[152:155], v[204:207], v[72:75]
	v_mfma_f32_16x16x32_bf16 v[124:127], v[148:151], v[180:183], v[124:127]
	v_mfma_f32_16x16x32_bf16 v[120:123], v[156:159], v[180:183], v[120:123]
	v_mfma_f32_16x16x32_bf16 v[108:111], v[148:151], v[188:191], v[108:111]
	v_mfma_f32_16x16x32_bf16 v[104:107], v[156:159], v[188:191], v[104:107]
	v_mfma_f32_16x16x32_bf16 v[92:95], v[148:151], v[200:203], v[92:95]
	v_mfma_f32_16x16x32_bf16 v[88:91], v[156:159], v[200:203], v[88:91]
	v_mfma_f32_16x16x32_bf16 v[76:79], v[148:151], v[208:211], v[76:79]
	v_mfma_f32_16x16x32_bf16 v[72:75], v[156:159], v[208:211], v[72:75]
	v_mfma_f32_16x16x32_bf16 v[116:119], v[160:163], v[176:179], v[116:119]
	v_mfma_f32_16x16x32_bf16 v[112:115], v[168:171], v[176:179], v[112:115]
	v_mfma_f32_16x16x32_bf16 v[100:103], v[160:163], v[184:187], v[100:103]
	v_mfma_f32_16x16x32_bf16 v[96:99], v[168:171], v[184:187], v[96:99]
	v_mfma_f32_16x16x32_bf16 v[84:87], v[160:163], v[192:195], v[84:87]
	v_mfma_f32_16x16x32_bf16 v[80:83], v[168:171], v[192:195], v[80:83]
	v_mfma_f32_16x16x32_bf16 v[68:71], v[160:163], v[204:207], v[68:71]
	v_mfma_f32_16x16x32_bf16 v[64:67], v[168:171], v[204:207], v[64:67]
	v_mfma_f32_16x16x32_bf16 v[116:119], v[164:167], v[180:183], v[116:119]
	v_mfma_f32_16x16x32_bf16 v[112:115], v[172:175], v[180:183], v[112:115]
	v_mfma_f32_16x16x32_bf16 v[100:103], v[164:167], v[188:191], v[100:103]
	v_mfma_f32_16x16x32_bf16 v[96:99], v[172:175], v[188:191], v[96:99]
	v_mfma_f32_16x16x32_bf16 v[84:87], v[164:167], v[200:203], v[84:87]
	v_mfma_f32_16x16x32_bf16 v[80:83], v[172:175], v[200:203], v[80:83]
	v_mfma_f32_16x16x32_bf16 v[68:71], v[164:167], v[208:211], v[68:71]
	v_mfma_f32_16x16x32_bf16 v[64:67], v[172:175], v[208:211], v[64:67]
	s_setprio 0
	s_barrier
; #define PG8_STAGE(bufoff, gbase, voff) do { _Pragma("unroll") for (int _i = 0; _i < 2; ++_i) \
;         __builtin_amdgcn_global_load_lds((const unsigned*)((const char*)(gbase) + (voff)[_i]), (PG8_LAS unsigned*)(lds + (bufoff) + ldsw + _i * 8192), 16, 0, 0); } while (0)
; #define PG8_LDA(dst, b, h) do { _Pragma("unroll") for (int m = 0; m < 4; ++m) _Pragma("unroll") for (int k = 0; k < 2; ++k) dst[m][k] = *(const PG8_LAS bf16x8*)(lds + PG8_SA(b, h) + aoff + m * 2048 + k * 1024); } while (0)
; #define PG8_MMA(ai, bj, At, Bt) do { __builtin_amdgcn_s_setprio(1); _Pragma("unroll") for (int m = 0; m < 4; ++m) _Pragma("unroll") for (int n = 0; n < 2; ++n) _Pragma("unroll") for (int k = 0; k < 2; ++k) \
;         acc[ai][bj][m][n] = __builtin_amdgcn_mfma_f32_16x16x32_bf16(Bt[n][k], At[m][k], acc[ai][bj][m][n], 0, 0, 0); __builtin_amdgcn_s_setprio(0); } while (0)
; #define PG8_WAIT_V(n) asm volatile("s_waitcnt vmcnt(" #n ")" ::: "memory")
; #define PG8_WAIT_L(n) asm volatile("s_waitcnt lgkmcnt(" #n ")" ::: "memory")
; #define PG8_BAR __builtin_amdgcn_s_barrier()
; #define PG8_SCHED __builtin_amdgcn_sched_barrier(0)
; template <class Epi, class Sched>
; __device__ __forceinline__ void gemm_phase(PG8_LAS unsigned char* lds, const Gemm g, const Sched& S, const Epi& E) {
;     ...
;             PG8_LDA(At, 1, 1); PG8_STAGE(PG8_SB(1, 0), b3, voffB); PG8_STAGE(PG8_SB(1, 1), b3 + hstepB, voffB); PG8_STAGE(PG8_SA(1, 0), a3, voffA);
;             PG8_WAIT_V(8); PG8_WAIT_L(0); PG8_BAR; PG8_MMA(1, 0, At, B0); PG8_MMA(1, 1, At, B1); PG8_BAR; PG8_SCHED;
;         }
;         if (wr == 0) PG8_BAR;
	s_mov_b32 m0, s64
	v_lshl_add_u64 v[196:197], v[196:197], 0, s[10:11]
	ds_read_b128 v[176:179], v145 offset:49152
	ds_read_b128 v[180:183], v145 offset:50176
	ds_read_b128 v[184:187], v145 offset:51200
	ds_read_b128 v[188:191], v145 offset:52224
	ds_read_b128 v[192:195], v145 offset:53248
	ds_read_b128 v[200:203], v145 offset:54272
	ds_read_b128 v[204:207], v145 offset:55296
	ds_read_b128 v[208:211], v145 offset:56320
	global_load_lds_dwordx4 v[196:197], off
	v_lshl_add_u64 v[196:197], v[212:213], 0, s[10:11]
	s_mov_b32 m0, s62
	s_nop 0
	global_load_lds_dwordx4 v[196:197], off
	v_lshl_add_u64 v[196:197], s[36:37], 0, v[130:131]
	s_mov_b32 m0, s63
	s_nop 0
	global_load_lds_dwordx4 v[196:197], off
	v_lshl_add_u64 v[196:197], s[36:37], 0, v[134:135]
	s_mov_b32 m0, s61
	s_nop 0
	global_load_lds_dwordx4 v[196:197], off
	v_lshl_add_u64 v[196:197], v[214:215], 0, s[10:11]
	s_mov_b32 m0, s53
	s_nop 0
	global_load_lds_dwordx4 v[196:197], off
	v_lshl_add_u64 v[196:197], v[216:217], 0, s[10:11]
	s_mov_b32 m0, s54
	s_nop 0
	global_load_lds_dwordx4 v[196:197], off
	s_waitcnt vmcnt(8)
	s_waitcnt lgkmcnt(0)
	s_barrier
	s_setprio 1
	s_waitcnt lgkmcnt(0)
	v_mfma_f32_16x16x32_bf16 v[60:63], v[136:139], v[176:179], v[60:63]
	v_mfma_f32_16x16x32_bf16 v[56:59], v[152:155], v[176:179], v[56:59]
	v_mfma_f32_16x16x32_bf16 v[44:47], v[136:139], v[184:187], v[44:47]
	v_mfma_f32_16x16x32_bf16 v[40:43], v[152:155], v[184:187], v[40:43]
	v_mfma_f32_16x16x32_bf16 v[28:31], v[136:139], v[192:195], v[28:31]
	v_mfma_f32_16x16x32_bf16 v[24:27], v[152:155], v[192:195], v[24:27]
	v_mfma_f32_16x16x32_bf16 v[12:15], v[136:139], v[204:207], v[12:15]
	v_mfma_f32_16x16x32_bf16 v[8:11], v[152:155], v[204:207], v[8:11]
	v_mfma_f32_16x16x32_bf16 v[60:63], v[148:151], v[180:183], v[60:63]
	v_mfma_f32_16x16x32_bf16 v[56:59], v[156:159], v[180:183], v[56:59]
	v_mfma_f32_16x16x32_bf16 v[44:47], v[148:151], v[188:191], v[44:47]
	v_mfma_f32_16x16x32_bf16 v[40:43], v[156:159], v[188:191], v[40:43]
	v_mfma_f32_16x16x32_bf16 v[28:31], v[148:151], v[200:203], v[28:31]
	v_mfma_f32_16x16x32_bf16 v[24:27], v[156:159], v[200:203], v[24:27]
	v_mfma_f32_16x16x32_bf16 v[12:15], v[148:151], v[208:211], v[12:15]
	v_mfma_f32_16x16x32_bf16 v[8:11], v[156:159], v[208:211], v[8:11]
	v_mfma_f32_16x16x32_bf16 v[52:55], v[160:163], v[176:179], v[52:55]
	v_mfma_f32_16x16x32_bf16 v[48:51], v[168:171], v[176:179], v[48:51]
	v_mfma_f32_16x16x32_bf16 v[36:39], v[160:163], v[184:187], v[36:39]
	v_mfma_f32_16x16x32_bf16 v[32:35], v[168:171], v[184:187], v[32:35]
	v_mfma_f32_16x16x32_bf16 v[20:23], v[160:163], v[192:195], v[20:23]
	v_mfma_f32_16x16x32_bf16 v[16:19], v[168:171], v[192:195], v[16:19]
	v_mfma_f32_16x16x32_bf16 v[4:7], v[160:163], v[204:207], v[4:7]
	v_mfma_f32_16x16x32_bf16 v[0:3], v[168:171], v[204:207], v[0:3]
	v_mfma_f32_16x16x32_bf16 v[52:55], v[164:167], v[180:183], v[52:55]
	v_mfma_f32_16x16x32_bf16 v[48:51], v[172:175], v[180:183], v[48:51]
	v_mfma_f32_16x16x32_bf16 v[36:39], v[164:167], v[188:191], v[36:39]
	v_mfma_f32_16x16x32_bf16 v[32:35], v[172:175], v[188:191], v[32:35]
	v_mfma_f32_16x16x32_bf16 v[20:23], v[164:167], v[200:203], v[20:23]
	v_mfma_f32_16x16x32_bf16 v[16:19], v[172:175], v[200:203], v[16:19]
	v_mfma_f32_16x16x32_bf16 v[4:7], v[164:167], v[208:211], v[4:7]
	v_mfma_f32_16x16x32_bf16 v[0:3], v[172:175], v[208:211], v[0:3]
	s_setprio 0
	s_barrier
	s_andn2_b64 vcc, exec, s[34:35]
	s_mov_b64 s[36:37], -1
	s_mov_b64 s[34:35], 0
	s_mov_b64 s[38:39], 0x100
	s_cbranch_vccz .LBB0_2993
	s_and_b64 vcc, exec, s[12:13]
	s_cbranch_vccz .LBB0_2996
	s_barrier

; #define PG8_STAGE(bufoff, gbase, voff) do { _Pragma("unroll") for (int _i = 0; _i < 2; ++_i) \
;         __builtin_amdgcn_global_load_lds((const unsigned*)((const char*)(gbase) + (voff)[_i]), (PG8_LAS unsigned*)(lds + (bufoff) + ldsw + _i * 8192), 16, 0, 0); } while (0)
; #define PG8_LDA(dst, b, h) do { _Pragma("unroll") for (int m = 0; m < 4; ++m) _Pragma("unroll") for (int k = 0; k < 2; ++k) dst[m][k] = *(const PG8_LAS bf16x8*)(lds + PG8_SA(b, h) + aoff + m * 2048 + k * 1024); } while (0)
; #define PG8_LDB(dst, b, h) do { _Pragma("unroll") for (int n = 0; n < 2; ++n) _Pragma("unroll") for (int k = 0; k < 2; ++k) dst[n][k] = *(const PG8_LAS bf16x8*)(lds + PG8_SB(b, h) + boff + n * 2048 + k * 1024); } while (0)
; #define PG8_MMA(ai, bj, At, Bt) do { __builtin_amdgcn_s_setprio(1); _Pragma("unroll") for (int m = 0; m < 4; ++m) _Pragma("unroll") for (int n = 0; n < 2; ++n) _Pragma("unroll") for (int k = 0; k < 2; ++k) \
;         acc[ai][bj][m][n] = __builtin_amdgcn_mfma_f32_16x16x32_bf16(Bt[n][k], At[m][k], acc[ai][bj][m][n], 0, 0, 0); __builtin_amdgcn_s_setprio(0); } while (0)
; #define PG8_WAIT_V(n) asm volatile("s_waitcnt vmcnt(" #n ")" ::: "memory")
; #define PG8_WAIT_L(n) asm volatile("s_waitcnt lgkmcnt(" #n ")" ::: "memory")
; template <class Epi, class Sched>
; __device__ __forceinline__ void gemm_phase(PG8_LAS unsigned char* lds, const Gemm g, const Sched& S, const Epi& E) {
;     ...
;         for (int t = 0; t < nt; t += 2) {
;             const bool last = (t == nt - 2);
;             const char* a1 = cA + (size_t)(t + 1) * kstepA;
;             const char* a2 = last ? nA : cA + (size_t)(t + 2) * kstepA; const char* b2 = last ? nB : cB + (size_t)(t + 2) * kstep;
;             const char* a3 = a2 + kstepA; const char* b3 = b2 + kstep;
;             if constexpr (epi_has_hook<Epi>::value) { if (t == nt / 2) E.hook(acc, cur, wr, wc, fr, fq); }
;             PG8_LDB(B0, 0, 0); PG8_LDB(B1, 0, 1); PG8_SCHED; PG8_LDA(At, 0, 0); PG8_STAGE(PG8_SA(1, 1), a1 + hstepA, voffA);
;             PG8_WAIT_V(8); PG8_WAIT_L(0); PG8_BAR; PG8_MMA(0, 0, At, B0); PG8_MMA(0, 1, At, B1); PG8_BAR; PG8_SCHED;
;             PG8_LDA(At, 0, 1); PG8_STAGE(PG8_SB(0, 0), b2, voffB); PG8_STAGE(PG8_SB(0, 1), b2 + hstepB, voffB); PG8_STAGE(PG8_SA(0, 0), a2, voffA);
;             PG8_WAIT_V(8); PG8_WAIT_L(0); PG8_BAR; PG8_MMA(1, 0, At, B0); PG8_MMA(1, 1, At, B1); PG8_BAR; PG8_SCHED;
.LBB0_3025:
	s_add_u32 s37, s28, s36
	s_addc_u32 s42, s29, 0
	s_add_u32 s40, s37, 0x100
	s_addc_u32 s41, s42, 0
	s_and_b64 s[38:39], s[34:35], exec
	s_cselect_b32 s39, s13, s41
	s_cselect_b32 s38, s25, s40
	s_add_u32 s36, s26, s36
	s_addc_u32 s40, s27, 0
	s_add_u32 s36, s36, 0x100
	s_addc_u32 s40, s40, 0
	s_and_b64 s[34:35], s[34:35], exec
	s_cselect_b32 s41, s56, s40
	s_cselect_b32 s40, s57, s36
	s_add_u32 s44, s37, 0x40080
	ds_read_b128 v[136:139], v147
	ds_read_b128 v[140:143], v147 offset:1024
	ds_read_b128 v[150:153], v147 offset:2048
	ds_read_b128 v[154:157], v147 offset:3072
	ds_read_b128 v[158:161], v148
	ds_read_b128 v[162:165], v148 offset:1024
	ds_read_b128 v[166:169], v148 offset:2048
	ds_read_b128 v[170:173], v148 offset:3072
	s_addc_u32 s45, s42, 0
	s_add_i32 s67, s53, s33
	s_add_i32 m0, s46, 0xc000
	s_add_i32 s68, s46, 0xe000
	s_add_i32 s64, s67, 0x2000
	s_add_u32 s42, s40, 0x80000
	s_addc_u32 s43, s41, 0
	s_add_i32 s66, s54, s33
	s_add_i32 s65, s66, 0x2000
	s_add_i32 s63, 0, 0x18000
	s_add_i32 s62, 0, 0x1c000
	s_add_u32 s36, s38, 0x40000
	s_addc_u32 s37, s39, 0
	s_add_i32 s61, s63, s33
	s_add_i32 s59, s61, 0x2000
	s_add_u32 s34, s40, 0x80080
	s_addc_u32 s35, s41, 0
	s_add_i32 s60, s62, s33
	s_add_i32 s58, s60, 0x2000
	v_lshl_add_u64 v[208:209], s[44:45], 0, v[134:135]
	ds_read_b128 v[174:177], v149
	ds_read_b128 v[178:181], v149 offset:1024
	ds_read_b128 v[182:185], v149 offset:2048
	ds_read_b128 v[186:189], v149 offset:3072
	ds_read_b128 v[190:193], v149 offset:4096
	ds_read_b128 v[194:197], v149 offset:5120
	ds_read_b128 v[200:203], v149 offset:6144
	ds_read_b128 v[204:207], v149 offset:7168
	global_load_lds_dwordx4 v[208:209], off
	v_lshl_add_u64 v[208:209], s[44:45], 0, v[130:131]
	s_mov_b32 m0, s68
	s_nop 0
	global_load_lds_dwordx4 v[208:209], off
	s_waitcnt vmcnt(8)
	s_waitcnt lgkmcnt(0)
	s_barrier
	s_setprio 1
	s_waitcnt lgkmcnt(0)
	v_mfma_f32_16x16x32_bf16 v[124:127], v[136:139], v[174:177], v[124:127]
	v_mfma_f32_16x16x32_bf16 v[120:123], v[150:153], v[174:177], v[120:123]
	v_mfma_f32_16x16x32_bf16 v[116:119], v[136:139], v[182:185], v[116:119]
	v_mfma_f32_16x16x32_bf16 v[108:111], v[150:153], v[182:185], v[108:111]
	v_mfma_f32_16x16x32_bf16 v[100:103], v[136:139], v[190:193], v[100:103]
	v_mfma_f32_16x16x32_bf16 v[92:95], v[150:153], v[190:193], v[92:95]
	v_mfma_f32_16x16x32_bf16 v[84:87], v[136:139], v[200:203], v[84:87]
	v_mfma_f32_16x16x32_bf16 v[76:79], v[150:153], v[200:203], v[76:79]
	v_mfma_f32_16x16x32_bf16 v[124:127], v[140:143], v[178:181], v[124:127]
	v_mfma_f32_16x16x32_bf16 v[120:123], v[154:157], v[178:181], v[120:123]
	v_mfma_f32_16x16x32_bf16 v[116:119], v[140:143], v[186:189], v[116:119]
	v_mfma_f32_16x16x32_bf16 v[108:111], v[154:157], v[186:189], v[108:111]
	v_mfma_f32_16x16x32_bf16 v[100:103], v[140:143], v[194:197], v[100:103]
	v_mfma_f32_16x16x32_bf16 v[92:95], v[154:157], v[194:197], v[92:95]
	v_mfma_f32_16x16x32_bf16 v[84:87], v[140:143], v[204:207], v[84:87]
	v_mfma_f32_16x16x32_bf16 v[76:79], v[154:157], v[204:207], v[76:79]
	v_mfma_f32_16x16x32_bf16 v[112:115], v[158:161], v[174:177], v[112:115]
	v_mfma_f32_16x16x32_bf16 v[104:107], v[166:169], v[174:177], v[104:107]
	v_mfma_f32_16x16x32_bf16 v[96:99], v[158:161], v[182:185], v[96:99]
	v_mfma_f32_16x16x32_bf16 v[88:91], v[166:169], v[182:185], v[88:91]
	v_mfma_f32_16x16x32_bf16 v[80:83], v[158:161], v[190:193], v[80:83]
	v_mfma_f32_16x16x32_bf16 v[72:75], v[166:169], v[190:193], v[72:75]
	v_mfma_f32_16x16x32_bf16 v[68:71], v[158:161], v[200:203], v[68:71]
	v_mfma_f32_16x16x32_bf16 v[64:67], v[166:169], v[200:203], v[64:67]
	v_mfma_f32_16x16x32_bf16 v[112:115], v[162:165], v[178:181], v[112:115]
	v_mfma_f32_16x16x32_bf16 v[104:107], v[170:173], v[178:181], v[104:107]
	v_mfma_f32_16x16x32_bf16 v[96:99], v[162:165], v[186:189], v[96:99]
	v_mfma_f32_16x16x32_bf16 v[88:91], v[170:173], v[186:189], v[88:91]
	v_mfma_f32_16x16x32_bf16 v[80:83], v[162:165], v[194:197], v[80:83]
	v_mfma_f32_16x16x32_bf16 v[72:75], v[170:173], v[194:197], v[72:75]
	v_mfma_f32_16x16x32_bf16 v[68:71], v[162:165], v[204:207], v[68:71]
	v_mfma_f32_16x16x32_bf16 v[64:67], v[170:173], v[204:207], v[64:67]
	s_setprio 0
	s_barrier
	s_mov_b32 m0, s67
	v_lshl_add_u64 v[208:209], s[40:41], 0, v[132:133]
	ds_read_b128 v[174:177], v149 offset:16384
	ds_read_b128 v[178:181], v149 offset:17408
	ds_read_b128 v[182:185], v149 offset:18432
	ds_read_b128 v[186:189], v149 offset:19456
	ds_read_b128 v[190:193], v149 offset:20480
	ds_read_b128 v[194:197], v149 offset:21504
	ds_read_b128 v[200:203], v149 offset:22528
	ds_read_b128 v[204:207], v149 offset:23552
	global_load_lds_dwordx4 v[208:209], off
	v_lshl_add_u64 v[210:211], s[40:41], 0, v[128:129]
	s_mov_b32 m0, s64
	v_lshl_add_u64 v[212:213], s[42:43], 0, v[132:133]
	global_load_lds_dwordx4 v[210:211], off
	s_mov_b32 m0, s66
	v_lshl_add_u64 v[214:215], s[38:39], 0, v[130:131]
	global_load_lds_dwordx4 v[212:213], off
	v_lshl_add_u64 v[212:213], s[42:43], 0, v[128:129]
	s_mov_b32 m0, s65
	s_nop 0
	global_load_lds_dwordx4 v[212:213], off
	v_lshl_add_u64 v[212:213], s[38:39], 0, v[134:135]
	s_mov_b32 m0, s46
	s_nop 0
	global_load_lds_dwordx4 v[212:213], off
	s_mov_b32 m0, s47
	s_nop 0
	global_load_lds_dwordx4 v[214:215], off
	s_waitcnt vmcnt(8)
	s_waitcnt lgkmcnt(0)
	s_barrier
; #define PG8_STAGE(bufoff, gbase, voff) do { _Pragma("unroll") for (int _i = 0; _i < 2; ++_i) \
;         __builtin_amdgcn_global_load_lds((const unsigned*)((const char*)(gbase) + (voff)[_i]), (PG8_LAS unsigned*)(lds + (bufoff) + ldsw + _i * 8192), 16, 0, 0); } while (0)
; #define PG8_LDA(dst, b, h) do { _Pragma("unroll") for (int m = 0; m < 4; ++m) _Pragma("unroll") for (int k = 0; k < 2; ++k) dst[m][k] = *(const PG8_LAS bf16x8*)(lds + PG8_SA(b, h) + aoff + m * 2048 + k * 1024); } while (0)
; #define PG8_LDB(dst, b, h) do { _Pragma("unroll") for (int n = 0; n < 2; ++n) _Pragma("unroll") for (int k = 0; k < 2; ++k) dst[n][k] = *(const PG8_LAS bf16x8*)(lds + PG8_SB(b, h) + boff + n * 2048 + k * 1024); } while (0)
; #define PG8_MMA(ai, bj, At, Bt) do { __builtin_amdgcn_s_setprio(1); _Pragma("unroll") for (int m = 0; m < 4; ++m) _Pragma("unroll") for (int n = 0; n < 2; ++n) _Pragma("unroll") for (int k = 0; k < 2; ++k) \
;         acc[ai][bj][m][n] = __builtin_amdgcn_mfma_f32_16x16x32_bf16(Bt[n][k], At[m][k], acc[ai][bj][m][n], 0, 0, 0); __builtin_amdgcn_s_setprio(0); } while (0)
; #define PG8_WAIT_V(n) asm volatile("s_waitcnt vmcnt(" #n ")" ::: "memory")
; #define PG8_WAIT_L(n) asm volatile("s_waitcnt lgkmcnt(" #n ")" ::: "memory")
; #define PG8_BAR __builtin_amdgcn_s_barrier()
; #define PG8_SCHED __builtin_amdgcn_sched_barrier(0)
; template <class Epi, class Sched>
; __device__ __forceinline__ void gemm_phase(PG8_LAS unsigned char* lds, const Gemm g, const Sched& S, const Epi& E) {
;     ...
;             PG8_WAIT_V(8); PG8_WAIT_L(0); PG8_BAR; PG8_MMA(1, 0, At, B0); PG8_MMA(1, 1, At, B1); PG8_BAR; PG8_SCHED;
;             PG8_LDB(B0, 1, 0); PG8_LDB(B1, 1, 1); PG8_SCHED; PG8_LDA(At, 1, 0); PG8_STAGE(PG8_SA(0, 1), a2 + hstepA, voffA);
;             PG8_WAIT_V(8); PG8_WAIT_L(0); PG8_BAR; PG8_MMA(0, 0, At, B0); PG8_MMA(0, 1, At, B1); PG8_BAR; PG8_SCHED;
	s_setprio 1
	s_waitcnt lgkmcnt(0)
	v_mfma_f32_16x16x32_bf16 v[60:63], v[136:139], v[174:177], v[60:63]
	v_mfma_f32_16x16x32_bf16 v[56:59], v[150:153], v[174:177], v[56:59]
	v_mfma_f32_16x16x32_bf16 v[52:55], v[136:139], v[182:185], v[52:55]
	v_mfma_f32_16x16x32_bf16 v[44:47], v[150:153], v[182:185], v[44:47]
	v_mfma_f32_16x16x32_bf16 v[36:39], v[136:139], v[190:193], v[36:39]
	v_mfma_f32_16x16x32_bf16 v[28:31], v[150:153], v[190:193], v[28:31]
	v_mfma_f32_16x16x32_bf16 v[20:23], v[136:139], v[200:203], v[20:23]
	v_mfma_f32_16x16x32_bf16 v[12:15], v[150:153], v[200:203], v[12:15]
	v_mfma_f32_16x16x32_bf16 v[60:63], v[140:143], v[178:181], v[60:63]
	v_mfma_f32_16x16x32_bf16 v[56:59], v[154:157], v[178:181], v[56:59]
	v_mfma_f32_16x16x32_bf16 v[52:55], v[140:143], v[186:189], v[52:55]
	v_mfma_f32_16x16x32_bf16 v[44:47], v[154:157], v[186:189], v[44:47]
	v_mfma_f32_16x16x32_bf16 v[36:39], v[140:143], v[194:197], v[36:39]
	v_mfma_f32_16x16x32_bf16 v[28:31], v[154:157], v[194:197], v[28:31]
	v_mfma_f32_16x16x32_bf16 v[20:23], v[140:143], v[204:207], v[20:23]
	v_mfma_f32_16x16x32_bf16 v[12:15], v[154:157], v[204:207], v[12:15]
	v_mfma_f32_16x16x32_bf16 v[48:51], v[158:161], v[174:177], v[48:51]
	v_mfma_f32_16x16x32_bf16 v[40:43], v[166:169], v[174:177], v[40:43]
	v_mfma_f32_16x16x32_bf16 v[32:35], v[158:161], v[182:185], v[32:35]
	v_mfma_f32_16x16x32_bf16 v[24:27], v[166:169], v[182:185], v[24:27]
	v_mfma_f32_16x16x32_bf16 v[16:19], v[158:161], v[190:193], v[16:19]
	v_mfma_f32_16x16x32_bf16 v[8:11], v[166:169], v[190:193], v[8:11]
	v_mfma_f32_16x16x32_bf16 v[4:7], v[158:161], v[200:203], v[4:7]
	v_mfma_f32_16x16x32_bf16 v[0:3], v[166:169], v[200:203], v[0:3]
	v_mfma_f32_16x16x32_bf16 v[48:51], v[162:165], v[178:181], v[48:51]
	v_mfma_f32_16x16x32_bf16 v[40:43], v[170:173], v[178:181], v[40:43]
	v_mfma_f32_16x16x32_bf16 v[32:35], v[162:165], v[186:189], v[32:35]
	v_mfma_f32_16x16x32_bf16 v[24:27], v[170:173], v[186:189], v[24:27]
	v_mfma_f32_16x16x32_bf16 v[16:19], v[162:165], v[194:197], v[16:19]
	v_mfma_f32_16x16x32_bf16 v[8:11], v[170:173], v[194:197], v[8:11]
	v_mfma_f32_16x16x32_bf16 v[4:7], v[162:165], v[204:207], v[4:7]
	v_mfma_f32_16x16x32_bf16 v[0:3], v[170:173], v[204:207], v[0:3]
	s_setprio 0
	s_barrier
	v_add_u32_e32 v154, s63, v145
	v_add_u32_e32 v170, s62, v145
	ds_read_b128 v[136:139], v154
	ds_read_b128 v[140:143], v154 offset:1024
	ds_read_b128 v[150:153], v154 offset:2048
	ds_read_b128 v[154:157], v154 offset:3072
	ds_read_b128 v[158:161], v170
	ds_read_b128 v[162:165], v170 offset:1024
	ds_read_b128 v[166:169], v170 offset:2048
	ds_read_b128 v[170:173], v170 offset:3072
	s_mov_b32 m0, s48
	v_lshl_add_u64 v[216:217], s[36:37], 0, v[134:135]
	ds_read_b128 v[174:177], v149 offset:32768
	ds_read_b128 v[178:181], v149 offset:33792
	ds_read_b128 v[182:185], v149 offset:34816
	ds_read_b128 v[186:189], v149 offset:35840
	ds_read_b128 v[190:193], v149 offset:36864
	ds_read_b128 v[194:197], v149 offset:37888
	ds_read_b128 v[200:203], v149 offset:38912
	ds_read_b128 v[204:207], v149 offset:39936
	global_load_lds_dwordx4 v[216:217], off
	v_lshl_add_u64 v[216:217], s[36:37], 0, v[130:131]
	s_mov_b32 m0, s49
	s_nop 0
	global_load_lds_dwordx4 v[216:217], off
	s_waitcnt vmcnt(8)
	s_waitcnt lgkmcnt(0)
	s_barrier
	s_setprio 1
	s_waitcnt lgkmcnt(0)
	v_mfma_f32_16x16x32_bf16 v[124:127], v[136:139], v[174:177], v[124:127]
	v_mfma_f32_16x16x32_bf16 v[120:123], v[150:153], v[174:177], v[120:123]
	v_mfma_f32_16x16x32_bf16 v[116:119], v[136:139], v[182:185], v[116:119]
	v_mfma_f32_16x16x32_bf16 v[108:111], v[150:153], v[182:185], v[108:111]
	v_mfma_f32_16x16x32_bf16 v[100:103], v[136:139], v[190:193], v[100:103]
	v_mfma_f32_16x16x32_bf16 v[92:95], v[150:153], v[190:193], v[92:95]
	v_mfma_f32_16x16x32_bf16 v[84:87], v[136:139], v[200:203], v[84:87]
	v_mfma_f32_16x16x32_bf16 v[76:79], v[150:153], v[200:203], v[76:79]
	v_mfma_f32_16x16x32_bf16 v[124:127], v[140:143], v[178:181], v[124:127]
	v_mfma_f32_16x16x32_bf16 v[120:123], v[154:157], v[178:181], v[120:123]
	v_mfma_f32_16x16x32_bf16 v[116:119], v[140:143], v[186:189], v[116:119]
	v_mfma_f32_16x16x32_bf16 v[108:111], v[154:157], v[186:189], v[108:111]
	v_mfma_f32_16x16x32_bf16 v[100:103], v[140:143], v[194:197], v[100:103]
	v_mfma_f32_16x16x32_bf16 v[92:95], v[154:157], v[194:197], v[92:95]
	v_mfma_f32_16x16x32_bf16 v[84:87], v[140:143], v[204:207], v[84:87]
	v_mfma_f32_16x16x32_bf16 v[76:79], v[154:157], v[204:207], v[76:79]
	v_mfma_f32_16x16x32_bf16 v[112:115], v[158:161], v[174:177], v[112:115]
	v_mfma_f32_16x16x32_bf16 v[104:107], v[166:169], v[174:177], v[104:107]
	v_mfma_f32_16x16x32_bf16 v[96:99], v[158:161], v[182:185], v[96:99]
	v_mfma_f32_16x16x32_bf16 v[88:91], v[166:169], v[182:185], v[88:91]
	v_mfma_f32_16x16x32_bf16 v[80:83], v[158:161], v[190:193], v[80:83]
	v_mfma_f32_16x16x32_bf16 v[72:75], v[166:169], v[190:193], v[72:75]
	v_mfma_f32_16x16x32_bf16 v[68:71], v[158:161], v[200:203], v[68:71]
	v_mfma_f32_16x16x32_bf16 v[64:67], v[166:169], v[200:203], v[64:67]
	v_mfma_f32_16x16x32_bf16 v[112:115], v[162:165], v[178:181], v[112:115]
	v_mfma_f32_16x16x32_bf16 v[104:107], v[170:173], v[178:181], v[104:107]
	v_mfma_f32_16x16x32_bf16 v[96:99], v[162:165], v[186:189], v[96:99]
	v_mfma_f32_16x16x32_bf16 v[88:91], v[170:173], v[186:189], v[88:91]
	v_mfma_f32_16x16x32_bf16 v[80:83], v[162:165], v[194:197], v[80:83]
	v_mfma_f32_16x16x32_bf16 v[72:75], v[170:173], v[194:197], v[72:75]
	v_mfma_f32_16x16x32_bf16 v[68:71], v[162:165], v[204:207], v[68:71]
	v_mfma_f32_16x16x32_bf16 v[64:67], v[170:173], v[204:207], v[64:67]
	s_setprio 0
	s_barrier
; #define PG8_STAGE(bufoff, gbase, voff) do { _Pragma("unroll") for (int _i = 0; _i < 2; ++_i) \
;         __builtin_amdgcn_global_load_lds((const unsigned*)((const char*)(gbase) + (voff)[_i]), (PG8_LAS unsigned*)(lds + (bufoff) + ldsw + _i * 8192), 16, 0, 0); } while (0)
; #define PG8_LDA(dst, b, h) do { _Pragma("unroll") for (int m = 0; m < 4; ++m) _Pragma("unroll") for (int k = 0; k < 2; ++k) dst[m][k] = *(const PG8_LAS bf16x8*)(lds + PG8_SA(b, h) + aoff + m * 2048 + k * 1024); } while (0)
; #define PG8_MMA(ai, bj, At, Bt) do { __builtin_amdgcn_s_setprio(1); _Pragma("unroll") for (int m = 0; m < 4; ++m) _Pragma("unroll") for (int n = 0; n < 2; ++n) _Pragma("unroll") for (int k = 0; k < 2; ++k) \
;         acc[ai][bj][m][n] = __builtin_amdgcn_mfma_f32_16x16x32_bf16(Bt[n][k], At[m][k], acc[ai][bj][m][n], 0, 0, 0); __builtin_amdgcn_s_setprio(0); } while (0)
; #define PG8_WAIT_V(n) asm volatile("s_waitcnt vmcnt(" #n ")" ::: "memory")
; #define PG8_WAIT_L(n) asm volatile("s_waitcnt lgkmcnt(" #n ")" ::: "memory")
; #define PG8_BAR __builtin_amdgcn_s_barrier()
; #define PG8_SCHED __builtin_amdgcn_sched_barrier(0)
; template <class Epi, class Sched>
; __device__ __forceinline__ void gemm_phase(PG8_LAS unsigned char* lds, const Gemm g, const Sched& S, const Epi& E) {
;     ...
;             PG8_LDA(At, 1, 1); PG8_STAGE(PG8_SB(1, 0), b3, voffB); PG8_STAGE(PG8_SB(1, 1), b3 + hstepB, voffB); PG8_STAGE(PG8_SA(1, 0), a3, voffA);
;             PG8_WAIT_V(8); PG8_WAIT_L(0); PG8_BAR; PG8_MMA(1, 0, At, B0); PG8_MMA(1, 1, At, B1); PG8_BAR; PG8_SCHED;
;         }
;         if (wr == 0) PG8_BAR;
	s_mov_b32 m0, s61
	v_lshl_add_u64 v[208:209], v[208:209], 0, s[8:9]
	ds_read_b128 v[174:177], v149 offset:49152
	ds_read_b128 v[178:181], v149 offset:50176
	ds_read_b128 v[182:185], v149 offset:51200
	ds_read_b128 v[186:189], v149 offset:52224
	ds_read_b128 v[190:193], v149 offset:53248
	ds_read_b128 v[194:197], v149 offset:54272
	ds_read_b128 v[200:203], v149 offset:55296
	ds_read_b128 v[204:207], v149 offset:56320
	global_load_lds_dwordx4 v[208:209], off
	v_lshl_add_u64 v[208:209], v[210:211], 0, s[8:9]
	s_mov_b32 m0, s59
	s_nop 0
	global_load_lds_dwordx4 v[208:209], off
	v_lshl_add_u64 v[208:209], s[34:35], 0, v[132:133]
	s_mov_b32 m0, s60
	s_nop 0
	global_load_lds_dwordx4 v[208:209], off
	v_lshl_add_u64 v[208:209], s[34:35], 0, v[128:129]
	s_mov_b32 m0, s58
	s_nop 0
	global_load_lds_dwordx4 v[208:209], off
	v_lshl_add_u64 v[208:209], v[212:213], 0, s[8:9]
	s_mov_b32 m0, s51
	s_nop 0
	global_load_lds_dwordx4 v[208:209], off
	v_lshl_add_u64 v[208:209], v[214:215], 0, s[8:9]
	s_mov_b32 m0, s52
	s_nop 0
	global_load_lds_dwordx4 v[208:209], off
	s_waitcnt vmcnt(8)
	s_waitcnt lgkmcnt(0)
	s_barrier
	s_setprio 1
	s_waitcnt lgkmcnt(0)
	v_mfma_f32_16x16x32_bf16 v[60:63], v[136:139], v[174:177], v[60:63]
	v_mfma_f32_16x16x32_bf16 v[56:59], v[150:153], v[174:177], v[56:59]
	v_mfma_f32_16x16x32_bf16 v[52:55], v[136:139], v[182:185], v[52:55]
	v_mfma_f32_16x16x32_bf16 v[44:47], v[150:153], v[182:185], v[44:47]
	v_mfma_f32_16x16x32_bf16 v[36:39], v[136:139], v[190:193], v[36:39]
	v_mfma_f32_16x16x32_bf16 v[28:31], v[150:153], v[190:193], v[28:31]
	v_mfma_f32_16x16x32_bf16 v[20:23], v[136:139], v[200:203], v[20:23]
	v_mfma_f32_16x16x32_bf16 v[12:15], v[150:153], v[200:203], v[12:15]
	v_mfma_f32_16x16x32_bf16 v[60:63], v[140:143], v[178:181], v[60:63]
	v_mfma_f32_16x16x32_bf16 v[56:59], v[154:157], v[178:181], v[56:59]
	v_mfma_f32_16x16x32_bf16 v[52:55], v[140:143], v[186:189], v[52:55]
	v_mfma_f32_16x16x32_bf16 v[44:47], v[154:157], v[186:189], v[44:47]
	v_mfma_f32_16x16x32_bf16 v[36:39], v[140:143], v[194:197], v[36:39]
	v_mfma_f32_16x16x32_bf16 v[28:31], v[154:157], v[194:197], v[28:31]
	v_mfma_f32_16x16x32_bf16 v[20:23], v[140:143], v[204:207], v[20:23]
	v_mfma_f32_16x16x32_bf16 v[12:15], v[154:157], v[204:207], v[12:15]
	v_mfma_f32_16x16x32_bf16 v[48:51], v[158:161], v[174:177], v[48:51]
	v_mfma_f32_16x16x32_bf16 v[40:43], v[166:169], v[174:177], v[40:43]
	v_mfma_f32_16x16x32_bf16 v[32:35], v[158:161], v[182:185], v[32:35]
	v_mfma_f32_16x16x32_bf16 v[24:27], v[166:169], v[182:185], v[24:27]
	v_mfma_f32_16x16x32_bf16 v[16:19], v[158:161], v[190:193], v[16:19]
	v_mfma_f32_16x16x32_bf16 v[8:11], v[166:169], v[190:193], v[8:11]
	v_mfma_f32_16x16x32_bf16 v[4:7], v[158:161], v[200:203], v[4:7]
	v_mfma_f32_16x16x32_bf16 v[0:3], v[166:169], v[200:203], v[0:3]
	v_mfma_f32_16x16x32_bf16 v[48:51], v[162:165], v[178:181], v[48:51]
	v_mfma_f32_16x16x32_bf16 v[40:43], v[170:173], v[178:181], v[40:43]
	v_mfma_f32_16x16x32_bf16 v[32:35], v[162:165], v[186:189], v[32:35]
	v_mfma_f32_16x16x32_bf16 v[24:27], v[170:173], v[186:189], v[24:27]
	v_mfma_f32_16x16x32_bf16 v[16:19], v[162:165], v[194:197], v[16:19]
	v_mfma_f32_16x16x32_bf16 v[8:11], v[170:173], v[194:197], v[8:11]
	v_mfma_f32_16x16x32_bf16 v[4:7], v[162:165], v[204:207], v[4:7]
	v_mfma_f32_16x16x32_bf16 v[0:3], v[170:173], v[204:207], v[0:3]
	s_setprio 0
	s_barrier
	s_movk_i32 s36, 0x100
	s_andn2_b64 vcc, exec, s[30:31]
	s_mov_b64 s[34:35], -1
	s_mov_b64 s[30:31], 0
	s_cbranch_vccz .LBB0_3025
	s_and_b64 vcc, exec, s[10:11]
	s_cbranch_vccz .LBB0_3028
	s_barrier

; #define PG8_STAGE(bufoff, gbase, voff) do { _Pragma("unroll") for (int _i = 0; _i < 2; ++_i) \
;         __builtin_amdgcn_global_load_lds((const unsigned*)((const char*)(gbase) + (voff)[_i]), (PG8_LAS unsigned*)(lds + (bufoff) + ldsw + _i * 8192), 16, 0, 0); } while (0)
; #define PG8_LDA(dst, b, h) do { _Pragma("unroll") for (int m = 0; m < 4; ++m) _Pragma("unroll") for (int k = 0; k < 2; ++k) dst[m][k] = *(const PG8_LAS bf16x8*)(lds + PG8_SA(b, h) + aoff + m * 2048 + k * 1024); } while (0)
; #define PG8_LDB(dst, b, h) do { _Pragma("unroll") for (int n = 0; n < 2; ++n) _Pragma("unroll") for (int k = 0; k < 2; ++k) dst[n][k] = *(const PG8_LAS bf16x8*)(lds + PG8_SB(b, h) + boff + n * 2048 + k * 1024); } while (0)
; #define PG8_MMA(ai, bj, At, Bt) do { __builtin_amdgcn_s_setprio(1); _Pragma("unroll") for (int m = 0; m < 4; ++m) _Pragma("unroll") for (int n = 0; n < 2; ++n) _Pragma("unroll") for (int k = 0; k < 2; ++k) \
;         acc[ai][bj][m][n] = __builtin_amdgcn_mfma_f32_16x16x32_bf16(Bt[n][k], At[m][k], acc[ai][bj][m][n], 0, 0, 0); __builtin_amdgcn_s_setprio(0); } while (0)
; #define PG8_WAIT_V(n) asm volatile("s_waitcnt vmcnt(" #n ")" ::: "memory")
; #define PG8_WAIT_L(n) asm volatile("s_waitcnt lgkmcnt(" #n ")" ::: "memory")
; template <class Epi, class Sched>
; __device__ __forceinline__ void gemm_phase(PG8_LAS unsigned char* lds, const Gemm g, const Sched& S, const Epi& E) {
;     ...
;         for (int t = 0; t < nt; t += 2) {
;             const bool last = (t == nt - 2);
;             const char* a1 = cA + (size_t)(t + 1) * kstepA;
;             const char* a2 = last ? nA : cA + (size_t)(t + 2) * kstepA; const char* b2 = last ? nB : cB + (size_t)(t + 2) * kstep;
;             const char* a3 = a2 + kstepA; const char* b3 = b2 + kstep;
;             if constexpr (epi_has_hook<Epi>::value) { if (t == nt / 2) E.hook(acc, cur, wr, wc, fr, fq); }
;             PG8_LDB(B0, 0, 0); PG8_LDB(B1, 0, 1); PG8_SCHED; PG8_LDA(At, 0, 0); PG8_STAGE(PG8_SA(1, 1), a1 + hstepA, voffA);
;             PG8_WAIT_V(8); PG8_WAIT_L(0); PG8_BAR; PG8_MMA(0, 0, At, B0); PG8_MMA(0, 1, At, B1); PG8_BAR; PG8_SCHED;
;             PG8_LDA(At, 0, 1); PG8_STAGE(PG8_SB(0, 0), b2, voffB); PG8_STAGE(PG8_SB(0, 1), b2 + hstepB, voffB); PG8_STAGE(PG8_SA(0, 0), a2, voffA);
;             PG8_WAIT_V(8); PG8_WAIT_L(0); PG8_BAR; PG8_MMA(1, 0, At, B0); PG8_MMA(1, 1, At, B1); PG8_BAR; PG8_SCHED;
.LBB0_3104:
	ds_read_b128 v[128:131], v165
	ds_read_b128 v[132:135], v165 offset:1024
	ds_read_b128 v[152:155], v165 offset:2048
	ds_read_b128 v[156:159], v165 offset:3072
	ds_read_b128 v[170:173], v166
	ds_read_b128 v[174:177], v166 offset:1024
	ds_read_b128 v[178:181], v166 offset:2048
	ds_read_b128 v[182:185], v166 offset:3072
	s_add_u32 s30, s28, 0xfffc0080
	s_addc_u32 s31, s29, -1
	s_cmp_eq_u32 s54, 12
	s_cselect_b32 s35, s17, s31
	s_cselect_b32 s34, s19, s30
	s_cselect_b32 s31, s50, s53
	s_cselect_b32 s30, s51, s52
	v_lshl_add_u64 v[160:161], s[28:29], 0, v[144:145]
	s_add_i32 m0, s36, 0xc000
	ds_read_b128 v[186:189], v167
	ds_read_b128 v[190:193], v167 offset:1024
	ds_read_b128 v[194:197], v167 offset:2048
	ds_read_b128 v[200:203], v167 offset:3072
	ds_read_b128 v[204:207], v167 offset:4096
	ds_read_b128 v[208:211], v167 offset:5120
	ds_read_b128 v[212:215], v167 offset:6144
	ds_read_b128 v[216:219], v167 offset:7168
	global_load_lds_dwordx4 v[160:161], off
	v_lshl_add_u64 v[160:161], s[28:29], 0, v[146:147]
	s_add_i32 m0, s36, 0xe000
	s_nop 0
	global_load_lds_dwordx4 v[160:161], off
	s_waitcnt vmcnt(8)
	s_waitcnt lgkmcnt(0)
	s_barrier
	s_setprio 1
	s_waitcnt lgkmcnt(0)
	v_mfma_f32_16x16x32_bf16 v[124:127], v[128:131], v[186:189], v[124:127]
	v_mfma_f32_16x16x32_bf16 v[120:123], v[152:155], v[186:189], v[120:123]
	v_mfma_f32_16x16x32_bf16 v[108:111], v[128:131], v[194:197], v[108:111]
	v_mfma_f32_16x16x32_bf16 v[104:107], v[152:155], v[194:197], v[104:107]
	v_mfma_f32_16x16x32_bf16 v[92:95], v[128:131], v[204:207], v[92:95]
	v_mfma_f32_16x16x32_bf16 v[88:91], v[152:155], v[204:207], v[88:91]
	v_mfma_f32_16x16x32_bf16 v[76:79], v[128:131], v[212:215], v[76:79]
	v_mfma_f32_16x16x32_bf16 v[72:75], v[152:155], v[212:215], v[72:75]
	v_mfma_f32_16x16x32_bf16 v[124:127], v[132:135], v[190:193], v[124:127]
	v_mfma_f32_16x16x32_bf16 v[120:123], v[156:159], v[190:193], v[120:123]
	v_mfma_f32_16x16x32_bf16 v[108:111], v[132:135], v[200:203], v[108:111]
	v_mfma_f32_16x16x32_bf16 v[104:107], v[156:159], v[200:203], v[104:107]
	v_mfma_f32_16x16x32_bf16 v[92:95], v[132:135], v[208:211], v[92:95]
	v_mfma_f32_16x16x32_bf16 v[88:91], v[156:159], v[208:211], v[88:91]
	v_mfma_f32_16x16x32_bf16 v[76:79], v[132:135], v[216:219], v[76:79]
	v_mfma_f32_16x16x32_bf16 v[72:75], v[156:159], v[216:219], v[72:75]
	v_mfma_f32_16x16x32_bf16 v[116:119], v[170:173], v[186:189], v[116:119]
	v_mfma_f32_16x16x32_bf16 v[112:115], v[178:181], v[186:189], v[112:115]
	v_mfma_f32_16x16x32_bf16 v[100:103], v[170:173], v[194:197], v[100:103]
	v_mfma_f32_16x16x32_bf16 v[96:99], v[178:181], v[194:197], v[96:99]
	v_mfma_f32_16x16x32_bf16 v[84:87], v[170:173], v[204:207], v[84:87]
	v_mfma_f32_16x16x32_bf16 v[80:83], v[178:181], v[204:207], v[80:83]
	v_mfma_f32_16x16x32_bf16 v[68:71], v[170:173], v[212:215], v[68:71]
	v_mfma_f32_16x16x32_bf16 v[64:67], v[178:181], v[212:215], v[64:67]
	v_mfma_f32_16x16x32_bf16 v[116:119], v[174:177], v[190:193], v[116:119]
	v_mfma_f32_16x16x32_bf16 v[112:115], v[182:185], v[190:193], v[112:115]
	v_mfma_f32_16x16x32_bf16 v[100:103], v[174:177], v[200:203], v[100:103]
	v_mfma_f32_16x16x32_bf16 v[96:99], v[182:185], v[200:203], v[96:99]
	v_mfma_f32_16x16x32_bf16 v[84:87], v[174:177], v[208:211], v[84:87]
	v_mfma_f32_16x16x32_bf16 v[80:83], v[182:185], v[208:211], v[80:83]
	v_mfma_f32_16x16x32_bf16 v[68:71], v[174:177], v[216:219], v[68:71]
	v_mfma_f32_16x16x32_bf16 v[64:67], v[182:185], v[216:219], v[64:67]
	s_setprio 0
	s_barrier
	s_add_i32 s55, s46, s33
	v_lshl_add_u64 v[160:161], s[30:31], 0, v[138:139]
	s_mov_b32 m0, s55
	ds_read_b128 v[186:189], v167 offset:16384
	ds_read_b128 v[190:193], v167 offset:17408
	ds_read_b128 v[194:197], v167 offset:18432
	ds_read_b128 v[200:203], v167 offset:19456
	ds_read_b128 v[204:207], v167 offset:20480
	ds_read_b128 v[208:211], v167 offset:21504
	ds_read_b128 v[212:215], v167 offset:22528
	ds_read_b128 v[216:219], v167 offset:23552
	global_load_lds_dwordx4 v[160:161], off
	s_add_i32 m0, s55, 0x2000
	s_add_u32 s56, s30, 0x40000
	v_lshl_add_u64 v[220:221], s[30:31], 0, v[142:143]
	s_addc_u32 s57, s31, 0
	s_add_i32 s55, s47, s33
	global_load_lds_dwordx4 v[220:221], off
	v_lshl_add_u64 v[222:223], s[56:57], 0, v[138:139]
	s_mov_b32 m0, s55
	v_lshl_add_u64 v[224:225], s[34:35], 0, v[140:141]
	global_load_lds_dwordx4 v[222:223], off
	v_lshl_add_u64 v[222:223], s[56:57], 0, v[142:143]
	s_add_i32 m0, s55, 0x2000
	s_nop 0
	global_load_lds_dwordx4 v[222:223], off
	v_lshl_add_u64 v[222:223], s[34:35], 0, v[136:137]
	s_mov_b32 m0, s36
	s_nop 0
	global_load_lds_dwordx4 v[222:223], off
	s_mov_b32 m0, s37
	s_nop 0
	global_load_lds_dwordx4 v[224:225], off
	s_waitcnt vmcnt(8)
	s_waitcnt lgkmcnt(0)
	s_barrier
; #define PG8_STAGE(bufoff, gbase, voff) do { _Pragma("unroll") for (int _i = 0; _i < 2; ++_i) \
;         __builtin_amdgcn_global_load_lds((const unsigned*)((const char*)(gbase) + (voff)[_i]), (PG8_LAS unsigned*)(lds + (bufoff) + ldsw + _i * 8192), 16, 0, 0); } while (0)
; #define PG8_LDA(dst, b, h) do { _Pragma("unroll") for (int m = 0; m < 4; ++m) _Pragma("unroll") for (int k = 0; k < 2; ++k) dst[m][k] = *(const PG8_LAS bf16x8*)(lds + PG8_SA(b, h) + aoff + m * 2048 + k * 1024); } while (0)
; #define PG8_LDB(dst, b, h) do { _Pragma("unroll") for (int n = 0; n < 2; ++n) _Pragma("unroll") for (int k = 0; k < 2; ++k) dst[n][k] = *(const PG8_LAS bf16x8*)(lds + PG8_SB(b, h) + boff + n * 2048 + k * 1024); } while (0)
; #define PG8_MMA(ai, bj, At, Bt) do { __builtin_amdgcn_s_setprio(1); _Pragma("unroll") for (int m = 0; m < 4; ++m) _Pragma("unroll") for (int n = 0; n < 2; ++n) _Pragma("unroll") for (int k = 0; k < 2; ++k) \
;         acc[ai][bj][m][n] = __builtin_amdgcn_mfma_f32_16x16x32_bf16(Bt[n][k], At[m][k], acc[ai][bj][m][n], 0, 0, 0); __builtin_amdgcn_s_setprio(0); } while (0)
; #define PG8_WAIT_V(n) asm volatile("s_waitcnt vmcnt(" #n ")" ::: "memory")
; #define PG8_WAIT_L(n) asm volatile("s_waitcnt lgkmcnt(" #n ")" ::: "memory")
; #define PG8_BAR __builtin_amdgcn_s_barrier()
; #define PG8_SCHED __builtin_amdgcn_sched_barrier(0)
; template <class Epi, class Sched>
; __device__ __forceinline__ void gemm_phase(PG8_LAS unsigned char* lds, const Gemm g, const Sched& S, const Epi& E) {
;     ...
;             PG8_WAIT_V(8); PG8_WAIT_L(0); PG8_BAR; PG8_MMA(1, 0, At, B0); PG8_MMA(1, 1, At, B1); PG8_BAR; PG8_SCHED;
;             PG8_LDB(B0, 1, 0); PG8_LDB(B1, 1, 1); PG8_SCHED; PG8_LDA(At, 1, 0); PG8_STAGE(PG8_SA(0, 1), a2 + hstepA, voffA);
;             PG8_WAIT_V(8); PG8_WAIT_L(0); PG8_BAR; PG8_MMA(0, 0, At, B0); PG8_MMA(0, 1, At, B1); PG8_BAR; PG8_SCHED;
	s_setprio 1
	s_waitcnt lgkmcnt(0)
	v_mfma_f32_16x16x32_bf16 v[60:63], v[128:131], v[186:189], v[60:63]
	v_mfma_f32_16x16x32_bf16 v[56:59], v[152:155], v[186:189], v[56:59]
	v_mfma_f32_16x16x32_bf16 v[44:47], v[128:131], v[194:197], v[44:47]
	v_mfma_f32_16x16x32_bf16 v[40:43], v[152:155], v[194:197], v[40:43]
	v_mfma_f32_16x16x32_bf16 v[28:31], v[128:131], v[204:207], v[28:31]
	v_mfma_f32_16x16x32_bf16 v[24:27], v[152:155], v[204:207], v[24:27]
	v_mfma_f32_16x16x32_bf16 v[12:15], v[128:131], v[212:215], v[12:15]
	v_mfma_f32_16x16x32_bf16 v[8:11], v[152:155], v[212:215], v[8:11]
	v_mfma_f32_16x16x32_bf16 v[60:63], v[132:135], v[190:193], v[60:63]
	v_mfma_f32_16x16x32_bf16 v[56:59], v[156:159], v[190:193], v[56:59]
	v_mfma_f32_16x16x32_bf16 v[44:47], v[132:135], v[200:203], v[44:47]
	v_mfma_f32_16x16x32_bf16 v[40:43], v[156:159], v[200:203], v[40:43]
	v_mfma_f32_16x16x32_bf16 v[28:31], v[132:135], v[208:211], v[28:31]
	v_mfma_f32_16x16x32_bf16 v[24:27], v[156:159], v[208:211], v[24:27]
	v_mfma_f32_16x16x32_bf16 v[12:15], v[132:135], v[216:219], v[12:15]
	v_mfma_f32_16x16x32_bf16 v[8:11], v[156:159], v[216:219], v[8:11]
	v_mfma_f32_16x16x32_bf16 v[52:55], v[170:173], v[186:189], v[52:55]
	v_mfma_f32_16x16x32_bf16 v[48:51], v[178:181], v[186:189], v[48:51]
	v_mfma_f32_16x16x32_bf16 v[36:39], v[170:173], v[194:197], v[36:39]
	v_mfma_f32_16x16x32_bf16 v[32:35], v[178:181], v[194:197], v[32:35]
	v_mfma_f32_16x16x32_bf16 v[20:23], v[170:173], v[204:207], v[20:23]
	v_mfma_f32_16x16x32_bf16 v[16:19], v[178:181], v[204:207], v[16:19]
	v_mfma_f32_16x16x32_bf16 v[4:7], v[170:173], v[212:215], v[4:7]
	v_mfma_f32_16x16x32_bf16 v[0:3], v[178:181], v[212:215], v[0:3]
	v_mfma_f32_16x16x32_bf16 v[52:55], v[174:177], v[190:193], v[52:55]
	v_mfma_f32_16x16x32_bf16 v[48:51], v[182:185], v[190:193], v[48:51]
	v_mfma_f32_16x16x32_bf16 v[36:39], v[174:177], v[200:203], v[36:39]
	v_mfma_f32_16x16x32_bf16 v[32:35], v[182:185], v[200:203], v[32:35]
	v_mfma_f32_16x16x32_bf16 v[20:23], v[174:177], v[208:211], v[20:23]
	v_mfma_f32_16x16x32_bf16 v[16:19], v[182:185], v[208:211], v[16:19]
	v_mfma_f32_16x16x32_bf16 v[4:7], v[174:177], v[216:219], v[4:7]
	v_mfma_f32_16x16x32_bf16 v[0:3], v[182:185], v[216:219], v[0:3]
	s_setprio 0
	s_barrier
	s_add_i32 s55, 0, 0x18000
	s_add_i32 s56, 0, 0x1c000
	v_add_u32_e32 v156, s55, v163
	v_add_u32_e32 v169, s56, v163
	ds_read_b128 v[128:131], v156
	ds_read_b128 v[132:135], v156 offset:1024
	ds_read_b128 v[152:155], v156 offset:2048
	ds_read_b128 v[156:159], v156 offset:3072
	ds_read_b128 v[170:173], v169
	ds_read_b128 v[174:177], v169 offset:1024
	ds_read_b128 v[178:181], v169 offset:2048
	ds_read_b128 v[182:185], v169 offset:3072
	s_add_u32 s34, s34, 0x40000
	s_addc_u32 s35, s35, 0
	s_mov_b32 m0, s38
	v_lshl_add_u64 v[226:227], s[34:35], 0, v[136:137]
	ds_read_b128 v[186:189], v167 offset:32768
	ds_read_b128 v[190:193], v167 offset:33792
	ds_read_b128 v[194:197], v167 offset:34816
	ds_read_b128 v[200:203], v167 offset:35840
	ds_read_b128 v[204:207], v167 offset:36864
	ds_read_b128 v[208:211], v167 offset:37888
	ds_read_b128 v[212:215], v167 offset:38912
	ds_read_b128 v[216:219], v167 offset:39936
	global_load_lds_dwordx4 v[226:227], off
	v_lshl_add_u64 v[226:227], s[34:35], 0, v[140:141]
	s_mov_b32 m0, s39
	s_nop 0
	global_load_lds_dwordx4 v[226:227], off
	s_waitcnt vmcnt(8)
	s_waitcnt lgkmcnt(0)
	s_barrier
	s_setprio 1
	s_waitcnt lgkmcnt(0)
	v_mfma_f32_16x16x32_bf16 v[124:127], v[128:131], v[186:189], v[124:127]
	v_mfma_f32_16x16x32_bf16 v[120:123], v[152:155], v[186:189], v[120:123]
	v_mfma_f32_16x16x32_bf16 v[108:111], v[128:131], v[194:197], v[108:111]
	v_mfma_f32_16x16x32_bf16 v[104:107], v[152:155], v[194:197], v[104:107]
	v_mfma_f32_16x16x32_bf16 v[92:95], v[128:131], v[204:207], v[92:95]
	v_mfma_f32_16x16x32_bf16 v[88:91], v[152:155], v[204:207], v[88:91]
	v_mfma_f32_16x16x32_bf16 v[76:79], v[128:131], v[212:215], v[76:79]
	v_mfma_f32_16x16x32_bf16 v[72:75], v[152:155], v[212:215], v[72:75]
	v_mfma_f32_16x16x32_bf16 v[124:127], v[132:135], v[190:193], v[124:127]
	v_mfma_f32_16x16x32_bf16 v[120:123], v[156:159], v[190:193], v[120:123]
	v_mfma_f32_16x16x32_bf16 v[108:111], v[132:135], v[200:203], v[108:111]
	v_mfma_f32_16x16x32_bf16 v[104:107], v[156:159], v[200:203], v[104:107]
	v_mfma_f32_16x16x32_bf16 v[92:95], v[132:135], v[208:211], v[92:95]
	v_mfma_f32_16x16x32_bf16 v[88:91], v[156:159], v[208:211], v[88:91]
	v_mfma_f32_16x16x32_bf16 v[76:79], v[132:135], v[216:219], v[76:79]
	v_mfma_f32_16x16x32_bf16 v[72:75], v[156:159], v[216:219], v[72:75]
	v_mfma_f32_16x16x32_bf16 v[116:119], v[170:173], v[186:189], v[116:119]
	v_mfma_f32_16x16x32_bf16 v[112:115], v[178:181], v[186:189], v[112:115]
	v_mfma_f32_16x16x32_bf16 v[100:103], v[170:173], v[194:197], v[100:103]
	v_mfma_f32_16x16x32_bf16 v[96:99], v[178:181], v[194:197], v[96:99]
	v_mfma_f32_16x16x32_bf16 v[84:87], v[170:173], v[204:207], v[84:87]
	v_mfma_f32_16x16x32_bf16 v[80:83], v[178:181], v[204:207], v[80:83]
	v_mfma_f32_16x16x32_bf16 v[68:71], v[170:173], v[212:215], v[68:71]
	v_mfma_f32_16x16x32_bf16 v[64:67], v[178:181], v[212:215], v[64:67]
	v_mfma_f32_16x16x32_bf16 v[116:119], v[174:177], v[190:193], v[116:119]
	v_mfma_f32_16x16x32_bf16 v[112:115], v[182:185], v[190:193], v[112:115]
	v_mfma_f32_16x16x32_bf16 v[100:103], v[174:177], v[200:203], v[100:103]
	v_mfma_f32_16x16x32_bf16 v[96:99], v[182:185], v[200:203], v[96:99]
	v_mfma_f32_16x16x32_bf16 v[84:87], v[174:177], v[208:211], v[84:87]
	v_mfma_f32_16x16x32_bf16 v[80:83], v[182:185], v[208:211], v[80:83]
	v_mfma_f32_16x16x32_bf16 v[68:71], v[174:177], v[216:219], v[68:71]
	v_mfma_f32_16x16x32_bf16 v[64:67], v[182:185], v[216:219], v[64:67]
	s_setprio 0
	s_barrier
; #define PG8_STAGE(bufoff, gbase, voff) do { _Pragma("unroll") for (int _i = 0; _i < 2; ++_i) \
;         __builtin_amdgcn_global_load_lds((const unsigned*)((const char*)(gbase) + (voff)[_i]), (PG8_LAS unsigned*)(lds + (bufoff) + ldsw + _i * 8192), 16, 0, 0); } while (0)
; #define PG8_LDA(dst, b, h) do { _Pragma("unroll") for (int m = 0; m < 4; ++m) _Pragma("unroll") for (int k = 0; k < 2; ++k) dst[m][k] = *(const PG8_LAS bf16x8*)(lds + PG8_SA(b, h) + aoff + m * 2048 + k * 1024); } while (0)
; #define PG8_MMA(ai, bj, At, Bt) do { __builtin_amdgcn_s_setprio(1); _Pragma("unroll") for (int m = 0; m < 4; ++m) _Pragma("unroll") for (int n = 0; n < 2; ++n) _Pragma("unroll") for (int k = 0; k < 2; ++k) \
;         acc[ai][bj][m][n] = __builtin_amdgcn_mfma_f32_16x16x32_bf16(Bt[n][k], At[m][k], acc[ai][bj][m][n], 0, 0, 0); __builtin_amdgcn_s_setprio(0); } while (0)
; #define PG8_WAIT_V(n) asm volatile("s_waitcnt vmcnt(" #n ")" ::: "memory")
; #define PG8_WAIT_L(n) asm volatile("s_waitcnt lgkmcnt(" #n ")" ::: "memory")
; #define PG8_BAR __builtin_amdgcn_s_barrier()
; #define PG8_SCHED __builtin_amdgcn_sched_barrier(0)
; template <class Epi, class Sched>
; __device__ __forceinline__ void gemm_phase(PG8_LAS unsigned char* lds, const Gemm g, const Sched& S, const Epi& E) {
;     ...
;             PG8_LDA(At, 1, 1); PG8_STAGE(PG8_SB(1, 0), b3, voffB); PG8_STAGE(PG8_SB(1, 1), b3 + hstepB, voffB); PG8_STAGE(PG8_SA(1, 0), a3, voffA);
;             PG8_WAIT_V(8); PG8_WAIT_L(0); PG8_BAR; PG8_MMA(1, 0, At, B0); PG8_MMA(1, 1, At, B1); PG8_BAR; PG8_SCHED;
;         }
;         if (wr == 0) PG8_BAR;
	s_add_i32 s34, s55, s33
	v_lshl_add_u64 v[160:161], v[160:161], 0, s[12:13]
	s_mov_b32 m0, s34
	ds_read_b128 v[186:189], v167 offset:49152
	ds_read_b128 v[190:193], v167 offset:50176
	ds_read_b128 v[194:197], v167 offset:51200
	ds_read_b128 v[200:203], v167 offset:52224
	ds_read_b128 v[204:207], v167 offset:53248
	ds_read_b128 v[208:211], v167 offset:54272
	ds_read_b128 v[212:215], v167 offset:55296
	ds_read_b128 v[216:219], v167 offset:56320
	global_load_lds_dwordx4 v[160:161], off
	s_add_i32 m0, s34, 0x2000
	s_add_u32 s30, s30, 0x40080
	v_lshl_add_u64 v[160:161], v[220:221], 0, s[12:13]
	s_addc_u32 s31, s31, 0
	s_add_i32 s34, s56, s33
	global_load_lds_dwordx4 v[160:161], off
	v_lshl_add_u64 v[160:161], s[30:31], 0, v[138:139]
	s_mov_b32 m0, s34
	s_nop 0
	global_load_lds_dwordx4 v[160:161], off
	v_lshl_add_u64 v[160:161], s[30:31], 0, v[142:143]
	s_add_i32 m0, s34, 0x2000
	s_nop 0
	global_load_lds_dwordx4 v[160:161], off
	v_lshl_add_u64 v[160:161], v[222:223], 0, s[12:13]
	s_mov_b32 m0, s41
	s_nop 0
	global_load_lds_dwordx4 v[160:161], off
	v_lshl_add_u64 v[160:161], v[224:225], 0, s[12:13]
	s_mov_b32 m0, s42
	s_nop 0
	global_load_lds_dwordx4 v[160:161], off
	s_waitcnt vmcnt(8)
	s_waitcnt lgkmcnt(0)
	s_barrier
	s_setprio 1
	s_waitcnt lgkmcnt(0)
	v_mfma_f32_16x16x32_bf16 v[60:63], v[128:131], v[186:189], v[60:63]
	v_mfma_f32_16x16x32_bf16 v[56:59], v[152:155], v[186:189], v[56:59]
	v_mfma_f32_16x16x32_bf16 v[44:47], v[128:131], v[194:197], v[44:47]
	v_mfma_f32_16x16x32_bf16 v[40:43], v[152:155], v[194:197], v[40:43]
	v_mfma_f32_16x16x32_bf16 v[28:31], v[128:131], v[204:207], v[28:31]
	v_mfma_f32_16x16x32_bf16 v[24:27], v[152:155], v[204:207], v[24:27]
	v_mfma_f32_16x16x32_bf16 v[12:15], v[128:131], v[212:215], v[12:15]
	v_mfma_f32_16x16x32_bf16 v[8:11], v[152:155], v[212:215], v[8:11]
	v_mfma_f32_16x16x32_bf16 v[60:63], v[132:135], v[190:193], v[60:63]
	v_mfma_f32_16x16x32_bf16 v[56:59], v[156:159], v[190:193], v[56:59]
	v_mfma_f32_16x16x32_bf16 v[44:47], v[132:135], v[200:203], v[44:47]
	v_mfma_f32_16x16x32_bf16 v[40:43], v[156:159], v[200:203], v[40:43]
	v_mfma_f32_16x16x32_bf16 v[28:31], v[132:135], v[208:211], v[28:31]
	v_mfma_f32_16x16x32_bf16 v[24:27], v[156:159], v[208:211], v[24:27]
	v_mfma_f32_16x16x32_bf16 v[12:15], v[132:135], v[216:219], v[12:15]
	v_mfma_f32_16x16x32_bf16 v[8:11], v[156:159], v[216:219], v[8:11]
	v_mfma_f32_16x16x32_bf16 v[52:55], v[170:173], v[186:189], v[52:55]
	v_mfma_f32_16x16x32_bf16 v[48:51], v[178:181], v[186:189], v[48:51]
	v_mfma_f32_16x16x32_bf16 v[36:39], v[170:173], v[194:197], v[36:39]
	v_mfma_f32_16x16x32_bf16 v[32:35], v[178:181], v[194:197], v[32:35]
	v_mfma_f32_16x16x32_bf16 v[20:23], v[170:173], v[204:207], v[20:23]
	v_mfma_f32_16x16x32_bf16 v[16:19], v[178:181], v[204:207], v[16:19]
	v_mfma_f32_16x16x32_bf16 v[4:7], v[170:173], v[212:215], v[4:7]
	v_mfma_f32_16x16x32_bf16 v[0:3], v[178:181], v[212:215], v[0:3]
	v_mfma_f32_16x16x32_bf16 v[52:55], v[174:177], v[190:193], v[52:55]
	v_mfma_f32_16x16x32_bf16 v[48:51], v[182:185], v[190:193], v[48:51]
	v_mfma_f32_16x16x32_bf16 v[36:39], v[174:177], v[200:203], v[36:39]
	v_mfma_f32_16x16x32_bf16 v[32:35], v[182:185], v[200:203], v[32:35]
	v_mfma_f32_16x16x32_bf16 v[20:23], v[174:177], v[208:211], v[20:23]
	v_mfma_f32_16x16x32_bf16 v[16:19], v[182:185], v[208:211], v[16:19]
	v_mfma_f32_16x16x32_bf16 v[4:7], v[174:177], v[216:219], v[4:7]
	v_mfma_f32_16x16x32_bf16 v[0:3], v[182:185], v[216:219], v[0:3]
	s_setprio 0
	s_barrier
	s_add_i32 s54, s54, 2
	s_add_u32 s28, s28, 0x100
	s_addc_u32 s29, s29, 0
	s_add_u32 s52, s52, 0x100
	s_addc_u32 s53, s53, 0
	s_cmp_gt_u32 s54, 13
	s_cbranch_scc0 .LBB0_3104
	s_and_b64 vcc, exec, s[14:15]
	s_cbranch_vccz .LBB0_3107
	s_barrier

; #define PG8_STAGE(bufoff, gbase, voff) do { _Pragma("unroll") for (int _i = 0; _i < 2; ++_i) \
;         __builtin_amdgcn_global_load_lds((const unsigned*)((const char*)(gbase) + (voff)[_i]), (PG8_LAS unsigned*)(lds + (bufoff) + ldsw + _i * 8192), 16, 0, 0); } while (0)
; #define PG8_LDA(dst, b, h) do { _Pragma("unroll") for (int m = 0; m < 4; ++m) _Pragma("unroll") for (int k = 0; k < 2; ++k) dst[m][k] = *(const PG8_LAS bf16x8*)(lds + PG8_SA(b, h) + aoff + m * 2048 + k * 1024); } while (0)
; #define PG8_LDB(dst, b, h) do { _Pragma("unroll") for (int n = 0; n < 2; ++n) _Pragma("unroll") for (int k = 0; k < 2; ++k) dst[n][k] = *(const PG8_LAS bf16x8*)(lds + PG8_SB(b, h) + boff + n * 2048 + k * 1024); } while (0)
; #define PG8_MMA(ai, bj, At, Bt) do { __builtin_amdgcn_s_setprio(1); _Pragma("unroll") for (int m = 0; m < 4; ++m) _Pragma("unroll") for (int n = 0; n < 2; ++n) _Pragma("unroll") for (int k = 0; k < 2; ++k) \
;         acc[ai][bj][m][n] = __builtin_amdgcn_mfma_f32_16x16x32_bf16(Bt[n][k], At[m][k], acc[ai][bj][m][n], 0, 0, 0); __builtin_amdgcn_s_setprio(0); } while (0)
; #define PG8_WAIT_V(n) asm volatile("s_waitcnt vmcnt(" #n ")" ::: "memory")
; #define PG8_WAIT_L(n) asm volatile("s_waitcnt lgkmcnt(" #n ")" ::: "memory")
; template <class Epi, class Sched>
; __device__ __forceinline__ void gemm_phase(PG8_LAS unsigned char* lds, const Gemm g, const Sched& S, const Epi& E) {
;     ...
;         for (int t = 0; t < nt; t += 2) {
;             const bool last = (t == nt - 2);
;             const char* a1 = cA + (size_t)(t + 1) * kstepA;
;             const char* a2 = last ? nA : cA + (size_t)(t + 2) * kstepA; const char* b2 = last ? nB : cB + (size_t)(t + 2) * kstep;
;             const char* a3 = a2 + kstepA; const char* b3 = b2 + kstep;
;             if constexpr (epi_has_hook<Epi>::value) { if (t == nt / 2) E.hook(acc, cur, wr, wc, fr, fq); }
;             PG8_LDB(B0, 0, 0); PG8_LDB(B1, 0, 1); PG8_SCHED; PG8_LDA(At, 0, 0); PG8_STAGE(PG8_SA(1, 1), a1 + hstepA, voffA);
;             PG8_WAIT_V(8); PG8_WAIT_L(0); PG8_BAR; PG8_MMA(0, 0, At, B0); PG8_MMA(0, 1, At, B1); PG8_BAR; PG8_SCHED;
;             PG8_LDA(At, 0, 1); PG8_STAGE(PG8_SB(0, 0), b2, voffB); PG8_STAGE(PG8_SB(0, 1), b2 + hstepB, voffB); PG8_STAGE(PG8_SA(0, 0), a2, voffA);
;             PG8_WAIT_V(8); PG8_WAIT_L(0); PG8_BAR; PG8_MMA(1, 0, At, B0); PG8_MMA(1, 1, At, B1); PG8_BAR; PG8_SCHED;
.LBB0_3188:
	ds_read_b128 v[144:147], v157
	ds_read_b128 v[162:165], v157 offset:1024
	ds_read_b128 v[166:169], v157 offset:2048
	ds_read_b128 v[170:173], v157 offset:3072
	ds_read_b128 v[174:177], v158
	ds_read_b128 v[178:181], v158 offset:1024
	ds_read_b128 v[182:185], v158 offset:2048
	ds_read_b128 v[186:189], v158 offset:3072
	s_add_u32 s26, s24, 0xfffc0080
	s_addc_u32 s27, s25, -1
	s_cmp_eq_u32 s50, 12
	s_cselect_b32 s29, s11, s27
	s_cselect_b32 s28, s13, s26
	s_cselect_b32 s27, s46, s49
	s_cselect_b32 s26, s47, s48
	v_lshl_add_u64 v[150:151], s[24:25], 0, v[136:137]
	s_add_i32 m0, s23, 0xc000
	ds_read_b128 v[190:193], v159
	ds_read_b128 v[194:197], v159 offset:1024
	ds_read_b128 v[200:203], v159 offset:2048
	ds_read_b128 v[204:207], v159 offset:3072
	ds_read_b128 v[208:211], v159 offset:4096
	ds_read_b128 v[212:215], v159 offset:5120
	ds_read_b128 v[216:219], v159 offset:6144
	ds_read_b128 v[220:223], v159 offset:7168
	global_load_lds_dwordx4 v[150:151], off
	v_lshl_add_u64 v[150:151], s[24:25], 0, v[138:139]
	s_add_i32 m0, s23, 0xe000
	s_nop 0
	global_load_lds_dwordx4 v[150:151], off
	s_waitcnt vmcnt(8)
	s_waitcnt lgkmcnt(0)
	s_barrier
	s_setprio 1
	s_waitcnt lgkmcnt(0)
	v_mfma_f32_16x16x32_bf16 v[124:127], v[144:147], v[190:193], v[124:127]
	v_mfma_f32_16x16x32_bf16 v[116:119], v[166:169], v[190:193], v[116:119]
	v_mfma_f32_16x16x32_bf16 v[108:111], v[144:147], v[200:203], v[108:111]
	v_mfma_f32_16x16x32_bf16 v[100:103], v[166:169], v[200:203], v[100:103]
	v_mfma_f32_16x16x32_bf16 v[92:95], v[144:147], v[208:211], v[92:95]
	v_mfma_f32_16x16x32_bf16 v[84:87], v[166:169], v[208:211], v[84:87]
	v_mfma_f32_16x16x32_bf16 v[76:79], v[144:147], v[216:219], v[76:79]
	v_mfma_f32_16x16x32_bf16 v[68:71], v[166:169], v[216:219], v[68:71]
	v_mfma_f32_16x16x32_bf16 v[124:127], v[162:165], v[194:197], v[124:127]
	v_mfma_f32_16x16x32_bf16 v[116:119], v[170:173], v[194:197], v[116:119]
	v_mfma_f32_16x16x32_bf16 v[108:111], v[162:165], v[204:207], v[108:111]
	v_mfma_f32_16x16x32_bf16 v[100:103], v[170:173], v[204:207], v[100:103]
	v_mfma_f32_16x16x32_bf16 v[92:95], v[162:165], v[212:215], v[92:95]
	v_mfma_f32_16x16x32_bf16 v[84:87], v[170:173], v[212:215], v[84:87]
	v_mfma_f32_16x16x32_bf16 v[76:79], v[162:165], v[220:223], v[76:79]
	v_mfma_f32_16x16x32_bf16 v[68:71], v[170:173], v[220:223], v[68:71]
	v_mfma_f32_16x16x32_bf16 v[120:123], v[174:177], v[190:193], v[120:123]
	v_mfma_f32_16x16x32_bf16 v[112:115], v[182:185], v[190:193], v[112:115]
	v_mfma_f32_16x16x32_bf16 v[104:107], v[174:177], v[200:203], v[104:107]
	v_mfma_f32_16x16x32_bf16 v[96:99], v[182:185], v[200:203], v[96:99]
	v_mfma_f32_16x16x32_bf16 v[88:91], v[174:177], v[208:211], v[88:91]
	v_mfma_f32_16x16x32_bf16 v[80:83], v[182:185], v[208:211], v[80:83]
	v_mfma_f32_16x16x32_bf16 v[72:75], v[174:177], v[216:219], v[72:75]
	v_mfma_f32_16x16x32_bf16 v[64:67], v[182:185], v[216:219], v[64:67]
	v_mfma_f32_16x16x32_bf16 v[120:123], v[178:181], v[194:197], v[120:123]
	v_mfma_f32_16x16x32_bf16 v[112:115], v[186:189], v[194:197], v[112:115]
	v_mfma_f32_16x16x32_bf16 v[104:107], v[178:181], v[204:207], v[104:107]
	v_mfma_f32_16x16x32_bf16 v[96:99], v[186:189], v[204:207], v[96:99]
	v_mfma_f32_16x16x32_bf16 v[88:91], v[178:181], v[212:215], v[88:91]
	v_mfma_f32_16x16x32_bf16 v[80:83], v[186:189], v[212:215], v[80:83]
	v_mfma_f32_16x16x32_bf16 v[72:75], v[178:181], v[220:223], v[72:75]
	v_mfma_f32_16x16x32_bf16 v[64:67], v[186:189], v[220:223], v[64:67]
	s_setprio 0
	s_barrier
	s_add_i32 s51, s42, s30
	v_lshl_add_u64 v[150:151], s[26:27], 0, v[132:133]
	s_mov_b32 m0, s51
	ds_read_b128 v[190:193], v159 offset:16384
	ds_read_b128 v[194:197], v159 offset:17408
	ds_read_b128 v[200:203], v159 offset:18432
	ds_read_b128 v[204:207], v159 offset:19456
	ds_read_b128 v[208:211], v159 offset:20480
	ds_read_b128 v[212:215], v159 offset:21504
	ds_read_b128 v[216:219], v159 offset:22528
	ds_read_b128 v[220:223], v159 offset:23552
	global_load_lds_dwordx4 v[150:151], off
	s_add_i32 m0, s51, 0x2000
	s_add_u32 s52, s26, 0x40000
	v_lshl_add_u64 v[154:155], s[26:27], 0, v[128:129]
	s_addc_u32 s53, s27, 0
	s_add_i32 s51, s43, s30
	global_load_lds_dwordx4 v[154:155], off
	v_lshl_add_u64 v[224:225], s[52:53], 0, v[132:133]
	s_mov_b32 m0, s51
	v_lshl_add_u64 v[226:227], s[28:29], 0, v[130:131]
	global_load_lds_dwordx4 v[224:225], off
	v_lshl_add_u64 v[224:225], s[52:53], 0, v[128:129]
	s_add_i32 m0, s51, 0x2000
	s_nop 0
	global_load_lds_dwordx4 v[224:225], off
	v_lshl_add_u64 v[224:225], s[28:29], 0, v[134:135]
	s_mov_b32 m0, s23
	s_nop 0
	global_load_lds_dwordx4 v[224:225], off
	s_mov_b32 m0, s34
	s_nop 0
	global_load_lds_dwordx4 v[226:227], off
	s_waitcnt vmcnt(8)
	s_waitcnt lgkmcnt(0)
	s_barrier
; #define PG8_STAGE(bufoff, gbase, voff) do { _Pragma("unroll") for (int _i = 0; _i < 2; ++_i) \
;         __builtin_amdgcn_global_load_lds((const unsigned*)((const char*)(gbase) + (voff)[_i]), (PG8_LAS unsigned*)(lds + (bufoff) + ldsw + _i * 8192), 16, 0, 0); } while (0)
; #define PG8_LDA(dst, b, h) do { _Pragma("unroll") for (int m = 0; m < 4; ++m) _Pragma("unroll") for (int k = 0; k < 2; ++k) dst[m][k] = *(const PG8_LAS bf16x8*)(lds + PG8_SA(b, h) + aoff + m * 2048 + k * 1024); } while (0)
; #define PG8_LDB(dst, b, h) do { _Pragma("unroll") for (int n = 0; n < 2; ++n) _Pragma("unroll") for (int k = 0; k < 2; ++k) dst[n][k] = *(const PG8_LAS bf16x8*)(lds + PG8_SB(b, h) + boff + n * 2048 + k * 1024); } while (0)
; #define PG8_MMA(ai, bj, At, Bt) do { __builtin_amdgcn_s_setprio(1); _Pragma("unroll") for (int m = 0; m < 4; ++m) _Pragma("unroll") for (int n = 0; n < 2; ++n) _Pragma("unroll") for (int k = 0; k < 2; ++k) \
;         acc[ai][bj][m][n] = __builtin_amdgcn_mfma_f32_16x16x32_bf16(Bt[n][k], At[m][k], acc[ai][bj][m][n], 0, 0, 0); __builtin_amdgcn_s_setprio(0); } while (0)
; #define PG8_WAIT_V(n) asm volatile("s_waitcnt vmcnt(" #n ")" ::: "memory")
; #define PG8_WAIT_L(n) asm volatile("s_waitcnt lgkmcnt(" #n ")" ::: "memory")
; #define PG8_BAR __builtin_amdgcn_s_barrier()
; #define PG8_SCHED __builtin_amdgcn_sched_barrier(0)
; template <class Epi, class Sched>
; __device__ __forceinline__ void gemm_phase(PG8_LAS unsigned char* lds, const Gemm g, const Sched& S, const Epi& E) {
;     ...
;             PG8_WAIT_V(8); PG8_WAIT_L(0); PG8_BAR; PG8_MMA(1, 0, At, B0); PG8_MMA(1, 1, At, B1); PG8_BAR; PG8_SCHED;
;             PG8_LDB(B0, 1, 0); PG8_LDB(B1, 1, 1); PG8_SCHED; PG8_LDA(At, 1, 0); PG8_STAGE(PG8_SA(0, 1), a2 + hstepA, voffA);
;             PG8_WAIT_V(8); PG8_WAIT_L(0); PG8_BAR; PG8_MMA(0, 0, At, B0); PG8_MMA(0, 1, At, B1); PG8_BAR; PG8_SCHED;
	s_setprio 1
	s_waitcnt lgkmcnt(0)
	v_mfma_f32_16x16x32_bf16 v[60:63], v[144:147], v[190:193], v[60:63]
	v_mfma_f32_16x16x32_bf16 v[52:55], v[166:169], v[190:193], v[52:55]
	v_mfma_f32_16x16x32_bf16 v[44:47], v[144:147], v[200:203], v[44:47]
	v_mfma_f32_16x16x32_bf16 v[36:39], v[166:169], v[200:203], v[36:39]
	v_mfma_f32_16x16x32_bf16 v[28:31], v[144:147], v[208:211], v[28:31]
	v_mfma_f32_16x16x32_bf16 v[20:23], v[166:169], v[208:211], v[20:23]
	v_mfma_f32_16x16x32_bf16 v[12:15], v[144:147], v[216:219], v[12:15]
	v_mfma_f32_16x16x32_bf16 v[4:7], v[166:169], v[216:219], v[4:7]
	v_mfma_f32_16x16x32_bf16 v[60:63], v[162:165], v[194:197], v[60:63]
	v_mfma_f32_16x16x32_bf16 v[52:55], v[170:173], v[194:197], v[52:55]
	v_mfma_f32_16x16x32_bf16 v[44:47], v[162:165], v[204:207], v[44:47]
	v_mfma_f32_16x16x32_bf16 v[36:39], v[170:173], v[204:207], v[36:39]
	v_mfma_f32_16x16x32_bf16 v[28:31], v[162:165], v[212:215], v[28:31]
	v_mfma_f32_16x16x32_bf16 v[20:23], v[170:173], v[212:215], v[20:23]
	v_mfma_f32_16x16x32_bf16 v[12:15], v[162:165], v[220:223], v[12:15]
	v_mfma_f32_16x16x32_bf16 v[4:7], v[170:173], v[220:223], v[4:7]
	v_mfma_f32_16x16x32_bf16 v[56:59], v[174:177], v[190:193], v[56:59]
	v_mfma_f32_16x16x32_bf16 v[48:51], v[182:185], v[190:193], v[48:51]
	v_mfma_f32_16x16x32_bf16 v[40:43], v[174:177], v[200:203], v[40:43]
	v_mfma_f32_16x16x32_bf16 v[32:35], v[182:185], v[200:203], v[32:35]
	v_mfma_f32_16x16x32_bf16 v[24:27], v[174:177], v[208:211], v[24:27]
	v_mfma_f32_16x16x32_bf16 v[16:19], v[182:185], v[208:211], v[16:19]
	v_mfma_f32_16x16x32_bf16 v[8:11], v[174:177], v[216:219], v[8:11]
	v_mfma_f32_16x16x32_bf16 v[0:3], v[182:185], v[216:219], v[0:3]
	v_mfma_f32_16x16x32_bf16 v[56:59], v[178:181], v[194:197], v[56:59]
	v_mfma_f32_16x16x32_bf16 v[48:51], v[186:189], v[194:197], v[48:51]
	v_mfma_f32_16x16x32_bf16 v[40:43], v[178:181], v[204:207], v[40:43]
	v_mfma_f32_16x16x32_bf16 v[32:35], v[186:189], v[204:207], v[32:35]
	v_mfma_f32_16x16x32_bf16 v[24:27], v[178:181], v[212:215], v[24:27]
	v_mfma_f32_16x16x32_bf16 v[16:19], v[186:189], v[212:215], v[16:19]
	v_mfma_f32_16x16x32_bf16 v[8:11], v[178:181], v[220:223], v[8:11]
	v_mfma_f32_16x16x32_bf16 v[0:3], v[186:189], v[220:223], v[0:3]
	s_setprio 0
	s_barrier
	s_add_i32 s51, 0, 0x18000
	v_add_u32_e32 v148, s51, v153
	s_add_i32 s52, 0, 0x1c000
	ds_read_b128 v[144:147], v148
	ds_read_b128 v[162:165], v148 offset:1024
	ds_read_b128 v[166:169], v148 offset:2048
	ds_read_b128 v[170:173], v148 offset:3072
	v_add_u32_e32 v148, s52, v153
	ds_read_b128 v[174:177], v148
	ds_read_b128 v[178:181], v148 offset:1024
	ds_read_b128 v[182:185], v148 offset:2048
	ds_read_b128 v[186:189], v148 offset:3072
	s_add_u32 s28, s28, 0x40000
	s_addc_u32 s29, s29, 0
	s_mov_b32 m0, s35
	v_lshl_add_u64 v[228:229], s[28:29], 0, v[134:135]
	ds_read_b128 v[190:193], v159 offset:32768
	ds_read_b128 v[194:197], v159 offset:33792
	ds_read_b128 v[200:203], v159 offset:34816
	ds_read_b128 v[204:207], v159 offset:35840
	ds_read_b128 v[208:211], v159 offset:36864
	ds_read_b128 v[212:215], v159 offset:37888
	ds_read_b128 v[216:219], v159 offset:38912
	ds_read_b128 v[220:223], v159 offset:39936
	global_load_lds_dwordx4 v[228:229], off
	v_lshl_add_u64 v[228:229], s[28:29], 0, v[130:131]
	s_mov_b32 m0, s36
	s_nop 0
	global_load_lds_dwordx4 v[228:229], off
	s_waitcnt vmcnt(8)
	s_waitcnt lgkmcnt(0)
	s_barrier
	s_setprio 1
	s_waitcnt lgkmcnt(0)
	v_mfma_f32_16x16x32_bf16 v[124:127], v[144:147], v[190:193], v[124:127]
	v_mfma_f32_16x16x32_bf16 v[116:119], v[166:169], v[190:193], v[116:119]
	v_mfma_f32_16x16x32_bf16 v[108:111], v[144:147], v[200:203], v[108:111]
	v_mfma_f32_16x16x32_bf16 v[100:103], v[166:169], v[200:203], v[100:103]
	v_mfma_f32_16x16x32_bf16 v[92:95], v[144:147], v[208:211], v[92:95]
	v_mfma_f32_16x16x32_bf16 v[84:87], v[166:169], v[208:211], v[84:87]
	v_mfma_f32_16x16x32_bf16 v[76:79], v[144:147], v[216:219], v[76:79]
	v_mfma_f32_16x16x32_bf16 v[68:71], v[166:169], v[216:219], v[68:71]
	v_mfma_f32_16x16x32_bf16 v[124:127], v[162:165], v[194:197], v[124:127]
	v_mfma_f32_16x16x32_bf16 v[116:119], v[170:173], v[194:197], v[116:119]
	v_mfma_f32_16x16x32_bf16 v[108:111], v[162:165], v[204:207], v[108:111]
	v_mfma_f32_16x16x32_bf16 v[100:103], v[170:173], v[204:207], v[100:103]
	v_mfma_f32_16x16x32_bf16 v[92:95], v[162:165], v[212:215], v[92:95]
	v_mfma_f32_16x16x32_bf16 v[84:87], v[170:173], v[212:215], v[84:87]
	v_mfma_f32_16x16x32_bf16 v[76:79], v[162:165], v[220:223], v[76:79]
	v_mfma_f32_16x16x32_bf16 v[68:71], v[170:173], v[220:223], v[68:71]
	v_mfma_f32_16x16x32_bf16 v[120:123], v[174:177], v[190:193], v[120:123]
	v_mfma_f32_16x16x32_bf16 v[112:115], v[182:185], v[190:193], v[112:115]
	v_mfma_f32_16x16x32_bf16 v[104:107], v[174:177], v[200:203], v[104:107]
	v_mfma_f32_16x16x32_bf16 v[96:99], v[182:185], v[200:203], v[96:99]
	v_mfma_f32_16x16x32_bf16 v[88:91], v[174:177], v[208:211], v[88:91]
	v_mfma_f32_16x16x32_bf16 v[80:83], v[182:185], v[208:211], v[80:83]
	v_mfma_f32_16x16x32_bf16 v[72:75], v[174:177], v[216:219], v[72:75]
	v_mfma_f32_16x16x32_bf16 v[64:67], v[182:185], v[216:219], v[64:67]
	v_mfma_f32_16x16x32_bf16 v[120:123], v[178:181], v[194:197], v[120:123]
	v_mfma_f32_16x16x32_bf16 v[112:115], v[186:189], v[194:197], v[112:115]
	v_mfma_f32_16x16x32_bf16 v[104:107], v[178:181], v[204:207], v[104:107]
	v_mfma_f32_16x16x32_bf16 v[96:99], v[186:189], v[204:207], v[96:99]
	v_mfma_f32_16x16x32_bf16 v[88:91], v[178:181], v[212:215], v[88:91]
	v_mfma_f32_16x16x32_bf16 v[80:83], v[186:189], v[212:215], v[80:83]
	v_mfma_f32_16x16x32_bf16 v[72:75], v[178:181], v[220:223], v[72:75]
	v_mfma_f32_16x16x32_bf16 v[64:67], v[186:189], v[220:223], v[64:67]
	s_setprio 0
	s_barrier
; #define PG8_STAGE(bufoff, gbase, voff) do { _Pragma("unroll") for (int _i = 0; _i < 2; ++_i) \
;         __builtin_amdgcn_global_load_lds((const unsigned*)((const char*)(gbase) + (voff)[_i]), (PG8_LAS unsigned*)(lds + (bufoff) + ldsw + _i * 8192), 16, 0, 0); } while (0)
; #define PG8_LDA(dst, b, h) do { _Pragma("unroll") for (int m = 0; m < 4; ++m) _Pragma("unroll") for (int k = 0; k < 2; ++k) dst[m][k] = *(const PG8_LAS bf16x8*)(lds + PG8_SA(b, h) + aoff + m * 2048 + k * 1024); } while (0)
; #define PG8_MMA(ai, bj, At, Bt) do { __builtin_amdgcn_s_setprio(1); _Pragma("unroll") for (int m = 0; m < 4; ++m) _Pragma("unroll") for (int n = 0; n < 2; ++n) _Pragma("unroll") for (int k = 0; k < 2; ++k) \
;         acc[ai][bj][m][n] = __builtin_amdgcn_mfma_f32_16x16x32_bf16(Bt[n][k], At[m][k], acc[ai][bj][m][n], 0, 0, 0); __builtin_amdgcn_s_setprio(0); } while (0)
; #define PG8_WAIT_V(n) asm volatile("s_waitcnt vmcnt(" #n ")" ::: "memory")
; #define PG8_WAIT_L(n) asm volatile("s_waitcnt lgkmcnt(" #n ")" ::: "memory")
; #define PG8_BAR __builtin_amdgcn_s_barrier()
; #define PG8_SCHED __builtin_amdgcn_sched_barrier(0)
; template <class Epi, class Sched>
; __device__ __forceinline__ void gemm_phase(PG8_LAS unsigned char* lds, const Gemm g, const Sched& S, const Epi& E) {
;     ...
;             PG8_LDA(At, 1, 1); PG8_STAGE(PG8_SB(1, 0), b3, voffB); PG8_STAGE(PG8_SB(1, 1), b3 + hstepB, voffB); PG8_STAGE(PG8_SA(1, 0), a3, voffA);
;             PG8_WAIT_V(8); PG8_WAIT_L(0); PG8_BAR; PG8_MMA(1, 0, At, B0); PG8_MMA(1, 1, At, B1); PG8_BAR; PG8_SCHED;
;         }
;         if (wr == 0) PG8_BAR;
	s_add_i32 s28, s51, s30
	v_lshl_add_u64 v[150:151], v[150:151], 0, s[4:5]
	s_mov_b32 m0, s28
	ds_read_b128 v[190:193], v159 offset:49152
	ds_read_b128 v[194:197], v159 offset:50176
	ds_read_b128 v[200:203], v159 offset:51200
	ds_read_b128 v[204:207], v159 offset:52224
	ds_read_b128 v[208:211], v159 offset:53248
	ds_read_b128 v[212:215], v159 offset:54272
	ds_read_b128 v[216:219], v159 offset:55296
	ds_read_b128 v[220:223], v159 offset:56320
	global_load_lds_dwordx4 v[150:151], off
	s_add_i32 m0, s28, 0x2000
	s_add_u32 s26, s26, 0x40080
	v_lshl_add_u64 v[150:151], v[154:155], 0, s[4:5]
	s_addc_u32 s27, s27, 0
	s_add_i32 s28, s52, s30
	global_load_lds_dwordx4 v[150:151], off
	v_lshl_add_u64 v[150:151], s[26:27], 0, v[132:133]
	s_mov_b32 m0, s28
	s_nop 0
	global_load_lds_dwordx4 v[150:151], off
	v_lshl_add_u64 v[150:151], s[26:27], 0, v[128:129]
	s_add_i32 m0, s28, 0x2000
	s_nop 0
	global_load_lds_dwordx4 v[150:151], off
	v_lshl_add_u64 v[150:151], v[224:225], 0, s[4:5]
	s_mov_b32 m0, s38
	s_nop 0
	global_load_lds_dwordx4 v[150:151], off
	v_lshl_add_u64 v[150:151], v[226:227], 0, s[4:5]
	s_mov_b32 m0, s39
	s_nop 0
	global_load_lds_dwordx4 v[150:151], off
	s_waitcnt vmcnt(8)
	s_waitcnt lgkmcnt(0)
	s_barrier
	s_setprio 1
	s_waitcnt lgkmcnt(0)
	v_mfma_f32_16x16x32_bf16 v[60:63], v[144:147], v[190:193], v[60:63]
	v_mfma_f32_16x16x32_bf16 v[52:55], v[166:169], v[190:193], v[52:55]
	v_mfma_f32_16x16x32_bf16 v[44:47], v[144:147], v[200:203], v[44:47]
	v_mfma_f32_16x16x32_bf16 v[36:39], v[166:169], v[200:203], v[36:39]
	v_mfma_f32_16x16x32_bf16 v[28:31], v[144:147], v[208:211], v[28:31]
	v_mfma_f32_16x16x32_bf16 v[20:23], v[166:169], v[208:211], v[20:23]
	v_mfma_f32_16x16x32_bf16 v[12:15], v[144:147], v[216:219], v[12:15]
	v_mfma_f32_16x16x32_bf16 v[4:7], v[166:169], v[216:219], v[4:7]
	v_mfma_f32_16x16x32_bf16 v[60:63], v[162:165], v[194:197], v[60:63]
	v_mfma_f32_16x16x32_bf16 v[52:55], v[170:173], v[194:197], v[52:55]
	v_mfma_f32_16x16x32_bf16 v[44:47], v[162:165], v[204:207], v[44:47]
	v_mfma_f32_16x16x32_bf16 v[36:39], v[170:173], v[204:207], v[36:39]
	v_mfma_f32_16x16x32_bf16 v[28:31], v[162:165], v[212:215], v[28:31]
	v_mfma_f32_16x16x32_bf16 v[20:23], v[170:173], v[212:215], v[20:23]
	v_mfma_f32_16x16x32_bf16 v[12:15], v[162:165], v[220:223], v[12:15]
	v_mfma_f32_16x16x32_bf16 v[4:7], v[170:173], v[220:223], v[4:7]
	v_mfma_f32_16x16x32_bf16 v[56:59], v[174:177], v[190:193], v[56:59]
	v_mfma_f32_16x16x32_bf16 v[48:51], v[182:185], v[190:193], v[48:51]
	v_mfma_f32_16x16x32_bf16 v[40:43], v[174:177], v[200:203], v[40:43]
	v_mfma_f32_16x16x32_bf16 v[32:35], v[182:185], v[200:203], v[32:35]
	v_mfma_f32_16x16x32_bf16 v[24:27], v[174:177], v[208:211], v[24:27]
	v_mfma_f32_16x16x32_bf16 v[16:19], v[182:185], v[208:211], v[16:19]
	v_mfma_f32_16x16x32_bf16 v[8:11], v[174:177], v[216:219], v[8:11]
	v_mfma_f32_16x16x32_bf16 v[0:3], v[182:185], v[216:219], v[0:3]
	v_mfma_f32_16x16x32_bf16 v[56:59], v[178:181], v[194:197], v[56:59]
	v_mfma_f32_16x16x32_bf16 v[48:51], v[186:189], v[194:197], v[48:51]
	v_mfma_f32_16x16x32_bf16 v[40:43], v[178:181], v[204:207], v[40:43]
	v_mfma_f32_16x16x32_bf16 v[32:35], v[186:189], v[204:207], v[32:35]
	v_mfma_f32_16x16x32_bf16 v[24:27], v[178:181], v[212:215], v[24:27]
	v_mfma_f32_16x16x32_bf16 v[16:19], v[186:189], v[212:215], v[16:19]
	v_mfma_f32_16x16x32_bf16 v[8:11], v[178:181], v[220:223], v[8:11]
	v_mfma_f32_16x16x32_bf16 v[0:3], v[186:189], v[220:223], v[0:3]
	s_setprio 0
	s_barrier
	s_add_i32 s50, s50, 2
	s_add_u32 s24, s24, 0x100
	s_addc_u32 s25, s25, 0
	s_add_u32 s48, s48, 0x100
	s_addc_u32 s49, s49, 0
	s_cmp_gt_u32 s50, 13
	s_cbranch_scc0 .LBB0_3188
	s_and_b64 vcc, exec, s[6:7]
	s_cbranch_vccz .LBB0_3191
	s_barrier

; #define PG8_STAGE(bufoff, gbase, voff) do { _Pragma("unroll") for (int _i = 0; _i < 2; ++_i) \
;         __builtin_amdgcn_global_load_lds((const unsigned*)((const char*)(gbase) + (voff)[_i]), (PG8_LAS unsigned*)(lds + (bufoff) + ldsw + _i * 8192), 16, 0, 0); } while (0)
; #define PG8_LDA(dst, b, h) do { _Pragma("unroll") for (int m = 0; m < 4; ++m) _Pragma("unroll") for (int k = 0; k < 2; ++k) dst[m][k] = *(const PG8_LAS bf16x8*)(lds + PG8_SA(b, h) + aoff + m * 2048 + k * 1024); } while (0)
; #define PG8_LDB(dst, b, h) do { _Pragma("unroll") for (int n = 0; n < 2; ++n) _Pragma("unroll") for (int k = 0; k < 2; ++k) dst[n][k] = *(const PG8_LAS bf16x8*)(lds + PG8_SB(b, h) + boff + n * 2048 + k * 1024); } while (0)
; #define PG8_MMA(ai, bj, At, Bt) do { __builtin_amdgcn_s_setprio(1); _Pragma("unroll") for (int m = 0; m < 4; ++m) _Pragma("unroll") for (int n = 0; n < 2; ++n) _Pragma("unroll") for (int k = 0; k < 2; ++k) \
;         acc[ai][bj][m][n] = __builtin_amdgcn_mfma_f32_16x16x32_bf16(Bt[n][k], At[m][k], acc[ai][bj][m][n], 0, 0, 0); __builtin_amdgcn_s_setprio(0); } while (0)
; #define PG8_WAIT_V(n) asm volatile("s_waitcnt vmcnt(" #n ")" ::: "memory")
; #define PG8_WAIT_L(n) asm volatile("s_waitcnt lgkmcnt(" #n ")" ::: "memory")
; template <class Epi, class Sched>
; __device__ __forceinline__ void gemm_phase(PG8_LAS unsigned char* lds, const Gemm g, const Sched& S, const Epi& E) {
;     ...
;         for (int t = 0; t < nt; t += 2) {
;             const bool last = (t == nt - 2);
;             const char* a1 = cA + (size_t)(t + 1) * kstepA;
;             const char* a2 = last ? nA : cA + (size_t)(t + 2) * kstepA; const char* b2 = last ? nB : cB + (size_t)(t + 2) * kstep;
;             const char* a3 = a2 + kstepA; const char* b3 = b2 + kstep;
;             if constexpr (epi_has_hook<Epi>::value) { if (t == nt / 2) E.hook(acc, cur, wr, wc, fr, fq); }
;             PG8_LDB(B0, 0, 0); PG8_LDB(B1, 0, 1); PG8_SCHED; PG8_LDA(At, 0, 0); PG8_STAGE(PG8_SA(1, 1), a1 + hstepA, voffA);
;             PG8_WAIT_V(8); PG8_WAIT_L(0); PG8_BAR; PG8_MMA(0, 0, At, B0); PG8_MMA(0, 1, At, B1); PG8_BAR; PG8_SCHED;
;             PG8_LDA(At, 0, 1); PG8_STAGE(PG8_SB(0, 0), b2, voffB); PG8_STAGE(PG8_SB(0, 1), b2 + hstepB, voffB); PG8_STAGE(PG8_SA(0, 0), a2, voffA);
;             PG8_WAIT_V(8); PG8_WAIT_L(0); PG8_BAR; PG8_MMA(1, 0, At, B0); PG8_MMA(1, 1, At, B1); PG8_BAR; PG8_SCHED;
.LBB0_3264:
	ds_read_b128 v[144:147], v153
	ds_read_b128 v[156:159], v153 offset:1024
	ds_read_b128 v[160:163], v153 offset:2048
	ds_read_b128 v[164:167], v153 offset:3072
	ds_read_b128 v[168:171], v154
	ds_read_b128 v[172:175], v154 offset:1024
	ds_read_b128 v[176:179], v154 offset:2048
	ds_read_b128 v[180:183], v154 offset:3072
	s_add_u32 s18, s16, 0x100
	s_addc_u32 s19, s17, 0
	s_cmp_eq_u32 s48, 40
	s_cselect_b32 s23, s42, s19
	s_cselect_b32 s22, s43, s18
	s_cselect_b32 s21, s44, s47
	s_cselect_b32 s20, s45, s46
	v_lshl_add_u64 v[148:149], s[16:17], 0, v[136:137]
	s_add_i32 m0, s26, 0xc000
	ds_read_b128 v[184:187], v155
	ds_read_b128 v[188:191], v155 offset:1024
	ds_read_b128 v[192:195], v155 offset:2048
	ds_read_b128 v[200:203], v155 offset:3072
	ds_read_b128 v[204:207], v155 offset:4096
	ds_read_b128 v[208:211], v155 offset:5120
	ds_read_b128 v[212:215], v155 offset:6144
	ds_read_b128 v[216:219], v155 offset:7168
	global_load_lds_dwordx4 v[148:149], off
	v_lshl_add_u64 v[148:149], s[16:17], 0, v[138:139]
	s_add_i32 m0, s26, 0xe000
	s_nop 0
	global_load_lds_dwordx4 v[148:149], off
	s_waitcnt vmcnt(8)
	s_waitcnt lgkmcnt(0)
	s_barrier
	s_setprio 1
	s_waitcnt lgkmcnt(0)
	v_mfma_f32_16x16x32_bf16 v[124:127], v[144:147], v[184:187], v[124:127]
	v_mfma_f32_16x16x32_bf16 v[120:123], v[160:163], v[184:187], v[120:123]
	v_mfma_f32_16x16x32_bf16 v[116:119], v[144:147], v[192:195], v[116:119]
	v_mfma_f32_16x16x32_bf16 v[112:115], v[160:163], v[192:195], v[112:115]
	v_mfma_f32_16x16x32_bf16 v[92:95], v[144:147], v[204:207], v[92:95]
	v_mfma_f32_16x16x32_bf16 v[88:91], v[160:163], v[204:207], v[88:91]
	v_mfma_f32_16x16x32_bf16 v[84:87], v[144:147], v[212:215], v[84:87]
	v_mfma_f32_16x16x32_bf16 v[72:75], v[160:163], v[212:215], v[72:75]
	v_mfma_f32_16x16x32_bf16 v[124:127], v[156:159], v[188:191], v[124:127]
	v_mfma_f32_16x16x32_bf16 v[120:123], v[164:167], v[188:191], v[120:123]
	v_mfma_f32_16x16x32_bf16 v[116:119], v[156:159], v[200:203], v[116:119]
	v_mfma_f32_16x16x32_bf16 v[112:115], v[164:167], v[200:203], v[112:115]
	v_mfma_f32_16x16x32_bf16 v[92:95], v[156:159], v[208:211], v[92:95]
	v_mfma_f32_16x16x32_bf16 v[88:91], v[164:167], v[208:211], v[88:91]
	v_mfma_f32_16x16x32_bf16 v[84:87], v[156:159], v[216:219], v[84:87]
	v_mfma_f32_16x16x32_bf16 v[72:75], v[164:167], v[216:219], v[72:75]
	v_mfma_f32_16x16x32_bf16 v[108:111], v[168:171], v[184:187], v[108:111]
	v_mfma_f32_16x16x32_bf16 v[104:107], v[176:179], v[184:187], v[104:107]
	v_mfma_f32_16x16x32_bf16 v[100:103], v[168:171], v[192:195], v[100:103]
	v_mfma_f32_16x16x32_bf16 v[96:99], v[176:179], v[192:195], v[96:99]
	v_mfma_f32_16x16x32_bf16 v[80:83], v[168:171], v[204:207], v[80:83]
	v_mfma_f32_16x16x32_bf16 v[76:79], v[176:179], v[204:207], v[76:79]
	v_mfma_f32_16x16x32_bf16 v[68:71], v[168:171], v[212:215], v[68:71]
	v_mfma_f32_16x16x32_bf16 v[64:67], v[176:179], v[212:215], v[64:67]
	v_mfma_f32_16x16x32_bf16 v[108:111], v[172:175], v[188:191], v[108:111]
	v_mfma_f32_16x16x32_bf16 v[104:107], v[180:183], v[188:191], v[104:107]
	v_mfma_f32_16x16x32_bf16 v[100:103], v[172:175], v[200:203], v[100:103]
	v_mfma_f32_16x16x32_bf16 v[96:99], v[180:183], v[200:203], v[96:99]
	v_mfma_f32_16x16x32_bf16 v[80:83], v[172:175], v[208:211], v[80:83]
	v_mfma_f32_16x16x32_bf16 v[76:79], v[180:183], v[208:211], v[76:79]
	v_mfma_f32_16x16x32_bf16 v[68:71], v[172:175], v[216:219], v[68:71]
	v_mfma_f32_16x16x32_bf16 v[64:67], v[180:183], v[216:219], v[64:67]
	s_setprio 0
	s_barrier
	s_add_i32 s16, s36, s25
	v_lshl_add_u64 v[148:149], s[20:21], 0, v[130:131]
	s_mov_b32 m0, s16
	ds_read_b128 v[184:187], v155 offset:16384
	ds_read_b128 v[188:191], v155 offset:17408
	ds_read_b128 v[192:195], v155 offset:18432
	ds_read_b128 v[200:203], v155 offset:19456
	ds_read_b128 v[204:207], v155 offset:20480
	ds_read_b128 v[208:211], v155 offset:21504
	ds_read_b128 v[212:215], v155 offset:22528
	ds_read_b128 v[216:219], v155 offset:23552
	global_load_lds_dwordx4 v[148:149], off
	s_add_i32 m0, s16, 0x2000
	s_add_u32 s16, s20, 0xb0000
	v_lshl_add_u64 v[196:197], s[20:21], 0, v[134:135]
	s_addc_u32 s17, s21, 0
	s_add_i32 s49, s37, s25
	global_load_lds_dwordx4 v[196:197], off
	v_lshl_add_u64 v[220:221], s[16:17], 0, v[130:131]
	s_mov_b32 m0, s49
	v_lshl_add_u64 v[222:223], s[22:23], 0, v[132:133]
	global_load_lds_dwordx4 v[220:221], off
	v_lshl_add_u64 v[220:221], s[16:17], 0, v[134:135]
	s_add_i32 m0, s49, 0x2000
	s_nop 0
	global_load_lds_dwordx4 v[220:221], off
	v_lshl_add_u64 v[220:221], s[22:23], 0, v[128:129]
	s_mov_b32 m0, s26
	s_nop 0
	global_load_lds_dwordx4 v[220:221], off
	s_mov_b32 m0, s27
	s_nop 0
	global_load_lds_dwordx4 v[222:223], off
	s_waitcnt vmcnt(8)
	s_waitcnt lgkmcnt(0)
	s_barrier
; #define PG8_STAGE(bufoff, gbase, voff) do { _Pragma("unroll") for (int _i = 0; _i < 2; ++_i) \
;         __builtin_amdgcn_global_load_lds((const unsigned*)((const char*)(gbase) + (voff)[_i]), (PG8_LAS unsigned*)(lds + (bufoff) + ldsw + _i * 8192), 16, 0, 0); } while (0)
; #define PG8_LDA(dst, b, h) do { _Pragma("unroll") for (int m = 0; m < 4; ++m) _Pragma("unroll") for (int k = 0; k < 2; ++k) dst[m][k] = *(const PG8_LAS bf16x8*)(lds + PG8_SA(b, h) + aoff + m * 2048 + k * 1024); } while (0)
; #define PG8_LDB(dst, b, h) do { _Pragma("unroll") for (int n = 0; n < 2; ++n) _Pragma("unroll") for (int k = 0; k < 2; ++k) dst[n][k] = *(const PG8_LAS bf16x8*)(lds + PG8_SB(b, h) + boff + n * 2048 + k * 1024); } while (0)
; #define PG8_MMA(ai, bj, At, Bt) do { __builtin_amdgcn_s_setprio(1); _Pragma("unroll") for (int m = 0; m < 4; ++m) _Pragma("unroll") for (int n = 0; n < 2; ++n) _Pragma("unroll") for (int k = 0; k < 2; ++k) \
;         acc[ai][bj][m][n] = __builtin_amdgcn_mfma_f32_16x16x32_bf16(Bt[n][k], At[m][k], acc[ai][bj][m][n], 0, 0, 0); __builtin_amdgcn_s_setprio(0); } while (0)
; #define PG8_WAIT_V(n) asm volatile("s_waitcnt vmcnt(" #n ")" ::: "memory")
; #define PG8_WAIT_L(n) asm volatile("s_waitcnt lgkmcnt(" #n ")" ::: "memory")
; #define PG8_BAR __builtin_amdgcn_s_barrier()
; #define PG8_SCHED __builtin_amdgcn_sched_barrier(0)
; template <class Epi, class Sched>
; __device__ __forceinline__ void gemm_phase(PG8_LAS unsigned char* lds, const Gemm g, const Sched& S, const Epi& E) {
;     ...
;             PG8_WAIT_V(8); PG8_WAIT_L(0); PG8_BAR; PG8_MMA(1, 0, At, B0); PG8_MMA(1, 1, At, B1); PG8_BAR; PG8_SCHED;
;             PG8_LDB(B0, 1, 0); PG8_LDB(B1, 1, 1); PG8_SCHED; PG8_LDA(At, 1, 0); PG8_STAGE(PG8_SA(0, 1), a2 + hstepA, voffA);
;             PG8_WAIT_V(8); PG8_WAIT_L(0); PG8_BAR; PG8_MMA(0, 0, At, B0); PG8_MMA(0, 1, At, B1); PG8_BAR; PG8_SCHED;
	s_setprio 1
	s_waitcnt lgkmcnt(0)
	v_mfma_f32_16x16x32_bf16 v[60:63], v[144:147], v[184:187], v[60:63]
	v_mfma_f32_16x16x32_bf16 v[56:59], v[160:163], v[184:187], v[56:59]
	v_mfma_f32_16x16x32_bf16 v[48:51], v[144:147], v[192:195], v[48:51]
	v_mfma_f32_16x16x32_bf16 v[40:43], v[160:163], v[192:195], v[40:43]
	v_mfma_f32_16x16x32_bf16 v[28:31], v[144:147], v[204:207], v[28:31]
	v_mfma_f32_16x16x32_bf16 v[24:27], v[160:163], v[204:207], v[24:27]
	v_mfma_f32_16x16x32_bf16 v[12:15], v[144:147], v[212:215], v[12:15]
	v_mfma_f32_16x16x32_bf16 v[8:11], v[160:163], v[212:215], v[8:11]
	v_mfma_f32_16x16x32_bf16 v[60:63], v[156:159], v[188:191], v[60:63]
	v_mfma_f32_16x16x32_bf16 v[56:59], v[164:167], v[188:191], v[56:59]
	v_mfma_f32_16x16x32_bf16 v[48:51], v[156:159], v[200:203], v[48:51]
	v_mfma_f32_16x16x32_bf16 v[40:43], v[164:167], v[200:203], v[40:43]
	v_mfma_f32_16x16x32_bf16 v[28:31], v[156:159], v[208:211], v[28:31]
	v_mfma_f32_16x16x32_bf16 v[24:27], v[164:167], v[208:211], v[24:27]
	v_mfma_f32_16x16x32_bf16 v[12:15], v[156:159], v[216:219], v[12:15]
	v_mfma_f32_16x16x32_bf16 v[8:11], v[164:167], v[216:219], v[8:11]
	v_mfma_f32_16x16x32_bf16 v[52:55], v[168:171], v[184:187], v[52:55]
	v_mfma_f32_16x16x32_bf16 v[44:47], v[176:179], v[184:187], v[44:47]
	v_mfma_f32_16x16x32_bf16 v[36:39], v[168:171], v[192:195], v[36:39]
	v_mfma_f32_16x16x32_bf16 v[32:35], v[176:179], v[192:195], v[32:35]
	v_mfma_f32_16x16x32_bf16 v[20:23], v[168:171], v[204:207], v[20:23]
	v_mfma_f32_16x16x32_bf16 v[16:19], v[176:179], v[204:207], v[16:19]
	v_mfma_f32_16x16x32_bf16 v[4:7], v[168:171], v[212:215], v[4:7]
	v_mfma_f32_16x16x32_bf16 v[0:3], v[176:179], v[212:215], v[0:3]
	v_mfma_f32_16x16x32_bf16 v[52:55], v[172:175], v[188:191], v[52:55]
	v_mfma_f32_16x16x32_bf16 v[44:47], v[180:183], v[188:191], v[44:47]
	v_mfma_f32_16x16x32_bf16 v[36:39], v[172:175], v[200:203], v[36:39]
	v_mfma_f32_16x16x32_bf16 v[32:35], v[180:183], v[200:203], v[32:35]
	v_mfma_f32_16x16x32_bf16 v[20:23], v[172:175], v[208:211], v[20:23]
	v_mfma_f32_16x16x32_bf16 v[16:19], v[180:183], v[208:211], v[16:19]
	v_mfma_f32_16x16x32_bf16 v[4:7], v[172:175], v[216:219], v[4:7]
	v_mfma_f32_16x16x32_bf16 v[0:3], v[180:183], v[216:219], v[0:3]
	s_setprio 0
	s_barrier
	s_add_i32 s49, 0, 0x18000
	s_add_i32 s50, 0, 0x1c000
	v_add_u32_e32 v164, s49, v151
	v_add_u32_e32 v180, s50, v151
	ds_read_b128 v[144:147], v164
	ds_read_b128 v[156:159], v164 offset:1024
	ds_read_b128 v[160:163], v164 offset:2048
	ds_read_b128 v[164:167], v164 offset:3072
	ds_read_b128 v[168:171], v180
	ds_read_b128 v[172:175], v180 offset:1024
	ds_read_b128 v[176:179], v180 offset:2048
	ds_read_b128 v[180:183], v180 offset:3072
	s_add_u32 s16, s22, 0xb0000
	s_addc_u32 s17, s23, 0
	s_mov_b32 m0, s28
	v_lshl_add_u64 v[224:225], s[16:17], 0, v[128:129]
	ds_read_b128 v[184:187], v155 offset:32768
	ds_read_b128 v[188:191], v155 offset:33792
	ds_read_b128 v[192:195], v155 offset:34816
	ds_read_b128 v[200:203], v155 offset:35840
	ds_read_b128 v[204:207], v155 offset:36864
	ds_read_b128 v[208:211], v155 offset:37888
	ds_read_b128 v[212:215], v155 offset:38912
	ds_read_b128 v[216:219], v155 offset:39936
	global_load_lds_dwordx4 v[224:225], off
	v_lshl_add_u64 v[224:225], s[16:17], 0, v[132:133]
	s_mov_b32 m0, s29
	s_nop 0
	global_load_lds_dwordx4 v[224:225], off
	s_waitcnt vmcnt(8)
	s_waitcnt lgkmcnt(0)
	s_barrier
	s_setprio 1
	s_waitcnt lgkmcnt(0)
	v_mfma_f32_16x16x32_bf16 v[124:127], v[144:147], v[184:187], v[124:127]
	v_mfma_f32_16x16x32_bf16 v[120:123], v[160:163], v[184:187], v[120:123]
	v_mfma_f32_16x16x32_bf16 v[116:119], v[144:147], v[192:195], v[116:119]
	v_mfma_f32_16x16x32_bf16 v[112:115], v[160:163], v[192:195], v[112:115]
	v_mfma_f32_16x16x32_bf16 v[92:95], v[144:147], v[204:207], v[92:95]
	v_mfma_f32_16x16x32_bf16 v[88:91], v[160:163], v[204:207], v[88:91]
	v_mfma_f32_16x16x32_bf16 v[84:87], v[144:147], v[212:215], v[84:87]
	v_mfma_f32_16x16x32_bf16 v[72:75], v[160:163], v[212:215], v[72:75]
	v_mfma_f32_16x16x32_bf16 v[124:127], v[156:159], v[188:191], v[124:127]
	v_mfma_f32_16x16x32_bf16 v[120:123], v[164:167], v[188:191], v[120:123]
	v_mfma_f32_16x16x32_bf16 v[116:119], v[156:159], v[200:203], v[116:119]
	v_mfma_f32_16x16x32_bf16 v[112:115], v[164:167], v[200:203], v[112:115]
	v_mfma_f32_16x16x32_bf16 v[92:95], v[156:159], v[208:211], v[92:95]
	v_mfma_f32_16x16x32_bf16 v[88:91], v[164:167], v[208:211], v[88:91]
	v_mfma_f32_16x16x32_bf16 v[84:87], v[156:159], v[216:219], v[84:87]
	v_mfma_f32_16x16x32_bf16 v[72:75], v[164:167], v[216:219], v[72:75]
	v_mfma_f32_16x16x32_bf16 v[108:111], v[168:171], v[184:187], v[108:111]
	v_mfma_f32_16x16x32_bf16 v[104:107], v[176:179], v[184:187], v[104:107]
	v_mfma_f32_16x16x32_bf16 v[100:103], v[168:171], v[192:195], v[100:103]
	v_mfma_f32_16x16x32_bf16 v[96:99], v[176:179], v[192:195], v[96:99]
	v_mfma_f32_16x16x32_bf16 v[80:83], v[168:171], v[204:207], v[80:83]
	v_mfma_f32_16x16x32_bf16 v[76:79], v[176:179], v[204:207], v[76:79]
	v_mfma_f32_16x16x32_bf16 v[68:71], v[168:171], v[212:215], v[68:71]
	v_mfma_f32_16x16x32_bf16 v[64:67], v[176:179], v[212:215], v[64:67]
	v_mfma_f32_16x16x32_bf16 v[108:111], v[172:175], v[188:191], v[108:111]
	v_mfma_f32_16x16x32_bf16 v[104:107], v[180:183], v[188:191], v[104:107]
	v_mfma_f32_16x16x32_bf16 v[100:103], v[172:175], v[200:203], v[100:103]
	v_mfma_f32_16x16x32_bf16 v[96:99], v[180:183], v[200:203], v[96:99]
	v_mfma_f32_16x16x32_bf16 v[80:83], v[172:175], v[208:211], v[80:83]
	v_mfma_f32_16x16x32_bf16 v[76:79], v[180:183], v[208:211], v[76:79]
	v_mfma_f32_16x16x32_bf16 v[68:71], v[172:175], v[216:219], v[68:71]
	v_mfma_f32_16x16x32_bf16 v[64:67], v[180:183], v[216:219], v[64:67]
	s_setprio 0
	s_barrier
; #define PG8_STAGE(bufoff, gbase, voff) do { _Pragma("unroll") for (int _i = 0; _i < 2; ++_i) \
;         __builtin_amdgcn_global_load_lds((const unsigned*)((const char*)(gbase) + (voff)[_i]), (PG8_LAS unsigned*)(lds + (bufoff) + ldsw + _i * 8192), 16, 0, 0); } while (0)
; #define PG8_LDA(dst, b, h) do { _Pragma("unroll") for (int m = 0; m < 4; ++m) _Pragma("unroll") for (int k = 0; k < 2; ++k) dst[m][k] = *(const PG8_LAS bf16x8*)(lds + PG8_SA(b, h) + aoff + m * 2048 + k * 1024); } while (0)
; #define PG8_MMA(ai, bj, At, Bt) do { __builtin_amdgcn_s_setprio(1); _Pragma("unroll") for (int m = 0; m < 4; ++m) _Pragma("unroll") for (int n = 0; n < 2; ++n) _Pragma("unroll") for (int k = 0; k < 2; ++k) \
;         acc[ai][bj][m][n] = __builtin_amdgcn_mfma_f32_16x16x32_bf16(Bt[n][k], At[m][k], acc[ai][bj][m][n], 0, 0, 0); __builtin_amdgcn_s_setprio(0); } while (0)
; #define PG8_WAIT_V(n) asm volatile("s_waitcnt vmcnt(" #n ")" ::: "memory")
; #define PG8_WAIT_L(n) asm volatile("s_waitcnt lgkmcnt(" #n ")" ::: "memory")
; #define PG8_BAR __builtin_amdgcn_s_barrier()
; #define PG8_SCHED __builtin_amdgcn_sched_barrier(0)
; template <class Epi, class Sched>
; __device__ __forceinline__ void gemm_phase(PG8_LAS unsigned char* lds, const Gemm g, const Sched& S, const Epi& E) {
;     ...
;             PG8_LDA(At, 1, 1); PG8_STAGE(PG8_SB(1, 0), b3, voffB); PG8_STAGE(PG8_SB(1, 1), b3 + hstepB, voffB); PG8_STAGE(PG8_SA(1, 0), a3, voffA);
;             PG8_WAIT_V(8); PG8_WAIT_L(0); PG8_BAR; PG8_MMA(1, 0, At, B0); PG8_MMA(1, 1, At, B1); PG8_BAR; PG8_SCHED;
;         }
;         if (wr == 0) PG8_BAR;
	s_add_i32 s16, s49, s25
	v_lshl_add_u64 v[148:149], v[148:149], 0, s[2:3]
	s_mov_b32 m0, s16
	ds_read_b128 v[184:187], v155 offset:49152
	ds_read_b128 v[188:191], v155 offset:50176
	ds_read_b128 v[192:195], v155 offset:51200
	ds_read_b128 v[200:203], v155 offset:52224
	ds_read_b128 v[204:207], v155 offset:53248
	ds_read_b128 v[208:211], v155 offset:54272
	ds_read_b128 v[212:215], v155 offset:55296
	ds_read_b128 v[216:219], v155 offset:56320
	global_load_lds_dwordx4 v[148:149], off
	s_add_i32 m0, s16, 0x2000
	s_add_u32 s16, s20, 0xb0080
	v_lshl_add_u64 v[148:149], v[196:197], 0, s[2:3]
	s_addc_u32 s17, s21, 0
	s_add_i32 s20, s50, s25
	global_load_lds_dwordx4 v[148:149], off
	v_lshl_add_u64 v[148:149], s[16:17], 0, v[130:131]
	s_mov_b32 m0, s20
	s_nop 0
	global_load_lds_dwordx4 v[148:149], off
	v_lshl_add_u64 v[148:149], s[16:17], 0, v[134:135]
	s_add_i32 m0, s20, 0x2000
	s_nop 0
	global_load_lds_dwordx4 v[148:149], off
	v_lshl_add_u64 v[148:149], v[220:221], 0, s[2:3]
	s_mov_b32 m0, s31
	s_nop 0
	global_load_lds_dwordx4 v[148:149], off
	v_lshl_add_u64 v[148:149], v[222:223], 0, s[2:3]
	s_mov_b32 m0, s33
	s_nop 0
	global_load_lds_dwordx4 v[148:149], off
	s_waitcnt vmcnt(8)
	s_waitcnt lgkmcnt(0)
	s_barrier
	s_setprio 1
	s_waitcnt lgkmcnt(0)
	v_mfma_f32_16x16x32_bf16 v[60:63], v[144:147], v[184:187], v[60:63]
	v_mfma_f32_16x16x32_bf16 v[56:59], v[160:163], v[184:187], v[56:59]
	v_mfma_f32_16x16x32_bf16 v[48:51], v[144:147], v[192:195], v[48:51]
	v_mfma_f32_16x16x32_bf16 v[40:43], v[160:163], v[192:195], v[40:43]
	v_mfma_f32_16x16x32_bf16 v[28:31], v[144:147], v[204:207], v[28:31]
	v_mfma_f32_16x16x32_bf16 v[24:27], v[160:163], v[204:207], v[24:27]
	v_mfma_f32_16x16x32_bf16 v[12:15], v[144:147], v[212:215], v[12:15]
	v_mfma_f32_16x16x32_bf16 v[8:11], v[160:163], v[212:215], v[8:11]
	v_mfma_f32_16x16x32_bf16 v[60:63], v[156:159], v[188:191], v[60:63]
	v_mfma_f32_16x16x32_bf16 v[56:59], v[164:167], v[188:191], v[56:59]
	v_mfma_f32_16x16x32_bf16 v[48:51], v[156:159], v[200:203], v[48:51]
	v_mfma_f32_16x16x32_bf16 v[40:43], v[164:167], v[200:203], v[40:43]
	v_mfma_f32_16x16x32_bf16 v[28:31], v[156:159], v[208:211], v[28:31]
	v_mfma_f32_16x16x32_bf16 v[24:27], v[164:167], v[208:211], v[24:27]
	v_mfma_f32_16x16x32_bf16 v[12:15], v[156:159], v[216:219], v[12:15]
	v_mfma_f32_16x16x32_bf16 v[8:11], v[164:167], v[216:219], v[8:11]
	v_mfma_f32_16x16x32_bf16 v[52:55], v[168:171], v[184:187], v[52:55]
	v_mfma_f32_16x16x32_bf16 v[44:47], v[176:179], v[184:187], v[44:47]
	v_mfma_f32_16x16x32_bf16 v[36:39], v[168:171], v[192:195], v[36:39]
	v_mfma_f32_16x16x32_bf16 v[32:35], v[176:179], v[192:195], v[32:35]
	v_mfma_f32_16x16x32_bf16 v[20:23], v[168:171], v[204:207], v[20:23]
	v_mfma_f32_16x16x32_bf16 v[16:19], v[176:179], v[204:207], v[16:19]
	v_mfma_f32_16x16x32_bf16 v[4:7], v[168:171], v[212:215], v[4:7]
	v_mfma_f32_16x16x32_bf16 v[0:3], v[176:179], v[212:215], v[0:3]
	v_mfma_f32_16x16x32_bf16 v[52:55], v[172:175], v[188:191], v[52:55]
	v_mfma_f32_16x16x32_bf16 v[44:47], v[180:183], v[188:191], v[44:47]
	v_mfma_f32_16x16x32_bf16 v[36:39], v[172:175], v[200:203], v[36:39]
	v_mfma_f32_16x16x32_bf16 v[32:35], v[180:183], v[200:203], v[32:35]
	v_mfma_f32_16x16x32_bf16 v[20:23], v[172:175], v[208:211], v[20:23]
	v_mfma_f32_16x16x32_bf16 v[16:19], v[180:183], v[208:211], v[16:19]
	v_mfma_f32_16x16x32_bf16 v[4:7], v[172:175], v[216:219], v[4:7]
	v_mfma_f32_16x16x32_bf16 v[0:3], v[180:183], v[216:219], v[0:3]
	s_setprio 0
	s_barrier
	s_add_i32 s48, s48, 2
	s_add_u32 s46, s46, 0x100
	s_addc_u32 s47, s47, 0
	s_cmp_gt_u32 s48, 41
	s_mov_b64 s[16:17], s[18:19]
	s_cbranch_scc0 .LBB0_3264
	s_and_b64 vcc, exec, s[4:5]
	s_cbranch_vccz .LBB0_3267
	s_barrier
